# K-loops: per-segment s_setprio flips replaced by one static s_setprio 1 for waves 4-7 per K-loop (reset after), on top of v11
# baseline (speedup 1.0000x reference)
; #define PG8_STAGE(bufoff, gbase, voff) do { _Pragma("unroll") for (int _i = 0; _i < 2; ++_i) \
;         __builtin_amdgcn_global_load_lds((const unsigned*)((const char*)(gbase) + (voff)[_i]), (PG8_LAS unsigned*)(lds + (bufoff) + ldsw + _i * 8192), 16, 0, 0); } while (0)
; #define PG8_LDA(dst, b, h) do { _Pragma("unroll") for (int m = 0; m < 4; ++m) _Pragma("unroll") for (int k = 0; k < 2; ++k) dst[m][k] = *(const PG8_LAS bf16x8*)(lds + PG8_SA(b, h) + aoff + m * 2048 + k * 1024); } while (0)
; #define PG8_LDB(dst, b, h) do { _Pragma("unroll") for (int n = 0; n < 2; ++n) _Pragma("unroll") for (int k = 0; k < 2; ++k) dst[n][k] = *(const PG8_LAS bf16x8*)(lds + PG8_SB(b, h) + boff + n * 2048 + k * 1024); } while (0)
; #define PG8_WAIT_V(n) asm volatile("s_waitcnt vmcnt(" #n ")" ::: "memory")
; #define PG8_WAIT_L(n) asm volatile("s_waitcnt lgkmcnt(" #n ")" ::: "memory")
; #define PG8_BAR __builtin_amdgcn_s_barrier()
; #define PG8_SCHED __builtin_amdgcn_sched_barrier(0)
; template <class Epi, class Sched, bool ALIGN_EPI = false, bool SP2 = false>
; __device__ __forceinline__ void gemm_phase(PG8_LAS unsigned char* lds, const Gemm g, const Sched& S, const Epi& E, const int tid_in) {
;     ...
;         const bool has_next = S.next(ui + 1, nxt);
;         const char* nA = has_next ? (const char*)g.A + (size_t)nxt.pm * tstepA : cA; const char* nB = has_next ? (const char*)g.Bt + (size_t)nxt.pn * tstep : cB;
;         for (int t = 0; t < nt; t += 2) {
;             const bool last = (t == nt - 2);
;             const char* a1 = cA + (size_t)(t + 1) * kstep;
;             const char* a2 = last ? nA : cA + (size_t)(t + 2) * kstep; const char* b2 = last ? nB : cB + (size_t)(t + 2) * kstep;
;             const char* a3 = a2 + kstep; const char* b3 = b2 + kstep;
;             if (last && has_next) S.a_ready(nxt);
;             if constexpr (SP2) {
;             PG8_LDB(B0, 0, 0); PG8_LDB(B1, 0, 1); PG8_SCHED; PG8_LDA(At, 0, 0); PG8_STAGE(PG8_SA(1, 1), a1 + hstepA, voffA);
;             PG8_WAIT_V(8); PG8_WAIT_L(0); PG8_BAR; PG8_MMA(0, 0, At, B0); PG8_MMA(0, 1, At, B1); PG8_BAR; PG8_SCHED;
;     ...
; #pragma unroll
;         for (int a = 0; a < 2; ++a)
; #pragma unroll
;             for (int b = 0; b < 2; ++b)
; #pragma unroll
;                 for (int m = 0; m < 4; ++m)
; #pragma unroll
;                     for (int n = 0; n < 2; ++n) acc[a][b][m][n] = (f32x4){0.f, 0.f, 0.f, 0.f};
.LBB0_153:
	s_ashr_i32 s15, s14, 31
	s_lshl_b64 s[16:17], s[14:15], 20
	s_add_u32 s16, s28, s16
	s_addc_u32 s17, s29, s17
	s_and_b64 s[18:19], s[0:1], exec
	s_cselect_b32 s15, s17, s25
	s_cselect_b32 s49, s16, s24
	s_ashr_i32 s13, s12, 31
	s_lshl_b64 s[18:19], s[12:13], 20
	s_add_u32 s18, s2, s18
	s_addc_u32 s19, s3, s19
	s_and_b64 s[26:27], s[0:1], exec
	s_cselect_b32 s13, s19, s23
	s_cselect_b32 s50, s18, s22
	s_add_u32 s51, s22, 0x100
	s_addc_u32 s52, s23, 0
	s_add_u32 s22, s24, 0x80080
	v_mov_b32_e32 v0, 0
	s_addc_u32 s23, s25, 0
	s_mov_b32 s53, -2
	v_mov_b32_e32 v1, v0
	v_mov_b32_e32 v2, v0
	v_mov_b32_e32 v3, v0
	v_mov_b32_e32 v4, v0
	v_mov_b32_e32 v5, v0
	v_mov_b32_e32 v6, v0
	v_mov_b32_e32 v7, v0
	v_mov_b32_e32 v16, v0
	v_mov_b32_e32 v17, v0
	v_mov_b32_e32 v18, v0
	v_mov_b32_e32 v19, v0
	v_mov_b32_e32 v20, v0
	v_mov_b32_e32 v21, v0
	v_mov_b32_e32 v22, v0
	v_mov_b32_e32 v23, v0
	v_mov_b32_e32 v28, v0
	v_mov_b32_e32 v29, v0
	v_mov_b32_e32 v30, v0
	v_mov_b32_e32 v31, v0
	v_mov_b32_e32 v36, v0
	v_mov_b32_e32 v37, v0
	v_mov_b32_e32 v38, v0
	v_mov_b32_e32 v39, v0
	v_mov_b32_e32 v44, v0
	v_mov_b32_e32 v45, v0
	v_mov_b32_e32 v46, v0
	v_mov_b32_e32 v47, v0
	v_mov_b32_e32 v52, v0
	v_mov_b32_e32 v53, v0
	v_mov_b32_e32 v54, v0
	v_mov_b32_e32 v55, v0
	v_mov_b32_e32 v8, v0
	v_mov_b32_e32 v9, v0
	v_mov_b32_e32 v10, v0
	v_mov_b32_e32 v11, v0
	v_mov_b32_e32 v12, v0
	v_mov_b32_e32 v13, v0
	v_mov_b32_e32 v14, v0
	v_mov_b32_e32 v15, v0
	v_mov_b32_e32 v24, v0
	v_mov_b32_e32 v25, v0
	v_mov_b32_e32 v26, v0
	v_mov_b32_e32 v27, v0
	v_mov_b32_e32 v32, v0
	v_mov_b32_e32 v33, v0
	v_mov_b32_e32 v34, v0
	v_mov_b32_e32 v35, v0
	v_mov_b32_e32 v40, v0
	v_mov_b32_e32 v41, v0
	v_mov_b32_e32 v42, v0
	v_mov_b32_e32 v43, v0
	v_mov_b32_e32 v48, v0
	v_mov_b32_e32 v49, v0
	v_mov_b32_e32 v50, v0
	v_mov_b32_e32 v51, v0
	v_mov_b32_e32 v56, v0
	v_mov_b32_e32 v57, v0
	v_mov_b32_e32 v58, v0
	v_mov_b32_e32 v59, v0
	v_mov_b32_e32 v60, v0
	v_mov_b32_e32 v61, v0
	v_mov_b32_e32 v62, v0
	v_mov_b32_e32 v63, v0
	v_mov_b32_e32 v64, v0
	v_mov_b32_e32 v65, v0
	v_mov_b32_e32 v66, v0
	v_mov_b32_e32 v67, v0
	v_mov_b32_e32 v68, v0
	v_mov_b32_e32 v69, v0
	v_mov_b32_e32 v70, v0
	v_mov_b32_e32 v71, v0
	v_mov_b32_e32 v76, v0
	v_mov_b32_e32 v77, v0
	v_mov_b32_e32 v78, v0
	v_mov_b32_e32 v79, v0
	v_mov_b32_e32 v84, v0
	v_mov_b32_e32 v85, v0
	v_mov_b32_e32 v86, v0
	v_mov_b32_e32 v87, v0
	v_mov_b32_e32 v92, v0
	v_mov_b32_e32 v93, v0
	v_mov_b32_e32 v94, v0
	v_mov_b32_e32 v95, v0
	v_mov_b32_e32 v100, v0
	v_mov_b32_e32 v101, v0
	v_mov_b32_e32 v102, v0
	v_mov_b32_e32 v103, v0
	v_mov_b32_e32 v108, v0
	v_mov_b32_e32 v109, v0
	v_mov_b32_e32 v110, v0
	v_mov_b32_e32 v111, v0
	v_mov_b32_e32 v116, v0
	v_mov_b32_e32 v117, v0
	v_mov_b32_e32 v118, v0
	v_mov_b32_e32 v119, v0
	v_mov_b32_e32 v72, v0
	v_mov_b32_e32 v73, v0
	v_mov_b32_e32 v74, v0
	v_mov_b32_e32 v75, v0
	v_mov_b32_e32 v80, v0
	v_mov_b32_e32 v81, v0
	v_mov_b32_e32 v82, v0
	v_mov_b32_e32 v83, v0
	v_mov_b32_e32 v88, v0
	v_mov_b32_e32 v89, v0
	v_mov_b32_e32 v90, v0
	v_mov_b32_e32 v91, v0
	v_mov_b32_e32 v96, v0
	v_mov_b32_e32 v97, v0
	v_mov_b32_e32 v98, v0
	v_mov_b32_e32 v99, v0
	v_mov_b32_e32 v104, v0
	v_mov_b32_e32 v105, v0
	v_mov_b32_e32 v106, v0
	v_mov_b32_e32 v107, v0
	v_mov_b32_e32 v112, v0
	v_mov_b32_e32 v113, v0
	v_mov_b32_e32 v114, v0
	v_mov_b32_e32 v115, v0
	v_mov_b32_e32 v120, v0
	v_mov_b32_e32 v121, v0
	v_mov_b32_e32 v122, v0
	v_mov_b32_e32 v123, v0
	v_mov_b32_e32 v124, v0
	v_mov_b32_e32 v125, v0
	v_mov_b32_e32 v126, v0
	v_mov_b32_e32 v127, v0
	s_cmp_lt_u32 s75, 4
	s_cbranch_scc1 .Lkprio_skip_0
	s_setprio 1
.Lkprio_skip_0:
.LBB0_154:
	ds_read_b128 v[144:147], v155
	ds_read_b128 v[158:161], v155 offset:1024
	ds_read_b128 v[162:165], v155 offset:2048
	ds_read_b128 v[166:169], v155 offset:3072
	ds_read_b128 v[170:173], v156
	ds_read_b128 v[174:177], v156 offset:1024
	ds_read_b128 v[178:181], v156 offset:2048
	ds_read_b128 v[182:185], v156 offset:3072
	s_add_u32 s24, s22, 0xfff80080
	s_addc_u32 s25, s23, -1
	s_cmp_eq_u32 s53, 28
	s_cselect_b32 s27, s15, s25
	s_cselect_b32 s26, s49, s24
	s_cselect_b32 s25, s13, s52
	s_cselect_b32 s24, s50, s51
	v_lshl_add_u64 v[220:221], s[22:23], 0, v[138:139]
	s_add_i32 m0, s21, 0xc000
	ds_read_b128 v[186:189], v157
	ds_read_b128 v[190:193], v157 offset:1024
	ds_read_b128 v[194:197], v157 offset:2048
	ds_read_b128 v[198:201], v157 offset:3072
	ds_read_b128 v[202:205], v157 offset:4096
	ds_read_b128 v[206:209], v157 offset:5120
	ds_read_b128 v[210:213], v157 offset:6144
	ds_read_b128 v[214:217], v157 offset:7168
	global_load_lds_dwordx4 v[220:221], off
	v_lshl_add_u64 v[220:221], s[22:23], 0, v[136:137]
	s_add_i32 m0, s21, 0xe000
	s_nop 0
	global_load_lds_dwordx4 v[220:221], off
	s_waitcnt vmcnt(8)
	s_waitcnt lgkmcnt(0)
	s_barrier
; #define PG8_STAGE(bufoff, gbase, voff) do { _Pragma("unroll") for (int _i = 0; _i < 2; ++_i) \
;         __builtin_amdgcn_global_load_lds((const unsigned*)((const char*)(gbase) + (voff)[_i]), (PG8_LAS unsigned*)(lds + (bufoff) + ldsw + _i * 8192), 16, 0, 0); } while (0)
; #define PG8_LDA(dst, b, h) do { _Pragma("unroll") for (int m = 0; m < 4; ++m) _Pragma("unroll") for (int k = 0; k < 2; ++k) dst[m][k] = *(const PG8_LAS bf16x8*)(lds + PG8_SA(b, h) + aoff + m * 2048 + k * 1024); } while (0)
; #define PG8_MMA(ai, bj, At, Bt) do { __builtin_amdgcn_s_setprio(1); _Pragma("unroll") for (int m = 0; m < 4; ++m) _Pragma("unroll") for (int n = 0; n < 2; ++n) _Pragma("unroll") for (int k = 0; k < 2; ++k) \
;         acc[ai][bj][m][n] = __builtin_amdgcn_mfma_f32_16x16x32_bf16(Bt[n][k], At[m][k], acc[ai][bj][m][n], 0, 0, 0); __builtin_amdgcn_s_setprio(0); } while (0)
; #define PG8_WAIT_V(n) asm volatile("s_waitcnt vmcnt(" #n ")" ::: "memory")
; #define PG8_WAIT_L(n) asm volatile("s_waitcnt lgkmcnt(" #n ")" ::: "memory")
; #define PG8_BAR __builtin_amdgcn_s_barrier()
; #define PG8_SCHED __builtin_amdgcn_sched_barrier(0)
; template <class Epi, class Sched, bool ALIGN_EPI = false, bool SP2 = false>
; __device__ __forceinline__ void gemm_phase(PG8_LAS unsigned char* lds, const Gemm g, const Sched& S, const Epi& E, const int tid_in) {
;     ...
;             PG8_WAIT_V(8); PG8_WAIT_L(0); PG8_BAR; PG8_MMA(0, 0, At, B0); PG8_MMA(0, 1, At, B1); PG8_BAR; PG8_SCHED;
;             PG8_LDA(At, 0, 1); PG8_STAGE(PG8_SB(0, 0), b2, voffB); PG8_STAGE(PG8_SB(0, 1), b2 + hstep, voffB); PG8_STAGE(PG8_SA(0, 0), a2, voffA);
;             PG8_WAIT_V(8); PG8_WAIT_L(0); PG8_BAR; PG8_MMA(1, 0, At, B0); PG8_MMA(1, 1, At, B1); PG8_BAR; PG8_SCHED;
	v_mfma_f32_16x16x32_bf16 v[124:127], v[144:147], v[186:189], v[124:127]
	v_mfma_f32_16x16x32_bf16 v[120:123], v[162:165], v[186:189], v[120:123]
	v_mfma_f32_16x16x32_bf16 v[112:115], v[144:147], v[194:197], v[112:115]
	v_mfma_f32_16x16x32_bf16 v[104:107], v[162:165], v[194:197], v[104:107]
	v_mfma_f32_16x16x32_bf16 v[96:99], v[144:147], v[202:205], v[96:99]
	v_mfma_f32_16x16x32_bf16 v[88:91], v[162:165], v[202:205], v[88:91]
	v_mfma_f32_16x16x32_bf16 v[80:83], v[144:147], v[210:213], v[80:83]
	v_mfma_f32_16x16x32_bf16 v[72:75], v[162:165], v[210:213], v[72:75]
	v_mfma_f32_16x16x32_bf16 v[124:127], v[158:161], v[190:193], v[124:127]
	v_mfma_f32_16x16x32_bf16 v[120:123], v[166:169], v[190:193], v[120:123]
	v_mfma_f32_16x16x32_bf16 v[112:115], v[158:161], v[198:201], v[112:115]
	v_mfma_f32_16x16x32_bf16 v[104:107], v[166:169], v[198:201], v[104:107]
	v_mfma_f32_16x16x32_bf16 v[96:99], v[158:161], v[206:209], v[96:99]
	v_mfma_f32_16x16x32_bf16 v[88:91], v[166:169], v[206:209], v[88:91]
	v_mfma_f32_16x16x32_bf16 v[80:83], v[158:161], v[214:217], v[80:83]
	v_mfma_f32_16x16x32_bf16 v[72:75], v[166:169], v[214:217], v[72:75]
	v_mfma_f32_16x16x32_bf16 v[116:119], v[170:173], v[186:189], v[116:119]
	v_mfma_f32_16x16x32_bf16 v[108:111], v[178:181], v[186:189], v[108:111]
	v_mfma_f32_16x16x32_bf16 v[100:103], v[170:173], v[194:197], v[100:103]
	v_mfma_f32_16x16x32_bf16 v[92:95], v[178:181], v[194:197], v[92:95]
	v_mfma_f32_16x16x32_bf16 v[84:87], v[170:173], v[202:205], v[84:87]
	v_mfma_f32_16x16x32_bf16 v[76:79], v[178:181], v[202:205], v[76:79]
	v_mfma_f32_16x16x32_bf16 v[68:71], v[170:173], v[210:213], v[68:71]
	v_mfma_f32_16x16x32_bf16 v[64:67], v[178:181], v[210:213], v[64:67]
	v_mfma_f32_16x16x32_bf16 v[116:119], v[174:177], v[190:193], v[116:119]
	v_mfma_f32_16x16x32_bf16 v[108:111], v[182:185], v[190:193], v[108:111]
	v_mfma_f32_16x16x32_bf16 v[100:103], v[174:177], v[198:201], v[100:103]
	v_mfma_f32_16x16x32_bf16 v[92:95], v[182:185], v[198:201], v[92:95]
	v_mfma_f32_16x16x32_bf16 v[84:87], v[174:177], v[206:209], v[84:87]
	v_mfma_f32_16x16x32_bf16 v[76:79], v[182:185], v[206:209], v[76:79]
	v_mfma_f32_16x16x32_bf16 v[68:71], v[174:177], v[214:217], v[68:71]
	v_mfma_f32_16x16x32_bf16 v[64:67], v[182:185], v[214:217], v[64:67]
	s_barrier
	s_add_i32 s54, s41, s30
	v_lshl_add_u64 v[220:221], s[24:25], 0, v[132:133]
	s_mov_b32 m0, s54
	ds_read_b128 v[186:189], v157 offset:16384
	ds_read_b128 v[190:193], v157 offset:17408
	ds_read_b128 v[194:197], v157 offset:18432
	ds_read_b128 v[198:201], v157 offset:19456
	ds_read_b128 v[202:205], v157 offset:20480
	ds_read_b128 v[206:209], v157 offset:21504
	ds_read_b128 v[210:213], v157 offset:22528
	ds_read_b128 v[214:217], v157 offset:23552
	global_load_lds_dwordx4 v[220:221], off
	s_add_i32 m0, s54, 0x2000
	s_add_u32 s54, s24, 0x80000
	v_lshl_add_u64 v[222:223], s[24:25], 0, v[128:129]
	s_addc_u32 s55, s25, 0
	s_add_i32 s56, s42, s30
	global_load_lds_dwordx4 v[222:223], off
	v_lshl_add_u64 v[224:225], s[54:55], 0, v[132:133]
	s_mov_b32 m0, s56
	v_lshl_add_u64 v[226:227], s[26:27], 0, v[130:131]
	global_load_lds_dwordx4 v[224:225], off
	v_lshl_add_u64 v[224:225], s[54:55], 0, v[128:129]
	s_add_i32 m0, s56, 0x2000
	s_nop 0
	global_load_lds_dwordx4 v[224:225], off
	v_lshl_add_u64 v[224:225], s[26:27], 0, v[134:135]
	s_mov_b32 m0, s21
	s_nop 0
	global_load_lds_dwordx4 v[224:225], off
	s_mov_b32 m0, s34
	s_nop 0
	global_load_lds_dwordx4 v[226:227], off
	s_waitcnt vmcnt(8)
	s_waitcnt lgkmcnt(0)
	s_barrier
	v_mfma_f32_16x16x32_bf16 v[60:63], v[144:147], v[186:189], v[60:63]
	v_mfma_f32_16x16x32_bf16 v[56:59], v[162:165], v[186:189], v[56:59]
	v_mfma_f32_16x16x32_bf16 v[48:51], v[144:147], v[194:197], v[48:51]
	v_mfma_f32_16x16x32_bf16 v[40:43], v[162:165], v[194:197], v[40:43]
	v_mfma_f32_16x16x32_bf16 v[32:35], v[144:147], v[202:205], v[32:35]
	v_mfma_f32_16x16x32_bf16 v[24:27], v[162:165], v[202:205], v[24:27]
	v_mfma_f32_16x16x32_bf16 v[12:15], v[144:147], v[210:213], v[12:15]
	v_mfma_f32_16x16x32_bf16 v[8:11], v[162:165], v[210:213], v[8:11]
	v_mfma_f32_16x16x32_bf16 v[60:63], v[158:161], v[190:193], v[60:63]
	v_mfma_f32_16x16x32_bf16 v[56:59], v[166:169], v[190:193], v[56:59]
	v_mfma_f32_16x16x32_bf16 v[48:51], v[158:161], v[198:201], v[48:51]
	v_mfma_f32_16x16x32_bf16 v[40:43], v[166:169], v[198:201], v[40:43]
	v_mfma_f32_16x16x32_bf16 v[32:35], v[158:161], v[206:209], v[32:35]
	v_mfma_f32_16x16x32_bf16 v[24:27], v[166:169], v[206:209], v[24:27]
	v_mfma_f32_16x16x32_bf16 v[12:15], v[158:161], v[214:217], v[12:15]
	v_mfma_f32_16x16x32_bf16 v[8:11], v[166:169], v[214:217], v[8:11]
	v_mfma_f32_16x16x32_bf16 v[52:55], v[170:173], v[186:189], v[52:55]
	v_mfma_f32_16x16x32_bf16 v[44:47], v[178:181], v[186:189], v[44:47]
	v_mfma_f32_16x16x32_bf16 v[36:39], v[170:173], v[194:197], v[36:39]
	v_mfma_f32_16x16x32_bf16 v[28:31], v[178:181], v[194:197], v[28:31]
	v_mfma_f32_16x16x32_bf16 v[20:23], v[170:173], v[202:205], v[20:23]
	v_mfma_f32_16x16x32_bf16 v[16:19], v[178:181], v[202:205], v[16:19]
	v_mfma_f32_16x16x32_bf16 v[4:7], v[170:173], v[210:213], v[4:7]
	v_mfma_f32_16x16x32_bf16 v[0:3], v[178:181], v[210:213], v[0:3]
	v_mfma_f32_16x16x32_bf16 v[52:55], v[174:177], v[190:193], v[52:55]
	v_mfma_f32_16x16x32_bf16 v[44:47], v[182:185], v[190:193], v[44:47]
	v_mfma_f32_16x16x32_bf16 v[36:39], v[174:177], v[198:201], v[36:39]
	v_mfma_f32_16x16x32_bf16 v[28:31], v[182:185], v[198:201], v[28:31]
	v_mfma_f32_16x16x32_bf16 v[20:23], v[174:177], v[206:209], v[20:23]
	v_mfma_f32_16x16x32_bf16 v[16:19], v[182:185], v[206:209], v[16:19]
	v_mfma_f32_16x16x32_bf16 v[4:7], v[174:177], v[214:217], v[4:7]
	v_mfma_f32_16x16x32_bf16 v[0:3], v[182:185], v[214:217], v[0:3]
	s_barrier
; #define PG8_STAGE(bufoff, gbase, voff) do { _Pragma("unroll") for (int _i = 0; _i < 2; ++_i) \
;         __builtin_amdgcn_global_load_lds((const unsigned*)((const char*)(gbase) + (voff)[_i]), (PG8_LAS unsigned*)(lds + (bufoff) + ldsw + _i * 8192), 16, 0, 0); } while (0)
; #define PG8_LDA(dst, b, h) do { _Pragma("unroll") for (int m = 0; m < 4; ++m) _Pragma("unroll") for (int k = 0; k < 2; ++k) dst[m][k] = *(const PG8_LAS bf16x8*)(lds + PG8_SA(b, h) + aoff + m * 2048 + k * 1024); } while (0)
; #define PG8_LDB(dst, b, h) do { _Pragma("unroll") for (int n = 0; n < 2; ++n) _Pragma("unroll") for (int k = 0; k < 2; ++k) dst[n][k] = *(const PG8_LAS bf16x8*)(lds + PG8_SB(b, h) + boff + n * 2048 + k * 1024); } while (0)
; #define PG8_MMA(ai, bj, At, Bt) do { __builtin_amdgcn_s_setprio(1); _Pragma("unroll") for (int m = 0; m < 4; ++m) _Pragma("unroll") for (int n = 0; n < 2; ++n) _Pragma("unroll") for (int k = 0; k < 2; ++k) \
;         acc[ai][bj][m][n] = __builtin_amdgcn_mfma_f32_16x16x32_bf16(Bt[n][k], At[m][k], acc[ai][bj][m][n], 0, 0, 0); __builtin_amdgcn_s_setprio(0); } while (0)
; #define PG8_WAIT_V(n) asm volatile("s_waitcnt vmcnt(" #n ")" ::: "memory")
; #define PG8_WAIT_L(n) asm volatile("s_waitcnt lgkmcnt(" #n ")" ::: "memory")
; #define PG8_BAR __builtin_amdgcn_s_barrier()
; #define PG8_SCHED __builtin_amdgcn_sched_barrier(0)
; template <class Epi, class Sched, bool ALIGN_EPI = false, bool SP2 = false>
; __device__ __forceinline__ void gemm_phase(PG8_LAS unsigned char* lds, const Gemm g, const Sched& S, const Epi& E, const int tid_in) {
;     ...
;             PG8_LDB(B0, 1, 0); PG8_LDB(B1, 1, 1); PG8_SCHED; PG8_LDA(At, 1, 0); PG8_STAGE(PG8_SA(0, 1), a2 + hstepA, voffA);
;             PG8_WAIT_V(8); PG8_WAIT_L(0); PG8_BAR; PG8_MMA(0, 0, At, B0); PG8_MMA(0, 1, At, B1); PG8_BAR; PG8_SCHED;
	s_add_i32 s54, 0, 0x18000
	v_add_u32_e32 v148, s54, v151
	s_add_i32 s55, 0, 0x1c000
	ds_read_b128 v[144:147], v148
	ds_read_b128 v[158:161], v148 offset:1024
	ds_read_b128 v[162:165], v148 offset:2048
	ds_read_b128 v[166:169], v148 offset:3072
	v_add_u32_e32 v148, s55, v151
	ds_read_b128 v[170:173], v148
	ds_read_b128 v[174:177], v148 offset:1024
	ds_read_b128 v[178:181], v148 offset:2048
	ds_read_b128 v[182:185], v148 offset:3072
	s_add_u32 s26, s26, 0x80000
	s_addc_u32 s27, s27, 0
	s_mov_b32 m0, s35
	v_lshl_add_u64 v[228:229], s[26:27], 0, v[134:135]
	ds_read_b128 v[186:189], v157 offset:32768
	ds_read_b128 v[190:193], v157 offset:33792
	ds_read_b128 v[194:197], v157 offset:34816
	ds_read_b128 v[198:201], v157 offset:35840
	ds_read_b128 v[202:205], v157 offset:36864
	ds_read_b128 v[206:209], v157 offset:37888
	ds_read_b128 v[210:213], v157 offset:38912
	ds_read_b128 v[214:217], v157 offset:39936
	global_load_lds_dwordx4 v[228:229], off
	v_lshl_add_u64 v[228:229], s[26:27], 0, v[130:131]
	s_mov_b32 m0, s36
	s_nop 0
	global_load_lds_dwordx4 v[228:229], off
	s_waitcnt vmcnt(8)
	s_waitcnt lgkmcnt(0)
	s_barrier
	v_mfma_f32_16x16x32_bf16 v[124:127], v[144:147], v[186:189], v[124:127]
	v_mfma_f32_16x16x32_bf16 v[120:123], v[162:165], v[186:189], v[120:123]
	v_mfma_f32_16x16x32_bf16 v[112:115], v[144:147], v[194:197], v[112:115]
	v_mfma_f32_16x16x32_bf16 v[104:107], v[162:165], v[194:197], v[104:107]
	v_mfma_f32_16x16x32_bf16 v[96:99], v[144:147], v[202:205], v[96:99]
	v_mfma_f32_16x16x32_bf16 v[88:91], v[162:165], v[202:205], v[88:91]
	v_mfma_f32_16x16x32_bf16 v[80:83], v[144:147], v[210:213], v[80:83]
	v_mfma_f32_16x16x32_bf16 v[72:75], v[162:165], v[210:213], v[72:75]
	v_mfma_f32_16x16x32_bf16 v[124:127], v[158:161], v[190:193], v[124:127]
	v_mfma_f32_16x16x32_bf16 v[120:123], v[166:169], v[190:193], v[120:123]
	v_mfma_f32_16x16x32_bf16 v[112:115], v[158:161], v[198:201], v[112:115]
	v_mfma_f32_16x16x32_bf16 v[104:107], v[166:169], v[198:201], v[104:107]
	v_mfma_f32_16x16x32_bf16 v[96:99], v[158:161], v[206:209], v[96:99]
	v_mfma_f32_16x16x32_bf16 v[88:91], v[166:169], v[206:209], v[88:91]
	v_mfma_f32_16x16x32_bf16 v[80:83], v[158:161], v[214:217], v[80:83]
	v_mfma_f32_16x16x32_bf16 v[72:75], v[166:169], v[214:217], v[72:75]
	v_mfma_f32_16x16x32_bf16 v[116:119], v[170:173], v[186:189], v[116:119]
	v_mfma_f32_16x16x32_bf16 v[108:111], v[178:181], v[186:189], v[108:111]
	v_mfma_f32_16x16x32_bf16 v[100:103], v[170:173], v[194:197], v[100:103]
	v_mfma_f32_16x16x32_bf16 v[92:95], v[178:181], v[194:197], v[92:95]
	v_mfma_f32_16x16x32_bf16 v[84:87], v[170:173], v[202:205], v[84:87]
	v_mfma_f32_16x16x32_bf16 v[76:79], v[178:181], v[202:205], v[76:79]
	v_mfma_f32_16x16x32_bf16 v[68:71], v[170:173], v[210:213], v[68:71]
	v_mfma_f32_16x16x32_bf16 v[64:67], v[178:181], v[210:213], v[64:67]
	v_mfma_f32_16x16x32_bf16 v[116:119], v[174:177], v[190:193], v[116:119]
	v_mfma_f32_16x16x32_bf16 v[108:111], v[182:185], v[190:193], v[108:111]
	v_mfma_f32_16x16x32_bf16 v[100:103], v[174:177], v[198:201], v[100:103]
	v_mfma_f32_16x16x32_bf16 v[92:95], v[182:185], v[198:201], v[92:95]
	v_mfma_f32_16x16x32_bf16 v[84:87], v[174:177], v[206:209], v[84:87]
	v_mfma_f32_16x16x32_bf16 v[76:79], v[182:185], v[206:209], v[76:79]
	v_mfma_f32_16x16x32_bf16 v[68:71], v[174:177], v[214:217], v[68:71]
	v_mfma_f32_16x16x32_bf16 v[64:67], v[182:185], v[214:217], v[64:67]
	s_barrier
; #define PG8_STAGE(bufoff, gbase, voff) do { _Pragma("unroll") for (int _i = 0; _i < 2; ++_i) \
;         __builtin_amdgcn_global_load_lds((const unsigned*)((const char*)(gbase) + (voff)[_i]), (PG8_LAS unsigned*)(lds + (bufoff) + ldsw + _i * 8192), 16, 0, 0); } while (0)
; #define PG8_LDA(dst, b, h) do { _Pragma("unroll") for (int m = 0; m < 4; ++m) _Pragma("unroll") for (int k = 0; k < 2; ++k) dst[m][k] = *(const PG8_LAS bf16x8*)(lds + PG8_SA(b, h) + aoff + m * 2048 + k * 1024); } while (0)
; #define PG8_MMA(ai, bj, At, Bt) do { __builtin_amdgcn_s_setprio(1); _Pragma("unroll") for (int m = 0; m < 4; ++m) _Pragma("unroll") for (int n = 0; n < 2; ++n) _Pragma("unroll") for (int k = 0; k < 2; ++k) \
;         acc[ai][bj][m][n] = __builtin_amdgcn_mfma_f32_16x16x32_bf16(Bt[n][k], At[m][k], acc[ai][bj][m][n], 0, 0, 0); __builtin_amdgcn_s_setprio(0); } while (0)
; #define PG8_WAIT_V(n) asm volatile("s_waitcnt vmcnt(" #n ")" ::: "memory")
; #define PG8_WAIT_L(n) asm volatile("s_waitcnt lgkmcnt(" #n ")" ::: "memory")
; #define PG8_BAR __builtin_amdgcn_s_barrier()
; #define PG8_SCHED __builtin_amdgcn_sched_barrier(0)
; template <class Epi, class Sched, bool ALIGN_EPI = false, bool SP2 = false>
; __device__ __forceinline__ void gemm_phase(PG8_LAS unsigned char* lds, const Gemm g, const Sched& S, const Epi& E, const int tid_in) {
;     ...
;             PG8_LDA(At, 1, 1); PG8_STAGE(PG8_SB(1, 0), b3, voffB); PG8_STAGE(PG8_SB(1, 1), b3 + hstep, voffB); PG8_STAGE(PG8_SA(1, 0), a3, voffA);
;             PG8_WAIT_V(8); PG8_WAIT_L(0); PG8_BAR; PG8_MMA(1, 0, At, B0); PG8_MMA(1, 1, At, B1); PG8_BAR; PG8_SCHED;
;     ...
;         if constexpr (ALIGN_EPI) { if (wr == 0) PG8_BAR; }
	s_add_i32 s26, s54, s30
	v_lshl_add_u64 v[220:221], v[220:221], 0, s[8:9]
	s_mov_b32 m0, s26
	ds_read_b128 v[186:189], v157 offset:49152
	ds_read_b128 v[190:193], v157 offset:50176
	ds_read_b128 v[194:197], v157 offset:51200
	ds_read_b128 v[198:201], v157 offset:52224
	ds_read_b128 v[202:205], v157 offset:53248
	ds_read_b128 v[206:209], v157 offset:54272
	ds_read_b128 v[210:213], v157 offset:55296
	ds_read_b128 v[214:217], v157 offset:56320
	global_load_lds_dwordx4 v[220:221], off
	s_add_i32 m0, s26, 0x2000
	s_add_u32 s24, s24, 0x80080
	v_lshl_add_u64 v[220:221], v[222:223], 0, s[8:9]
	s_addc_u32 s25, s25, 0
	s_add_i32 s26, s55, s30
	global_load_lds_dwordx4 v[220:221], off
	v_lshl_add_u64 v[220:221], s[24:25], 0, v[132:133]
	s_mov_b32 m0, s26
	s_nop 0
	global_load_lds_dwordx4 v[220:221], off
	v_lshl_add_u64 v[220:221], s[24:25], 0, v[128:129]
	s_add_i32 m0, s26, 0x2000
	s_nop 0
	global_load_lds_dwordx4 v[220:221], off
	v_lshl_add_u64 v[220:221], v[224:225], 0, s[8:9]
	s_mov_b32 m0, s37
	s_nop 0
	global_load_lds_dwordx4 v[220:221], off
	v_lshl_add_u64 v[220:221], v[226:227], 0, s[8:9]
	s_mov_b32 m0, s38
	s_nop 0
	global_load_lds_dwordx4 v[220:221], off
	s_waitcnt vmcnt(8)
	s_waitcnt lgkmcnt(0)
	s_barrier
	v_mfma_f32_16x16x32_bf16 v[60:63], v[144:147], v[186:189], v[60:63]
	v_mfma_f32_16x16x32_bf16 v[56:59], v[162:165], v[186:189], v[56:59]
	v_mfma_f32_16x16x32_bf16 v[48:51], v[144:147], v[194:197], v[48:51]
	v_mfma_f32_16x16x32_bf16 v[40:43], v[162:165], v[194:197], v[40:43]
	v_mfma_f32_16x16x32_bf16 v[32:35], v[144:147], v[202:205], v[32:35]
	v_mfma_f32_16x16x32_bf16 v[24:27], v[162:165], v[202:205], v[24:27]
	v_mfma_f32_16x16x32_bf16 v[12:15], v[144:147], v[210:213], v[12:15]
	v_mfma_f32_16x16x32_bf16 v[8:11], v[162:165], v[210:213], v[8:11]
	v_mfma_f32_16x16x32_bf16 v[60:63], v[158:161], v[190:193], v[60:63]
	v_mfma_f32_16x16x32_bf16 v[56:59], v[166:169], v[190:193], v[56:59]
	v_mfma_f32_16x16x32_bf16 v[48:51], v[158:161], v[198:201], v[48:51]
	v_mfma_f32_16x16x32_bf16 v[40:43], v[166:169], v[198:201], v[40:43]
	v_mfma_f32_16x16x32_bf16 v[32:35], v[158:161], v[206:209], v[32:35]
	v_mfma_f32_16x16x32_bf16 v[24:27], v[166:169], v[206:209], v[24:27]
	v_mfma_f32_16x16x32_bf16 v[12:15], v[158:161], v[214:217], v[12:15]
	v_mfma_f32_16x16x32_bf16 v[8:11], v[166:169], v[214:217], v[8:11]
	v_mfma_f32_16x16x32_bf16 v[52:55], v[170:173], v[186:189], v[52:55]
	v_mfma_f32_16x16x32_bf16 v[44:47], v[178:181], v[186:189], v[44:47]
	v_mfma_f32_16x16x32_bf16 v[36:39], v[170:173], v[194:197], v[36:39]
	v_mfma_f32_16x16x32_bf16 v[28:31], v[178:181], v[194:197], v[28:31]
	v_mfma_f32_16x16x32_bf16 v[20:23], v[170:173], v[202:205], v[20:23]
	v_mfma_f32_16x16x32_bf16 v[16:19], v[178:181], v[202:205], v[16:19]
	v_mfma_f32_16x16x32_bf16 v[4:7], v[170:173], v[210:213], v[4:7]
	v_mfma_f32_16x16x32_bf16 v[0:3], v[178:181], v[210:213], v[0:3]
	v_mfma_f32_16x16x32_bf16 v[52:55], v[174:177], v[190:193], v[52:55]
	v_mfma_f32_16x16x32_bf16 v[44:47], v[182:185], v[190:193], v[44:47]
	v_mfma_f32_16x16x32_bf16 v[36:39], v[174:177], v[198:201], v[36:39]
	v_mfma_f32_16x16x32_bf16 v[28:31], v[182:185], v[198:201], v[28:31]
	v_mfma_f32_16x16x32_bf16 v[20:23], v[174:177], v[206:209], v[20:23]
	v_mfma_f32_16x16x32_bf16 v[16:19], v[182:185], v[206:209], v[16:19]
	v_mfma_f32_16x16x32_bf16 v[4:7], v[174:177], v[214:217], v[4:7]
	v_mfma_f32_16x16x32_bf16 v[0:3], v[182:185], v[214:217], v[0:3]
	s_barrier
	s_add_i32 s53, s53, 2
	s_add_u32 s51, s51, 0x100
	s_addc_u32 s52, s52, 0
	s_add_u32 s22, s22, 0x100
	s_addc_u32 s23, s23, 0
	s_cmp_gt_u32 s53, 29
	s_cbranch_scc0 .LBB0_154
	s_setprio 0
	s_and_b64 vcc, exec, s[10:11]
	s_cbranch_vccz .LBB0_157
	s_barrier

; #define PG8_STAGE(bufoff, gbase, voff) do { _Pragma("unroll") for (int _i = 0; _i < 2; ++_i) \
;         __builtin_amdgcn_global_load_lds((const unsigned*)((const char*)(gbase) + (voff)[_i]), (PG8_LAS unsigned*)(lds + (bufoff) + ldsw + _i * 8192), 16, 0, 0); } while (0)
; #define PG8_LDA(dst, b, h) do { _Pragma("unroll") for (int m = 0; m < 4; ++m) _Pragma("unroll") for (int k = 0; k < 2; ++k) dst[m][k] = *(const PG8_LAS bf16x8*)(lds + PG8_SA(b, h) + aoff + m * 2048 + k * 1024); } while (0)
; #define PG8_LDB(dst, b, h) do { _Pragma("unroll") for (int n = 0; n < 2; ++n) _Pragma("unroll") for (int k = 0; k < 2; ++k) dst[n][k] = *(const PG8_LAS bf16x8*)(lds + PG8_SB(b, h) + boff + n * 2048 + k * 1024); } while (0)
; #define PG8_WAIT_V(n) asm volatile("s_waitcnt vmcnt(" #n ")" ::: "memory")
; #define PG8_WAIT_L(n) asm volatile("s_waitcnt lgkmcnt(" #n ")" ::: "memory")
; #define PG8_BAR __builtin_amdgcn_s_barrier()
; #define PG8_SCHED __builtin_amdgcn_sched_barrier(0)
; template <class Epi, class Sched, bool ALIGN_EPI = false, bool SP2 = false>
; __device__ __forceinline__ void gemm_phase(PG8_LAS unsigned char* lds, const Gemm g, const Sched& S, const Epi& E, const int tid_in) {
;     ...
;         const bool has_next = S.next(ui + 1, nxt);
;         const char* nA = has_next ? (const char*)g.A + (size_t)nxt.pm * tstepA : cA; const char* nB = has_next ? (const char*)g.Bt + (size_t)nxt.pn * tstep : cB;
;         for (int t = 0; t < nt; t += 2) {
;             const bool last = (t == nt - 2);
;             const char* a1 = cA + (size_t)(t + 1) * kstep;
;             const char* a2 = last ? nA : cA + (size_t)(t + 2) * kstep; const char* b2 = last ? nB : cB + (size_t)(t + 2) * kstep;
;             const char* a3 = a2 + kstep; const char* b3 = b2 + kstep;
;             if (last && has_next) S.a_ready(nxt);
;             if constexpr (SP2) {
;             PG8_LDB(B0, 0, 0); PG8_LDB(B1, 0, 1); PG8_SCHED; PG8_LDA(At, 0, 0); PG8_STAGE(PG8_SA(1, 1), a1 + hstepA, voffA);
;             PG8_WAIT_V(8); PG8_WAIT_L(0); PG8_BAR; PG8_MMA(0, 0, At, B0); PG8_MMA(0, 1, At, B1); PG8_BAR; PG8_SCHED;
;     ...
; #pragma unroll
;         for (int a = 0; a < 2; ++a)
; #pragma unroll
;             for (int b = 0; b < 2; ++b)
; #pragma unroll
;                 for (int m = 0; m < 4; ++m)
; #pragma unroll
;                     for (int n = 0; n < 2; ++n) acc[a][b][m][n] = (f32x4){0.f, 0.f, 0.f, 0.f};
.LBB0_217:
	s_add_u32 s47, s20, 0x100
	v_mov_b32_e32 v0, 0
	s_addc_u32 s48, s21, 0
	s_mov_b32 s49, -2
	s_waitcnt lgkmcnt(0)
	v_mov_b32_e32 v1, v0
	v_mov_b32_e32 v2, v0
	v_mov_b32_e32 v3, v0
	v_mov_b32_e32 v4, v0
	v_mov_b32_e32 v5, v0
	v_mov_b32_e32 v6, v0
	v_mov_b32_e32 v7, v0
	v_mov_b32_e32 v16, v0
	v_mov_b32_e32 v17, v0
	v_mov_b32_e32 v18, v0
	v_mov_b32_e32 v19, v0
	v_mov_b32_e32 v20, v0
	v_mov_b32_e32 v21, v0
	v_mov_b32_e32 v22, v0
	v_mov_b32_e32 v23, v0
	v_mov_b32_e32 v32, v0
	v_mov_b32_e32 v33, v0
	v_mov_b32_e32 v34, v0
	v_mov_b32_e32 v35, v0
	v_mov_b32_e32 v36, v0
	v_mov_b32_e32 v37, v0
	v_mov_b32_e32 v38, v0
	v_mov_b32_e32 v39, v0
	v_mov_b32_e32 v48, v0
	v_mov_b32_e32 v49, v0
	v_mov_b32_e32 v50, v0
	v_mov_b32_e32 v51, v0
	v_mov_b32_e32 v52, v0
	v_mov_b32_e32 v53, v0
	v_mov_b32_e32 v54, v0
	v_mov_b32_e32 v55, v0
	v_mov_b32_e32 v8, v0
	v_mov_b32_e32 v9, v0
	v_mov_b32_e32 v10, v0
	v_mov_b32_e32 v11, v0
	v_mov_b32_e32 v12, v0
	v_mov_b32_e32 v13, v0
	v_mov_b32_e32 v14, v0
	v_mov_b32_e32 v15, v0
	v_mov_b32_e32 v24, v0
	v_mov_b32_e32 v25, v0
	v_mov_b32_e32 v26, v0
	v_mov_b32_e32 v27, v0
	v_mov_b32_e32 v28, v0
	v_mov_b32_e32 v29, v0
	v_mov_b32_e32 v30, v0
	v_mov_b32_e32 v31, v0
	v_mov_b32_e32 v40, v0
	v_mov_b32_e32 v41, v0
	v_mov_b32_e32 v42, v0
	v_mov_b32_e32 v43, v0
	v_mov_b32_e32 v44, v0
	v_mov_b32_e32 v45, v0
	v_mov_b32_e32 v46, v0
	v_mov_b32_e32 v47, v0
	v_mov_b32_e32 v56, v0
	v_mov_b32_e32 v57, v0
	v_mov_b32_e32 v58, v0
	v_mov_b32_e32 v59, v0
	v_mov_b32_e32 v60, v0
	v_mov_b32_e32 v61, v0
	v_mov_b32_e32 v62, v0
	v_mov_b32_e32 v63, v0
	v_mov_b32_e32 v64, v0
	v_mov_b32_e32 v65, v0
	v_mov_b32_e32 v66, v0
	v_mov_b32_e32 v67, v0
	v_mov_b32_e32 v68, v0
	v_mov_b32_e32 v69, v0
	v_mov_b32_e32 v70, v0
	v_mov_b32_e32 v71, v0
	v_mov_b32_e32 v80, v0
	v_mov_b32_e32 v81, v0
	v_mov_b32_e32 v82, v0
	v_mov_b32_e32 v83, v0
	v_mov_b32_e32 v84, v0
	v_mov_b32_e32 v85, v0
	v_mov_b32_e32 v86, v0
	v_mov_b32_e32 v87, v0
	v_mov_b32_e32 v96, v0
	v_mov_b32_e32 v97, v0
	v_mov_b32_e32 v98, v0
	v_mov_b32_e32 v99, v0
	v_mov_b32_e32 v100, v0
	v_mov_b32_e32 v101, v0
	v_mov_b32_e32 v102, v0
	v_mov_b32_e32 v103, v0
	v_mov_b32_e32 v120, v0
	v_mov_b32_e32 v121, v0
	v_mov_b32_e32 v122, v0
	v_mov_b32_e32 v123, v0
	v_mov_b32_e32 v124, v0
	v_mov_b32_e32 v125, v0
	v_mov_b32_e32 v126, v0
	v_mov_b32_e32 v127, v0
	v_mov_b32_e32 v72, v0
	v_mov_b32_e32 v73, v0
	v_mov_b32_e32 v74, v0
	v_mov_b32_e32 v75, v0
	v_mov_b32_e32 v76, v0
	v_mov_b32_e32 v77, v0
	v_mov_b32_e32 v78, v0
	v_mov_b32_e32 v79, v0
	v_mov_b32_e32 v88, v0
	v_mov_b32_e32 v89, v0
	v_mov_b32_e32 v90, v0
	v_mov_b32_e32 v91, v0
	v_mov_b32_e32 v92, v0
	v_mov_b32_e32 v93, v0
	v_mov_b32_e32 v94, v0
	v_mov_b32_e32 v95, v0
	v_mov_b32_e32 v108, v0
	v_mov_b32_e32 v109, v0
	v_mov_b32_e32 v110, v0
	v_mov_b32_e32 v111, v0
	v_mov_b32_e32 v112, v0
	v_mov_b32_e32 v113, v0
	v_mov_b32_e32 v114, v0
	v_mov_b32_e32 v115, v0
	v_mov_b32_e32 v132, v0
	v_mov_b32_e32 v133, v0
	v_mov_b32_e32 v134, v0
	v_mov_b32_e32 v135, v0
	v_mov_b32_e32 v136, v0
	v_mov_b32_e32 v137, v0
	v_mov_b32_e32 v138, v0
	v_mov_b32_e32 v139, v0
	s_cmp_lt_u32 s75, 4
	s_cbranch_scc1 .Lkprio_skip_1
	s_setprio 1
.Lkprio_skip_1:
.LBB0_218:
	ds_read_b128 v[104:107], v222
	ds_read_b128 v[116:119], v222 offset:1024
	ds_read_b128 v[128:131], v222 offset:2048
	ds_read_b128 v[140:143], v222 offset:3072
	ds_read_b128 v[144:147], v223
	ds_read_b128 v[148:151], v223 offset:1024
	ds_read_b128 v[152:155], v223 offset:2048
	ds_read_b128 v[156:159], v223 offset:3072
	s_add_u32 s20, s18, 0x100
	s_addc_u32 s21, s19, 0
	s_cmpk_eq_i32 s49, 0x52
	s_cselect_b32 s25, s5, s21
	s_cselect_b32 s24, s4, s20
	s_cselect_b32 s23, s17, s48
	s_cselect_b32 s22, s16, s47
	v_lshl_add_u64 v[208:209], s[18:19], 0, v[194:195]
	s_add_i32 m0, s31, 0xc000
	ds_read_b128 v[160:163], v224
	ds_read_b128 v[164:167], v224 offset:1024
	ds_read_b128 v[168:171], v224 offset:2048
	ds_read_b128 v[172:175], v224 offset:3072
	ds_read_b128 v[176:179], v224 offset:4096
	ds_read_b128 v[180:183], v224 offset:5120
	ds_read_b128 v[200:203], v224 offset:6144
	ds_read_b128 v[204:207], v224 offset:7168
	global_load_lds_dwordx4 v[208:209], off
	v_lshl_add_u64 v[208:209], s[18:19], 0, v[192:193]
	s_add_i32 m0, s31, 0xe000
	s_nop 0
	global_load_lds_dwordx4 v[208:209], off
	s_waitcnt vmcnt(8)
	s_waitcnt lgkmcnt(0)
	s_barrier
	v_mfma_f32_16x16x32_bf16 v[136:139], v[104:107], v[160:163], v[136:139]
	v_mfma_f32_16x16x32_bf16 v[132:135], v[128:131], v[160:163], v[132:135]
	v_mfma_f32_16x16x32_bf16 v[112:115], v[104:107], v[168:171], v[112:115]
	v_mfma_f32_16x16x32_bf16 v[108:111], v[128:131], v[168:171], v[108:111]
	v_mfma_f32_16x16x32_bf16 v[92:95], v[104:107], v[176:179], v[92:95]
	v_mfma_f32_16x16x32_bf16 v[88:91], v[128:131], v[176:179], v[88:91]
	v_mfma_f32_16x16x32_bf16 v[76:79], v[104:107], v[200:203], v[76:79]
	v_mfma_f32_16x16x32_bf16 v[72:75], v[128:131], v[200:203], v[72:75]
	v_mfma_f32_16x16x32_bf16 v[136:139], v[116:119], v[164:167], v[136:139]
	v_mfma_f32_16x16x32_bf16 v[132:135], v[140:143], v[164:167], v[132:135]
	v_mfma_f32_16x16x32_bf16 v[112:115], v[116:119], v[172:175], v[112:115]
	v_mfma_f32_16x16x32_bf16 v[108:111], v[140:143], v[172:175], v[108:111]
	v_mfma_f32_16x16x32_bf16 v[92:95], v[116:119], v[180:183], v[92:95]
	v_mfma_f32_16x16x32_bf16 v[88:91], v[140:143], v[180:183], v[88:91]
	v_mfma_f32_16x16x32_bf16 v[76:79], v[116:119], v[204:207], v[76:79]
	v_mfma_f32_16x16x32_bf16 v[72:75], v[140:143], v[204:207], v[72:75]
	v_mfma_f32_16x16x32_bf16 v[124:127], v[144:147], v[160:163], v[124:127]
	v_mfma_f32_16x16x32_bf16 v[120:123], v[152:155], v[160:163], v[120:123]
	v_mfma_f32_16x16x32_bf16 v[100:103], v[144:147], v[168:171], v[100:103]
	v_mfma_f32_16x16x32_bf16 v[96:99], v[152:155], v[168:171], v[96:99]
	v_mfma_f32_16x16x32_bf16 v[84:87], v[144:147], v[176:179], v[84:87]
	v_mfma_f32_16x16x32_bf16 v[80:83], v[152:155], v[176:179], v[80:83]
	v_mfma_f32_16x16x32_bf16 v[68:71], v[144:147], v[200:203], v[68:71]
	v_mfma_f32_16x16x32_bf16 v[64:67], v[152:155], v[200:203], v[64:67]
	v_mfma_f32_16x16x32_bf16 v[124:127], v[148:151], v[164:167], v[124:127]
	v_mfma_f32_16x16x32_bf16 v[120:123], v[156:159], v[164:167], v[120:123]
	v_mfma_f32_16x16x32_bf16 v[100:103], v[148:151], v[172:175], v[100:103]
	v_mfma_f32_16x16x32_bf16 v[96:99], v[156:159], v[172:175], v[96:99]
	v_mfma_f32_16x16x32_bf16 v[84:87], v[148:151], v[180:183], v[84:87]
	v_mfma_f32_16x16x32_bf16 v[80:83], v[156:159], v[180:183], v[80:83]
	v_mfma_f32_16x16x32_bf16 v[68:71], v[148:151], v[204:207], v[68:71]
	v_mfma_f32_16x16x32_bf16 v[64:67], v[156:159], v[204:207], v[64:67]
	s_barrier
; #define PG8_STAGE(bufoff, gbase, voff) do { _Pragma("unroll") for (int _i = 0; _i < 2; ++_i) \
;         __builtin_amdgcn_global_load_lds((const unsigned*)((const char*)(gbase) + (voff)[_i]), (PG8_LAS unsigned*)(lds + (bufoff) + ldsw + _i * 8192), 16, 0, 0); } while (0)
; #define PG8_LDA(dst, b, h) do { _Pragma("unroll") for (int m = 0; m < 4; ++m) _Pragma("unroll") for (int k = 0; k < 2; ++k) dst[m][k] = *(const PG8_LAS bf16x8*)(lds + PG8_SA(b, h) + aoff + m * 2048 + k * 1024); } while (0)
; #define PG8_LDB(dst, b, h) do { _Pragma("unroll") for (int n = 0; n < 2; ++n) _Pragma("unroll") for (int k = 0; k < 2; ++k) dst[n][k] = *(const PG8_LAS bf16x8*)(lds + PG8_SB(b, h) + boff + n * 2048 + k * 1024); } while (0)
; #define PG8_MMA(ai, bj, At, Bt) do { __builtin_amdgcn_s_setprio(1); _Pragma("unroll") for (int m = 0; m < 4; ++m) _Pragma("unroll") for (int n = 0; n < 2; ++n) _Pragma("unroll") for (int k = 0; k < 2; ++k) \
;         acc[ai][bj][m][n] = __builtin_amdgcn_mfma_f32_16x16x32_bf16(Bt[n][k], At[m][k], acc[ai][bj][m][n], 0, 0, 0); __builtin_amdgcn_s_setprio(0); } while (0)
; #define PG8_WAIT_V(n) asm volatile("s_waitcnt vmcnt(" #n ")" ::: "memory")
; #define PG8_WAIT_L(n) asm volatile("s_waitcnt lgkmcnt(" #n ")" ::: "memory")
; #define PG8_BAR __builtin_amdgcn_s_barrier()
; #define PG8_SCHED __builtin_amdgcn_sched_barrier(0)
; template <class Epi, class Sched, bool ALIGN_EPI = false, bool SP2 = false>
; __device__ __forceinline__ void gemm_phase(PG8_LAS unsigned char* lds, const Gemm g, const Sched& S, const Epi& E, const int tid_in) {
;     ...
;             PG8_LDA(At, 0, 1); PG8_STAGE(PG8_SB(0, 0), b2, voffB); PG8_STAGE(PG8_SB(0, 1), b2 + hstep, voffB); PG8_STAGE(PG8_SA(0, 0), a2, voffA);
;             PG8_WAIT_V(8); PG8_WAIT_L(0); PG8_BAR; PG8_MMA(1, 0, At, B0); PG8_MMA(1, 1, At, B1); PG8_BAR; PG8_SCHED;
;             PG8_LDB(B0, 1, 0); PG8_LDB(B1, 1, 1); PG8_SCHED; PG8_LDA(At, 1, 0); PG8_STAGE(PG8_SA(0, 1), a2 + hstepA, voffA);
;             PG8_WAIT_V(8); PG8_WAIT_L(0); PG8_BAR; PG8_MMA(0, 0, At, B0); PG8_MMA(0, 1, At, B1); PG8_BAR; PG8_SCHED;
	s_add_i32 s18, s41, s30
	v_lshl_add_u64 v[208:209], s[22:23], 0, v[186:187]
	s_mov_b32 m0, s18
	ds_read_b128 v[160:163], v224 offset:16384
	ds_read_b128 v[164:167], v224 offset:17408
	ds_read_b128 v[168:171], v224 offset:18432
	ds_read_b128 v[172:175], v224 offset:19456
	ds_read_b128 v[176:179], v224 offset:20480
	ds_read_b128 v[180:183], v224 offset:21504
	ds_read_b128 v[200:203], v224 offset:22528
	ds_read_b128 v[204:207], v224 offset:23552
	global_load_lds_dwordx4 v[208:209], off
	s_add_i32 m0, s18, 0x2000
	s_add_u32 s18, s22, 0x158000
	v_lshl_add_u64 v[210:211], s[22:23], 0, v[190:191]
	s_addc_u32 s19, s23, 0
	s_add_i32 s50, s42, s30
	global_load_lds_dwordx4 v[210:211], off
	v_lshl_add_u64 v[212:213], s[18:19], 0, v[186:187]
	s_mov_b32 m0, s50
	v_lshl_add_u64 v[214:215], s[24:25], 0, v[188:189]
	global_load_lds_dwordx4 v[212:213], off
	v_lshl_add_u64 v[212:213], s[18:19], 0, v[190:191]
	s_add_i32 m0, s50, 0x2000
	s_nop 0
	global_load_lds_dwordx4 v[212:213], off
	v_lshl_add_u64 v[212:213], s[24:25], 0, v[184:185]
	s_mov_b32 m0, s31
	s_nop 0
	global_load_lds_dwordx4 v[212:213], off
	s_mov_b32 m0, s33
	s_nop 0
	global_load_lds_dwordx4 v[214:215], off
	s_waitcnt vmcnt(8)
	s_waitcnt lgkmcnt(0)
	s_barrier
	v_mfma_f32_16x16x32_bf16 v[60:63], v[104:107], v[160:163], v[60:63]
	v_mfma_f32_16x16x32_bf16 v[56:59], v[128:131], v[160:163], v[56:59]
	v_mfma_f32_16x16x32_bf16 v[44:47], v[104:107], v[168:171], v[44:47]
	v_mfma_f32_16x16x32_bf16 v[40:43], v[128:131], v[168:171], v[40:43]
	v_mfma_f32_16x16x32_bf16 v[28:31], v[104:107], v[176:179], v[28:31]
	v_mfma_f32_16x16x32_bf16 v[24:27], v[128:131], v[176:179], v[24:27]
	v_mfma_f32_16x16x32_bf16 v[12:15], v[104:107], v[200:203], v[12:15]
	v_mfma_f32_16x16x32_bf16 v[8:11], v[128:131], v[200:203], v[8:11]
	v_mfma_f32_16x16x32_bf16 v[60:63], v[116:119], v[164:167], v[60:63]
	v_mfma_f32_16x16x32_bf16 v[56:59], v[140:143], v[164:167], v[56:59]
	v_mfma_f32_16x16x32_bf16 v[44:47], v[116:119], v[172:175], v[44:47]
	v_mfma_f32_16x16x32_bf16 v[40:43], v[140:143], v[172:175], v[40:43]
	v_mfma_f32_16x16x32_bf16 v[28:31], v[116:119], v[180:183], v[28:31]
	v_mfma_f32_16x16x32_bf16 v[24:27], v[140:143], v[180:183], v[24:27]
	v_mfma_f32_16x16x32_bf16 v[12:15], v[116:119], v[204:207], v[12:15]
	v_mfma_f32_16x16x32_bf16 v[8:11], v[140:143], v[204:207], v[8:11]
	v_mfma_f32_16x16x32_bf16 v[52:55], v[144:147], v[160:163], v[52:55]
	v_mfma_f32_16x16x32_bf16 v[48:51], v[152:155], v[160:163], v[48:51]
	v_mfma_f32_16x16x32_bf16 v[36:39], v[144:147], v[168:171], v[36:39]
	v_mfma_f32_16x16x32_bf16 v[32:35], v[152:155], v[168:171], v[32:35]
	v_mfma_f32_16x16x32_bf16 v[20:23], v[144:147], v[176:179], v[20:23]
	v_mfma_f32_16x16x32_bf16 v[16:19], v[152:155], v[176:179], v[16:19]
	v_mfma_f32_16x16x32_bf16 v[4:7], v[144:147], v[200:203], v[4:7]
	v_mfma_f32_16x16x32_bf16 v[0:3], v[152:155], v[200:203], v[0:3]
	v_mfma_f32_16x16x32_bf16 v[52:55], v[148:151], v[164:167], v[52:55]
	v_mfma_f32_16x16x32_bf16 v[48:51], v[156:159], v[164:167], v[48:51]
	v_mfma_f32_16x16x32_bf16 v[36:39], v[148:151], v[172:175], v[36:39]
	v_mfma_f32_16x16x32_bf16 v[32:35], v[156:159], v[172:175], v[32:35]
	v_mfma_f32_16x16x32_bf16 v[20:23], v[148:151], v[180:183], v[20:23]
	v_mfma_f32_16x16x32_bf16 v[16:19], v[156:159], v[180:183], v[16:19]
	v_mfma_f32_16x16x32_bf16 v[4:7], v[148:151], v[204:207], v[4:7]
	v_mfma_f32_16x16x32_bf16 v[0:3], v[156:159], v[204:207], v[0:3]
	s_barrier
	s_add_i32 s50, 0, 0x18000
	s_add_i32 s51, 0, 0x1c000
	v_add_u32_e32 v140, s50, v220
	v_add_u32_e32 v156, s51, v220
	ds_read_b128 v[104:107], v140
	ds_read_b128 v[116:119], v140 offset:1024
	ds_read_b128 v[128:131], v140 offset:2048
	ds_read_b128 v[140:143], v140 offset:3072
	ds_read_b128 v[144:147], v156
	ds_read_b128 v[148:151], v156 offset:1024
	ds_read_b128 v[152:155], v156 offset:2048
	ds_read_b128 v[156:159], v156 offset:3072
	s_add_u32 s18, s24, 0x158000
	s_addc_u32 s19, s25, 0
	s_mov_b32 m0, s34
	v_lshl_add_u64 v[216:217], s[18:19], 0, v[184:185]
	ds_read_b128 v[160:163], v224 offset:32768
	ds_read_b128 v[164:167], v224 offset:33792
	ds_read_b128 v[168:171], v224 offset:34816
	ds_read_b128 v[172:175], v224 offset:35840
	ds_read_b128 v[176:179], v224 offset:36864
	ds_read_b128 v[180:183], v224 offset:37888
	ds_read_b128 v[200:203], v224 offset:38912
	ds_read_b128 v[204:207], v224 offset:39936
	global_load_lds_dwordx4 v[216:217], off
	v_lshl_add_u64 v[216:217], s[18:19], 0, v[188:189]
	s_mov_b32 m0, s35
	s_nop 0
	global_load_lds_dwordx4 v[216:217], off
	s_waitcnt vmcnt(8)
	s_waitcnt lgkmcnt(0)
	s_barrier
; #define PG8_STAGE(bufoff, gbase, voff) do { _Pragma("unroll") for (int _i = 0; _i < 2; ++_i) \
;         __builtin_amdgcn_global_load_lds((const unsigned*)((const char*)(gbase) + (voff)[_i]), (PG8_LAS unsigned*)(lds + (bufoff) + ldsw + _i * 8192), 16, 0, 0); } while (0)
; #define PG8_LDA(dst, b, h) do { _Pragma("unroll") for (int m = 0; m < 4; ++m) _Pragma("unroll") for (int k = 0; k < 2; ++k) dst[m][k] = *(const PG8_LAS bf16x8*)(lds + PG8_SA(b, h) + aoff + m * 2048 + k * 1024); } while (0)
; #define PG8_MMA(ai, bj, At, Bt) do { __builtin_amdgcn_s_setprio(1); _Pragma("unroll") for (int m = 0; m < 4; ++m) _Pragma("unroll") for (int n = 0; n < 2; ++n) _Pragma("unroll") for (int k = 0; k < 2; ++k) \
;         acc[ai][bj][m][n] = __builtin_amdgcn_mfma_f32_16x16x32_bf16(Bt[n][k], At[m][k], acc[ai][bj][m][n], 0, 0, 0); __builtin_amdgcn_s_setprio(0); } while (0)
; #define PG8_WAIT_V(n) asm volatile("s_waitcnt vmcnt(" #n ")" ::: "memory")
; #define PG8_WAIT_L(n) asm volatile("s_waitcnt lgkmcnt(" #n ")" ::: "memory")
; #define PG8_BAR __builtin_amdgcn_s_barrier()
; #define PG8_SCHED __builtin_amdgcn_sched_barrier(0)
; template <class Epi, class Sched, bool ALIGN_EPI = false, bool SP2 = false>
; __device__ __forceinline__ void gemm_phase(PG8_LAS unsigned char* lds, const Gemm g, const Sched& S, const Epi& E, const int tid_in) {
;     ...
;             PG8_LDA(At, 1, 1); PG8_STAGE(PG8_SB(1, 0), b3, voffB); PG8_STAGE(PG8_SB(1, 1), b3 + hstep, voffB); PG8_STAGE(PG8_SA(1, 0), a3, voffA);
;             PG8_WAIT_V(8); PG8_WAIT_L(0); PG8_BAR; PG8_MMA(1, 0, At, B0); PG8_MMA(1, 1, At, B1); PG8_BAR; PG8_SCHED;
;     ...
;         if constexpr (ALIGN_EPI) { if (wr == 0) PG8_BAR; }
	v_mfma_f32_16x16x32_bf16 v[136:139], v[104:107], v[160:163], v[136:139]
	v_mfma_f32_16x16x32_bf16 v[132:135], v[128:131], v[160:163], v[132:135]
	v_mfma_f32_16x16x32_bf16 v[112:115], v[104:107], v[168:171], v[112:115]
	v_mfma_f32_16x16x32_bf16 v[108:111], v[128:131], v[168:171], v[108:111]
	v_mfma_f32_16x16x32_bf16 v[92:95], v[104:107], v[176:179], v[92:95]
	v_mfma_f32_16x16x32_bf16 v[88:91], v[128:131], v[176:179], v[88:91]
	v_mfma_f32_16x16x32_bf16 v[76:79], v[104:107], v[200:203], v[76:79]
	v_mfma_f32_16x16x32_bf16 v[72:75], v[128:131], v[200:203], v[72:75]
	v_mfma_f32_16x16x32_bf16 v[136:139], v[116:119], v[164:167], v[136:139]
	v_mfma_f32_16x16x32_bf16 v[132:135], v[140:143], v[164:167], v[132:135]
	v_mfma_f32_16x16x32_bf16 v[112:115], v[116:119], v[172:175], v[112:115]
	v_mfma_f32_16x16x32_bf16 v[108:111], v[140:143], v[172:175], v[108:111]
	v_mfma_f32_16x16x32_bf16 v[92:95], v[116:119], v[180:183], v[92:95]
	v_mfma_f32_16x16x32_bf16 v[88:91], v[140:143], v[180:183], v[88:91]
	v_mfma_f32_16x16x32_bf16 v[76:79], v[116:119], v[204:207], v[76:79]
	v_mfma_f32_16x16x32_bf16 v[72:75], v[140:143], v[204:207], v[72:75]
	v_mfma_f32_16x16x32_bf16 v[124:127], v[144:147], v[160:163], v[124:127]
	v_mfma_f32_16x16x32_bf16 v[120:123], v[152:155], v[160:163], v[120:123]
	v_mfma_f32_16x16x32_bf16 v[100:103], v[144:147], v[168:171], v[100:103]
	v_mfma_f32_16x16x32_bf16 v[96:99], v[152:155], v[168:171], v[96:99]
	v_mfma_f32_16x16x32_bf16 v[84:87], v[144:147], v[176:179], v[84:87]
	v_mfma_f32_16x16x32_bf16 v[80:83], v[152:155], v[176:179], v[80:83]
	v_mfma_f32_16x16x32_bf16 v[68:71], v[144:147], v[200:203], v[68:71]
	v_mfma_f32_16x16x32_bf16 v[64:67], v[152:155], v[200:203], v[64:67]
	v_mfma_f32_16x16x32_bf16 v[124:127], v[148:151], v[164:167], v[124:127]
	v_mfma_f32_16x16x32_bf16 v[120:123], v[156:159], v[164:167], v[120:123]
	v_mfma_f32_16x16x32_bf16 v[100:103], v[148:151], v[172:175], v[100:103]
	v_mfma_f32_16x16x32_bf16 v[96:99], v[156:159], v[172:175], v[96:99]
	v_mfma_f32_16x16x32_bf16 v[84:87], v[148:151], v[180:183], v[84:87]
	v_mfma_f32_16x16x32_bf16 v[80:83], v[156:159], v[180:183], v[80:83]
	v_mfma_f32_16x16x32_bf16 v[68:71], v[148:151], v[204:207], v[68:71]
	v_mfma_f32_16x16x32_bf16 v[64:67], v[156:159], v[204:207], v[64:67]
	s_barrier
	s_add_i32 s18, s50, s30
	v_lshl_add_u64 v[208:209], v[208:209], 0, s[12:13]
	s_mov_b32 m0, s18
	ds_read_b128 v[160:163], v224 offset:49152
	ds_read_b128 v[164:167], v224 offset:50176
	ds_read_b128 v[168:171], v224 offset:51200
	ds_read_b128 v[172:175], v224 offset:52224
	ds_read_b128 v[176:179], v224 offset:53248
	ds_read_b128 v[180:183], v224 offset:54272
	ds_read_b128 v[200:203], v224 offset:55296
	ds_read_b128 v[204:207], v224 offset:56320
	global_load_lds_dwordx4 v[208:209], off
	s_add_i32 m0, s18, 0x2000
	s_add_u32 s18, s22, 0x158080
	v_lshl_add_u64 v[208:209], v[210:211], 0, s[12:13]
	s_addc_u32 s19, s23, 0
	s_add_i32 s22, s51, s30
	global_load_lds_dwordx4 v[208:209], off
	v_lshl_add_u64 v[208:209], s[18:19], 0, v[186:187]
	s_mov_b32 m0, s22
	s_nop 0
	global_load_lds_dwordx4 v[208:209], off
	v_lshl_add_u64 v[208:209], s[18:19], 0, v[190:191]
	s_add_i32 m0, s22, 0x2000
	s_nop 0
	global_load_lds_dwordx4 v[208:209], off
	v_lshl_add_u64 v[208:209], v[212:213], 0, s[12:13]
	s_mov_b32 m0, s37
	s_nop 0
	global_load_lds_dwordx4 v[208:209], off
	v_lshl_add_u64 v[208:209], v[214:215], 0, s[12:13]
	s_mov_b32 m0, s38
	s_nop 0
	global_load_lds_dwordx4 v[208:209], off
	s_waitcnt vmcnt(8)
	s_waitcnt lgkmcnt(0)
	s_barrier
	v_mfma_f32_16x16x32_bf16 v[60:63], v[104:107], v[160:163], v[60:63]
	v_mfma_f32_16x16x32_bf16 v[56:59], v[128:131], v[160:163], v[56:59]
	v_mfma_f32_16x16x32_bf16 v[44:47], v[104:107], v[168:171], v[44:47]
	v_mfma_f32_16x16x32_bf16 v[40:43], v[128:131], v[168:171], v[40:43]
	v_mfma_f32_16x16x32_bf16 v[28:31], v[104:107], v[176:179], v[28:31]
	v_mfma_f32_16x16x32_bf16 v[24:27], v[128:131], v[176:179], v[24:27]
	v_mfma_f32_16x16x32_bf16 v[12:15], v[104:107], v[200:203], v[12:15]
	v_mfma_f32_16x16x32_bf16 v[8:11], v[128:131], v[200:203], v[8:11]
	v_mfma_f32_16x16x32_bf16 v[60:63], v[116:119], v[164:167], v[60:63]
	v_mfma_f32_16x16x32_bf16 v[56:59], v[140:143], v[164:167], v[56:59]
	v_mfma_f32_16x16x32_bf16 v[44:47], v[116:119], v[172:175], v[44:47]
	v_mfma_f32_16x16x32_bf16 v[40:43], v[140:143], v[172:175], v[40:43]
	v_mfma_f32_16x16x32_bf16 v[28:31], v[116:119], v[180:183], v[28:31]
	v_mfma_f32_16x16x32_bf16 v[24:27], v[140:143], v[180:183], v[24:27]
	v_mfma_f32_16x16x32_bf16 v[12:15], v[116:119], v[204:207], v[12:15]
	v_mfma_f32_16x16x32_bf16 v[8:11], v[140:143], v[204:207], v[8:11]
	v_mfma_f32_16x16x32_bf16 v[52:55], v[144:147], v[160:163], v[52:55]
	v_mfma_f32_16x16x32_bf16 v[48:51], v[152:155], v[160:163], v[48:51]
	v_mfma_f32_16x16x32_bf16 v[36:39], v[144:147], v[168:171], v[36:39]
	v_mfma_f32_16x16x32_bf16 v[32:35], v[152:155], v[168:171], v[32:35]
	v_mfma_f32_16x16x32_bf16 v[20:23], v[144:147], v[176:179], v[20:23]
	v_mfma_f32_16x16x32_bf16 v[16:19], v[152:155], v[176:179], v[16:19]
	v_mfma_f32_16x16x32_bf16 v[4:7], v[144:147], v[200:203], v[4:7]
	v_mfma_f32_16x16x32_bf16 v[0:3], v[152:155], v[200:203], v[0:3]
	v_mfma_f32_16x16x32_bf16 v[52:55], v[148:151], v[164:167], v[52:55]
	v_mfma_f32_16x16x32_bf16 v[48:51], v[156:159], v[164:167], v[48:51]
	v_mfma_f32_16x16x32_bf16 v[36:39], v[148:151], v[172:175], v[36:39]
	v_mfma_f32_16x16x32_bf16 v[32:35], v[156:159], v[172:175], v[32:35]
	v_mfma_f32_16x16x32_bf16 v[20:23], v[148:151], v[180:183], v[20:23]
	v_mfma_f32_16x16x32_bf16 v[16:19], v[156:159], v[180:183], v[16:19]
	v_mfma_f32_16x16x32_bf16 v[4:7], v[148:151], v[204:207], v[4:7]
	v_mfma_f32_16x16x32_bf16 v[0:3], v[156:159], v[204:207], v[0:3]
	s_barrier
	s_add_i32 s49, s49, 2
	s_add_u32 s47, s47, 0x100
	s_addc_u32 s48, s48, 0
	s_cmpk_gt_u32 s49, 0x53
	s_mov_b64 s[18:19], s[20:21]
	s_cbranch_scc0 .LBB0_218
	s_setprio 0
	s_and_b64 vcc, exec, s[14:15]
	s_cbranch_vccz .LBB0_221
	s_barrier

; #define PG8_STAGE(bufoff, gbase, voff) do { _Pragma("unroll") for (int _i = 0; _i < 2; ++_i) \
;         __builtin_amdgcn_global_load_lds((const unsigned*)((const char*)(gbase) + (voff)[_i]), (PG8_LAS unsigned*)(lds + (bufoff) + ldsw + _i * 8192), 16, 0, 0); } while (0)
; #define PG8_LDA(dst, b, h) do { _Pragma("unroll") for (int m = 0; m < 4; ++m) _Pragma("unroll") for (int k = 0; k < 2; ++k) dst[m][k] = *(const PG8_LAS bf16x8*)(lds + PG8_SA(b, h) + aoff + m * 2048 + k * 1024); } while (0)
; #define PG8_LDB(dst, b, h) do { _Pragma("unroll") for (int n = 0; n < 2; ++n) _Pragma("unroll") for (int k = 0; k < 2; ++k) dst[n][k] = *(const PG8_LAS bf16x8*)(lds + PG8_SB(b, h) + boff + n * 2048 + k * 1024); } while (0)
; #define PG8_WAIT_V(n) asm volatile("s_waitcnt vmcnt(" #n ")" ::: "memory")
; #define PG8_WAIT_L(n) asm volatile("s_waitcnt lgkmcnt(" #n ")" ::: "memory")
; #define PG8_BAR __builtin_amdgcn_s_barrier()
; #define PG8_SCHED __builtin_amdgcn_sched_barrier(0)
; template <class Epi, class Sched, bool ALIGN_EPI = false, bool SP2 = false>
; __device__ __forceinline__ void gemm_phase(PG8_LAS unsigned char* lds, const Gemm g, const Sched& S, const Epi& E, const int tid_in) {
;     ...
;         const bool has_next = S.next(ui + 1, nxt);
;         const char* nA = has_next ? (const char*)g.A + (size_t)nxt.pm * tstepA : cA; const char* nB = has_next ? (const char*)g.Bt + (size_t)nxt.pn * tstep : cB;
;         for (int t = 0; t < nt; t += 2) {
;             const bool last = (t == nt - 2);
;             const char* a1 = cA + (size_t)(t + 1) * kstep;
;             const char* a2 = last ? nA : cA + (size_t)(t + 2) * kstep; const char* b2 = last ? nB : cB + (size_t)(t + 2) * kstep;
;             const char* a3 = a2 + kstep; const char* b3 = b2 + kstep;
;             if (last && has_next) S.a_ready(nxt);
;             if constexpr (SP2) {
;             PG8_LDB(B0, 0, 0); PG8_LDB(B1, 0, 1); PG8_SCHED; PG8_LDA(At, 0, 0); PG8_STAGE(PG8_SA(1, 1), a1 + hstepA, voffA);
;             PG8_WAIT_V(8); PG8_WAIT_L(0); PG8_BAR; PG8_MMA(0, 0, At, B0); PG8_MMA(0, 1, At, B1); PG8_BAR; PG8_SCHED;
;     ...
; #pragma unroll
;         for (int a = 0; a < 2; ++a)
; #pragma unroll
;             for (int b = 0; b < 2; ++b)
; #pragma unroll
;                 for (int m = 0; m < 4; ++m)
; #pragma unroll
;                     for (int n = 0; n < 2; ++n) acc[a][b][m][n] = (f32x4){0.f, 0.f, 0.f, 0.f};
.LBB0_260:
	s_ashr_i32 s19, s18, 31
	s_lshl_b64 s[20:21], s[18:19], 20
	s_add_u32 s20, s33, s20
	s_addc_u32 s21, s34, s21
	s_and_b64 s[22:23], s[2:3], exec
	s_cselect_b32 s5, s21, s29
	s_cselect_b32 s19, s20, s28
	s_ashr_i32 s17, s16, 31
	s_lshl_b64 s[22:23], s[16:17], 20
	s_add_u32 s22, s35, s22
	s_addc_u32 s23, s36, s23
	s_and_b64 s[30:31], s[2:3], exec
	s_cselect_b32 s17, s23, s27
	s_cselect_b32 s25, s22, s26
	s_add_u32 s55, s26, 0x100
	s_addc_u32 s56, s27, 0
	s_add_u32 s26, s28, 0x80080
	v_mov_b32_e32 v0, 0
	s_addc_u32 s27, s29, 0
	s_mov_b32 s57, -2
	s_waitcnt lgkmcnt(0)
	v_mov_b32_e32 v1, v0
	v_mov_b32_e32 v2, v0
	v_mov_b32_e32 v3, v0
	v_mov_b32_e32 v4, v0
	v_mov_b32_e32 v5, v0
	v_mov_b32_e32 v6, v0
	v_mov_b32_e32 v7, v0
	v_mov_b32_e32 v16, v0
	v_mov_b32_e32 v17, v0
	v_mov_b32_e32 v18, v0
	v_mov_b32_e32 v19, v0
	v_mov_b32_e32 v20, v0
	v_mov_b32_e32 v21, v0
	v_mov_b32_e32 v22, v0
	v_mov_b32_e32 v23, v0
	v_mov_b32_e32 v32, v0
	v_mov_b32_e32 v33, v0
	v_mov_b32_e32 v34, v0
	v_mov_b32_e32 v35, v0
	v_mov_b32_e32 v36, v0
	v_mov_b32_e32 v37, v0
	v_mov_b32_e32 v38, v0
	v_mov_b32_e32 v39, v0
	v_mov_b32_e32 v48, v0
	v_mov_b32_e32 v49, v0
	v_mov_b32_e32 v50, v0
	v_mov_b32_e32 v51, v0
	v_mov_b32_e32 v52, v0
	v_mov_b32_e32 v53, v0
	v_mov_b32_e32 v54, v0
	v_mov_b32_e32 v55, v0
	v_mov_b32_e32 v8, v0
	v_mov_b32_e32 v9, v0
	v_mov_b32_e32 v10, v0
	v_mov_b32_e32 v11, v0
	v_mov_b32_e32 v12, v0
	v_mov_b32_e32 v13, v0
	v_mov_b32_e32 v14, v0
	v_mov_b32_e32 v15, v0
	v_mov_b32_e32 v24, v0
	v_mov_b32_e32 v25, v0
	v_mov_b32_e32 v26, v0
	v_mov_b32_e32 v27, v0
	v_mov_b32_e32 v28, v0
	v_mov_b32_e32 v29, v0
	v_mov_b32_e32 v30, v0
	v_mov_b32_e32 v31, v0
	v_mov_b32_e32 v40, v0
	v_mov_b32_e32 v41, v0
	v_mov_b32_e32 v42, v0
	v_mov_b32_e32 v43, v0
	v_mov_b32_e32 v44, v0
	v_mov_b32_e32 v45, v0
	v_mov_b32_e32 v46, v0
	v_mov_b32_e32 v47, v0
	v_mov_b32_e32 v56, v0
	v_mov_b32_e32 v57, v0
	v_mov_b32_e32 v58, v0
	v_mov_b32_e32 v59, v0
	v_mov_b32_e32 v60, v0
	v_mov_b32_e32 v61, v0
	v_mov_b32_e32 v62, v0
	v_mov_b32_e32 v63, v0
	v_mov_b32_e32 v64, v0
	v_mov_b32_e32 v65, v0
	v_mov_b32_e32 v66, v0
	v_mov_b32_e32 v67, v0
	v_mov_b32_e32 v68, v0
	v_mov_b32_e32 v69, v0
	v_mov_b32_e32 v70, v0
	v_mov_b32_e32 v71, v0
	v_mov_b32_e32 v80, v0
	v_mov_b32_e32 v81, v0
	v_mov_b32_e32 v82, v0
	v_mov_b32_e32 v83, v0
	v_mov_b32_e32 v84, v0
	v_mov_b32_e32 v85, v0
	v_mov_b32_e32 v86, v0
	v_mov_b32_e32 v87, v0
	v_mov_b32_e32 v96, v0
	v_mov_b32_e32 v97, v0
	v_mov_b32_e32 v98, v0
	v_mov_b32_e32 v99, v0
	v_mov_b32_e32 v100, v0
	v_mov_b32_e32 v101, v0
	v_mov_b32_e32 v102, v0
	v_mov_b32_e32 v103, v0
	v_mov_b32_e32 v112, v0
	v_mov_b32_e32 v113, v0
	v_mov_b32_e32 v114, v0
	v_mov_b32_e32 v115, v0
	v_mov_b32_e32 v116, v0
	v_mov_b32_e32 v117, v0
	v_mov_b32_e32 v118, v0
	v_mov_b32_e32 v119, v0
	v_mov_b32_e32 v72, v0
	v_mov_b32_e32 v73, v0
	v_mov_b32_e32 v74, v0
	v_mov_b32_e32 v75, v0
	v_mov_b32_e32 v76, v0
	v_mov_b32_e32 v77, v0
	v_mov_b32_e32 v78, v0
	v_mov_b32_e32 v79, v0
	v_mov_b32_e32 v88, v0
	v_mov_b32_e32 v89, v0
	v_mov_b32_e32 v90, v0
	v_mov_b32_e32 v91, v0
	v_mov_b32_e32 v92, v0
	v_mov_b32_e32 v93, v0
	v_mov_b32_e32 v94, v0
	v_mov_b32_e32 v95, v0
	v_mov_b32_e32 v104, v0
	v_mov_b32_e32 v105, v0
	v_mov_b32_e32 v106, v0
	v_mov_b32_e32 v107, v0
	v_mov_b32_e32 v108, v0
	v_mov_b32_e32 v109, v0
	v_mov_b32_e32 v110, v0
	v_mov_b32_e32 v111, v0
	v_mov_b32_e32 v120, v0
	v_mov_b32_e32 v121, v0
	v_mov_b32_e32 v122, v0
	v_mov_b32_e32 v123, v0
	v_mov_b32_e32 v124, v0
	v_mov_b32_e32 v125, v0
	v_mov_b32_e32 v126, v0
	v_mov_b32_e32 v127, v0
	s_cmp_lt_u32 s75, 4
	s_cbranch_scc1 .Lkprio_skip_2
	s_setprio 1
.Lkprio_skip_2:
.LBB0_261:
	ds_read_b128 v[144:147], v151
	ds_read_b128 v[156:159], v151 offset:1024
	ds_read_b128 v[160:163], v151 offset:2048
	ds_read_b128 v[164:167], v151 offset:3072
	ds_read_b128 v[168:171], v152
	ds_read_b128 v[172:175], v152 offset:1024
	ds_read_b128 v[176:179], v152 offset:2048
	ds_read_b128 v[180:183], v152 offset:3072
	s_add_u32 s28, s26, 0xfff80080
	s_addc_u32 s29, s27, -1
	s_cmp_eq_u32 s57, 28
	s_cselect_b32 s31, s5, s29
	s_cselect_b32 s30, s19, s28
	s_cselect_b32 s29, s17, s56
	s_cselect_b32 s28, s25, s55
	v_lshl_add_u64 v[216:217], s[26:27], 0, v[138:139]
	s_add_i32 m0, s38, 0xc000
	ds_read_b128 v[184:187], v153
	ds_read_b128 v[188:191], v153 offset:1024
	ds_read_b128 v[192:195], v153 offset:2048
	ds_read_b128 v[196:199], v153 offset:3072
	ds_read_b128 v[200:203], v153 offset:4096
	ds_read_b128 v[204:207], v153 offset:5120
	ds_read_b128 v[208:211], v153 offset:6144
	ds_read_b128 v[212:215], v153 offset:7168
	global_load_lds_dwordx4 v[216:217], off
	v_lshl_add_u64 v[216:217], s[26:27], 0, v[136:137]
	s_add_i32 m0, s38, 0xe000
	s_nop 0
	global_load_lds_dwordx4 v[216:217], off
	s_waitcnt vmcnt(8)
	s_waitcnt lgkmcnt(0)
	s_barrier
; #define PG8_STAGE(bufoff, gbase, voff) do { _Pragma("unroll") for (int _i = 0; _i < 2; ++_i) \
;         __builtin_amdgcn_global_load_lds((const unsigned*)((const char*)(gbase) + (voff)[_i]), (PG8_LAS unsigned*)(lds + (bufoff) + ldsw + _i * 8192), 16, 0, 0); } while (0)
; #define PG8_LDA(dst, b, h) do { _Pragma("unroll") for (int m = 0; m < 4; ++m) _Pragma("unroll") for (int k = 0; k < 2; ++k) dst[m][k] = *(const PG8_LAS bf16x8*)(lds + PG8_SA(b, h) + aoff + m * 2048 + k * 1024); } while (0)
; #define PG8_MMA(ai, bj, At, Bt) do { __builtin_amdgcn_s_setprio(1); _Pragma("unroll") for (int m = 0; m < 4; ++m) _Pragma("unroll") for (int n = 0; n < 2; ++n) _Pragma("unroll") for (int k = 0; k < 2; ++k) \
;         acc[ai][bj][m][n] = __builtin_amdgcn_mfma_f32_16x16x32_bf16(Bt[n][k], At[m][k], acc[ai][bj][m][n], 0, 0, 0); __builtin_amdgcn_s_setprio(0); } while (0)
; #define PG8_WAIT_V(n) asm volatile("s_waitcnt vmcnt(" #n ")" ::: "memory")
; #define PG8_WAIT_L(n) asm volatile("s_waitcnt lgkmcnt(" #n ")" ::: "memory")
; #define PG8_BAR __builtin_amdgcn_s_barrier()
; #define PG8_SCHED __builtin_amdgcn_sched_barrier(0)
; template <class Epi, class Sched, bool ALIGN_EPI = false, bool SP2 = false>
; __device__ __forceinline__ void gemm_phase(PG8_LAS unsigned char* lds, const Gemm g, const Sched& S, const Epi& E, const int tid_in) {
;     ...
;             PG8_WAIT_V(8); PG8_WAIT_L(0); PG8_BAR; PG8_MMA(0, 0, At, B0); PG8_MMA(0, 1, At, B1); PG8_BAR; PG8_SCHED;
;             PG8_LDA(At, 0, 1); PG8_STAGE(PG8_SB(0, 0), b2, voffB); PG8_STAGE(PG8_SB(0, 1), b2 + hstep, voffB); PG8_STAGE(PG8_SA(0, 0), a2, voffA);
;             PG8_WAIT_V(8); PG8_WAIT_L(0); PG8_BAR; PG8_MMA(1, 0, At, B0); PG8_MMA(1, 1, At, B1); PG8_BAR; PG8_SCHED;
	v_mfma_f32_16x16x32_bf16 v[124:127], v[144:147], v[184:187], v[124:127]
	v_mfma_f32_16x16x32_bf16 v[120:123], v[160:163], v[184:187], v[120:123]
	v_mfma_f32_16x16x32_bf16 v[108:111], v[144:147], v[192:195], v[108:111]
	v_mfma_f32_16x16x32_bf16 v[104:107], v[160:163], v[192:195], v[104:107]
	v_mfma_f32_16x16x32_bf16 v[92:95], v[144:147], v[200:203], v[92:95]
	v_mfma_f32_16x16x32_bf16 v[88:91], v[160:163], v[200:203], v[88:91]
	v_mfma_f32_16x16x32_bf16 v[76:79], v[144:147], v[208:211], v[76:79]
	v_mfma_f32_16x16x32_bf16 v[72:75], v[160:163], v[208:211], v[72:75]
	v_mfma_f32_16x16x32_bf16 v[124:127], v[156:159], v[188:191], v[124:127]
	v_mfma_f32_16x16x32_bf16 v[120:123], v[164:167], v[188:191], v[120:123]
	v_mfma_f32_16x16x32_bf16 v[108:111], v[156:159], v[196:199], v[108:111]
	v_mfma_f32_16x16x32_bf16 v[104:107], v[164:167], v[196:199], v[104:107]
	v_mfma_f32_16x16x32_bf16 v[92:95], v[156:159], v[204:207], v[92:95]
	v_mfma_f32_16x16x32_bf16 v[88:91], v[164:167], v[204:207], v[88:91]
	v_mfma_f32_16x16x32_bf16 v[76:79], v[156:159], v[212:215], v[76:79]
	v_mfma_f32_16x16x32_bf16 v[72:75], v[164:167], v[212:215], v[72:75]
	v_mfma_f32_16x16x32_bf16 v[116:119], v[168:171], v[184:187], v[116:119]
	v_mfma_f32_16x16x32_bf16 v[112:115], v[176:179], v[184:187], v[112:115]
	v_mfma_f32_16x16x32_bf16 v[100:103], v[168:171], v[192:195], v[100:103]
	v_mfma_f32_16x16x32_bf16 v[96:99], v[176:179], v[192:195], v[96:99]
	v_mfma_f32_16x16x32_bf16 v[84:87], v[168:171], v[200:203], v[84:87]
	v_mfma_f32_16x16x32_bf16 v[80:83], v[176:179], v[200:203], v[80:83]
	v_mfma_f32_16x16x32_bf16 v[68:71], v[168:171], v[208:211], v[68:71]
	v_mfma_f32_16x16x32_bf16 v[64:67], v[176:179], v[208:211], v[64:67]
	v_mfma_f32_16x16x32_bf16 v[116:119], v[172:175], v[188:191], v[116:119]
	v_mfma_f32_16x16x32_bf16 v[112:115], v[180:183], v[188:191], v[112:115]
	v_mfma_f32_16x16x32_bf16 v[100:103], v[172:175], v[196:199], v[100:103]
	v_mfma_f32_16x16x32_bf16 v[96:99], v[180:183], v[196:199], v[96:99]
	v_mfma_f32_16x16x32_bf16 v[84:87], v[172:175], v[204:207], v[84:87]
	v_mfma_f32_16x16x32_bf16 v[80:83], v[180:183], v[204:207], v[80:83]
	v_mfma_f32_16x16x32_bf16 v[68:71], v[172:175], v[212:215], v[68:71]
	v_mfma_f32_16x16x32_bf16 v[64:67], v[180:183], v[212:215], v[64:67]
	s_barrier
	s_add_i32 s58, s48, s37
	v_lshl_add_u64 v[216:217], s[28:29], 0, v[130:131]
	s_mov_b32 m0, s58
	ds_read_b128 v[184:187], v153 offset:16384
	ds_read_b128 v[188:191], v153 offset:17408
	ds_read_b128 v[192:195], v153 offset:18432
	ds_read_b128 v[196:199], v153 offset:19456
	ds_read_b128 v[200:203], v153 offset:20480
	ds_read_b128 v[204:207], v153 offset:21504
	ds_read_b128 v[208:211], v153 offset:22528
	ds_read_b128 v[212:215], v153 offset:23552
	global_load_lds_dwordx4 v[216:217], off
	s_add_i32 m0, s58, 0x2000
	s_add_u32 s58, s28, 0x80000
	v_lshl_add_u64 v[218:219], s[28:29], 0, v[134:135]
	s_addc_u32 s59, s29, 0
	s_add_i32 s60, s49, s37
	global_load_lds_dwordx4 v[218:219], off
	v_lshl_add_u64 v[220:221], s[58:59], 0, v[130:131]
	s_mov_b32 m0, s60
	v_lshl_add_u64 v[222:223], s[30:31], 0, v[132:133]
	global_load_lds_dwordx4 v[220:221], off
	v_lshl_add_u64 v[220:221], s[58:59], 0, v[134:135]
	s_add_i32 m0, s60, 0x2000
	s_nop 0
	global_load_lds_dwordx4 v[220:221], off
	v_lshl_add_u64 v[220:221], s[30:31], 0, v[128:129]
	s_mov_b32 m0, s38
	s_nop 0
	global_load_lds_dwordx4 v[220:221], off
	s_mov_b32 m0, s39
	s_nop 0
	global_load_lds_dwordx4 v[222:223], off
	s_waitcnt vmcnt(8)
	s_waitcnt lgkmcnt(0)
	s_barrier
	v_mfma_f32_16x16x32_bf16 v[60:63], v[144:147], v[184:187], v[60:63]
	v_mfma_f32_16x16x32_bf16 v[56:59], v[160:163], v[184:187], v[56:59]
	v_mfma_f32_16x16x32_bf16 v[44:47], v[144:147], v[192:195], v[44:47]
	v_mfma_f32_16x16x32_bf16 v[40:43], v[160:163], v[192:195], v[40:43]
	v_mfma_f32_16x16x32_bf16 v[28:31], v[144:147], v[200:203], v[28:31]
	v_mfma_f32_16x16x32_bf16 v[24:27], v[160:163], v[200:203], v[24:27]
	v_mfma_f32_16x16x32_bf16 v[12:15], v[144:147], v[208:211], v[12:15]
	v_mfma_f32_16x16x32_bf16 v[8:11], v[160:163], v[208:211], v[8:11]
	v_mfma_f32_16x16x32_bf16 v[60:63], v[156:159], v[188:191], v[60:63]
	v_mfma_f32_16x16x32_bf16 v[56:59], v[164:167], v[188:191], v[56:59]
	v_mfma_f32_16x16x32_bf16 v[44:47], v[156:159], v[196:199], v[44:47]
	v_mfma_f32_16x16x32_bf16 v[40:43], v[164:167], v[196:199], v[40:43]
	v_mfma_f32_16x16x32_bf16 v[28:31], v[156:159], v[204:207], v[28:31]
	v_mfma_f32_16x16x32_bf16 v[24:27], v[164:167], v[204:207], v[24:27]
	v_mfma_f32_16x16x32_bf16 v[12:15], v[156:159], v[212:215], v[12:15]
	v_mfma_f32_16x16x32_bf16 v[8:11], v[164:167], v[212:215], v[8:11]
	v_mfma_f32_16x16x32_bf16 v[52:55], v[168:171], v[184:187], v[52:55]
	v_mfma_f32_16x16x32_bf16 v[48:51], v[176:179], v[184:187], v[48:51]
	v_mfma_f32_16x16x32_bf16 v[36:39], v[168:171], v[192:195], v[36:39]
	v_mfma_f32_16x16x32_bf16 v[32:35], v[176:179], v[192:195], v[32:35]
	v_mfma_f32_16x16x32_bf16 v[20:23], v[168:171], v[200:203], v[20:23]
	v_mfma_f32_16x16x32_bf16 v[16:19], v[176:179], v[200:203], v[16:19]
	v_mfma_f32_16x16x32_bf16 v[4:7], v[168:171], v[208:211], v[4:7]
	v_mfma_f32_16x16x32_bf16 v[0:3], v[176:179], v[208:211], v[0:3]
	v_mfma_f32_16x16x32_bf16 v[52:55], v[172:175], v[188:191], v[52:55]
	v_mfma_f32_16x16x32_bf16 v[48:51], v[180:183], v[188:191], v[48:51]
	v_mfma_f32_16x16x32_bf16 v[36:39], v[172:175], v[196:199], v[36:39]
	v_mfma_f32_16x16x32_bf16 v[32:35], v[180:183], v[196:199], v[32:35]
	v_mfma_f32_16x16x32_bf16 v[20:23], v[172:175], v[204:207], v[20:23]
	v_mfma_f32_16x16x32_bf16 v[16:19], v[180:183], v[204:207], v[16:19]
	v_mfma_f32_16x16x32_bf16 v[4:7], v[172:175], v[212:215], v[4:7]
	v_mfma_f32_16x16x32_bf16 v[0:3], v[180:183], v[212:215], v[0:3]
	s_barrier
; #define PG8_STAGE(bufoff, gbase, voff) do { _Pragma("unroll") for (int _i = 0; _i < 2; ++_i) \
;         __builtin_amdgcn_global_load_lds((const unsigned*)((const char*)(gbase) + (voff)[_i]), (PG8_LAS unsigned*)(lds + (bufoff) + ldsw + _i * 8192), 16, 0, 0); } while (0)
; #define PG8_LDA(dst, b, h) do { _Pragma("unroll") for (int m = 0; m < 4; ++m) _Pragma("unroll") for (int k = 0; k < 2; ++k) dst[m][k] = *(const PG8_LAS bf16x8*)(lds + PG8_SA(b, h) + aoff + m * 2048 + k * 1024); } while (0)
; #define PG8_LDB(dst, b, h) do { _Pragma("unroll") for (int n = 0; n < 2; ++n) _Pragma("unroll") for (int k = 0; k < 2; ++k) dst[n][k] = *(const PG8_LAS bf16x8*)(lds + PG8_SB(b, h) + boff + n * 2048 + k * 1024); } while (0)
; #define PG8_MMA(ai, bj, At, Bt) do { __builtin_amdgcn_s_setprio(1); _Pragma("unroll") for (int m = 0; m < 4; ++m) _Pragma("unroll") for (int n = 0; n < 2; ++n) _Pragma("unroll") for (int k = 0; k < 2; ++k) \
;         acc[ai][bj][m][n] = __builtin_amdgcn_mfma_f32_16x16x32_bf16(Bt[n][k], At[m][k], acc[ai][bj][m][n], 0, 0, 0); __builtin_amdgcn_s_setprio(0); } while (0)
; #define PG8_WAIT_V(n) asm volatile("s_waitcnt vmcnt(" #n ")" ::: "memory")
; #define PG8_WAIT_L(n) asm volatile("s_waitcnt lgkmcnt(" #n ")" ::: "memory")
; #define PG8_BAR __builtin_amdgcn_s_barrier()
; #define PG8_SCHED __builtin_amdgcn_sched_barrier(0)
; template <class Epi, class Sched, bool ALIGN_EPI = false, bool SP2 = false>
; __device__ __forceinline__ void gemm_phase(PG8_LAS unsigned char* lds, const Gemm g, const Sched& S, const Epi& E, const int tid_in) {
;     ...
;             PG8_LDB(B0, 1, 0); PG8_LDB(B1, 1, 1); PG8_SCHED; PG8_LDA(At, 1, 0); PG8_STAGE(PG8_SA(0, 1), a2 + hstepA, voffA);
;             PG8_WAIT_V(8); PG8_WAIT_L(0); PG8_BAR; PG8_MMA(0, 0, At, B0); PG8_MMA(0, 1, At, B1); PG8_BAR; PG8_SCHED;
	s_add_i32 s58, 0, 0x18000
	v_add_u32_e32 v155, s58, v149
	s_add_i32 s59, 0, 0x1c000
	ds_read_b128 v[144:147], v155
	ds_read_b128 v[156:159], v155 offset:1024
	ds_read_b128 v[160:163], v155 offset:2048
	ds_read_b128 v[164:167], v155 offset:3072
	v_add_u32_e32 v155, s59, v149
	ds_read_b128 v[168:171], v155
	ds_read_b128 v[172:175], v155 offset:1024
	ds_read_b128 v[176:179], v155 offset:2048
	ds_read_b128 v[180:183], v155 offset:3072
	s_add_u32 s30, s30, 0x80000
	s_addc_u32 s31, s31, 0
	s_mov_b32 m0, s40
	v_lshl_add_u64 v[224:225], s[30:31], 0, v[128:129]
	ds_read_b128 v[184:187], v153 offset:32768
	ds_read_b128 v[188:191], v153 offset:33792
	ds_read_b128 v[192:195], v153 offset:34816
	ds_read_b128 v[196:199], v153 offset:35840
	ds_read_b128 v[200:203], v153 offset:36864
	ds_read_b128 v[204:207], v153 offset:37888
	ds_read_b128 v[208:211], v153 offset:38912
	ds_read_b128 v[212:215], v153 offset:39936
	global_load_lds_dwordx4 v[224:225], off
	v_lshl_add_u64 v[224:225], s[30:31], 0, v[132:133]
	s_mov_b32 m0, s41
	s_nop 0
	global_load_lds_dwordx4 v[224:225], off
	s_waitcnt vmcnt(8)
	s_waitcnt lgkmcnt(0)
	s_barrier
	v_mfma_f32_16x16x32_bf16 v[124:127], v[144:147], v[184:187], v[124:127]
	v_mfma_f32_16x16x32_bf16 v[120:123], v[160:163], v[184:187], v[120:123]
	v_mfma_f32_16x16x32_bf16 v[108:111], v[144:147], v[192:195], v[108:111]
	v_mfma_f32_16x16x32_bf16 v[104:107], v[160:163], v[192:195], v[104:107]
	v_mfma_f32_16x16x32_bf16 v[92:95], v[144:147], v[200:203], v[92:95]
	v_mfma_f32_16x16x32_bf16 v[88:91], v[160:163], v[200:203], v[88:91]
	v_mfma_f32_16x16x32_bf16 v[76:79], v[144:147], v[208:211], v[76:79]
	v_mfma_f32_16x16x32_bf16 v[72:75], v[160:163], v[208:211], v[72:75]
	v_mfma_f32_16x16x32_bf16 v[124:127], v[156:159], v[188:191], v[124:127]
	v_mfma_f32_16x16x32_bf16 v[120:123], v[164:167], v[188:191], v[120:123]
	v_mfma_f32_16x16x32_bf16 v[108:111], v[156:159], v[196:199], v[108:111]
	v_mfma_f32_16x16x32_bf16 v[104:107], v[164:167], v[196:199], v[104:107]
	v_mfma_f32_16x16x32_bf16 v[92:95], v[156:159], v[204:207], v[92:95]
	v_mfma_f32_16x16x32_bf16 v[88:91], v[164:167], v[204:207], v[88:91]
	v_mfma_f32_16x16x32_bf16 v[76:79], v[156:159], v[212:215], v[76:79]
	v_mfma_f32_16x16x32_bf16 v[72:75], v[164:167], v[212:215], v[72:75]
	v_mfma_f32_16x16x32_bf16 v[116:119], v[168:171], v[184:187], v[116:119]
	v_mfma_f32_16x16x32_bf16 v[112:115], v[176:179], v[184:187], v[112:115]
	v_mfma_f32_16x16x32_bf16 v[100:103], v[168:171], v[192:195], v[100:103]
	v_mfma_f32_16x16x32_bf16 v[96:99], v[176:179], v[192:195], v[96:99]
	v_mfma_f32_16x16x32_bf16 v[84:87], v[168:171], v[200:203], v[84:87]
	v_mfma_f32_16x16x32_bf16 v[80:83], v[176:179], v[200:203], v[80:83]
	v_mfma_f32_16x16x32_bf16 v[68:71], v[168:171], v[208:211], v[68:71]
	v_mfma_f32_16x16x32_bf16 v[64:67], v[176:179], v[208:211], v[64:67]
	v_mfma_f32_16x16x32_bf16 v[116:119], v[172:175], v[188:191], v[116:119]
	v_mfma_f32_16x16x32_bf16 v[112:115], v[180:183], v[188:191], v[112:115]
	v_mfma_f32_16x16x32_bf16 v[100:103], v[172:175], v[196:199], v[100:103]
	v_mfma_f32_16x16x32_bf16 v[96:99], v[180:183], v[196:199], v[96:99]
	v_mfma_f32_16x16x32_bf16 v[84:87], v[172:175], v[204:207], v[84:87]
	v_mfma_f32_16x16x32_bf16 v[80:83], v[180:183], v[204:207], v[80:83]
	v_mfma_f32_16x16x32_bf16 v[68:71], v[172:175], v[212:215], v[68:71]
	v_mfma_f32_16x16x32_bf16 v[64:67], v[180:183], v[212:215], v[64:67]
	s_barrier
; #define PG8_STAGE(bufoff, gbase, voff) do { _Pragma("unroll") for (int _i = 0; _i < 2; ++_i) \
;         __builtin_amdgcn_global_load_lds((const unsigned*)((const char*)(gbase) + (voff)[_i]), (PG8_LAS unsigned*)(lds + (bufoff) + ldsw + _i * 8192), 16, 0, 0); } while (0)
; #define PG8_LDA(dst, b, h) do { _Pragma("unroll") for (int m = 0; m < 4; ++m) _Pragma("unroll") for (int k = 0; k < 2; ++k) dst[m][k] = *(const PG8_LAS bf16x8*)(lds + PG8_SA(b, h) + aoff + m * 2048 + k * 1024); } while (0)
; #define PG8_MMA(ai, bj, At, Bt) do { __builtin_amdgcn_s_setprio(1); _Pragma("unroll") for (int m = 0; m < 4; ++m) _Pragma("unroll") for (int n = 0; n < 2; ++n) _Pragma("unroll") for (int k = 0; k < 2; ++k) \
;         acc[ai][bj][m][n] = __builtin_amdgcn_mfma_f32_16x16x32_bf16(Bt[n][k], At[m][k], acc[ai][bj][m][n], 0, 0, 0); __builtin_amdgcn_s_setprio(0); } while (0)
; #define PG8_WAIT_V(n) asm volatile("s_waitcnt vmcnt(" #n ")" ::: "memory")
; #define PG8_WAIT_L(n) asm volatile("s_waitcnt lgkmcnt(" #n ")" ::: "memory")
; #define PG8_BAR __builtin_amdgcn_s_barrier()
; #define PG8_SCHED __builtin_amdgcn_sched_barrier(0)
; template <class Epi, class Sched, bool ALIGN_EPI = false, bool SP2 = false>
; __device__ __forceinline__ void gemm_phase(PG8_LAS unsigned char* lds, const Gemm g, const Sched& S, const Epi& E, const int tid_in) {
;     ...
;             PG8_LDA(At, 1, 1); PG8_STAGE(PG8_SB(1, 0), b3, voffB); PG8_STAGE(PG8_SB(1, 1), b3 + hstep, voffB); PG8_STAGE(PG8_SA(1, 0), a3, voffA);
;             PG8_WAIT_V(8); PG8_WAIT_L(0); PG8_BAR; PG8_MMA(1, 0, At, B0); PG8_MMA(1, 1, At, B1); PG8_BAR; PG8_SCHED;
;     ...
;         if constexpr (ALIGN_EPI) { if (wr == 0) PG8_BAR; }
	s_add_i32 s30, s58, s37
	v_lshl_add_u64 v[216:217], v[216:217], 0, s[12:13]
	s_mov_b32 m0, s30
	ds_read_b128 v[184:187], v153 offset:49152
	ds_read_b128 v[188:191], v153 offset:50176
	ds_read_b128 v[192:195], v153 offset:51200
	ds_read_b128 v[196:199], v153 offset:52224
	ds_read_b128 v[200:203], v153 offset:53248
	ds_read_b128 v[204:207], v153 offset:54272
	ds_read_b128 v[208:211], v153 offset:55296
	ds_read_b128 v[212:215], v153 offset:56320
	global_load_lds_dwordx4 v[216:217], off
	s_add_i32 m0, s30, 0x2000
	s_add_u32 s28, s28, 0x80080
	v_lshl_add_u64 v[216:217], v[218:219], 0, s[12:13]
	s_addc_u32 s29, s29, 0
	s_add_i32 s30, s59, s37
	global_load_lds_dwordx4 v[216:217], off
	v_lshl_add_u64 v[216:217], s[28:29], 0, v[130:131]
	s_mov_b32 m0, s30
	s_nop 0
	global_load_lds_dwordx4 v[216:217], off
	v_lshl_add_u64 v[216:217], s[28:29], 0, v[134:135]
	s_add_i32 m0, s30, 0x2000
	s_nop 0
	global_load_lds_dwordx4 v[216:217], off
	v_lshl_add_u64 v[216:217], v[220:221], 0, s[12:13]
	s_mov_b32 m0, s42
	s_nop 0
	global_load_lds_dwordx4 v[216:217], off
	v_lshl_add_u64 v[216:217], v[222:223], 0, s[12:13]
	s_mov_b32 m0, s43
	s_nop 0
	global_load_lds_dwordx4 v[216:217], off
	s_waitcnt vmcnt(8)
	s_waitcnt lgkmcnt(0)
	s_barrier
	v_mfma_f32_16x16x32_bf16 v[60:63], v[144:147], v[184:187], v[60:63]
	v_mfma_f32_16x16x32_bf16 v[56:59], v[160:163], v[184:187], v[56:59]
	v_mfma_f32_16x16x32_bf16 v[44:47], v[144:147], v[192:195], v[44:47]
	v_mfma_f32_16x16x32_bf16 v[40:43], v[160:163], v[192:195], v[40:43]
	v_mfma_f32_16x16x32_bf16 v[28:31], v[144:147], v[200:203], v[28:31]
	v_mfma_f32_16x16x32_bf16 v[24:27], v[160:163], v[200:203], v[24:27]
	v_mfma_f32_16x16x32_bf16 v[12:15], v[144:147], v[208:211], v[12:15]
	v_mfma_f32_16x16x32_bf16 v[8:11], v[160:163], v[208:211], v[8:11]
	v_mfma_f32_16x16x32_bf16 v[60:63], v[156:159], v[188:191], v[60:63]
	v_mfma_f32_16x16x32_bf16 v[56:59], v[164:167], v[188:191], v[56:59]
	v_mfma_f32_16x16x32_bf16 v[44:47], v[156:159], v[196:199], v[44:47]
	v_mfma_f32_16x16x32_bf16 v[40:43], v[164:167], v[196:199], v[40:43]
	v_mfma_f32_16x16x32_bf16 v[28:31], v[156:159], v[204:207], v[28:31]
	v_mfma_f32_16x16x32_bf16 v[24:27], v[164:167], v[204:207], v[24:27]
	v_mfma_f32_16x16x32_bf16 v[12:15], v[156:159], v[212:215], v[12:15]
	v_mfma_f32_16x16x32_bf16 v[8:11], v[164:167], v[212:215], v[8:11]
	v_mfma_f32_16x16x32_bf16 v[52:55], v[168:171], v[184:187], v[52:55]
	v_mfma_f32_16x16x32_bf16 v[48:51], v[176:179], v[184:187], v[48:51]
	v_mfma_f32_16x16x32_bf16 v[36:39], v[168:171], v[192:195], v[36:39]
	v_mfma_f32_16x16x32_bf16 v[32:35], v[176:179], v[192:195], v[32:35]
	v_mfma_f32_16x16x32_bf16 v[20:23], v[168:171], v[200:203], v[20:23]
	v_mfma_f32_16x16x32_bf16 v[16:19], v[176:179], v[200:203], v[16:19]
	v_mfma_f32_16x16x32_bf16 v[4:7], v[168:171], v[208:211], v[4:7]
	v_mfma_f32_16x16x32_bf16 v[0:3], v[176:179], v[208:211], v[0:3]
	v_mfma_f32_16x16x32_bf16 v[52:55], v[172:175], v[188:191], v[52:55]
	v_mfma_f32_16x16x32_bf16 v[48:51], v[180:183], v[188:191], v[48:51]
	v_mfma_f32_16x16x32_bf16 v[36:39], v[172:175], v[196:199], v[36:39]
	v_mfma_f32_16x16x32_bf16 v[32:35], v[180:183], v[196:199], v[32:35]
	v_mfma_f32_16x16x32_bf16 v[20:23], v[172:175], v[204:207], v[20:23]
	v_mfma_f32_16x16x32_bf16 v[16:19], v[180:183], v[204:207], v[16:19]
	v_mfma_f32_16x16x32_bf16 v[4:7], v[172:175], v[212:215], v[4:7]
	v_mfma_f32_16x16x32_bf16 v[0:3], v[180:183], v[212:215], v[0:3]
	s_barrier
	s_add_i32 s57, s57, 2
	s_add_u32 s55, s55, 0x100
	s_addc_u32 s56, s56, 0
	s_add_u32 s26, s26, 0x100
	s_addc_u32 s27, s27, 0
	s_cmp_gt_u32 s57, 29
	s_cbranch_scc0 .LBB0_261
	s_setprio 0
	s_and_b64 vcc, exec, s[14:15]
	s_cbranch_vccz .LBB0_264
	s_barrier

; #define PG8_STAGE(bufoff, gbase, voff) do { _Pragma("unroll") for (int _i = 0; _i < 2; ++_i) \
;         __builtin_amdgcn_global_load_lds((const unsigned*)((const char*)(gbase) + (voff)[_i]), (PG8_LAS unsigned*)(lds + (bufoff) + ldsw + _i * 8192), 16, 0, 0); } while (0)
; #define PG8_LDA(dst, b, h) do { _Pragma("unroll") for (int m = 0; m < 4; ++m) _Pragma("unroll") for (int k = 0; k < 2; ++k) dst[m][k] = *(const PG8_LAS bf16x8*)(lds + PG8_SA(b, h) + aoff + m * 2048 + k * 1024); } while (0)
; #define PG8_LDB(dst, b, h) do { _Pragma("unroll") for (int n = 0; n < 2; ++n) _Pragma("unroll") for (int k = 0; k < 2; ++k) dst[n][k] = *(const PG8_LAS bf16x8*)(lds + PG8_SB(b, h) + boff + n * 2048 + k * 1024); } while (0)
; #define PG8_MMA(ai, bj, At, Bt) do { __builtin_amdgcn_s_setprio(1); _Pragma("unroll") for (int m = 0; m < 4; ++m) _Pragma("unroll") for (int n = 0; n < 2; ++n) _Pragma("unroll") for (int k = 0; k < 2; ++k) \
;         acc[ai][bj][m][n] = __builtin_amdgcn_mfma_f32_16x16x32_bf16(Bt[n][k], At[m][k], acc[ai][bj][m][n], 0, 0, 0); __builtin_amdgcn_s_setprio(0); } while (0)
; #define PG8_WAIT_V(n) asm volatile("s_waitcnt vmcnt(" #n ")" ::: "memory")
; #define PG8_WAIT_L(n) asm volatile("s_waitcnt lgkmcnt(" #n ")" ::: "memory")
; template <class Epi, class Sched, bool ALIGN_EPI = false, bool SP2 = false>
; __device__ __forceinline__ void gemm_phase(PG8_LAS unsigned char* lds, const Gemm g, const Sched& S, const Epi& E, const int tid_in) {
;     ...
;         const bool has_next = S.next(ui + 1, nxt);
;         const char* nA = has_next ? (const char*)g.A + (size_t)nxt.pm * tstepA : cA; const char* nB = has_next ? (const char*)g.Bt + (size_t)nxt.pn * tstep : cB;
;         for (int t = 0; t < nt; t += 2) {
;             const bool last = (t == nt - 2);
;             const char* a1 = cA + (size_t)(t + 1) * kstep;
;             const char* a2 = last ? nA : cA + (size_t)(t + 2) * kstep; const char* b2 = last ? nB : cB + (size_t)(t + 2) * kstep;
;             const char* a3 = a2 + kstep; const char* b3 = b2 + kstep;
;             if (last && has_next) S.a_ready(nxt);
;             if constexpr (SP2) {
;             PG8_LDB(B0, 0, 0); PG8_LDB(B1, 0, 1); PG8_SCHED; PG8_LDA(At, 0, 0); PG8_STAGE(PG8_SA(1, 1), a1 + hstepA, voffA);
;             PG8_WAIT_V(8); PG8_WAIT_L(0); PG8_BAR; PG8_MMA(0, 0, At, B0); PG8_MMA(0, 1, At, B1); PG8_BAR; PG8_SCHED;
.LBB0_319:
	s_ashr_i32 s13, s12, 31
	s_lshl_b64 s[16:17], s[12:13], 18
	s_add_u32 s16, s26, s16
	s_addc_u32 s17, s27, s17
	s_and_b64 s[2:3], s[2:3], exec
	s_cselect_b32 s13, s17, s21
	s_cselect_b32 s50, s16, s20
	s_add_u32 s51, s20, 0x100
	v_mov_b32_e32 v0, 0
	s_addc_u32 s52, s21, 0
	s_mov_b32 s53, -2
	v_mov_b32_e32 v1, v0
	v_mov_b32_e32 v2, v0
	v_mov_b32_e32 v3, v0
	v_mov_b32_e32 v4, v0
	v_mov_b32_e32 v5, v0
	v_mov_b32_e32 v6, v0
	v_mov_b32_e32 v7, v0
	v_mov_b32_e32 v8, v0
	v_mov_b32_e32 v9, v0
	v_mov_b32_e32 v10, v0
	v_mov_b32_e32 v11, v0
	v_mov_b32_e32 v12, v0
	v_mov_b32_e32 v13, v0
	v_mov_b32_e32 v14, v0
	v_mov_b32_e32 v15, v0
	v_mov_b32_e32 v24, v0
	v_mov_b32_e32 v25, v0
	v_mov_b32_e32 v26, v0
	v_mov_b32_e32 v27, v0
	v_mov_b32_e32 v28, v0
	v_mov_b32_e32 v29, v0
	v_mov_b32_e32 v30, v0
	v_mov_b32_e32 v31, v0
	v_mov_b32_e32 v40, v0
	v_mov_b32_e32 v41, v0
	v_mov_b32_e32 v42, v0
	v_mov_b32_e32 v43, v0
	v_mov_b32_e32 v44, v0
	v_mov_b32_e32 v45, v0
	v_mov_b32_e32 v46, v0
	v_mov_b32_e32 v47, v0
	v_mov_b32_e32 v16, v0
	v_mov_b32_e32 v17, v0
	v_mov_b32_e32 v18, v0
	v_mov_b32_e32 v19, v0
	v_mov_b32_e32 v20, v0
	v_mov_b32_e32 v21, v0
	v_mov_b32_e32 v22, v0
	v_mov_b32_e32 v23, v0
	v_mov_b32_e32 v32, v0
	v_mov_b32_e32 v33, v0
	v_mov_b32_e32 v34, v0
	v_mov_b32_e32 v35, v0
	v_mov_b32_e32 v36, v0
	v_mov_b32_e32 v37, v0
	v_mov_b32_e32 v38, v0
	v_mov_b32_e32 v39, v0
	v_mov_b32_e32 v48, v0
	v_mov_b32_e32 v49, v0
	v_mov_b32_e32 v50, v0
	v_mov_b32_e32 v51, v0
	v_mov_b32_e32 v52, v0
	v_mov_b32_e32 v53, v0
	v_mov_b32_e32 v54, v0
	v_mov_b32_e32 v55, v0
	v_mov_b32_e32 v56, v0
	v_mov_b32_e32 v57, v0
	v_mov_b32_e32 v58, v0
	v_mov_b32_e32 v59, v0
	v_mov_b32_e32 v60, v0
	v_mov_b32_e32 v61, v0
	v_mov_b32_e32 v62, v0
	v_mov_b32_e32 v63, v0
	v_mov_b32_e32 v64, v0
	v_mov_b32_e32 v65, v0
	v_mov_b32_e32 v66, v0
	v_mov_b32_e32 v67, v0
	v_mov_b32_e32 v68, v0
	v_mov_b32_e32 v69, v0
	v_mov_b32_e32 v70, v0
	v_mov_b32_e32 v71, v0
	v_mov_b32_e32 v72, v0
	v_mov_b32_e32 v73, v0
	v_mov_b32_e32 v74, v0
	v_mov_b32_e32 v75, v0
	v_mov_b32_e32 v76, v0
	v_mov_b32_e32 v77, v0
	v_mov_b32_e32 v78, v0
	v_mov_b32_e32 v79, v0
	v_mov_b32_e32 v88, v0
	v_mov_b32_e32 v89, v0
	v_mov_b32_e32 v90, v0
	v_mov_b32_e32 v91, v0
	v_mov_b32_e32 v92, v0
	v_mov_b32_e32 v93, v0
	v_mov_b32_e32 v94, v0
	v_mov_b32_e32 v95, v0
	v_mov_b32_e32 v104, v0
	v_mov_b32_e32 v105, v0
	v_mov_b32_e32 v106, v0
	v_mov_b32_e32 v107, v0
	v_mov_b32_e32 v108, v0
	v_mov_b32_e32 v109, v0
	v_mov_b32_e32 v110, v0
	v_mov_b32_e32 v111, v0
	v_mov_b32_e32 v80, v0
	v_mov_b32_e32 v81, v0
	v_mov_b32_e32 v82, v0
	v_mov_b32_e32 v83, v0
	v_mov_b32_e32 v84, v0
	v_mov_b32_e32 v85, v0
	v_mov_b32_e32 v86, v0
	v_mov_b32_e32 v87, v0
	v_mov_b32_e32 v96, v0
	v_mov_b32_e32 v97, v0
	v_mov_b32_e32 v98, v0
	v_mov_b32_e32 v99, v0
	v_mov_b32_e32 v100, v0
	v_mov_b32_e32 v101, v0
	v_mov_b32_e32 v102, v0
	v_mov_b32_e32 v103, v0
	v_mov_b32_e32 v112, v0
	v_mov_b32_e32 v113, v0
	v_mov_b32_e32 v114, v0
	v_mov_b32_e32 v115, v0
	v_mov_b32_e32 v116, v0
	v_mov_b32_e32 v117, v0
	v_mov_b32_e32 v118, v0
	v_mov_b32_e32 v119, v0
	v_mov_b32_e32 v120, v0
	v_mov_b32_e32 v121, v0
	v_mov_b32_e32 v122, v0
	v_mov_b32_e32 v123, v0
	v_mov_b32_e32 v124, v0
	v_mov_b32_e32 v125, v0
	v_mov_b32_e32 v126, v0
	v_mov_b32_e32 v127, v0
	s_cmp_lt_u32 s75, 4
	s_cbranch_scc1 .Lkprio_skip_3
	s_setprio 1
.Lkprio_skip_3:
.LBB0_320:
	ds_read_b128 v[144:147], v153
	ds_read_b128 v[156:159], v153 offset:1024
	ds_read_b128 v[160:163], v153 offset:2048
	ds_read_b128 v[164:167], v153 offset:3072
	ds_read_b128 v[168:171], v154
	ds_read_b128 v[172:175], v154 offset:1024
	ds_read_b128 v[176:179], v154 offset:2048
	ds_read_b128 v[180:183], v154 offset:3072
	s_add_u32 s2, s18, 0x100
	s_addc_u32 s3, s19, 0
	s_cmp_eq_u32 s53, 4
	s_cselect_b32 s23, s15, s3
	s_cselect_b32 s22, s14, s2
	s_cselect_b32 s21, s13, s52
	s_cselect_b32 s20, s50, s51
	v_lshl_add_u64 v[148:149], s[18:19], 0, v[138:139]
	s_add_i32 m0, s33, 0xc000
	ds_read_b128 v[184:187], v155
	ds_read_b128 v[188:191], v155 offset:1024
	ds_read_b128 v[192:195], v155 offset:2048
	ds_read_b128 v[196:199], v155 offset:3072
	ds_read_b128 v[200:203], v155 offset:4096
	ds_read_b128 v[204:207], v155 offset:5120
	ds_read_b128 v[208:211], v155 offset:6144
	ds_read_b128 v[212:215], v155 offset:7168
	global_load_lds_dwordx4 v[148:149], off
	v_lshl_add_u64 v[148:149], s[18:19], 0, v[136:137]
	s_add_i32 m0, s33, 0xe000
	s_nop 0
	global_load_lds_dwordx4 v[148:149], off
	s_waitcnt vmcnt(8)
	s_waitcnt lgkmcnt(0)
	s_barrier
	v_mfma_f32_16x16x32_bf16 v[124:127], v[144:147], v[184:187], v[124:127]
	v_mfma_f32_16x16x32_bf16 v[120:123], v[160:163], v[184:187], v[120:123]
	v_mfma_f32_16x16x32_bf16 v[116:119], v[144:147], v[192:195], v[116:119]
	v_mfma_f32_16x16x32_bf16 v[112:115], v[160:163], v[192:195], v[112:115]
	v_mfma_f32_16x16x32_bf16 v[100:103], v[144:147], v[200:203], v[100:103]
	v_mfma_f32_16x16x32_bf16 v[96:99], v[160:163], v[200:203], v[96:99]
	v_mfma_f32_16x16x32_bf16 v[84:87], v[144:147], v[208:211], v[84:87]
	v_mfma_f32_16x16x32_bf16 v[80:83], v[160:163], v[208:211], v[80:83]
	v_mfma_f32_16x16x32_bf16 v[124:127], v[156:159], v[188:191], v[124:127]
	v_mfma_f32_16x16x32_bf16 v[120:123], v[164:167], v[188:191], v[120:123]
	v_mfma_f32_16x16x32_bf16 v[116:119], v[156:159], v[196:199], v[116:119]
	v_mfma_f32_16x16x32_bf16 v[112:115], v[164:167], v[196:199], v[112:115]
	v_mfma_f32_16x16x32_bf16 v[100:103], v[156:159], v[204:207], v[100:103]
	v_mfma_f32_16x16x32_bf16 v[96:99], v[164:167], v[204:207], v[96:99]
	v_mfma_f32_16x16x32_bf16 v[84:87], v[156:159], v[212:215], v[84:87]
	v_mfma_f32_16x16x32_bf16 v[80:83], v[164:167], v[212:215], v[80:83]
	v_mfma_f32_16x16x32_bf16 v[108:111], v[168:171], v[184:187], v[108:111]
	v_mfma_f32_16x16x32_bf16 v[104:107], v[176:179], v[184:187], v[104:107]
	v_mfma_f32_16x16x32_bf16 v[92:95], v[168:171], v[192:195], v[92:95]
	v_mfma_f32_16x16x32_bf16 v[88:91], v[176:179], v[192:195], v[88:91]
	v_mfma_f32_16x16x32_bf16 v[76:79], v[168:171], v[200:203], v[76:79]
	v_mfma_f32_16x16x32_bf16 v[72:75], v[176:179], v[200:203], v[72:75]
	v_mfma_f32_16x16x32_bf16 v[68:71], v[168:171], v[208:211], v[68:71]
	v_mfma_f32_16x16x32_bf16 v[64:67], v[176:179], v[208:211], v[64:67]
	v_mfma_f32_16x16x32_bf16 v[108:111], v[172:175], v[188:191], v[108:111]
	v_mfma_f32_16x16x32_bf16 v[104:107], v[180:183], v[188:191], v[104:107]
	v_mfma_f32_16x16x32_bf16 v[92:95], v[172:175], v[196:199], v[92:95]
	v_mfma_f32_16x16x32_bf16 v[88:91], v[180:183], v[196:199], v[88:91]
	v_mfma_f32_16x16x32_bf16 v[76:79], v[172:175], v[204:207], v[76:79]
	v_mfma_f32_16x16x32_bf16 v[72:75], v[180:183], v[204:207], v[72:75]
	v_mfma_f32_16x16x32_bf16 v[68:71], v[172:175], v[212:215], v[68:71]
	v_mfma_f32_16x16x32_bf16 v[64:67], v[180:183], v[212:215], v[64:67]
	s_barrier
; #define PG8_STAGE(bufoff, gbase, voff) do { _Pragma("unroll") for (int _i = 0; _i < 2; ++_i) \
;         __builtin_amdgcn_global_load_lds((const unsigned*)((const char*)(gbase) + (voff)[_i]), (PG8_LAS unsigned*)(lds + (bufoff) + ldsw + _i * 8192), 16, 0, 0); } while (0)
; #define PG8_LDA(dst, b, h) do { _Pragma("unroll") for (int m = 0; m < 4; ++m) _Pragma("unroll") for (int k = 0; k < 2; ++k) dst[m][k] = *(const PG8_LAS bf16x8*)(lds + PG8_SA(b, h) + aoff + m * 2048 + k * 1024); } while (0)
; #define PG8_LDB(dst, b, h) do { _Pragma("unroll") for (int n = 0; n < 2; ++n) _Pragma("unroll") for (int k = 0; k < 2; ++k) dst[n][k] = *(const PG8_LAS bf16x8*)(lds + PG8_SB(b, h) + boff + n * 2048 + k * 1024); } while (0)
; #define PG8_MMA(ai, bj, At, Bt) do { __builtin_amdgcn_s_setprio(1); _Pragma("unroll") for (int m = 0; m < 4; ++m) _Pragma("unroll") for (int n = 0; n < 2; ++n) _Pragma("unroll") for (int k = 0; k < 2; ++k) \
;         acc[ai][bj][m][n] = __builtin_amdgcn_mfma_f32_16x16x32_bf16(Bt[n][k], At[m][k], acc[ai][bj][m][n], 0, 0, 0); __builtin_amdgcn_s_setprio(0); } while (0)
; #define PG8_WAIT_V(n) asm volatile("s_waitcnt vmcnt(" #n ")" ::: "memory")
; #define PG8_WAIT_L(n) asm volatile("s_waitcnt lgkmcnt(" #n ")" ::: "memory")
; #define PG8_BAR __builtin_amdgcn_s_barrier()
; #define PG8_SCHED __builtin_amdgcn_sched_barrier(0)
; template <class Epi, class Sched, bool ALIGN_EPI = false, bool SP2 = false>
; __device__ __forceinline__ void gemm_phase(PG8_LAS unsigned char* lds, const Gemm g, const Sched& S, const Epi& E, const int tid_in) {
;     ...
;             PG8_WAIT_V(8); PG8_WAIT_L(0); PG8_BAR; PG8_MMA(0, 0, At, B0); PG8_MMA(0, 1, At, B1); PG8_BAR; PG8_SCHED;
;             PG8_LDA(At, 0, 1); PG8_STAGE(PG8_SB(0, 0), b2, voffB); PG8_STAGE(PG8_SB(0, 1), b2 + hstep, voffB); PG8_STAGE(PG8_SA(0, 0), a2, voffA);
;             PG8_WAIT_V(8); PG8_WAIT_L(0); PG8_BAR; PG8_MMA(1, 0, At, B0); PG8_MMA(1, 1, At, B1); PG8_BAR; PG8_SCHED;
;             PG8_LDB(B0, 1, 0); PG8_LDB(B1, 1, 1); PG8_SCHED; PG8_LDA(At, 1, 0); PG8_STAGE(PG8_SA(0, 1), a2 + hstepA, voffA);
;             PG8_WAIT_V(8); PG8_WAIT_L(0); PG8_BAR; PG8_MMA(0, 0, At, B0); PG8_MMA(0, 1, At, B1); PG8_BAR; PG8_SCHED;
	s_add_i32 s18, s41, s28
	v_lshl_add_u64 v[148:149], s[20:21], 0, v[132:133]
	s_mov_b32 m0, s18
	ds_read_b128 v[184:187], v155 offset:16384
	ds_read_b128 v[188:191], v155 offset:17408
	ds_read_b128 v[192:195], v155 offset:18432
	ds_read_b128 v[196:199], v155 offset:19456
	ds_read_b128 v[200:203], v155 offset:20480
	ds_read_b128 v[204:207], v155 offset:21504
	ds_read_b128 v[208:211], v155 offset:22528
	ds_read_b128 v[212:215], v155 offset:23552
	global_load_lds_dwordx4 v[148:149], off
	s_add_i32 m0, s18, 0x2000
	s_add_u32 s18, s20, 0x20000
	v_lshl_add_u64 v[216:217], s[20:21], 0, v[128:129]
	s_addc_u32 s19, s21, 0
	s_add_i32 s54, s42, s28
	global_load_lds_dwordx4 v[216:217], off
	v_lshl_add_u64 v[218:219], s[18:19], 0, v[132:133]
	s_mov_b32 m0, s54
	v_lshl_add_u64 v[220:221], s[22:23], 0, v[130:131]
	global_load_lds_dwordx4 v[218:219], off
	v_lshl_add_u64 v[218:219], s[18:19], 0, v[128:129]
	s_add_i32 m0, s54, 0x2000
	s_nop 0
	global_load_lds_dwordx4 v[218:219], off
	v_lshl_add_u64 v[218:219], s[22:23], 0, v[134:135]
	s_mov_b32 m0, s33
	s_nop 0
	global_load_lds_dwordx4 v[218:219], off
	s_mov_b32 m0, s34
	s_nop 0
	global_load_lds_dwordx4 v[220:221], off
	s_waitcnt vmcnt(8)
	s_waitcnt lgkmcnt(0)
	s_barrier
	v_mfma_f32_16x16x32_bf16 v[60:63], v[144:147], v[184:187], v[60:63]
	v_mfma_f32_16x16x32_bf16 v[56:59], v[160:163], v[184:187], v[56:59]
	v_mfma_f32_16x16x32_bf16 v[52:55], v[144:147], v[192:195], v[52:55]
	v_mfma_f32_16x16x32_bf16 v[48:51], v[160:163], v[192:195], v[48:51]
	v_mfma_f32_16x16x32_bf16 v[36:39], v[144:147], v[200:203], v[36:39]
	v_mfma_f32_16x16x32_bf16 v[32:35], v[160:163], v[200:203], v[32:35]
	v_mfma_f32_16x16x32_bf16 v[20:23], v[144:147], v[208:211], v[20:23]
	v_mfma_f32_16x16x32_bf16 v[16:19], v[160:163], v[208:211], v[16:19]
	v_mfma_f32_16x16x32_bf16 v[60:63], v[156:159], v[188:191], v[60:63]
	v_mfma_f32_16x16x32_bf16 v[56:59], v[164:167], v[188:191], v[56:59]
	v_mfma_f32_16x16x32_bf16 v[52:55], v[156:159], v[196:199], v[52:55]
	v_mfma_f32_16x16x32_bf16 v[48:51], v[164:167], v[196:199], v[48:51]
	v_mfma_f32_16x16x32_bf16 v[36:39], v[156:159], v[204:207], v[36:39]
	v_mfma_f32_16x16x32_bf16 v[32:35], v[164:167], v[204:207], v[32:35]
	v_mfma_f32_16x16x32_bf16 v[20:23], v[156:159], v[212:215], v[20:23]
	v_mfma_f32_16x16x32_bf16 v[16:19], v[164:167], v[212:215], v[16:19]
	v_mfma_f32_16x16x32_bf16 v[44:47], v[168:171], v[184:187], v[44:47]
	v_mfma_f32_16x16x32_bf16 v[40:43], v[176:179], v[184:187], v[40:43]
	v_mfma_f32_16x16x32_bf16 v[28:31], v[168:171], v[192:195], v[28:31]
	v_mfma_f32_16x16x32_bf16 v[24:27], v[176:179], v[192:195], v[24:27]
	v_mfma_f32_16x16x32_bf16 v[12:15], v[168:171], v[200:203], v[12:15]
	v_mfma_f32_16x16x32_bf16 v[8:11], v[176:179], v[200:203], v[8:11]
	v_mfma_f32_16x16x32_bf16 v[4:7], v[168:171], v[208:211], v[4:7]
	v_mfma_f32_16x16x32_bf16 v[0:3], v[176:179], v[208:211], v[0:3]
	v_mfma_f32_16x16x32_bf16 v[44:47], v[172:175], v[188:191], v[44:47]
	v_mfma_f32_16x16x32_bf16 v[40:43], v[180:183], v[188:191], v[40:43]
	v_mfma_f32_16x16x32_bf16 v[28:31], v[172:175], v[196:199], v[28:31]
	v_mfma_f32_16x16x32_bf16 v[24:27], v[180:183], v[196:199], v[24:27]
	v_mfma_f32_16x16x32_bf16 v[12:15], v[172:175], v[204:207], v[12:15]
	v_mfma_f32_16x16x32_bf16 v[8:11], v[180:183], v[204:207], v[8:11]
	v_mfma_f32_16x16x32_bf16 v[4:7], v[172:175], v[212:215], v[4:7]
	v_mfma_f32_16x16x32_bf16 v[0:3], v[180:183], v[212:215], v[0:3]
	s_barrier
	s_add_i32 s54, 0, 0x18000
	s_add_i32 s55, 0, 0x1c000
	v_add_u32_e32 v164, s54, v151
	v_add_u32_e32 v180, s55, v151
	ds_read_b128 v[144:147], v164
	ds_read_b128 v[156:159], v164 offset:1024
	ds_read_b128 v[160:163], v164 offset:2048
	ds_read_b128 v[164:167], v164 offset:3072
	ds_read_b128 v[168:171], v180
	ds_read_b128 v[172:175], v180 offset:1024
	ds_read_b128 v[176:179], v180 offset:2048
	ds_read_b128 v[180:183], v180 offset:3072
	s_add_u32 s18, s22, 0xc0000
	s_addc_u32 s19, s23, 0
	s_mov_b32 m0, s35
	v_lshl_add_u64 v[222:223], s[18:19], 0, v[134:135]
	ds_read_b128 v[184:187], v155 offset:32768
	ds_read_b128 v[188:191], v155 offset:33792
	ds_read_b128 v[192:195], v155 offset:34816
	ds_read_b128 v[196:199], v155 offset:35840
	ds_read_b128 v[200:203], v155 offset:36864
	ds_read_b128 v[204:207], v155 offset:37888
	ds_read_b128 v[208:211], v155 offset:38912
	ds_read_b128 v[212:215], v155 offset:39936
	global_load_lds_dwordx4 v[222:223], off
	v_lshl_add_u64 v[222:223], s[18:19], 0, v[130:131]
	s_mov_b32 m0, s36
	s_nop 0
	global_load_lds_dwordx4 v[222:223], off
	s_waitcnt vmcnt(8)
	s_waitcnt lgkmcnt(0)
	s_barrier
; #define PG8_STAGE(bufoff, gbase, voff) do { _Pragma("unroll") for (int _i = 0; _i < 2; ++_i) \
;         __builtin_amdgcn_global_load_lds((const unsigned*)((const char*)(gbase) + (voff)[_i]), (PG8_LAS unsigned*)(lds + (bufoff) + ldsw + _i * 8192), 16, 0, 0); } while (0)
; #define PG8_LDA(dst, b, h) do { _Pragma("unroll") for (int m = 0; m < 4; ++m) _Pragma("unroll") for (int k = 0; k < 2; ++k) dst[m][k] = *(const PG8_LAS bf16x8*)(lds + PG8_SA(b, h) + aoff + m * 2048 + k * 1024); } while (0)
; #define PG8_MMA(ai, bj, At, Bt) do { __builtin_amdgcn_s_setprio(1); _Pragma("unroll") for (int m = 0; m < 4; ++m) _Pragma("unroll") for (int n = 0; n < 2; ++n) _Pragma("unroll") for (int k = 0; k < 2; ++k) \
;         acc[ai][bj][m][n] = __builtin_amdgcn_mfma_f32_16x16x32_bf16(Bt[n][k], At[m][k], acc[ai][bj][m][n], 0, 0, 0); __builtin_amdgcn_s_setprio(0); } while (0)
; #define PG8_WAIT_V(n) asm volatile("s_waitcnt vmcnt(" #n ")" ::: "memory")
; #define PG8_WAIT_L(n) asm volatile("s_waitcnt lgkmcnt(" #n ")" ::: "memory")
; #define PG8_BAR __builtin_amdgcn_s_barrier()
; #define PG8_SCHED __builtin_amdgcn_sched_barrier(0)
; template <class Epi, class Sched, bool ALIGN_EPI = false, bool SP2 = false>
; __device__ __forceinline__ void gemm_phase(PG8_LAS unsigned char* lds, const Gemm g, const Sched& S, const Epi& E, const int tid_in) {
;     ...
;             PG8_WAIT_V(8); PG8_WAIT_L(0); PG8_BAR; PG8_MMA(0, 0, At, B0); PG8_MMA(0, 1, At, B1); PG8_BAR; PG8_SCHED;
;             PG8_LDA(At, 1, 1); PG8_STAGE(PG8_SB(1, 0), b3, voffB); PG8_STAGE(PG8_SB(1, 1), b3 + hstep, voffB); PG8_STAGE(PG8_SA(1, 0), a3, voffA);
;             PG8_WAIT_V(8); PG8_WAIT_L(0); PG8_BAR; PG8_MMA(1, 0, At, B0); PG8_MMA(1, 1, At, B1); PG8_BAR; PG8_SCHED;
;     ...
;         }
	v_mfma_f32_16x16x32_bf16 v[124:127], v[144:147], v[184:187], v[124:127]
	v_mfma_f32_16x16x32_bf16 v[120:123], v[160:163], v[184:187], v[120:123]
	v_mfma_f32_16x16x32_bf16 v[116:119], v[144:147], v[192:195], v[116:119]
	v_mfma_f32_16x16x32_bf16 v[112:115], v[160:163], v[192:195], v[112:115]
	v_mfma_f32_16x16x32_bf16 v[100:103], v[144:147], v[200:203], v[100:103]
	v_mfma_f32_16x16x32_bf16 v[96:99], v[160:163], v[200:203], v[96:99]
	v_mfma_f32_16x16x32_bf16 v[84:87], v[144:147], v[208:211], v[84:87]
	v_mfma_f32_16x16x32_bf16 v[80:83], v[160:163], v[208:211], v[80:83]
	v_mfma_f32_16x16x32_bf16 v[124:127], v[156:159], v[188:191], v[124:127]
	v_mfma_f32_16x16x32_bf16 v[120:123], v[164:167], v[188:191], v[120:123]
	v_mfma_f32_16x16x32_bf16 v[116:119], v[156:159], v[196:199], v[116:119]
	v_mfma_f32_16x16x32_bf16 v[112:115], v[164:167], v[196:199], v[112:115]
	v_mfma_f32_16x16x32_bf16 v[100:103], v[156:159], v[204:207], v[100:103]
	v_mfma_f32_16x16x32_bf16 v[96:99], v[164:167], v[204:207], v[96:99]
	v_mfma_f32_16x16x32_bf16 v[84:87], v[156:159], v[212:215], v[84:87]
	v_mfma_f32_16x16x32_bf16 v[80:83], v[164:167], v[212:215], v[80:83]
	v_mfma_f32_16x16x32_bf16 v[108:111], v[168:171], v[184:187], v[108:111]
	v_mfma_f32_16x16x32_bf16 v[104:107], v[176:179], v[184:187], v[104:107]
	v_mfma_f32_16x16x32_bf16 v[92:95], v[168:171], v[192:195], v[92:95]
	v_mfma_f32_16x16x32_bf16 v[88:91], v[176:179], v[192:195], v[88:91]
	v_mfma_f32_16x16x32_bf16 v[76:79], v[168:171], v[200:203], v[76:79]
	v_mfma_f32_16x16x32_bf16 v[72:75], v[176:179], v[200:203], v[72:75]
	v_mfma_f32_16x16x32_bf16 v[68:71], v[168:171], v[208:211], v[68:71]
	v_mfma_f32_16x16x32_bf16 v[64:67], v[176:179], v[208:211], v[64:67]
	v_mfma_f32_16x16x32_bf16 v[108:111], v[172:175], v[188:191], v[108:111]
	v_mfma_f32_16x16x32_bf16 v[104:107], v[180:183], v[188:191], v[104:107]
	v_mfma_f32_16x16x32_bf16 v[92:95], v[172:175], v[196:199], v[92:95]
	v_mfma_f32_16x16x32_bf16 v[88:91], v[180:183], v[196:199], v[88:91]
	v_mfma_f32_16x16x32_bf16 v[76:79], v[172:175], v[204:207], v[76:79]
	v_mfma_f32_16x16x32_bf16 v[72:75], v[180:183], v[204:207], v[72:75]
	v_mfma_f32_16x16x32_bf16 v[68:71], v[172:175], v[212:215], v[68:71]
	v_mfma_f32_16x16x32_bf16 v[64:67], v[180:183], v[212:215], v[64:67]
	s_barrier
	s_add_i32 s18, s54, s28
	v_lshl_add_u64 v[148:149], v[148:149], 0, s[8:9]
	s_mov_b32 m0, s18
	ds_read_b128 v[184:187], v155 offset:49152
	ds_read_b128 v[188:191], v155 offset:50176
	ds_read_b128 v[192:195], v155 offset:51200
	ds_read_b128 v[196:199], v155 offset:52224
	ds_read_b128 v[200:203], v155 offset:53248
	ds_read_b128 v[204:207], v155 offset:54272
	ds_read_b128 v[208:211], v155 offset:55296
	ds_read_b128 v[212:215], v155 offset:56320
	global_load_lds_dwordx4 v[148:149], off
	s_add_i32 m0, s18, 0x2000
	s_add_u32 s18, s20, 0x20080
	v_lshl_add_u64 v[148:149], v[216:217], 0, s[8:9]
	s_addc_u32 s19, s21, 0
	s_add_i32 s20, s55, s28
	global_load_lds_dwordx4 v[148:149], off
	v_lshl_add_u64 v[148:149], s[18:19], 0, v[132:133]
	s_mov_b32 m0, s20
	s_nop 0
	global_load_lds_dwordx4 v[148:149], off
	v_lshl_add_u64 v[148:149], s[18:19], 0, v[128:129]
	s_add_i32 m0, s20, 0x2000
	s_nop 0
	global_load_lds_dwordx4 v[148:149], off
	v_lshl_add_u64 v[148:149], v[218:219], 0, s[8:9]
	s_mov_b32 m0, s37
	s_nop 0
	global_load_lds_dwordx4 v[148:149], off
	v_lshl_add_u64 v[148:149], v[220:221], 0, s[8:9]
	s_mov_b32 m0, s38
	s_nop 0
	global_load_lds_dwordx4 v[148:149], off
	s_waitcnt vmcnt(8)
	s_waitcnt lgkmcnt(0)
	s_barrier
	v_mfma_f32_16x16x32_bf16 v[60:63], v[144:147], v[184:187], v[60:63]
	v_mfma_f32_16x16x32_bf16 v[56:59], v[160:163], v[184:187], v[56:59]
	v_mfma_f32_16x16x32_bf16 v[52:55], v[144:147], v[192:195], v[52:55]
	v_mfma_f32_16x16x32_bf16 v[48:51], v[160:163], v[192:195], v[48:51]
	v_mfma_f32_16x16x32_bf16 v[36:39], v[144:147], v[200:203], v[36:39]
	v_mfma_f32_16x16x32_bf16 v[32:35], v[160:163], v[200:203], v[32:35]
	v_mfma_f32_16x16x32_bf16 v[20:23], v[144:147], v[208:211], v[20:23]
	v_mfma_f32_16x16x32_bf16 v[16:19], v[160:163], v[208:211], v[16:19]
	v_mfma_f32_16x16x32_bf16 v[60:63], v[156:159], v[188:191], v[60:63]
	v_mfma_f32_16x16x32_bf16 v[56:59], v[164:167], v[188:191], v[56:59]
	v_mfma_f32_16x16x32_bf16 v[52:55], v[156:159], v[196:199], v[52:55]
	v_mfma_f32_16x16x32_bf16 v[48:51], v[164:167], v[196:199], v[48:51]
	v_mfma_f32_16x16x32_bf16 v[36:39], v[156:159], v[204:207], v[36:39]
	v_mfma_f32_16x16x32_bf16 v[32:35], v[164:167], v[204:207], v[32:35]
	v_mfma_f32_16x16x32_bf16 v[20:23], v[156:159], v[212:215], v[20:23]
	v_mfma_f32_16x16x32_bf16 v[16:19], v[164:167], v[212:215], v[16:19]
	v_mfma_f32_16x16x32_bf16 v[44:47], v[168:171], v[184:187], v[44:47]
	v_mfma_f32_16x16x32_bf16 v[40:43], v[176:179], v[184:187], v[40:43]
	v_mfma_f32_16x16x32_bf16 v[28:31], v[168:171], v[192:195], v[28:31]
	v_mfma_f32_16x16x32_bf16 v[24:27], v[176:179], v[192:195], v[24:27]
	v_mfma_f32_16x16x32_bf16 v[12:15], v[168:171], v[200:203], v[12:15]
	v_mfma_f32_16x16x32_bf16 v[8:11], v[176:179], v[200:203], v[8:11]
	v_mfma_f32_16x16x32_bf16 v[4:7], v[168:171], v[208:211], v[4:7]
	v_mfma_f32_16x16x32_bf16 v[0:3], v[176:179], v[208:211], v[0:3]
	v_mfma_f32_16x16x32_bf16 v[44:47], v[172:175], v[188:191], v[44:47]
	v_mfma_f32_16x16x32_bf16 v[40:43], v[180:183], v[188:191], v[40:43]
	v_mfma_f32_16x16x32_bf16 v[28:31], v[172:175], v[196:199], v[28:31]
	v_mfma_f32_16x16x32_bf16 v[24:27], v[180:183], v[196:199], v[24:27]
	v_mfma_f32_16x16x32_bf16 v[12:15], v[172:175], v[204:207], v[12:15]
	v_mfma_f32_16x16x32_bf16 v[8:11], v[180:183], v[204:207], v[8:11]
	v_mfma_f32_16x16x32_bf16 v[4:7], v[172:175], v[212:215], v[4:7]
	v_mfma_f32_16x16x32_bf16 v[0:3], v[180:183], v[212:215], v[0:3]
	s_barrier
	s_add_i32 s53, s53, 2
	s_add_u32 s51, s51, 0x100
	s_addc_u32 s52, s52, 0
	s_cmp_gt_u32 s53, 5
	s_mov_b64 s[18:19], s[2:3]
	s_cbranch_scc0 .LBB0_320
	s_setprio 0
	s_and_b64 vcc, exec, s[10:11]
	s_cbranch_vccz .LBB0_323
	s_barrier

; #define PG8_STAGE(bufoff, gbase, voff) do { _Pragma("unroll") for (int _i = 0; _i < 2; ++_i) \
;         __builtin_amdgcn_global_load_lds((const unsigned*)((const char*)(gbase) + (voff)[_i]), (PG8_LAS unsigned*)(lds + (bufoff) + ldsw + _i * 8192), 16, 0, 0); } while (0)
; #define PG8_LDA(dst, b, h) do { _Pragma("unroll") for (int m = 0; m < 4; ++m) _Pragma("unroll") for (int k = 0; k < 2; ++k) dst[m][k] = *(const PG8_LAS bf16x8*)(lds + PG8_SA(b, h) + aoff + m * 2048 + k * 1024); } while (0)
; #define PG8_LDB(dst, b, h) do { _Pragma("unroll") for (int n = 0; n < 2; ++n) _Pragma("unroll") for (int k = 0; k < 2; ++k) dst[n][k] = *(const PG8_LAS bf16x8*)(lds + PG8_SB(b, h) + boff + n * 2048 + k * 1024); } while (0)
; #define PG8_MMA(ai, bj, At, Bt) do { __builtin_amdgcn_s_setprio(1); _Pragma("unroll") for (int m = 0; m < 4; ++m) _Pragma("unroll") for (int n = 0; n < 2; ++n) _Pragma("unroll") for (int k = 0; k < 2; ++k) \
;         acc[ai][bj][m][n] = __builtin_amdgcn_mfma_f32_16x16x32_bf16(Bt[n][k], At[m][k], acc[ai][bj][m][n], 0, 0, 0); __builtin_amdgcn_s_setprio(0); } while (0)
; #define PG8_WAIT_V(n) asm volatile("s_waitcnt vmcnt(" #n ")" ::: "memory")
; #define PG8_WAIT_L(n) asm volatile("s_waitcnt lgkmcnt(" #n ")" ::: "memory")
; template <class Epi, class Sched, bool ALIGN_EPI = false, bool SP2 = false>
; __device__ __forceinline__ void gemm_phase(PG8_LAS unsigned char* lds, const Gemm g, const Sched& S, const Epi& E, const int tid_in) {
;     ...
;         const bool has_next = S.next(ui + 1, nxt);
;         const char* nA = has_next ? (const char*)g.A + (size_t)nxt.pm * tstepA : cA; const char* nB = has_next ? (const char*)g.Bt + (size_t)nxt.pn * tstep : cB;
;         for (int t = 0; t < nt; t += 2) {
;             const bool last = (t == nt - 2);
;             const char* a1 = cA + (size_t)(t + 1) * kstep;
;             const char* a2 = last ? nA : cA + (size_t)(t + 2) * kstep; const char* b2 = last ? nB : cB + (size_t)(t + 2) * kstep;
;             const char* a3 = a2 + kstep; const char* b3 = b2 + kstep;
;             if (last && has_next) S.a_ready(nxt);
;             if constexpr (SP2) {
;             PG8_LDB(B0, 0, 0); PG8_LDB(B1, 0, 1); PG8_SCHED; PG8_LDA(At, 0, 0); PG8_STAGE(PG8_SA(1, 1), a1 + hstepA, voffA);
;             PG8_WAIT_V(8); PG8_WAIT_L(0); PG8_BAR; PG8_MMA(0, 0, At, B0); PG8_MMA(0, 1, At, B1); PG8_BAR; PG8_SCHED;
.LBB0_340:
	s_ashr_i32 s13, s12, 31
	s_lshl_b64 s[16:17], s[12:13], 17
	s_add_u32 s16, s37, s16
	s_addc_u32 s17, s38, s17
	s_and_b64 s[2:3], s[2:3], exec
	v_mov_b32_e32 v0, 0
	s_cselect_b32 s13, s17, s19
	s_cselect_b32 s56, s16, s18
	s_mov_b32 s24, 0
	s_mov_b64 s[2:3], -1
	s_mov_b64 s[22:23], 0
	v_mov_b32_e32 v1, v0
	v_mov_b32_e32 v2, v0
	v_mov_b32_e32 v3, v0
	v_mov_b32_e32 v4, v0
	v_mov_b32_e32 v5, v0
	v_mov_b32_e32 v6, v0
	v_mov_b32_e32 v7, v0
	v_mov_b32_e32 v8, v0
	v_mov_b32_e32 v9, v0
	v_mov_b32_e32 v10, v0
	v_mov_b32_e32 v11, v0
	v_mov_b32_e32 v12, v0
	v_mov_b32_e32 v13, v0
	v_mov_b32_e32 v14, v0
	v_mov_b32_e32 v15, v0
	v_mov_b32_e32 v24, v0
	v_mov_b32_e32 v25, v0
	v_mov_b32_e32 v26, v0
	v_mov_b32_e32 v27, v0
	v_mov_b32_e32 v28, v0
	v_mov_b32_e32 v29, v0
	v_mov_b32_e32 v30, v0
	v_mov_b32_e32 v31, v0
	v_mov_b32_e32 v40, v0
	v_mov_b32_e32 v41, v0
	v_mov_b32_e32 v42, v0
	v_mov_b32_e32 v43, v0
	v_mov_b32_e32 v44, v0
	v_mov_b32_e32 v45, v0
	v_mov_b32_e32 v46, v0
	v_mov_b32_e32 v47, v0
	v_mov_b32_e32 v16, v0
	v_mov_b32_e32 v17, v0
	v_mov_b32_e32 v18, v0
	v_mov_b32_e32 v19, v0
	v_mov_b32_e32 v20, v0
	v_mov_b32_e32 v21, v0
	v_mov_b32_e32 v22, v0
	v_mov_b32_e32 v23, v0
	v_mov_b32_e32 v32, v0
	v_mov_b32_e32 v33, v0
	v_mov_b32_e32 v34, v0
	v_mov_b32_e32 v35, v0
	v_mov_b32_e32 v36, v0
	v_mov_b32_e32 v37, v0
	v_mov_b32_e32 v38, v0
	v_mov_b32_e32 v39, v0
	v_mov_b32_e32 v48, v0
	v_mov_b32_e32 v49, v0
	v_mov_b32_e32 v50, v0
	v_mov_b32_e32 v51, v0
	v_mov_b32_e32 v52, v0
	v_mov_b32_e32 v53, v0
	v_mov_b32_e32 v54, v0
	v_mov_b32_e32 v55, v0
	v_mov_b32_e32 v56, v0
	v_mov_b32_e32 v57, v0
	v_mov_b32_e32 v58, v0
	v_mov_b32_e32 v59, v0
	v_mov_b32_e32 v60, v0
	v_mov_b32_e32 v61, v0
	v_mov_b32_e32 v62, v0
	v_mov_b32_e32 v63, v0
	v_mov_b32_e32 v64, v0
	v_mov_b32_e32 v65, v0
	v_mov_b32_e32 v66, v0
	v_mov_b32_e32 v67, v0
	v_mov_b32_e32 v68, v0
	v_mov_b32_e32 v69, v0
	v_mov_b32_e32 v70, v0
	v_mov_b32_e32 v71, v0
	v_mov_b32_e32 v72, v0
	v_mov_b32_e32 v73, v0
	v_mov_b32_e32 v74, v0
	v_mov_b32_e32 v75, v0
	v_mov_b32_e32 v76, v0
	v_mov_b32_e32 v77, v0
	v_mov_b32_e32 v78, v0
	v_mov_b32_e32 v79, v0
	v_mov_b32_e32 v88, v0
	v_mov_b32_e32 v89, v0
	v_mov_b32_e32 v90, v0
	v_mov_b32_e32 v91, v0
	v_mov_b32_e32 v92, v0
	v_mov_b32_e32 v93, v0
	v_mov_b32_e32 v94, v0
	v_mov_b32_e32 v95, v0
	v_mov_b32_e32 v104, v0
	v_mov_b32_e32 v105, v0
	v_mov_b32_e32 v106, v0
	v_mov_b32_e32 v107, v0
	v_mov_b32_e32 v108, v0
	v_mov_b32_e32 v109, v0
	v_mov_b32_e32 v110, v0
	v_mov_b32_e32 v111, v0
	v_mov_b32_e32 v80, v0
	v_mov_b32_e32 v81, v0
	v_mov_b32_e32 v82, v0
	v_mov_b32_e32 v83, v0
	v_mov_b32_e32 v84, v0
	v_mov_b32_e32 v85, v0
	v_mov_b32_e32 v86, v0
	v_mov_b32_e32 v87, v0
	v_mov_b32_e32 v96, v0
	v_mov_b32_e32 v97, v0
	v_mov_b32_e32 v98, v0
	v_mov_b32_e32 v99, v0
	v_mov_b32_e32 v100, v0
	v_mov_b32_e32 v101, v0
	v_mov_b32_e32 v102, v0
	v_mov_b32_e32 v103, v0
	v_mov_b32_e32 v112, v0
	v_mov_b32_e32 v113, v0
	v_mov_b32_e32 v114, v0
	v_mov_b32_e32 v115, v0
	v_mov_b32_e32 v116, v0
	v_mov_b32_e32 v117, v0
	v_mov_b32_e32 v118, v0
	v_mov_b32_e32 v119, v0
	v_mov_b32_e32 v120, v0
	v_mov_b32_e32 v121, v0
	v_mov_b32_e32 v122, v0
	v_mov_b32_e32 v123, v0
	v_mov_b32_e32 v124, v0
	v_mov_b32_e32 v125, v0
	v_mov_b32_e32 v126, v0
	v_mov_b32_e32 v127, v0
	s_cmp_lt_u32 s75, 4
	s_cbranch_scc1 .Lkprio_skip_4
	s_setprio 1
.Lkprio_skip_4:
.LBB0_341:
	s_add_u32 s25, s20, s24
	s_addc_u32 s30, s21, 0
	s_add_u32 s28, s25, 0x100
	s_addc_u32 s29, s30, 0
	s_and_b64 s[26:27], s[22:23], exec
	s_cselect_b32 s27, s15, s29
	s_cselect_b32 s26, s14, s28
	s_add_u32 s24, s18, s24
	s_addc_u32 s28, s19, 0
	s_add_u32 s24, s24, 0x100
	s_addc_u32 s28, s28, 0
	s_and_b64 s[22:23], s[22:23], exec
	s_cselect_b32 s29, s13, s28
	s_cselect_b32 s28, s56, s24
	s_add_u32 s34, s25, 0xc0080
	ds_read_b128 v[140:143], v149
	ds_read_b128 v[152:155], v149 offset:1024
	ds_read_b128 v[156:159], v149 offset:2048
	ds_read_b128 v[160:163], v149 offset:3072
	ds_read_b128 v[164:167], v150
	ds_read_b128 v[168:171], v150 offset:1024
	ds_read_b128 v[172:175], v150 offset:2048
	ds_read_b128 v[176:179], v150 offset:3072
	s_addc_u32 s35, s30, 0
	s_add_i32 s66, s50, s39
	s_add_i32 m0, s42, 0xc000
	s_add_i32 s67, s42, 0xe000
	s_add_i32 s63, s66, 0x2000
	s_add_u32 s30, s28, 0x10000
	s_addc_u32 s31, s29, 0
	s_add_i32 s65, s51, s39
	s_add_i32 s64, s65, 0x2000
	s_add_i32 s62, 0, 0x18000
	s_add_i32 s61, 0, 0x1c000
	s_add_u32 s24, s26, 0xc0000
	s_addc_u32 s25, s27, 0
	s_add_i32 s60, s62, s39
	s_add_i32 s58, s60, 0x2000
	s_add_u32 s22, s28, 0x10080
	s_addc_u32 s23, s29, 0
	s_add_i32 s59, s61, s39
	s_add_i32 s57, s59, 0x2000
	v_lshl_add_u64 v[144:145], s[34:35], 0, v[134:135]
	ds_read_b128 v[180:183], v151
	ds_read_b128 v[184:187], v151 offset:1024
	ds_read_b128 v[188:191], v151 offset:2048
	ds_read_b128 v[192:195], v151 offset:3072
	ds_read_b128 v[196:199], v151 offset:4096
	ds_read_b128 v[200:203], v151 offset:5120
	ds_read_b128 v[204:207], v151 offset:6144
	ds_read_b128 v[208:211], v151 offset:7168
	global_load_lds_dwordx4 v[144:145], off
	v_lshl_add_u64 v[144:145], s[34:35], 0, v[130:131]
	s_mov_b32 m0, s67
	s_nop 0
	global_load_lds_dwordx4 v[144:145], off
	s_waitcnt vmcnt(8)
	s_waitcnt lgkmcnt(0)
	s_barrier
; #define PG8_STAGE(bufoff, gbase, voff) do { _Pragma("unroll") for (int _i = 0; _i < 2; ++_i) \
;         __builtin_amdgcn_global_load_lds((const unsigned*)((const char*)(gbase) + (voff)[_i]), (PG8_LAS unsigned*)(lds + (bufoff) + ldsw + _i * 8192), 16, 0, 0); } while (0)
; #define PG8_LDA(dst, b, h) do { _Pragma("unroll") for (int m = 0; m < 4; ++m) _Pragma("unroll") for (int k = 0; k < 2; ++k) dst[m][k] = *(const PG8_LAS bf16x8*)(lds + PG8_SA(b, h) + aoff + m * 2048 + k * 1024); } while (0)
; #define PG8_MMA(ai, bj, At, Bt) do { __builtin_amdgcn_s_setprio(1); _Pragma("unroll") for (int m = 0; m < 4; ++m) _Pragma("unroll") for (int n = 0; n < 2; ++n) _Pragma("unroll") for (int k = 0; k < 2; ++k) \
;         acc[ai][bj][m][n] = __builtin_amdgcn_mfma_f32_16x16x32_bf16(Bt[n][k], At[m][k], acc[ai][bj][m][n], 0, 0, 0); __builtin_amdgcn_s_setprio(0); } while (0)
; #define PG8_WAIT_V(n) asm volatile("s_waitcnt vmcnt(" #n ")" ::: "memory")
; #define PG8_WAIT_L(n) asm volatile("s_waitcnt lgkmcnt(" #n ")" ::: "memory")
; #define PG8_BAR __builtin_amdgcn_s_barrier()
; #define PG8_SCHED __builtin_amdgcn_sched_barrier(0)
; template <class Epi, class Sched, bool ALIGN_EPI = false, bool SP2 = false>
; __device__ __forceinline__ void gemm_phase(PG8_LAS unsigned char* lds, const Gemm g, const Sched& S, const Epi& E, const int tid_in) {
;     ...
;             PG8_WAIT_V(8); PG8_WAIT_L(0); PG8_BAR; PG8_MMA(0, 0, At, B0); PG8_MMA(0, 1, At, B1); PG8_BAR; PG8_SCHED;
;             PG8_LDA(At, 0, 1); PG8_STAGE(PG8_SB(0, 0), b2, voffB); PG8_STAGE(PG8_SB(0, 1), b2 + hstep, voffB); PG8_STAGE(PG8_SA(0, 0), a2, voffA);
;             PG8_WAIT_V(8); PG8_WAIT_L(0); PG8_BAR; PG8_MMA(1, 0, At, B0); PG8_MMA(1, 1, At, B1); PG8_BAR; PG8_SCHED;
	v_mfma_f32_16x16x32_bf16 v[124:127], v[140:143], v[180:183], v[124:127]
	v_mfma_f32_16x16x32_bf16 v[120:123], v[156:159], v[180:183], v[120:123]
	v_mfma_f32_16x16x32_bf16 v[116:119], v[140:143], v[188:191], v[116:119]
	v_mfma_f32_16x16x32_bf16 v[112:115], v[156:159], v[188:191], v[112:115]
	v_mfma_f32_16x16x32_bf16 v[100:103], v[140:143], v[196:199], v[100:103]
	v_mfma_f32_16x16x32_bf16 v[96:99], v[156:159], v[196:199], v[96:99]
	v_mfma_f32_16x16x32_bf16 v[84:87], v[140:143], v[204:207], v[84:87]
	v_mfma_f32_16x16x32_bf16 v[80:83], v[156:159], v[204:207], v[80:83]
	v_mfma_f32_16x16x32_bf16 v[124:127], v[152:155], v[184:187], v[124:127]
	v_mfma_f32_16x16x32_bf16 v[120:123], v[160:163], v[184:187], v[120:123]
	v_mfma_f32_16x16x32_bf16 v[116:119], v[152:155], v[192:195], v[116:119]
	v_mfma_f32_16x16x32_bf16 v[112:115], v[160:163], v[192:195], v[112:115]
	v_mfma_f32_16x16x32_bf16 v[100:103], v[152:155], v[200:203], v[100:103]
	v_mfma_f32_16x16x32_bf16 v[96:99], v[160:163], v[200:203], v[96:99]
	v_mfma_f32_16x16x32_bf16 v[84:87], v[152:155], v[208:211], v[84:87]
	v_mfma_f32_16x16x32_bf16 v[80:83], v[160:163], v[208:211], v[80:83]
	v_mfma_f32_16x16x32_bf16 v[108:111], v[164:167], v[180:183], v[108:111]
	v_mfma_f32_16x16x32_bf16 v[104:107], v[172:175], v[180:183], v[104:107]
	v_mfma_f32_16x16x32_bf16 v[92:95], v[164:167], v[188:191], v[92:95]
	v_mfma_f32_16x16x32_bf16 v[88:91], v[172:175], v[188:191], v[88:91]
	v_mfma_f32_16x16x32_bf16 v[76:79], v[164:167], v[196:199], v[76:79]
	v_mfma_f32_16x16x32_bf16 v[72:75], v[172:175], v[196:199], v[72:75]
	v_mfma_f32_16x16x32_bf16 v[68:71], v[164:167], v[204:207], v[68:71]
	v_mfma_f32_16x16x32_bf16 v[64:67], v[172:175], v[204:207], v[64:67]
	v_mfma_f32_16x16x32_bf16 v[108:111], v[168:171], v[184:187], v[108:111]
	v_mfma_f32_16x16x32_bf16 v[104:107], v[176:179], v[184:187], v[104:107]
	v_mfma_f32_16x16x32_bf16 v[92:95], v[168:171], v[192:195], v[92:95]
	v_mfma_f32_16x16x32_bf16 v[88:91], v[176:179], v[192:195], v[88:91]
	v_mfma_f32_16x16x32_bf16 v[76:79], v[168:171], v[200:203], v[76:79]
	v_mfma_f32_16x16x32_bf16 v[72:75], v[176:179], v[200:203], v[72:75]
	v_mfma_f32_16x16x32_bf16 v[68:71], v[168:171], v[208:211], v[68:71]
	v_mfma_f32_16x16x32_bf16 v[64:67], v[176:179], v[208:211], v[64:67]
	s_barrier
	s_mov_b32 m0, s66
	v_lshl_add_u64 v[144:145], s[28:29], 0, v[132:133]
	ds_read_b128 v[180:183], v151 offset:16384
	ds_read_b128 v[184:187], v151 offset:17408
	ds_read_b128 v[188:191], v151 offset:18432
	ds_read_b128 v[192:195], v151 offset:19456
	ds_read_b128 v[196:199], v151 offset:20480
	ds_read_b128 v[200:203], v151 offset:21504
	ds_read_b128 v[204:207], v151 offset:22528
	ds_read_b128 v[208:211], v151 offset:23552
	global_load_lds_dwordx4 v[144:145], off
	v_lshl_add_u64 v[212:213], s[28:29], 0, v[128:129]
	s_mov_b32 m0, s63
	v_lshl_add_u64 v[214:215], s[30:31], 0, v[132:133]
	global_load_lds_dwordx4 v[212:213], off
	s_mov_b32 m0, s65
	v_lshl_add_u64 v[216:217], s[26:27], 0, v[130:131]
	global_load_lds_dwordx4 v[214:215], off
	v_lshl_add_u64 v[214:215], s[30:31], 0, v[128:129]
	s_mov_b32 m0, s64
	s_nop 0
	global_load_lds_dwordx4 v[214:215], off
	v_lshl_add_u64 v[214:215], s[26:27], 0, v[134:135]
	s_mov_b32 m0, s42
	s_nop 0
	global_load_lds_dwordx4 v[214:215], off
	s_mov_b32 m0, s43
	s_nop 0
	global_load_lds_dwordx4 v[216:217], off
	s_waitcnt vmcnt(8)
	s_waitcnt lgkmcnt(0)
	s_barrier
	v_mfma_f32_16x16x32_bf16 v[60:63], v[140:143], v[180:183], v[60:63]
	v_mfma_f32_16x16x32_bf16 v[56:59], v[156:159], v[180:183], v[56:59]
	v_mfma_f32_16x16x32_bf16 v[52:55], v[140:143], v[188:191], v[52:55]
	v_mfma_f32_16x16x32_bf16 v[48:51], v[156:159], v[188:191], v[48:51]
	v_mfma_f32_16x16x32_bf16 v[36:39], v[140:143], v[196:199], v[36:39]
	v_mfma_f32_16x16x32_bf16 v[32:35], v[156:159], v[196:199], v[32:35]
	v_mfma_f32_16x16x32_bf16 v[20:23], v[140:143], v[204:207], v[20:23]
	v_mfma_f32_16x16x32_bf16 v[16:19], v[156:159], v[204:207], v[16:19]
	v_mfma_f32_16x16x32_bf16 v[60:63], v[152:155], v[184:187], v[60:63]
	v_mfma_f32_16x16x32_bf16 v[56:59], v[160:163], v[184:187], v[56:59]
	v_mfma_f32_16x16x32_bf16 v[52:55], v[152:155], v[192:195], v[52:55]
	v_mfma_f32_16x16x32_bf16 v[48:51], v[160:163], v[192:195], v[48:51]
	v_mfma_f32_16x16x32_bf16 v[36:39], v[152:155], v[200:203], v[36:39]
	v_mfma_f32_16x16x32_bf16 v[32:35], v[160:163], v[200:203], v[32:35]
	v_mfma_f32_16x16x32_bf16 v[20:23], v[152:155], v[208:211], v[20:23]
	v_mfma_f32_16x16x32_bf16 v[16:19], v[160:163], v[208:211], v[16:19]
	v_mfma_f32_16x16x32_bf16 v[44:47], v[164:167], v[180:183], v[44:47]
	v_mfma_f32_16x16x32_bf16 v[40:43], v[172:175], v[180:183], v[40:43]
	v_mfma_f32_16x16x32_bf16 v[28:31], v[164:167], v[188:191], v[28:31]
	v_mfma_f32_16x16x32_bf16 v[24:27], v[172:175], v[188:191], v[24:27]
	v_mfma_f32_16x16x32_bf16 v[12:15], v[164:167], v[196:199], v[12:15]
	v_mfma_f32_16x16x32_bf16 v[8:11], v[172:175], v[196:199], v[8:11]
	v_mfma_f32_16x16x32_bf16 v[4:7], v[164:167], v[204:207], v[4:7]
	v_mfma_f32_16x16x32_bf16 v[0:3], v[172:175], v[204:207], v[0:3]
	v_mfma_f32_16x16x32_bf16 v[44:47], v[168:171], v[184:187], v[44:47]
	v_mfma_f32_16x16x32_bf16 v[40:43], v[176:179], v[184:187], v[40:43]
	v_mfma_f32_16x16x32_bf16 v[28:31], v[168:171], v[192:195], v[28:31]
	v_mfma_f32_16x16x32_bf16 v[24:27], v[176:179], v[192:195], v[24:27]
	v_mfma_f32_16x16x32_bf16 v[12:15], v[168:171], v[200:203], v[12:15]
	v_mfma_f32_16x16x32_bf16 v[8:11], v[176:179], v[200:203], v[8:11]
	v_mfma_f32_16x16x32_bf16 v[4:7], v[168:171], v[208:211], v[4:7]
	v_mfma_f32_16x16x32_bf16 v[0:3], v[176:179], v[208:211], v[0:3]
	s_barrier
; #define PG8_STAGE(bufoff, gbase, voff) do { _Pragma("unroll") for (int _i = 0; _i < 2; ++_i) \
;         __builtin_amdgcn_global_load_lds((const unsigned*)((const char*)(gbase) + (voff)[_i]), (PG8_LAS unsigned*)(lds + (bufoff) + ldsw + _i * 8192), 16, 0, 0); } while (0)
; #define PG8_LDA(dst, b, h) do { _Pragma("unroll") for (int m = 0; m < 4; ++m) _Pragma("unroll") for (int k = 0; k < 2; ++k) dst[m][k] = *(const PG8_LAS bf16x8*)(lds + PG8_SA(b, h) + aoff + m * 2048 + k * 1024); } while (0)
; #define PG8_LDB(dst, b, h) do { _Pragma("unroll") for (int n = 0; n < 2; ++n) _Pragma("unroll") for (int k = 0; k < 2; ++k) dst[n][k] = *(const PG8_LAS bf16x8*)(lds + PG8_SB(b, h) + boff + n * 2048 + k * 1024); } while (0)
; #define PG8_MMA(ai, bj, At, Bt) do { __builtin_amdgcn_s_setprio(1); _Pragma("unroll") for (int m = 0; m < 4; ++m) _Pragma("unroll") for (int n = 0; n < 2; ++n) _Pragma("unroll") for (int k = 0; k < 2; ++k) \
;         acc[ai][bj][m][n] = __builtin_amdgcn_mfma_f32_16x16x32_bf16(Bt[n][k], At[m][k], acc[ai][bj][m][n], 0, 0, 0); __builtin_amdgcn_s_setprio(0); } while (0)
; #define PG8_WAIT_V(n) asm volatile("s_waitcnt vmcnt(" #n ")" ::: "memory")
; #define PG8_WAIT_L(n) asm volatile("s_waitcnt lgkmcnt(" #n ")" ::: "memory")
; #define PG8_BAR __builtin_amdgcn_s_barrier()
; #define PG8_SCHED __builtin_amdgcn_sched_barrier(0)
; template <class Epi, class Sched, bool ALIGN_EPI = false, bool SP2 = false>
; __device__ __forceinline__ void gemm_phase(PG8_LAS unsigned char* lds, const Gemm g, const Sched& S, const Epi& E, const int tid_in) {
;     ...
;             PG8_LDB(B0, 1, 0); PG8_LDB(B1, 1, 1); PG8_SCHED; PG8_LDA(At, 1, 0); PG8_STAGE(PG8_SA(0, 1), a2 + hstepA, voffA);
;             PG8_WAIT_V(8); PG8_WAIT_L(0); PG8_BAR; PG8_MMA(0, 0, At, B0); PG8_MMA(0, 1, At, B1); PG8_BAR; PG8_SCHED;
;             PG8_LDA(At, 1, 1); PG8_STAGE(PG8_SB(1, 0), b3, voffB); PG8_STAGE(PG8_SB(1, 1), b3 + hstep, voffB); PG8_STAGE(PG8_SA(1, 0), a3, voffA);
;             PG8_WAIT_V(8); PG8_WAIT_L(0); PG8_BAR; PG8_MMA(1, 0, At, B0); PG8_MMA(1, 1, At, B1); PG8_BAR; PG8_SCHED;
;     ...
;         }
	v_add_u32_e32 v160, s62, v147
	v_add_u32_e32 v176, s61, v147
	ds_read_b128 v[140:143], v160
	ds_read_b128 v[152:155], v160 offset:1024
	ds_read_b128 v[156:159], v160 offset:2048
	ds_read_b128 v[160:163], v160 offset:3072
	ds_read_b128 v[164:167], v176
	ds_read_b128 v[168:171], v176 offset:1024
	ds_read_b128 v[172:175], v176 offset:2048
	ds_read_b128 v[176:179], v176 offset:3072
	s_mov_b32 m0, s44
	v_lshl_add_u64 v[218:219], s[24:25], 0, v[134:135]
	ds_read_b128 v[180:183], v151 offset:32768
	ds_read_b128 v[184:187], v151 offset:33792
	ds_read_b128 v[188:191], v151 offset:34816
	ds_read_b128 v[192:195], v151 offset:35840
	ds_read_b128 v[196:199], v151 offset:36864
	ds_read_b128 v[200:203], v151 offset:37888
	ds_read_b128 v[204:207], v151 offset:38912
	ds_read_b128 v[208:211], v151 offset:39936
	global_load_lds_dwordx4 v[218:219], off
	v_lshl_add_u64 v[218:219], s[24:25], 0, v[130:131]
	s_mov_b32 m0, s45
	s_nop 0
	global_load_lds_dwordx4 v[218:219], off
	s_waitcnt vmcnt(8)
	s_waitcnt lgkmcnt(0)
	s_barrier
	v_mfma_f32_16x16x32_bf16 v[124:127], v[140:143], v[180:183], v[124:127]
	v_mfma_f32_16x16x32_bf16 v[120:123], v[156:159], v[180:183], v[120:123]
	v_mfma_f32_16x16x32_bf16 v[116:119], v[140:143], v[188:191], v[116:119]
	v_mfma_f32_16x16x32_bf16 v[112:115], v[156:159], v[188:191], v[112:115]
	v_mfma_f32_16x16x32_bf16 v[100:103], v[140:143], v[196:199], v[100:103]
	v_mfma_f32_16x16x32_bf16 v[96:99], v[156:159], v[196:199], v[96:99]
	v_mfma_f32_16x16x32_bf16 v[84:87], v[140:143], v[204:207], v[84:87]
	v_mfma_f32_16x16x32_bf16 v[80:83], v[156:159], v[204:207], v[80:83]
	v_mfma_f32_16x16x32_bf16 v[124:127], v[152:155], v[184:187], v[124:127]
	v_mfma_f32_16x16x32_bf16 v[120:123], v[160:163], v[184:187], v[120:123]
	v_mfma_f32_16x16x32_bf16 v[116:119], v[152:155], v[192:195], v[116:119]
	v_mfma_f32_16x16x32_bf16 v[112:115], v[160:163], v[192:195], v[112:115]
	v_mfma_f32_16x16x32_bf16 v[100:103], v[152:155], v[200:203], v[100:103]
	v_mfma_f32_16x16x32_bf16 v[96:99], v[160:163], v[200:203], v[96:99]
	v_mfma_f32_16x16x32_bf16 v[84:87], v[152:155], v[208:211], v[84:87]
	v_mfma_f32_16x16x32_bf16 v[80:83], v[160:163], v[208:211], v[80:83]
	v_mfma_f32_16x16x32_bf16 v[108:111], v[164:167], v[180:183], v[108:111]
	v_mfma_f32_16x16x32_bf16 v[104:107], v[172:175], v[180:183], v[104:107]
	v_mfma_f32_16x16x32_bf16 v[92:95], v[164:167], v[188:191], v[92:95]
	v_mfma_f32_16x16x32_bf16 v[88:91], v[172:175], v[188:191], v[88:91]
	v_mfma_f32_16x16x32_bf16 v[76:79], v[164:167], v[196:199], v[76:79]
	v_mfma_f32_16x16x32_bf16 v[72:75], v[172:175], v[196:199], v[72:75]
	v_mfma_f32_16x16x32_bf16 v[68:71], v[164:167], v[204:207], v[68:71]
	v_mfma_f32_16x16x32_bf16 v[64:67], v[172:175], v[204:207], v[64:67]
	v_mfma_f32_16x16x32_bf16 v[108:111], v[168:171], v[184:187], v[108:111]
	v_mfma_f32_16x16x32_bf16 v[104:107], v[176:179], v[184:187], v[104:107]
	v_mfma_f32_16x16x32_bf16 v[92:95], v[168:171], v[192:195], v[92:95]
	v_mfma_f32_16x16x32_bf16 v[88:91], v[176:179], v[192:195], v[88:91]
	v_mfma_f32_16x16x32_bf16 v[76:79], v[168:171], v[200:203], v[76:79]
	v_mfma_f32_16x16x32_bf16 v[72:75], v[176:179], v[200:203], v[72:75]
	v_mfma_f32_16x16x32_bf16 v[68:71], v[168:171], v[208:211], v[68:71]
	v_mfma_f32_16x16x32_bf16 v[64:67], v[176:179], v[208:211], v[64:67]
	s_barrier
	s_mov_b32 m0, s60
	v_lshl_add_u64 v[144:145], v[144:145], 0, s[8:9]
	ds_read_b128 v[180:183], v151 offset:49152
	ds_read_b128 v[184:187], v151 offset:50176
	ds_read_b128 v[188:191], v151 offset:51200
	ds_read_b128 v[192:195], v151 offset:52224
	ds_read_b128 v[196:199], v151 offset:53248
	ds_read_b128 v[200:203], v151 offset:54272
	ds_read_b128 v[204:207], v151 offset:55296
	ds_read_b128 v[208:211], v151 offset:56320
	global_load_lds_dwordx4 v[144:145], off
	v_lshl_add_u64 v[144:145], v[212:213], 0, s[8:9]
	s_mov_b32 m0, s58
	s_nop 0
	global_load_lds_dwordx4 v[144:145], off
	v_lshl_add_u64 v[144:145], s[22:23], 0, v[132:133]
	s_mov_b32 m0, s59
	s_nop 0
	global_load_lds_dwordx4 v[144:145], off
	v_lshl_add_u64 v[144:145], s[22:23], 0, v[128:129]
	s_mov_b32 m0, s57
	s_nop 0
	global_load_lds_dwordx4 v[144:145], off
	v_lshl_add_u64 v[144:145], v[214:215], 0, s[8:9]
	s_mov_b32 m0, s46
	s_nop 0
	global_load_lds_dwordx4 v[144:145], off
	v_lshl_add_u64 v[144:145], v[216:217], 0, s[8:9]
	s_mov_b32 m0, s47
	s_nop 0
	global_load_lds_dwordx4 v[144:145], off
	s_waitcnt vmcnt(8)
	s_waitcnt lgkmcnt(0)
	s_barrier
	v_mfma_f32_16x16x32_bf16 v[60:63], v[140:143], v[180:183], v[60:63]
	v_mfma_f32_16x16x32_bf16 v[56:59], v[156:159], v[180:183], v[56:59]
	v_mfma_f32_16x16x32_bf16 v[52:55], v[140:143], v[188:191], v[52:55]
	v_mfma_f32_16x16x32_bf16 v[48:51], v[156:159], v[188:191], v[48:51]
	v_mfma_f32_16x16x32_bf16 v[36:39], v[140:143], v[196:199], v[36:39]
	v_mfma_f32_16x16x32_bf16 v[32:35], v[156:159], v[196:199], v[32:35]
	v_mfma_f32_16x16x32_bf16 v[20:23], v[140:143], v[204:207], v[20:23]
	v_mfma_f32_16x16x32_bf16 v[16:19], v[156:159], v[204:207], v[16:19]
	v_mfma_f32_16x16x32_bf16 v[60:63], v[152:155], v[184:187], v[60:63]
	v_mfma_f32_16x16x32_bf16 v[56:59], v[160:163], v[184:187], v[56:59]
	v_mfma_f32_16x16x32_bf16 v[52:55], v[152:155], v[192:195], v[52:55]
	v_mfma_f32_16x16x32_bf16 v[48:51], v[160:163], v[192:195], v[48:51]
	v_mfma_f32_16x16x32_bf16 v[36:39], v[152:155], v[200:203], v[36:39]
	v_mfma_f32_16x16x32_bf16 v[32:35], v[160:163], v[200:203], v[32:35]
	v_mfma_f32_16x16x32_bf16 v[20:23], v[152:155], v[208:211], v[20:23]
	v_mfma_f32_16x16x32_bf16 v[16:19], v[160:163], v[208:211], v[16:19]
	v_mfma_f32_16x16x32_bf16 v[44:47], v[164:167], v[180:183], v[44:47]
	v_mfma_f32_16x16x32_bf16 v[40:43], v[172:175], v[180:183], v[40:43]
	v_mfma_f32_16x16x32_bf16 v[28:31], v[164:167], v[188:191], v[28:31]
	v_mfma_f32_16x16x32_bf16 v[24:27], v[172:175], v[188:191], v[24:27]
	v_mfma_f32_16x16x32_bf16 v[12:15], v[164:167], v[196:199], v[12:15]
	v_mfma_f32_16x16x32_bf16 v[8:11], v[172:175], v[196:199], v[8:11]
	v_mfma_f32_16x16x32_bf16 v[4:7], v[164:167], v[204:207], v[4:7]
	v_mfma_f32_16x16x32_bf16 v[0:3], v[172:175], v[204:207], v[0:3]
	v_mfma_f32_16x16x32_bf16 v[44:47], v[168:171], v[184:187], v[44:47]
	v_mfma_f32_16x16x32_bf16 v[40:43], v[176:179], v[184:187], v[40:43]
	v_mfma_f32_16x16x32_bf16 v[28:31], v[168:171], v[192:195], v[28:31]
	v_mfma_f32_16x16x32_bf16 v[24:27], v[176:179], v[192:195], v[24:27]
	v_mfma_f32_16x16x32_bf16 v[12:15], v[168:171], v[200:203], v[12:15]
	v_mfma_f32_16x16x32_bf16 v[8:11], v[176:179], v[200:203], v[8:11]
	v_mfma_f32_16x16x32_bf16 v[4:7], v[168:171], v[208:211], v[4:7]
	v_mfma_f32_16x16x32_bf16 v[0:3], v[176:179], v[208:211], v[0:3]
	s_barrier
	s_movk_i32 s24, 0x100
	s_andn2_b64 vcc, exec, s[2:3]
	s_mov_b64 s[22:23], -1
	s_mov_b64 s[2:3], 0
	s_cbranch_vccz .LBB0_341
	s_setprio 0
	s_and_b64 vcc, exec, s[10:11]
	s_cbranch_vccz .LBB0_344
	s_barrier

; #define PG8_STAGE(bufoff, gbase, voff) do { _Pragma("unroll") for (int _i = 0; _i < 2; ++_i) \
;         __builtin_amdgcn_global_load_lds((const unsigned*)((const char*)(gbase) + (voff)[_i]), (PG8_LAS unsigned*)(lds + (bufoff) + ldsw + _i * 8192), 16, 0, 0); } while (0)
; #define PG8_LDA(dst, b, h) do { _Pragma("unroll") for (int m = 0; m < 4; ++m) _Pragma("unroll") for (int k = 0; k < 2; ++k) dst[m][k] = *(const PG8_LAS bf16x8*)(lds + PG8_SA(b, h) + aoff + m * 2048 + k * 1024); } while (0)
; #define PG8_LDB(dst, b, h) do { _Pragma("unroll") for (int n = 0; n < 2; ++n) _Pragma("unroll") for (int k = 0; k < 2; ++k) dst[n][k] = *(const PG8_LAS bf16x8*)(lds + PG8_SB(b, h) + boff + n * 2048 + k * 1024); } while (0)
; #define PG8_MMA(ai, bj, At, Bt) do { __builtin_amdgcn_s_setprio(1); _Pragma("unroll") for (int m = 0; m < 4; ++m) _Pragma("unroll") for (int n = 0; n < 2; ++n) _Pragma("unroll") for (int k = 0; k < 2; ++k) \
;         acc[ai][bj][m][n] = __builtin_amdgcn_mfma_f32_16x16x32_bf16(Bt[n][k], At[m][k], acc[ai][bj][m][n], 0, 0, 0); __builtin_amdgcn_s_setprio(0); } while (0)
; #define PG8_WAIT_V(n) asm volatile("s_waitcnt vmcnt(" #n ")" ::: "memory")
; #define PG8_WAIT_L(n) asm volatile("s_waitcnt lgkmcnt(" #n ")" ::: "memory")
; template <class Epi, class Sched, bool ALIGN_EPI = false, bool SP2 = false>
; __device__ __forceinline__ void gemm_phase(PG8_LAS unsigned char* lds, const Gemm g, const Sched& S, const Epi& E, const int tid_in) {
;     ...
;         const bool has_next = S.next(ui + 1, nxt);
;         const char* nA = has_next ? (const char*)g.A + (size_t)nxt.pm * tstepA : cA; const char* nB = has_next ? (const char*)g.Bt + (size_t)nxt.pn * tstep : cB;
;         for (int t = 0; t < nt; t += 2) {
;             const bool last = (t == nt - 2);
;             const char* a1 = cA + (size_t)(t + 1) * kstep;
;             const char* a2 = last ? nA : cA + (size_t)(t + 2) * kstep; const char* b2 = last ? nB : cB + (size_t)(t + 2) * kstep;
;             const char* a3 = a2 + kstep; const char* b3 = b2 + kstep;
;             if (last && has_next) S.a_ready(nxt);
;             if constexpr (SP2) {
;             PG8_LDB(B0, 0, 0); PG8_LDB(B1, 0, 1); PG8_SCHED; PG8_LDA(At, 0, 0); PG8_STAGE(PG8_SA(1, 1), a1 + hstepA, voffA);
;             PG8_WAIT_V(8); PG8_WAIT_L(0); PG8_BAR; PG8_MMA(0, 0, At, B0); PG8_MMA(0, 1, At, B1); PG8_BAR; PG8_SCHED;
.LBB0_617:
	s_ashr_i32 s17, s16, 31
	s_lshl_b64 s[18:19], s[16:17], 20
	s_add_u32 s18, s33, s18
	s_addc_u32 s19, s34, s19
	s_and_b64 s[20:21], s[2:3], exec
	s_cselect_b32 s17, s19, s29
	s_cselect_b32 s23, s18, s28
	s_ashr_i32 s15, s14, 31
	s_lshl_b64 s[20:21], s[14:15], 20
	s_add_u32 s20, s35, s20
	s_addc_u32 s21, s36, s21
	s_and_b64 s[30:31], s[2:3], exec
	s_cselect_b32 s15, s21, s27
	s_cselect_b32 s48, s20, s26
	s_add_u32 s49, s26, 0x100
	s_addc_u32 s50, s27, 0
	s_add_u32 s26, s28, 0x80080
	v_mov_b32_e32 v0, 0
	s_addc_u32 s27, s29, 0
	s_mov_b32 s51, -2
	s_waitcnt lgkmcnt(0)
	v_mov_b32_e32 v1, v0
	v_mov_b32_e32 v2, v0
	v_mov_b32_e32 v3, v0
	v_mov_b32_e32 v4, v0
	v_mov_b32_e32 v5, v0
	v_mov_b32_e32 v6, v0
	v_mov_b32_e32 v7, v0
	v_mov_b32_e32 v16, v0
	v_mov_b32_e32 v17, v0
	v_mov_b32_e32 v18, v0
	v_mov_b32_e32 v19, v0
	v_mov_b32_e32 v20, v0
	v_mov_b32_e32 v21, v0
	v_mov_b32_e32 v22, v0
	v_mov_b32_e32 v23, v0
	v_mov_b32_e32 v32, v0
	v_mov_b32_e32 v33, v0
	v_mov_b32_e32 v34, v0
	v_mov_b32_e32 v35, v0
	v_mov_b32_e32 v36, v0
	v_mov_b32_e32 v37, v0
	v_mov_b32_e32 v38, v0
	v_mov_b32_e32 v39, v0
	v_mov_b32_e32 v48, v0
	v_mov_b32_e32 v49, v0
	v_mov_b32_e32 v50, v0
	v_mov_b32_e32 v51, v0
	v_mov_b32_e32 v52, v0
	v_mov_b32_e32 v53, v0
	v_mov_b32_e32 v54, v0
	v_mov_b32_e32 v55, v0
	v_mov_b32_e32 v8, v0
	v_mov_b32_e32 v9, v0
	v_mov_b32_e32 v10, v0
	v_mov_b32_e32 v11, v0
	v_mov_b32_e32 v12, v0
	v_mov_b32_e32 v13, v0
	v_mov_b32_e32 v14, v0
	v_mov_b32_e32 v15, v0
	v_mov_b32_e32 v24, v0
	v_mov_b32_e32 v25, v0
	v_mov_b32_e32 v26, v0
	v_mov_b32_e32 v27, v0
	v_mov_b32_e32 v28, v0
	v_mov_b32_e32 v29, v0
	v_mov_b32_e32 v30, v0
	v_mov_b32_e32 v31, v0
	v_mov_b32_e32 v40, v0
	v_mov_b32_e32 v41, v0
	v_mov_b32_e32 v42, v0
	v_mov_b32_e32 v43, v0
	v_mov_b32_e32 v44, v0
	v_mov_b32_e32 v45, v0
	v_mov_b32_e32 v46, v0
	v_mov_b32_e32 v47, v0
	v_mov_b32_e32 v56, v0
	v_mov_b32_e32 v57, v0
	v_mov_b32_e32 v58, v0
	v_mov_b32_e32 v59, v0
	v_mov_b32_e32 v60, v0
	v_mov_b32_e32 v61, v0
	v_mov_b32_e32 v62, v0
	v_mov_b32_e32 v63, v0
	v_mov_b32_e32 v64, v0
	v_mov_b32_e32 v65, v0
	v_mov_b32_e32 v66, v0
	v_mov_b32_e32 v67, v0
	v_mov_b32_e32 v68, v0
	v_mov_b32_e32 v69, v0
	v_mov_b32_e32 v70, v0
	v_mov_b32_e32 v71, v0
	v_mov_b32_e32 v80, v0
	v_mov_b32_e32 v81, v0
	v_mov_b32_e32 v82, v0
	v_mov_b32_e32 v83, v0
	v_mov_b32_e32 v84, v0
	v_mov_b32_e32 v85, v0
	v_mov_b32_e32 v86, v0
	v_mov_b32_e32 v87, v0
	v_mov_b32_e32 v96, v0
	v_mov_b32_e32 v97, v0
	v_mov_b32_e32 v98, v0
	v_mov_b32_e32 v99, v0
	v_mov_b32_e32 v100, v0
	v_mov_b32_e32 v101, v0
	v_mov_b32_e32 v102, v0
	v_mov_b32_e32 v103, v0
	v_mov_b32_e32 v120, v0
	v_mov_b32_e32 v121, v0
	v_mov_b32_e32 v122, v0
	v_mov_b32_e32 v123, v0
	v_mov_b32_e32 v124, v0
	v_mov_b32_e32 v125, v0
	v_mov_b32_e32 v126, v0
	v_mov_b32_e32 v127, v0
	v_mov_b32_e32 v72, v0
	v_mov_b32_e32 v73, v0
	v_mov_b32_e32 v74, v0
	v_mov_b32_e32 v75, v0
	v_mov_b32_e32 v76, v0
	v_mov_b32_e32 v77, v0
	v_mov_b32_e32 v78, v0
	v_mov_b32_e32 v79, v0
	v_mov_b32_e32 v88, v0
	v_mov_b32_e32 v89, v0
	v_mov_b32_e32 v90, v0
	v_mov_b32_e32 v91, v0
	v_mov_b32_e32 v92, v0
	v_mov_b32_e32 v93, v0
	v_mov_b32_e32 v94, v0
	v_mov_b32_e32 v95, v0
	v_mov_b32_e32 v108, v0
	v_mov_b32_e32 v109, v0
	v_mov_b32_e32 v110, v0
	v_mov_b32_e32 v111, v0
	v_mov_b32_e32 v112, v0
	v_mov_b32_e32 v113, v0
	v_mov_b32_e32 v114, v0
	v_mov_b32_e32 v115, v0
	v_mov_b32_e32 v132, v0
	v_mov_b32_e32 v133, v0
	v_mov_b32_e32 v134, v0
	v_mov_b32_e32 v135, v0
	v_mov_b32_e32 v136, v0
	v_mov_b32_e32 v137, v0
	v_mov_b32_e32 v138, v0
	v_mov_b32_e32 v139, v0
	s_cmp_lt_u32 s75, 4
	s_cbranch_scc1 .Lkprio_skip_5
	s_setprio 1
.Lkprio_skip_5:
.LBB0_618:
	ds_read_b128 v[104:107], v222
	ds_read_b128 v[116:119], v222 offset:1024
	ds_read_b128 v[128:131], v222 offset:2048
	ds_read_b128 v[140:143], v222 offset:3072
	ds_read_b128 v[144:147], v223
	ds_read_b128 v[148:151], v223 offset:1024
	ds_read_b128 v[152:155], v223 offset:2048
	ds_read_b128 v[156:159], v223 offset:3072
	s_add_u32 s28, s26, 0xfff80080
	s_addc_u32 s29, s27, -1
	s_cmp_eq_u32 s51, 28
	s_cselect_b32 s31, s17, s29
	s_cselect_b32 s30, s23, s28
	s_cselect_b32 s29, s15, s50
	s_cselect_b32 s28, s48, s49
	v_lshl_add_u64 v[208:209], s[26:27], 0, v[194:195]
	s_add_i32 m0, s25, 0xc000
	ds_read_b128 v[160:163], v224
	ds_read_b128 v[164:167], v224 offset:1024
	ds_read_b128 v[168:171], v224 offset:2048
	ds_read_b128 v[172:175], v224 offset:3072
	ds_read_b128 v[176:179], v224 offset:4096
	ds_read_b128 v[180:183], v224 offset:5120
	ds_read_b128 v[200:203], v224 offset:6144
	ds_read_b128 v[204:207], v224 offset:7168
	global_load_lds_dwordx4 v[208:209], off
	v_lshl_add_u64 v[208:209], s[26:27], 0, v[192:193]
	s_add_i32 m0, s25, 0xe000
	s_nop 0
	global_load_lds_dwordx4 v[208:209], off
	s_waitcnt vmcnt(8)
	s_waitcnt lgkmcnt(0)
	s_barrier
; #define PG8_STAGE(bufoff, gbase, voff) do { _Pragma("unroll") for (int _i = 0; _i < 2; ++_i) \
;         __builtin_amdgcn_global_load_lds((const unsigned*)((const char*)(gbase) + (voff)[_i]), (PG8_LAS unsigned*)(lds + (bufoff) + ldsw + _i * 8192), 16, 0, 0); } while (0)
; #define PG8_LDA(dst, b, h) do { _Pragma("unroll") for (int m = 0; m < 4; ++m) _Pragma("unroll") for (int k = 0; k < 2; ++k) dst[m][k] = *(const PG8_LAS bf16x8*)(lds + PG8_SA(b, h) + aoff + m * 2048 + k * 1024); } while (0)
; #define PG8_MMA(ai, bj, At, Bt) do { __builtin_amdgcn_s_setprio(1); _Pragma("unroll") for (int m = 0; m < 4; ++m) _Pragma("unroll") for (int n = 0; n < 2; ++n) _Pragma("unroll") for (int k = 0; k < 2; ++k) \
;         acc[ai][bj][m][n] = __builtin_amdgcn_mfma_f32_16x16x32_bf16(Bt[n][k], At[m][k], acc[ai][bj][m][n], 0, 0, 0); __builtin_amdgcn_s_setprio(0); } while (0)
; #define PG8_WAIT_V(n) asm volatile("s_waitcnt vmcnt(" #n ")" ::: "memory")
; #define PG8_WAIT_L(n) asm volatile("s_waitcnt lgkmcnt(" #n ")" ::: "memory")
; #define PG8_BAR __builtin_amdgcn_s_barrier()
; #define PG8_SCHED __builtin_amdgcn_sched_barrier(0)
; template <class Epi, class Sched, bool ALIGN_EPI = false, bool SP2 = false>
; __device__ __forceinline__ void gemm_phase(PG8_LAS unsigned char* lds, const Gemm g, const Sched& S, const Epi& E, const int tid_in) {
;     ...
;             PG8_WAIT_V(8); PG8_WAIT_L(0); PG8_BAR; PG8_MMA(0, 0, At, B0); PG8_MMA(0, 1, At, B1); PG8_BAR; PG8_SCHED;
;             PG8_LDA(At, 0, 1); PG8_STAGE(PG8_SB(0, 0), b2, voffB); PG8_STAGE(PG8_SB(0, 1), b2 + hstep, voffB); PG8_STAGE(PG8_SA(0, 0), a2, voffA);
;             PG8_WAIT_V(8); PG8_WAIT_L(0); PG8_BAR; PG8_MMA(1, 0, At, B0); PG8_MMA(1, 1, At, B1); PG8_BAR; PG8_SCHED;
	v_mfma_f32_16x16x32_bf16 v[136:139], v[104:107], v[160:163], v[136:139]
	v_mfma_f32_16x16x32_bf16 v[132:135], v[128:131], v[160:163], v[132:135]
	v_mfma_f32_16x16x32_bf16 v[112:115], v[104:107], v[168:171], v[112:115]
	v_mfma_f32_16x16x32_bf16 v[108:111], v[128:131], v[168:171], v[108:111]
	v_mfma_f32_16x16x32_bf16 v[92:95], v[104:107], v[176:179], v[92:95]
	v_mfma_f32_16x16x32_bf16 v[88:91], v[128:131], v[176:179], v[88:91]
	v_mfma_f32_16x16x32_bf16 v[76:79], v[104:107], v[200:203], v[76:79]
	v_mfma_f32_16x16x32_bf16 v[72:75], v[128:131], v[200:203], v[72:75]
	v_mfma_f32_16x16x32_bf16 v[136:139], v[116:119], v[164:167], v[136:139]
	v_mfma_f32_16x16x32_bf16 v[132:135], v[140:143], v[164:167], v[132:135]
	v_mfma_f32_16x16x32_bf16 v[112:115], v[116:119], v[172:175], v[112:115]
	v_mfma_f32_16x16x32_bf16 v[108:111], v[140:143], v[172:175], v[108:111]
	v_mfma_f32_16x16x32_bf16 v[92:95], v[116:119], v[180:183], v[92:95]
	v_mfma_f32_16x16x32_bf16 v[88:91], v[140:143], v[180:183], v[88:91]
	v_mfma_f32_16x16x32_bf16 v[76:79], v[116:119], v[204:207], v[76:79]
	v_mfma_f32_16x16x32_bf16 v[72:75], v[140:143], v[204:207], v[72:75]
	v_mfma_f32_16x16x32_bf16 v[124:127], v[144:147], v[160:163], v[124:127]
	v_mfma_f32_16x16x32_bf16 v[120:123], v[152:155], v[160:163], v[120:123]
	v_mfma_f32_16x16x32_bf16 v[100:103], v[144:147], v[168:171], v[100:103]
	v_mfma_f32_16x16x32_bf16 v[96:99], v[152:155], v[168:171], v[96:99]
	v_mfma_f32_16x16x32_bf16 v[84:87], v[144:147], v[176:179], v[84:87]
	v_mfma_f32_16x16x32_bf16 v[80:83], v[152:155], v[176:179], v[80:83]
	v_mfma_f32_16x16x32_bf16 v[68:71], v[144:147], v[200:203], v[68:71]
	v_mfma_f32_16x16x32_bf16 v[64:67], v[152:155], v[200:203], v[64:67]
	v_mfma_f32_16x16x32_bf16 v[124:127], v[148:151], v[164:167], v[124:127]
	v_mfma_f32_16x16x32_bf16 v[120:123], v[156:159], v[164:167], v[120:123]
	v_mfma_f32_16x16x32_bf16 v[100:103], v[148:151], v[172:175], v[100:103]
	v_mfma_f32_16x16x32_bf16 v[96:99], v[156:159], v[172:175], v[96:99]
	v_mfma_f32_16x16x32_bf16 v[84:87], v[148:151], v[180:183], v[84:87]
	v_mfma_f32_16x16x32_bf16 v[80:83], v[156:159], v[180:183], v[80:83]
	v_mfma_f32_16x16x32_bf16 v[68:71], v[148:151], v[204:207], v[68:71]
	v_mfma_f32_16x16x32_bf16 v[64:67], v[156:159], v[204:207], v[64:67]
	s_barrier
	s_add_i32 s52, s46, s37
	v_lshl_add_u64 v[208:209], s[28:29], 0, v[186:187]
	s_mov_b32 m0, s52
	ds_read_b128 v[160:163], v224 offset:16384
	ds_read_b128 v[164:167], v224 offset:17408
	ds_read_b128 v[168:171], v224 offset:18432
	ds_read_b128 v[172:175], v224 offset:19456
	ds_read_b128 v[176:179], v224 offset:20480
	ds_read_b128 v[180:183], v224 offset:21504
	ds_read_b128 v[200:203], v224 offset:22528
	ds_read_b128 v[204:207], v224 offset:23552
	global_load_lds_dwordx4 v[208:209], off
	s_add_i32 m0, s52, 0x2000
	s_add_u32 s52, s28, 0x80000
	v_lshl_add_u64 v[210:211], s[28:29], 0, v[190:191]
	s_addc_u32 s53, s29, 0
	s_add_i32 s54, s47, s37
	global_load_lds_dwordx4 v[210:211], off
	v_lshl_add_u64 v[212:213], s[52:53], 0, v[186:187]
	s_mov_b32 m0, s54
	v_lshl_add_u64 v[214:215], s[30:31], 0, v[188:189]
	global_load_lds_dwordx4 v[212:213], off
	v_lshl_add_u64 v[212:213], s[52:53], 0, v[190:191]
	s_add_i32 m0, s54, 0x2000
	s_nop 0
	global_load_lds_dwordx4 v[212:213], off
	v_lshl_add_u64 v[212:213], s[30:31], 0, v[184:185]
	s_mov_b32 m0, s25
	s_nop 0
	global_load_lds_dwordx4 v[212:213], off
	s_mov_b32 m0, s38
	s_nop 0
	global_load_lds_dwordx4 v[214:215], off
	s_waitcnt vmcnt(8)
	s_waitcnt lgkmcnt(0)
	s_barrier
	v_mfma_f32_16x16x32_bf16 v[60:63], v[104:107], v[160:163], v[60:63]
	v_mfma_f32_16x16x32_bf16 v[56:59], v[128:131], v[160:163], v[56:59]
	v_mfma_f32_16x16x32_bf16 v[44:47], v[104:107], v[168:171], v[44:47]
	v_mfma_f32_16x16x32_bf16 v[40:43], v[128:131], v[168:171], v[40:43]
	v_mfma_f32_16x16x32_bf16 v[28:31], v[104:107], v[176:179], v[28:31]
	v_mfma_f32_16x16x32_bf16 v[24:27], v[128:131], v[176:179], v[24:27]
	v_mfma_f32_16x16x32_bf16 v[12:15], v[104:107], v[200:203], v[12:15]
	v_mfma_f32_16x16x32_bf16 v[8:11], v[128:131], v[200:203], v[8:11]
	v_mfma_f32_16x16x32_bf16 v[60:63], v[116:119], v[164:167], v[60:63]
	v_mfma_f32_16x16x32_bf16 v[56:59], v[140:143], v[164:167], v[56:59]
	v_mfma_f32_16x16x32_bf16 v[44:47], v[116:119], v[172:175], v[44:47]
	v_mfma_f32_16x16x32_bf16 v[40:43], v[140:143], v[172:175], v[40:43]
	v_mfma_f32_16x16x32_bf16 v[28:31], v[116:119], v[180:183], v[28:31]
	v_mfma_f32_16x16x32_bf16 v[24:27], v[140:143], v[180:183], v[24:27]
	v_mfma_f32_16x16x32_bf16 v[12:15], v[116:119], v[204:207], v[12:15]
	v_mfma_f32_16x16x32_bf16 v[8:11], v[140:143], v[204:207], v[8:11]
	v_mfma_f32_16x16x32_bf16 v[52:55], v[144:147], v[160:163], v[52:55]
	v_mfma_f32_16x16x32_bf16 v[48:51], v[152:155], v[160:163], v[48:51]
	v_mfma_f32_16x16x32_bf16 v[36:39], v[144:147], v[168:171], v[36:39]
	v_mfma_f32_16x16x32_bf16 v[32:35], v[152:155], v[168:171], v[32:35]
	v_mfma_f32_16x16x32_bf16 v[20:23], v[144:147], v[176:179], v[20:23]
	v_mfma_f32_16x16x32_bf16 v[16:19], v[152:155], v[176:179], v[16:19]
	v_mfma_f32_16x16x32_bf16 v[4:7], v[144:147], v[200:203], v[4:7]
	v_mfma_f32_16x16x32_bf16 v[0:3], v[152:155], v[200:203], v[0:3]
	v_mfma_f32_16x16x32_bf16 v[52:55], v[148:151], v[164:167], v[52:55]
	v_mfma_f32_16x16x32_bf16 v[48:51], v[156:159], v[164:167], v[48:51]
	v_mfma_f32_16x16x32_bf16 v[36:39], v[148:151], v[172:175], v[36:39]
	v_mfma_f32_16x16x32_bf16 v[32:35], v[156:159], v[172:175], v[32:35]
	v_mfma_f32_16x16x32_bf16 v[20:23], v[148:151], v[180:183], v[20:23]
	v_mfma_f32_16x16x32_bf16 v[16:19], v[156:159], v[180:183], v[16:19]
	v_mfma_f32_16x16x32_bf16 v[4:7], v[148:151], v[204:207], v[4:7]
	v_mfma_f32_16x16x32_bf16 v[0:3], v[156:159], v[204:207], v[0:3]
	s_barrier
; #define PG8_STAGE(bufoff, gbase, voff) do { _Pragma("unroll") for (int _i = 0; _i < 2; ++_i) \
;         __builtin_amdgcn_global_load_lds((const unsigned*)((const char*)(gbase) + (voff)[_i]), (PG8_LAS unsigned*)(lds + (bufoff) + ldsw + _i * 8192), 16, 0, 0); } while (0)
; #define PG8_LDA(dst, b, h) do { _Pragma("unroll") for (int m = 0; m < 4; ++m) _Pragma("unroll") for (int k = 0; k < 2; ++k) dst[m][k] = *(const PG8_LAS bf16x8*)(lds + PG8_SA(b, h) + aoff + m * 2048 + k * 1024); } while (0)
; #define PG8_LDB(dst, b, h) do { _Pragma("unroll") for (int n = 0; n < 2; ++n) _Pragma("unroll") for (int k = 0; k < 2; ++k) dst[n][k] = *(const PG8_LAS bf16x8*)(lds + PG8_SB(b, h) + boff + n * 2048 + k * 1024); } while (0)
; #define PG8_MMA(ai, bj, At, Bt) do { __builtin_amdgcn_s_setprio(1); _Pragma("unroll") for (int m = 0; m < 4; ++m) _Pragma("unroll") for (int n = 0; n < 2; ++n) _Pragma("unroll") for (int k = 0; k < 2; ++k) \
;         acc[ai][bj][m][n] = __builtin_amdgcn_mfma_f32_16x16x32_bf16(Bt[n][k], At[m][k], acc[ai][bj][m][n], 0, 0, 0); __builtin_amdgcn_s_setprio(0); } while (0)
; #define PG8_WAIT_V(n) asm volatile("s_waitcnt vmcnt(" #n ")" ::: "memory")
; #define PG8_WAIT_L(n) asm volatile("s_waitcnt lgkmcnt(" #n ")" ::: "memory")
; #define PG8_BAR __builtin_amdgcn_s_barrier()
; #define PG8_SCHED __builtin_amdgcn_sched_barrier(0)
; template <class Epi, class Sched, bool ALIGN_EPI = false, bool SP2 = false>
; __device__ __forceinline__ void gemm_phase(PG8_LAS unsigned char* lds, const Gemm g, const Sched& S, const Epi& E, const int tid_in) {
;     ...
;             PG8_LDB(B0, 1, 0); PG8_LDB(B1, 1, 1); PG8_SCHED; PG8_LDA(At, 1, 0); PG8_STAGE(PG8_SA(0, 1), a2 + hstepA, voffA);
;             PG8_WAIT_V(8); PG8_WAIT_L(0); PG8_BAR; PG8_MMA(0, 0, At, B0); PG8_MMA(0, 1, At, B1); PG8_BAR; PG8_SCHED;
	s_add_i32 s52, 0, 0x18000
	s_add_i32 s53, 0, 0x1c000
	v_add_u32_e32 v140, s52, v220
	v_add_u32_e32 v156, s53, v220
	ds_read_b128 v[104:107], v140
	ds_read_b128 v[116:119], v140 offset:1024
	ds_read_b128 v[128:131], v140 offset:2048
	ds_read_b128 v[140:143], v140 offset:3072
	ds_read_b128 v[144:147], v156
	ds_read_b128 v[148:151], v156 offset:1024
	ds_read_b128 v[152:155], v156 offset:2048
	ds_read_b128 v[156:159], v156 offset:3072
	s_add_u32 s30, s30, 0x80000
	s_addc_u32 s31, s31, 0
	s_mov_b32 m0, s39
	v_lshl_add_u64 v[216:217], s[30:31], 0, v[184:185]
	ds_read_b128 v[160:163], v224 offset:32768
	ds_read_b128 v[164:167], v224 offset:33792
	ds_read_b128 v[168:171], v224 offset:34816
	ds_read_b128 v[172:175], v224 offset:35840
	ds_read_b128 v[176:179], v224 offset:36864
	ds_read_b128 v[180:183], v224 offset:37888
	ds_read_b128 v[200:203], v224 offset:38912
	ds_read_b128 v[204:207], v224 offset:39936
	global_load_lds_dwordx4 v[216:217], off
	v_lshl_add_u64 v[216:217], s[30:31], 0, v[188:189]
	s_mov_b32 m0, s40
	s_nop 0
	global_load_lds_dwordx4 v[216:217], off
	s_waitcnt vmcnt(8)
	s_waitcnt lgkmcnt(0)
	s_barrier
	v_mfma_f32_16x16x32_bf16 v[136:139], v[104:107], v[160:163], v[136:139]
	v_mfma_f32_16x16x32_bf16 v[132:135], v[128:131], v[160:163], v[132:135]
	v_mfma_f32_16x16x32_bf16 v[112:115], v[104:107], v[168:171], v[112:115]
	v_mfma_f32_16x16x32_bf16 v[108:111], v[128:131], v[168:171], v[108:111]
	v_mfma_f32_16x16x32_bf16 v[92:95], v[104:107], v[176:179], v[92:95]
	v_mfma_f32_16x16x32_bf16 v[88:91], v[128:131], v[176:179], v[88:91]
	v_mfma_f32_16x16x32_bf16 v[76:79], v[104:107], v[200:203], v[76:79]
	v_mfma_f32_16x16x32_bf16 v[72:75], v[128:131], v[200:203], v[72:75]
	v_mfma_f32_16x16x32_bf16 v[136:139], v[116:119], v[164:167], v[136:139]
	v_mfma_f32_16x16x32_bf16 v[132:135], v[140:143], v[164:167], v[132:135]
	v_mfma_f32_16x16x32_bf16 v[112:115], v[116:119], v[172:175], v[112:115]
	v_mfma_f32_16x16x32_bf16 v[108:111], v[140:143], v[172:175], v[108:111]
	v_mfma_f32_16x16x32_bf16 v[92:95], v[116:119], v[180:183], v[92:95]
	v_mfma_f32_16x16x32_bf16 v[88:91], v[140:143], v[180:183], v[88:91]
	v_mfma_f32_16x16x32_bf16 v[76:79], v[116:119], v[204:207], v[76:79]
	v_mfma_f32_16x16x32_bf16 v[72:75], v[140:143], v[204:207], v[72:75]
	v_mfma_f32_16x16x32_bf16 v[124:127], v[144:147], v[160:163], v[124:127]
	v_mfma_f32_16x16x32_bf16 v[120:123], v[152:155], v[160:163], v[120:123]
	v_mfma_f32_16x16x32_bf16 v[100:103], v[144:147], v[168:171], v[100:103]
	v_mfma_f32_16x16x32_bf16 v[96:99], v[152:155], v[168:171], v[96:99]
	v_mfma_f32_16x16x32_bf16 v[84:87], v[144:147], v[176:179], v[84:87]
	v_mfma_f32_16x16x32_bf16 v[80:83], v[152:155], v[176:179], v[80:83]
	v_mfma_f32_16x16x32_bf16 v[68:71], v[144:147], v[200:203], v[68:71]
	v_mfma_f32_16x16x32_bf16 v[64:67], v[152:155], v[200:203], v[64:67]
	v_mfma_f32_16x16x32_bf16 v[124:127], v[148:151], v[164:167], v[124:127]
	v_mfma_f32_16x16x32_bf16 v[120:123], v[156:159], v[164:167], v[120:123]
	v_mfma_f32_16x16x32_bf16 v[100:103], v[148:151], v[172:175], v[100:103]
	v_mfma_f32_16x16x32_bf16 v[96:99], v[156:159], v[172:175], v[96:99]
	v_mfma_f32_16x16x32_bf16 v[84:87], v[148:151], v[180:183], v[84:87]
	v_mfma_f32_16x16x32_bf16 v[80:83], v[156:159], v[180:183], v[80:83]
	v_mfma_f32_16x16x32_bf16 v[68:71], v[148:151], v[204:207], v[68:71]
	v_mfma_f32_16x16x32_bf16 v[64:67], v[156:159], v[204:207], v[64:67]
	s_barrier
; #define PG8_STAGE(bufoff, gbase, voff) do { _Pragma("unroll") for (int _i = 0; _i < 2; ++_i) \
;         __builtin_amdgcn_global_load_lds((const unsigned*)((const char*)(gbase) + (voff)[_i]), (PG8_LAS unsigned*)(lds + (bufoff) + ldsw + _i * 8192), 16, 0, 0); } while (0)
; #define PG8_LDA(dst, b, h) do { _Pragma("unroll") for (int m = 0; m < 4; ++m) _Pragma("unroll") for (int k = 0; k < 2; ++k) dst[m][k] = *(const PG8_LAS bf16x8*)(lds + PG8_SA(b, h) + aoff + m * 2048 + k * 1024); } while (0)
; #define PG8_MMA(ai, bj, At, Bt) do { __builtin_amdgcn_s_setprio(1); _Pragma("unroll") for (int m = 0; m < 4; ++m) _Pragma("unroll") for (int n = 0; n < 2; ++n) _Pragma("unroll") for (int k = 0; k < 2; ++k) \
;         acc[ai][bj][m][n] = __builtin_amdgcn_mfma_f32_16x16x32_bf16(Bt[n][k], At[m][k], acc[ai][bj][m][n], 0, 0, 0); __builtin_amdgcn_s_setprio(0); } while (0)
; #define PG8_WAIT_V(n) asm volatile("s_waitcnt vmcnt(" #n ")" ::: "memory")
; #define PG8_WAIT_L(n) asm volatile("s_waitcnt lgkmcnt(" #n ")" ::: "memory")
; #define PG8_BAR __builtin_amdgcn_s_barrier()
; #define PG8_SCHED __builtin_amdgcn_sched_barrier(0)
; template <class Epi, class Sched, bool ALIGN_EPI = false, bool SP2 = false>
; __device__ __forceinline__ void gemm_phase(PG8_LAS unsigned char* lds, const Gemm g, const Sched& S, const Epi& E, const int tid_in) {
;     ...
;             PG8_LDA(At, 1, 1); PG8_STAGE(PG8_SB(1, 0), b3, voffB); PG8_STAGE(PG8_SB(1, 1), b3 + hstep, voffB); PG8_STAGE(PG8_SA(1, 0), a3, voffA);
;             PG8_WAIT_V(8); PG8_WAIT_L(0); PG8_BAR; PG8_MMA(1, 0, At, B0); PG8_MMA(1, 1, At, B1); PG8_BAR; PG8_SCHED;
;     ...
;         }
	s_add_i32 s30, s52, s37
	v_lshl_add_u64 v[208:209], v[208:209], 0, s[10:11]
	s_mov_b32 m0, s30
	ds_read_b128 v[160:163], v224 offset:49152
	ds_read_b128 v[164:167], v224 offset:50176
	ds_read_b128 v[168:171], v224 offset:51200
	ds_read_b128 v[172:175], v224 offset:52224
	ds_read_b128 v[176:179], v224 offset:53248
	ds_read_b128 v[180:183], v224 offset:54272
	ds_read_b128 v[200:203], v224 offset:55296
	ds_read_b128 v[204:207], v224 offset:56320
	global_load_lds_dwordx4 v[208:209], off
	s_add_i32 m0, s30, 0x2000
	s_add_u32 s28, s28, 0x80080
	v_lshl_add_u64 v[208:209], v[210:211], 0, s[10:11]
	s_addc_u32 s29, s29, 0
	s_add_i32 s30, s53, s37
	global_load_lds_dwordx4 v[208:209], off
	v_lshl_add_u64 v[208:209], s[28:29], 0, v[186:187]
	s_mov_b32 m0, s30
	s_nop 0
	global_load_lds_dwordx4 v[208:209], off
	v_lshl_add_u64 v[208:209], s[28:29], 0, v[190:191]
	s_add_i32 m0, s30, 0x2000
	s_nop 0
	global_load_lds_dwordx4 v[208:209], off
	v_lshl_add_u64 v[208:209], v[212:213], 0, s[10:11]
	s_mov_b32 m0, s42
	s_nop 0
	global_load_lds_dwordx4 v[208:209], off
	v_lshl_add_u64 v[208:209], v[214:215], 0, s[10:11]
	s_mov_b32 m0, s43
	s_nop 0
	global_load_lds_dwordx4 v[208:209], off
	s_waitcnt vmcnt(8)
	s_waitcnt lgkmcnt(0)
	s_barrier
	v_mfma_f32_16x16x32_bf16 v[60:63], v[104:107], v[160:163], v[60:63]
	v_mfma_f32_16x16x32_bf16 v[56:59], v[128:131], v[160:163], v[56:59]
	v_mfma_f32_16x16x32_bf16 v[44:47], v[104:107], v[168:171], v[44:47]
	v_mfma_f32_16x16x32_bf16 v[40:43], v[128:131], v[168:171], v[40:43]
	v_mfma_f32_16x16x32_bf16 v[28:31], v[104:107], v[176:179], v[28:31]
	v_mfma_f32_16x16x32_bf16 v[24:27], v[128:131], v[176:179], v[24:27]
	v_mfma_f32_16x16x32_bf16 v[12:15], v[104:107], v[200:203], v[12:15]
	v_mfma_f32_16x16x32_bf16 v[8:11], v[128:131], v[200:203], v[8:11]
	v_mfma_f32_16x16x32_bf16 v[60:63], v[116:119], v[164:167], v[60:63]
	v_mfma_f32_16x16x32_bf16 v[56:59], v[140:143], v[164:167], v[56:59]
	v_mfma_f32_16x16x32_bf16 v[44:47], v[116:119], v[172:175], v[44:47]
	v_mfma_f32_16x16x32_bf16 v[40:43], v[140:143], v[172:175], v[40:43]
	v_mfma_f32_16x16x32_bf16 v[28:31], v[116:119], v[180:183], v[28:31]
	v_mfma_f32_16x16x32_bf16 v[24:27], v[140:143], v[180:183], v[24:27]
	v_mfma_f32_16x16x32_bf16 v[12:15], v[116:119], v[204:207], v[12:15]
	v_mfma_f32_16x16x32_bf16 v[8:11], v[140:143], v[204:207], v[8:11]
	v_mfma_f32_16x16x32_bf16 v[52:55], v[144:147], v[160:163], v[52:55]
	v_mfma_f32_16x16x32_bf16 v[48:51], v[152:155], v[160:163], v[48:51]
	v_mfma_f32_16x16x32_bf16 v[36:39], v[144:147], v[168:171], v[36:39]
	v_mfma_f32_16x16x32_bf16 v[32:35], v[152:155], v[168:171], v[32:35]
	v_mfma_f32_16x16x32_bf16 v[20:23], v[144:147], v[176:179], v[20:23]
	v_mfma_f32_16x16x32_bf16 v[16:19], v[152:155], v[176:179], v[16:19]
	v_mfma_f32_16x16x32_bf16 v[4:7], v[144:147], v[200:203], v[4:7]
	v_mfma_f32_16x16x32_bf16 v[0:3], v[152:155], v[200:203], v[0:3]
	v_mfma_f32_16x16x32_bf16 v[52:55], v[148:151], v[164:167], v[52:55]
	v_mfma_f32_16x16x32_bf16 v[48:51], v[156:159], v[164:167], v[48:51]
	v_mfma_f32_16x16x32_bf16 v[36:39], v[148:151], v[172:175], v[36:39]
	v_mfma_f32_16x16x32_bf16 v[32:35], v[156:159], v[172:175], v[32:35]
	v_mfma_f32_16x16x32_bf16 v[20:23], v[148:151], v[180:183], v[20:23]
	v_mfma_f32_16x16x32_bf16 v[16:19], v[156:159], v[180:183], v[16:19]
	v_mfma_f32_16x16x32_bf16 v[4:7], v[148:151], v[204:207], v[4:7]
	v_mfma_f32_16x16x32_bf16 v[0:3], v[156:159], v[204:207], v[0:3]
	s_barrier
	s_add_i32 s51, s51, 2
	s_add_u32 s49, s49, 0x100
	s_addc_u32 s50, s50, 0
	s_add_u32 s26, s26, 0x100
	s_addc_u32 s27, s27, 0
	s_cmp_gt_u32 s51, 29
	s_cbranch_scc0 .LBB0_618
	s_setprio 0
	s_and_b64 vcc, exec, s[12:13]
	s_cbranch_vccz .LBB0_621
	s_barrier

; #define PG8_STAGE(bufoff, gbase, voff) do { _Pragma("unroll") for (int _i = 0; _i < 2; ++_i) \
;         __builtin_amdgcn_global_load_lds((const unsigned*)((const char*)(gbase) + (voff)[_i]), (PG8_LAS unsigned*)(lds + (bufoff) + ldsw + _i * 8192), 16, 0, 0); } while (0)
; #define PG8_LDA(dst, b, h) do { _Pragma("unroll") for (int m = 0; m < 4; ++m) _Pragma("unroll") for (int k = 0; k < 2; ++k) dst[m][k] = *(const PG8_LAS bf16x8*)(lds + PG8_SA(b, h) + aoff + m * 2048 + k * 1024); } while (0)
; #define PG8_LDB(dst, b, h) do { _Pragma("unroll") for (int n = 0; n < 2; ++n) _Pragma("unroll") for (int k = 0; k < 2; ++k) dst[n][k] = *(const PG8_LAS bf16x8*)(lds + PG8_SB(b, h) + boff + n * 2048 + k * 1024); } while (0)
; #define PG8_MMA(ai, bj, At, Bt) do { __builtin_amdgcn_s_setprio(1); _Pragma("unroll") for (int m = 0; m < 4; ++m) _Pragma("unroll") for (int n = 0; n < 2; ++n) _Pragma("unroll") for (int k = 0; k < 2; ++k) \
;         acc[ai][bj][m][n] = __builtin_amdgcn_mfma_f32_16x16x32_bf16(Bt[n][k], At[m][k], acc[ai][bj][m][n], 0, 0, 0); __builtin_amdgcn_s_setprio(0); } while (0)
; #define PG8_WAIT_V(n) asm volatile("s_waitcnt vmcnt(" #n ")" ::: "memory")
; #define PG8_WAIT_L(n) asm volatile("s_waitcnt lgkmcnt(" #n ")" ::: "memory")
; template <class Epi, class Sched, bool ALIGN_EPI = false, bool SP2 = false>
; __device__ __forceinline__ void gemm_phase(PG8_LAS unsigned char* lds, const Gemm g, const Sched& S, const Epi& E, const int tid_in) {
;     ...
;         const bool has_next = S.next(ui + 1, nxt);
;         const char* nA = has_next ? (const char*)g.A + (size_t)nxt.pm * tstepA : cA; const char* nB = has_next ? (const char*)g.Bt + (size_t)nxt.pn * tstep : cB;
;         for (int t = 0; t < nt; t += 2) {
;             const bool last = (t == nt - 2);
;             const char* a1 = cA + (size_t)(t + 1) * kstep;
;             const char* a2 = last ? nA : cA + (size_t)(t + 2) * kstep; const char* b2 = last ? nB : cB + (size_t)(t + 2) * kstep;
;             const char* a3 = a2 + kstep; const char* b3 = b2 + kstep;
;             if (last && has_next) S.a_ready(nxt);
;             if constexpr (SP2) {
;             PG8_LDB(B0, 0, 0); PG8_LDB(B1, 0, 1); PG8_SCHED; PG8_LDA(At, 0, 0); PG8_STAGE(PG8_SA(1, 1), a1 + hstepA, voffA);
;             PG8_WAIT_V(8); PG8_WAIT_L(0); PG8_BAR; PG8_MMA(0, 0, At, B0); PG8_MMA(0, 1, At, B1); PG8_BAR; PG8_SCHED;
.LBB0_658:
	s_ashr_i32 s13, s12, 31
	s_lshl_b64 s[14:15], s[12:13], 20
	s_add_u32 s14, s26, s14
	s_addc_u32 s15, s27, s15
	s_and_b64 s[16:17], s[0:1], exec
	s_cselect_b32 s13, s15, s23
	s_cselect_b32 s48, s14, s22
	s_ashr_i32 s11, s10, 31
	s_lshl_b64 s[16:17], s[10:11], 20
	s_add_u32 s16, s28, s16
	s_addc_u32 s17, s29, s17
	s_and_b64 s[24:25], s[0:1], exec
	s_cselect_b32 s11, s17, s21
	s_cselect_b32 s49, s16, s20
	s_add_u32 s50, s20, 0x100
	s_addc_u32 s51, s21, 0
	s_add_u32 s20, s22, 0x80080
	v_mov_b32_e32 v0, 0
	s_addc_u32 s21, s23, 0
	s_mov_b32 s52, -2
	v_mov_b32_e32 v1, v0
	v_mov_b32_e32 v2, v0
	v_mov_b32_e32 v3, v0
	v_mov_b32_e32 v4, v0
	v_mov_b32_e32 v5, v0
	v_mov_b32_e32 v6, v0
	v_mov_b32_e32 v7, v0
	v_mov_b32_e32 v16, v0
	v_mov_b32_e32 v17, v0
	v_mov_b32_e32 v18, v0
	v_mov_b32_e32 v19, v0
	v_mov_b32_e32 v20, v0
	v_mov_b32_e32 v21, v0
	v_mov_b32_e32 v22, v0
	v_mov_b32_e32 v23, v0
	v_mov_b32_e32 v28, v0
	v_mov_b32_e32 v29, v0
	v_mov_b32_e32 v30, v0
	v_mov_b32_e32 v31, v0
	v_mov_b32_e32 v36, v0
	v_mov_b32_e32 v37, v0
	v_mov_b32_e32 v38, v0
	v_mov_b32_e32 v39, v0
	v_mov_b32_e32 v44, v0
	v_mov_b32_e32 v45, v0
	v_mov_b32_e32 v46, v0
	v_mov_b32_e32 v47, v0
	v_mov_b32_e32 v52, v0
	v_mov_b32_e32 v53, v0
	v_mov_b32_e32 v54, v0
	v_mov_b32_e32 v55, v0
	v_mov_b32_e32 v8, v0
	v_mov_b32_e32 v9, v0
	v_mov_b32_e32 v10, v0
	v_mov_b32_e32 v11, v0
	v_mov_b32_e32 v12, v0
	v_mov_b32_e32 v13, v0
	v_mov_b32_e32 v14, v0
	v_mov_b32_e32 v15, v0
	v_mov_b32_e32 v24, v0
	v_mov_b32_e32 v25, v0
	v_mov_b32_e32 v26, v0
	v_mov_b32_e32 v27, v0
	v_mov_b32_e32 v32, v0
	v_mov_b32_e32 v33, v0
	v_mov_b32_e32 v34, v0
	v_mov_b32_e32 v35, v0
	v_mov_b32_e32 v40, v0
	v_mov_b32_e32 v41, v0
	v_mov_b32_e32 v42, v0
	v_mov_b32_e32 v43, v0
	v_mov_b32_e32 v48, v0
	v_mov_b32_e32 v49, v0
	v_mov_b32_e32 v50, v0
	v_mov_b32_e32 v51, v0
	v_mov_b32_e32 v56, v0
	v_mov_b32_e32 v57, v0
	v_mov_b32_e32 v58, v0
	v_mov_b32_e32 v59, v0
	v_mov_b32_e32 v60, v0
	v_mov_b32_e32 v61, v0
	v_mov_b32_e32 v62, v0
	v_mov_b32_e32 v63, v0
	v_mov_b32_e32 v64, v0
	v_mov_b32_e32 v65, v0
	v_mov_b32_e32 v66, v0
	v_mov_b32_e32 v67, v0
	v_mov_b32_e32 v68, v0
	v_mov_b32_e32 v69, v0
	v_mov_b32_e32 v70, v0
	v_mov_b32_e32 v71, v0
	v_mov_b32_e32 v76, v0
	v_mov_b32_e32 v77, v0
	v_mov_b32_e32 v78, v0
	v_mov_b32_e32 v79, v0
	v_mov_b32_e32 v84, v0
	v_mov_b32_e32 v85, v0
	v_mov_b32_e32 v86, v0
	v_mov_b32_e32 v87, v0
	v_mov_b32_e32 v92, v0
	v_mov_b32_e32 v93, v0
	v_mov_b32_e32 v94, v0
	v_mov_b32_e32 v95, v0
	v_mov_b32_e32 v100, v0
	v_mov_b32_e32 v101, v0
	v_mov_b32_e32 v102, v0
	v_mov_b32_e32 v103, v0
	v_mov_b32_e32 v108, v0
	v_mov_b32_e32 v109, v0
	v_mov_b32_e32 v110, v0
	v_mov_b32_e32 v111, v0
	v_mov_b32_e32 v116, v0
	v_mov_b32_e32 v117, v0
	v_mov_b32_e32 v118, v0
	v_mov_b32_e32 v119, v0
	v_mov_b32_e32 v72, v0
	v_mov_b32_e32 v73, v0
	v_mov_b32_e32 v74, v0
	v_mov_b32_e32 v75, v0
	v_mov_b32_e32 v80, v0
	v_mov_b32_e32 v81, v0
	v_mov_b32_e32 v82, v0
	v_mov_b32_e32 v83, v0
	v_mov_b32_e32 v88, v0
	v_mov_b32_e32 v89, v0
	v_mov_b32_e32 v90, v0
	v_mov_b32_e32 v91, v0
	v_mov_b32_e32 v96, v0
	v_mov_b32_e32 v97, v0
	v_mov_b32_e32 v98, v0
	v_mov_b32_e32 v99, v0
	v_mov_b32_e32 v104, v0
	v_mov_b32_e32 v105, v0
	v_mov_b32_e32 v106, v0
	v_mov_b32_e32 v107, v0
	v_mov_b32_e32 v112, v0
	v_mov_b32_e32 v113, v0
	v_mov_b32_e32 v114, v0
	v_mov_b32_e32 v115, v0
	v_mov_b32_e32 v120, v0
	v_mov_b32_e32 v121, v0
	v_mov_b32_e32 v122, v0
	v_mov_b32_e32 v123, v0
	v_mov_b32_e32 v124, v0
	v_mov_b32_e32 v125, v0
	v_mov_b32_e32 v126, v0
	v_mov_b32_e32 v127, v0
	s_cmp_lt_u32 s75, 4
	s_cbranch_scc1 .Lkprio_skip_6
	s_setprio 1
.Lkprio_skip_6:
.LBB0_659:
	ds_read_b128 v[144:147], v155
	ds_read_b128 v[158:161], v155 offset:1024
	ds_read_b128 v[162:165], v155 offset:2048
	ds_read_b128 v[166:169], v155 offset:3072
	ds_read_b128 v[170:173], v156
	ds_read_b128 v[174:177], v156 offset:1024
	ds_read_b128 v[178:181], v156 offset:2048
	ds_read_b128 v[182:185], v156 offset:3072
	s_add_u32 s22, s20, 0xfff80080
	s_addc_u32 s23, s21, -1
	s_cmp_eq_u32 s52, 28
	s_cselect_b32 s25, s13, s23
	s_cselect_b32 s24, s48, s22
	s_cselect_b32 s23, s11, s51
	s_cselect_b32 s22, s49, s50
	v_lshl_add_u64 v[218:219], s[20:21], 0, v[138:139]
	s_add_i32 m0, s19, 0xc000
	ds_read_b128 v[186:189], v157
	ds_read_b128 v[190:193], v157 offset:1024
	ds_read_b128 v[194:197], v157 offset:2048
	ds_read_b128 v[198:201], v157 offset:3072
	ds_read_b128 v[202:205], v157 offset:4096
	ds_read_b128 v[206:209], v157 offset:5120
	ds_read_b128 v[210:213], v157 offset:6144
	ds_read_b128 v[214:217], v157 offset:7168
	global_load_lds_dwordx4 v[218:219], off
	v_lshl_add_u64 v[218:219], s[20:21], 0, v[136:137]
	s_add_i32 m0, s19, 0xe000
	s_nop 0
	global_load_lds_dwordx4 v[218:219], off
	s_waitcnt vmcnt(8)
	s_waitcnt lgkmcnt(0)
	s_barrier
; #define PG8_STAGE(bufoff, gbase, voff) do { _Pragma("unroll") for (int _i = 0; _i < 2; ++_i) \
;         __builtin_amdgcn_global_load_lds((const unsigned*)((const char*)(gbase) + (voff)[_i]), (PG8_LAS unsigned*)(lds + (bufoff) + ldsw + _i * 8192), 16, 0, 0); } while (0)
; #define PG8_LDA(dst, b, h) do { _Pragma("unroll") for (int m = 0; m < 4; ++m) _Pragma("unroll") for (int k = 0; k < 2; ++k) dst[m][k] = *(const PG8_LAS bf16x8*)(lds + PG8_SA(b, h) + aoff + m * 2048 + k * 1024); } while (0)
; #define PG8_MMA(ai, bj, At, Bt) do { __builtin_amdgcn_s_setprio(1); _Pragma("unroll") for (int m = 0; m < 4; ++m) _Pragma("unroll") for (int n = 0; n < 2; ++n) _Pragma("unroll") for (int k = 0; k < 2; ++k) \
;         acc[ai][bj][m][n] = __builtin_amdgcn_mfma_f32_16x16x32_bf16(Bt[n][k], At[m][k], acc[ai][bj][m][n], 0, 0, 0); __builtin_amdgcn_s_setprio(0); } while (0)
; #define PG8_WAIT_V(n) asm volatile("s_waitcnt vmcnt(" #n ")" ::: "memory")
; #define PG8_WAIT_L(n) asm volatile("s_waitcnt lgkmcnt(" #n ")" ::: "memory")
; #define PG8_BAR __builtin_amdgcn_s_barrier()
; #define PG8_SCHED __builtin_amdgcn_sched_barrier(0)
; template <class Epi, class Sched, bool ALIGN_EPI = false, bool SP2 = false>
; __device__ __forceinline__ void gemm_phase(PG8_LAS unsigned char* lds, const Gemm g, const Sched& S, const Epi& E, const int tid_in) {
;     ...
;             PG8_WAIT_V(8); PG8_WAIT_L(0); PG8_BAR; PG8_MMA(0, 0, At, B0); PG8_MMA(0, 1, At, B1); PG8_BAR; PG8_SCHED;
;             PG8_LDA(At, 0, 1); PG8_STAGE(PG8_SB(0, 0), b2, voffB); PG8_STAGE(PG8_SB(0, 1), b2 + hstep, voffB); PG8_STAGE(PG8_SA(0, 0), a2, voffA);
;             PG8_WAIT_V(8); PG8_WAIT_L(0); PG8_BAR; PG8_MMA(1, 0, At, B0); PG8_MMA(1, 1, At, B1); PG8_BAR; PG8_SCHED;
	v_mfma_f32_16x16x32_bf16 v[124:127], v[144:147], v[186:189], v[124:127]
	v_mfma_f32_16x16x32_bf16 v[120:123], v[162:165], v[186:189], v[120:123]
	v_mfma_f32_16x16x32_bf16 v[112:115], v[144:147], v[194:197], v[112:115]
	v_mfma_f32_16x16x32_bf16 v[104:107], v[162:165], v[194:197], v[104:107]
	v_mfma_f32_16x16x32_bf16 v[96:99], v[144:147], v[202:205], v[96:99]
	v_mfma_f32_16x16x32_bf16 v[88:91], v[162:165], v[202:205], v[88:91]
	v_mfma_f32_16x16x32_bf16 v[80:83], v[144:147], v[210:213], v[80:83]
	v_mfma_f32_16x16x32_bf16 v[72:75], v[162:165], v[210:213], v[72:75]
	v_mfma_f32_16x16x32_bf16 v[124:127], v[158:161], v[190:193], v[124:127]
	v_mfma_f32_16x16x32_bf16 v[120:123], v[166:169], v[190:193], v[120:123]
	v_mfma_f32_16x16x32_bf16 v[112:115], v[158:161], v[198:201], v[112:115]
	v_mfma_f32_16x16x32_bf16 v[104:107], v[166:169], v[198:201], v[104:107]
	v_mfma_f32_16x16x32_bf16 v[96:99], v[158:161], v[206:209], v[96:99]
	v_mfma_f32_16x16x32_bf16 v[88:91], v[166:169], v[206:209], v[88:91]
	v_mfma_f32_16x16x32_bf16 v[80:83], v[158:161], v[214:217], v[80:83]
	v_mfma_f32_16x16x32_bf16 v[72:75], v[166:169], v[214:217], v[72:75]
	v_mfma_f32_16x16x32_bf16 v[116:119], v[170:173], v[186:189], v[116:119]
	v_mfma_f32_16x16x32_bf16 v[108:111], v[178:181], v[186:189], v[108:111]
	v_mfma_f32_16x16x32_bf16 v[100:103], v[170:173], v[194:197], v[100:103]
	v_mfma_f32_16x16x32_bf16 v[92:95], v[178:181], v[194:197], v[92:95]
	v_mfma_f32_16x16x32_bf16 v[84:87], v[170:173], v[202:205], v[84:87]
	v_mfma_f32_16x16x32_bf16 v[76:79], v[178:181], v[202:205], v[76:79]
	v_mfma_f32_16x16x32_bf16 v[68:71], v[170:173], v[210:213], v[68:71]
	v_mfma_f32_16x16x32_bf16 v[64:67], v[178:181], v[210:213], v[64:67]
	v_mfma_f32_16x16x32_bf16 v[116:119], v[174:177], v[190:193], v[116:119]
	v_mfma_f32_16x16x32_bf16 v[108:111], v[182:185], v[190:193], v[108:111]
	v_mfma_f32_16x16x32_bf16 v[100:103], v[174:177], v[198:201], v[100:103]
	v_mfma_f32_16x16x32_bf16 v[92:95], v[182:185], v[198:201], v[92:95]
	v_mfma_f32_16x16x32_bf16 v[84:87], v[174:177], v[206:209], v[84:87]
	v_mfma_f32_16x16x32_bf16 v[76:79], v[182:185], v[206:209], v[76:79]
	v_mfma_f32_16x16x32_bf16 v[68:71], v[174:177], v[214:217], v[68:71]
	v_mfma_f32_16x16x32_bf16 v[64:67], v[182:185], v[214:217], v[64:67]
	s_barrier
	s_add_i32 s53, s41, s30
	v_lshl_add_u64 v[218:219], s[22:23], 0, v[132:133]
	s_mov_b32 m0, s53
	ds_read_b128 v[186:189], v157 offset:16384
	ds_read_b128 v[190:193], v157 offset:17408
	ds_read_b128 v[194:197], v157 offset:18432
	ds_read_b128 v[198:201], v157 offset:19456
	ds_read_b128 v[202:205], v157 offset:20480
	ds_read_b128 v[206:209], v157 offset:21504
	ds_read_b128 v[210:213], v157 offset:22528
	ds_read_b128 v[214:217], v157 offset:23552
	global_load_lds_dwordx4 v[218:219], off
	s_add_i32 m0, s53, 0x2000
	s_add_u32 s54, s22, 0x80000
	v_lshl_add_u64 v[220:221], s[22:23], 0, v[128:129]
	s_addc_u32 s55, s23, 0
	s_add_i32 s53, s42, s30
	global_load_lds_dwordx4 v[220:221], off
	v_lshl_add_u64 v[222:223], s[54:55], 0, v[132:133]
	s_mov_b32 m0, s53
	v_lshl_add_u64 v[224:225], s[24:25], 0, v[130:131]
	global_load_lds_dwordx4 v[222:223], off
	v_lshl_add_u64 v[222:223], s[54:55], 0, v[128:129]
	s_add_i32 m0, s53, 0x2000
	s_nop 0
	global_load_lds_dwordx4 v[222:223], off
	v_lshl_add_u64 v[222:223], s[24:25], 0, v[134:135]
	s_mov_b32 m0, s19
	s_nop 0
	global_load_lds_dwordx4 v[222:223], off
	s_mov_b32 m0, s34
	s_nop 0
	global_load_lds_dwordx4 v[224:225], off
	s_waitcnt vmcnt(8)
	s_waitcnt lgkmcnt(0)
	s_barrier
	v_mfma_f32_16x16x32_bf16 v[60:63], v[144:147], v[186:189], v[60:63]
	v_mfma_f32_16x16x32_bf16 v[56:59], v[162:165], v[186:189], v[56:59]
	v_mfma_f32_16x16x32_bf16 v[48:51], v[144:147], v[194:197], v[48:51]
	v_mfma_f32_16x16x32_bf16 v[40:43], v[162:165], v[194:197], v[40:43]
	v_mfma_f32_16x16x32_bf16 v[32:35], v[144:147], v[202:205], v[32:35]
	v_mfma_f32_16x16x32_bf16 v[24:27], v[162:165], v[202:205], v[24:27]
	v_mfma_f32_16x16x32_bf16 v[12:15], v[144:147], v[210:213], v[12:15]
	v_mfma_f32_16x16x32_bf16 v[8:11], v[162:165], v[210:213], v[8:11]
	v_mfma_f32_16x16x32_bf16 v[60:63], v[158:161], v[190:193], v[60:63]
	v_mfma_f32_16x16x32_bf16 v[56:59], v[166:169], v[190:193], v[56:59]
	v_mfma_f32_16x16x32_bf16 v[48:51], v[158:161], v[198:201], v[48:51]
	v_mfma_f32_16x16x32_bf16 v[40:43], v[166:169], v[198:201], v[40:43]
	v_mfma_f32_16x16x32_bf16 v[32:35], v[158:161], v[206:209], v[32:35]
	v_mfma_f32_16x16x32_bf16 v[24:27], v[166:169], v[206:209], v[24:27]
	v_mfma_f32_16x16x32_bf16 v[12:15], v[158:161], v[214:217], v[12:15]
	v_mfma_f32_16x16x32_bf16 v[8:11], v[166:169], v[214:217], v[8:11]
	v_mfma_f32_16x16x32_bf16 v[52:55], v[170:173], v[186:189], v[52:55]
	v_mfma_f32_16x16x32_bf16 v[44:47], v[178:181], v[186:189], v[44:47]
	v_mfma_f32_16x16x32_bf16 v[36:39], v[170:173], v[194:197], v[36:39]
	v_mfma_f32_16x16x32_bf16 v[28:31], v[178:181], v[194:197], v[28:31]
	v_mfma_f32_16x16x32_bf16 v[20:23], v[170:173], v[202:205], v[20:23]
	v_mfma_f32_16x16x32_bf16 v[16:19], v[178:181], v[202:205], v[16:19]
	v_mfma_f32_16x16x32_bf16 v[4:7], v[170:173], v[210:213], v[4:7]
	v_mfma_f32_16x16x32_bf16 v[0:3], v[178:181], v[210:213], v[0:3]
	v_mfma_f32_16x16x32_bf16 v[52:55], v[174:177], v[190:193], v[52:55]
	v_mfma_f32_16x16x32_bf16 v[44:47], v[182:185], v[190:193], v[44:47]
	v_mfma_f32_16x16x32_bf16 v[36:39], v[174:177], v[198:201], v[36:39]
	v_mfma_f32_16x16x32_bf16 v[28:31], v[182:185], v[198:201], v[28:31]
	v_mfma_f32_16x16x32_bf16 v[20:23], v[174:177], v[206:209], v[20:23]
	v_mfma_f32_16x16x32_bf16 v[16:19], v[182:185], v[206:209], v[16:19]
	v_mfma_f32_16x16x32_bf16 v[4:7], v[174:177], v[214:217], v[4:7]
	v_mfma_f32_16x16x32_bf16 v[0:3], v[182:185], v[214:217], v[0:3]
	s_barrier
; #define PG8_STAGE(bufoff, gbase, voff) do { _Pragma("unroll") for (int _i = 0; _i < 2; ++_i) \
;         __builtin_amdgcn_global_load_lds((const unsigned*)((const char*)(gbase) + (voff)[_i]), (PG8_LAS unsigned*)(lds + (bufoff) + ldsw + _i * 8192), 16, 0, 0); } while (0)
; #define PG8_LDA(dst, b, h) do { _Pragma("unroll") for (int m = 0; m < 4; ++m) _Pragma("unroll") for (int k = 0; k < 2; ++k) dst[m][k] = *(const PG8_LAS bf16x8*)(lds + PG8_SA(b, h) + aoff + m * 2048 + k * 1024); } while (0)
; #define PG8_LDB(dst, b, h) do { _Pragma("unroll") for (int n = 0; n < 2; ++n) _Pragma("unroll") for (int k = 0; k < 2; ++k) dst[n][k] = *(const PG8_LAS bf16x8*)(lds + PG8_SB(b, h) + boff + n * 2048 + k * 1024); } while (0)
; #define PG8_MMA(ai, bj, At, Bt) do { __builtin_amdgcn_s_setprio(1); _Pragma("unroll") for (int m = 0; m < 4; ++m) _Pragma("unroll") for (int n = 0; n < 2; ++n) _Pragma("unroll") for (int k = 0; k < 2; ++k) \
;         acc[ai][bj][m][n] = __builtin_amdgcn_mfma_f32_16x16x32_bf16(Bt[n][k], At[m][k], acc[ai][bj][m][n], 0, 0, 0); __builtin_amdgcn_s_setprio(0); } while (0)
; #define PG8_WAIT_V(n) asm volatile("s_waitcnt vmcnt(" #n ")" ::: "memory")
; #define PG8_WAIT_L(n) asm volatile("s_waitcnt lgkmcnt(" #n ")" ::: "memory")
; #define PG8_BAR __builtin_amdgcn_s_barrier()
; #define PG8_SCHED __builtin_amdgcn_sched_barrier(0)
; template <class Epi, class Sched, bool ALIGN_EPI = false, bool SP2 = false>
; __device__ __forceinline__ void gemm_phase(PG8_LAS unsigned char* lds, const Gemm g, const Sched& S, const Epi& E, const int tid_in) {
;     ...
;             PG8_LDB(B0, 1, 0); PG8_LDB(B1, 1, 1); PG8_SCHED; PG8_LDA(At, 1, 0); PG8_STAGE(PG8_SA(0, 1), a2 + hstepA, voffA);
;             PG8_WAIT_V(8); PG8_WAIT_L(0); PG8_BAR; PG8_MMA(0, 0, At, B0); PG8_MMA(0, 1, At, B1); PG8_BAR; PG8_SCHED;
	s_add_i32 s53, 0, 0x18000
	v_add_u32_e32 v148, s53, v151
	s_add_i32 s54, 0, 0x1c000
	ds_read_b128 v[144:147], v148
	ds_read_b128 v[158:161], v148 offset:1024
	ds_read_b128 v[162:165], v148 offset:2048
	ds_read_b128 v[166:169], v148 offset:3072
	v_add_u32_e32 v148, s54, v151
	ds_read_b128 v[170:173], v148
	ds_read_b128 v[174:177], v148 offset:1024
	ds_read_b128 v[178:181], v148 offset:2048
	ds_read_b128 v[182:185], v148 offset:3072
	s_add_u32 s24, s24, 0x80000
	s_addc_u32 s25, s25, 0
	s_mov_b32 m0, s35
	v_lshl_add_u64 v[226:227], s[24:25], 0, v[134:135]
	ds_read_b128 v[186:189], v157 offset:32768
	ds_read_b128 v[190:193], v157 offset:33792
	ds_read_b128 v[194:197], v157 offset:34816
	ds_read_b128 v[198:201], v157 offset:35840
	ds_read_b128 v[202:205], v157 offset:36864
	ds_read_b128 v[206:209], v157 offset:37888
	ds_read_b128 v[210:213], v157 offset:38912
	ds_read_b128 v[214:217], v157 offset:39936
	global_load_lds_dwordx4 v[226:227], off
	v_lshl_add_u64 v[226:227], s[24:25], 0, v[130:131]
	s_mov_b32 m0, s36
	s_nop 0
	global_load_lds_dwordx4 v[226:227], off
	s_waitcnt vmcnt(8)
	s_waitcnt lgkmcnt(0)
	s_barrier
	v_mfma_f32_16x16x32_bf16 v[124:127], v[144:147], v[186:189], v[124:127]
	v_mfma_f32_16x16x32_bf16 v[120:123], v[162:165], v[186:189], v[120:123]
	v_mfma_f32_16x16x32_bf16 v[112:115], v[144:147], v[194:197], v[112:115]
	v_mfma_f32_16x16x32_bf16 v[104:107], v[162:165], v[194:197], v[104:107]
	v_mfma_f32_16x16x32_bf16 v[96:99], v[144:147], v[202:205], v[96:99]
	v_mfma_f32_16x16x32_bf16 v[88:91], v[162:165], v[202:205], v[88:91]
	v_mfma_f32_16x16x32_bf16 v[80:83], v[144:147], v[210:213], v[80:83]
	v_mfma_f32_16x16x32_bf16 v[72:75], v[162:165], v[210:213], v[72:75]
	v_mfma_f32_16x16x32_bf16 v[124:127], v[158:161], v[190:193], v[124:127]
	v_mfma_f32_16x16x32_bf16 v[120:123], v[166:169], v[190:193], v[120:123]
	v_mfma_f32_16x16x32_bf16 v[112:115], v[158:161], v[198:201], v[112:115]
	v_mfma_f32_16x16x32_bf16 v[104:107], v[166:169], v[198:201], v[104:107]
	v_mfma_f32_16x16x32_bf16 v[96:99], v[158:161], v[206:209], v[96:99]
	v_mfma_f32_16x16x32_bf16 v[88:91], v[166:169], v[206:209], v[88:91]
	v_mfma_f32_16x16x32_bf16 v[80:83], v[158:161], v[214:217], v[80:83]
	v_mfma_f32_16x16x32_bf16 v[72:75], v[166:169], v[214:217], v[72:75]
	v_mfma_f32_16x16x32_bf16 v[116:119], v[170:173], v[186:189], v[116:119]
	v_mfma_f32_16x16x32_bf16 v[108:111], v[178:181], v[186:189], v[108:111]
	v_mfma_f32_16x16x32_bf16 v[100:103], v[170:173], v[194:197], v[100:103]
	v_mfma_f32_16x16x32_bf16 v[92:95], v[178:181], v[194:197], v[92:95]
	v_mfma_f32_16x16x32_bf16 v[84:87], v[170:173], v[202:205], v[84:87]
	v_mfma_f32_16x16x32_bf16 v[76:79], v[178:181], v[202:205], v[76:79]
	v_mfma_f32_16x16x32_bf16 v[68:71], v[170:173], v[210:213], v[68:71]
	v_mfma_f32_16x16x32_bf16 v[64:67], v[178:181], v[210:213], v[64:67]
	v_mfma_f32_16x16x32_bf16 v[116:119], v[174:177], v[190:193], v[116:119]
	v_mfma_f32_16x16x32_bf16 v[108:111], v[182:185], v[190:193], v[108:111]
	v_mfma_f32_16x16x32_bf16 v[100:103], v[174:177], v[198:201], v[100:103]
	v_mfma_f32_16x16x32_bf16 v[92:95], v[182:185], v[198:201], v[92:95]
	v_mfma_f32_16x16x32_bf16 v[84:87], v[174:177], v[206:209], v[84:87]
	v_mfma_f32_16x16x32_bf16 v[76:79], v[182:185], v[206:209], v[76:79]
	v_mfma_f32_16x16x32_bf16 v[68:71], v[174:177], v[214:217], v[68:71]
	v_mfma_f32_16x16x32_bf16 v[64:67], v[182:185], v[214:217], v[64:67]
	s_barrier
; #define PG8_STAGE(bufoff, gbase, voff) do { _Pragma("unroll") for (int _i = 0; _i < 2; ++_i) \
;         __builtin_amdgcn_global_load_lds((const unsigned*)((const char*)(gbase) + (voff)[_i]), (PG8_LAS unsigned*)(lds + (bufoff) + ldsw + _i * 8192), 16, 0, 0); } while (0)
; #define PG8_LDA(dst, b, h) do { _Pragma("unroll") for (int m = 0; m < 4; ++m) _Pragma("unroll") for (int k = 0; k < 2; ++k) dst[m][k] = *(const PG8_LAS bf16x8*)(lds + PG8_SA(b, h) + aoff + m * 2048 + k * 1024); } while (0)
; #define PG8_MMA(ai, bj, At, Bt) do { __builtin_amdgcn_s_setprio(1); _Pragma("unroll") for (int m = 0; m < 4; ++m) _Pragma("unroll") for (int n = 0; n < 2; ++n) _Pragma("unroll") for (int k = 0; k < 2; ++k) \
;         acc[ai][bj][m][n] = __builtin_amdgcn_mfma_f32_16x16x32_bf16(Bt[n][k], At[m][k], acc[ai][bj][m][n], 0, 0, 0); __builtin_amdgcn_s_setprio(0); } while (0)
; #define PG8_WAIT_V(n) asm volatile("s_waitcnt vmcnt(" #n ")" ::: "memory")
; #define PG8_WAIT_L(n) asm volatile("s_waitcnt lgkmcnt(" #n ")" ::: "memory")
; #define PG8_BAR __builtin_amdgcn_s_barrier()
; #define PG8_SCHED __builtin_amdgcn_sched_barrier(0)
; template <class Epi, class Sched, bool ALIGN_EPI = false, bool SP2 = false>
; __device__ __forceinline__ void gemm_phase(PG8_LAS unsigned char* lds, const Gemm g, const Sched& S, const Epi& E, const int tid_in) {
;     ...
;             PG8_LDA(At, 1, 1); PG8_STAGE(PG8_SB(1, 0), b3, voffB); PG8_STAGE(PG8_SB(1, 1), b3 + hstep, voffB); PG8_STAGE(PG8_SA(1, 0), a3, voffA);
;             PG8_WAIT_V(8); PG8_WAIT_L(0); PG8_BAR; PG8_MMA(1, 0, At, B0); PG8_MMA(1, 1, At, B1); PG8_BAR; PG8_SCHED;
;     ...
;         }
	s_add_i32 s24, s53, s30
	v_lshl_add_u64 v[218:219], v[218:219], 0, s[6:7]
	s_mov_b32 m0, s24
	ds_read_b128 v[186:189], v157 offset:49152
	ds_read_b128 v[190:193], v157 offset:50176
	ds_read_b128 v[194:197], v157 offset:51200
	ds_read_b128 v[198:201], v157 offset:52224
	ds_read_b128 v[202:205], v157 offset:53248
	ds_read_b128 v[206:209], v157 offset:54272
	ds_read_b128 v[210:213], v157 offset:55296
	ds_read_b128 v[214:217], v157 offset:56320
	global_load_lds_dwordx4 v[218:219], off
	s_add_i32 m0, s24, 0x2000
	s_add_u32 s22, s22, 0x80080
	v_lshl_add_u64 v[218:219], v[220:221], 0, s[6:7]
	s_addc_u32 s23, s23, 0
	s_add_i32 s24, s54, s30
	global_load_lds_dwordx4 v[218:219], off
	v_lshl_add_u64 v[218:219], s[22:23], 0, v[132:133]
	s_mov_b32 m0, s24
	s_nop 0
	global_load_lds_dwordx4 v[218:219], off
	v_lshl_add_u64 v[218:219], s[22:23], 0, v[128:129]
	s_add_i32 m0, s24, 0x2000
	s_nop 0
	global_load_lds_dwordx4 v[218:219], off
	v_lshl_add_u64 v[218:219], v[222:223], 0, s[6:7]
	s_mov_b32 m0, s38
	s_nop 0
	global_load_lds_dwordx4 v[218:219], off
	v_lshl_add_u64 v[218:219], v[224:225], 0, s[6:7]
	s_mov_b32 m0, s39
	s_nop 0
	global_load_lds_dwordx4 v[218:219], off
	s_waitcnt vmcnt(8)
	s_waitcnt lgkmcnt(0)
	s_barrier
	v_mfma_f32_16x16x32_bf16 v[60:63], v[144:147], v[186:189], v[60:63]
	v_mfma_f32_16x16x32_bf16 v[56:59], v[162:165], v[186:189], v[56:59]
	v_mfma_f32_16x16x32_bf16 v[48:51], v[144:147], v[194:197], v[48:51]
	v_mfma_f32_16x16x32_bf16 v[40:43], v[162:165], v[194:197], v[40:43]
	v_mfma_f32_16x16x32_bf16 v[32:35], v[144:147], v[202:205], v[32:35]
	v_mfma_f32_16x16x32_bf16 v[24:27], v[162:165], v[202:205], v[24:27]
	v_mfma_f32_16x16x32_bf16 v[12:15], v[144:147], v[210:213], v[12:15]
	v_mfma_f32_16x16x32_bf16 v[8:11], v[162:165], v[210:213], v[8:11]
	v_mfma_f32_16x16x32_bf16 v[60:63], v[158:161], v[190:193], v[60:63]
	v_mfma_f32_16x16x32_bf16 v[56:59], v[166:169], v[190:193], v[56:59]
	v_mfma_f32_16x16x32_bf16 v[48:51], v[158:161], v[198:201], v[48:51]
	v_mfma_f32_16x16x32_bf16 v[40:43], v[166:169], v[198:201], v[40:43]
	v_mfma_f32_16x16x32_bf16 v[32:35], v[158:161], v[206:209], v[32:35]
	v_mfma_f32_16x16x32_bf16 v[24:27], v[166:169], v[206:209], v[24:27]
	v_mfma_f32_16x16x32_bf16 v[12:15], v[158:161], v[214:217], v[12:15]
	v_mfma_f32_16x16x32_bf16 v[8:11], v[166:169], v[214:217], v[8:11]
	v_mfma_f32_16x16x32_bf16 v[52:55], v[170:173], v[186:189], v[52:55]
	v_mfma_f32_16x16x32_bf16 v[44:47], v[178:181], v[186:189], v[44:47]
	v_mfma_f32_16x16x32_bf16 v[36:39], v[170:173], v[194:197], v[36:39]
	v_mfma_f32_16x16x32_bf16 v[28:31], v[178:181], v[194:197], v[28:31]
	v_mfma_f32_16x16x32_bf16 v[20:23], v[170:173], v[202:205], v[20:23]
	v_mfma_f32_16x16x32_bf16 v[16:19], v[178:181], v[202:205], v[16:19]
	v_mfma_f32_16x16x32_bf16 v[4:7], v[170:173], v[210:213], v[4:7]
	v_mfma_f32_16x16x32_bf16 v[0:3], v[178:181], v[210:213], v[0:3]
	v_mfma_f32_16x16x32_bf16 v[52:55], v[174:177], v[190:193], v[52:55]
	v_mfma_f32_16x16x32_bf16 v[44:47], v[182:185], v[190:193], v[44:47]
	v_mfma_f32_16x16x32_bf16 v[36:39], v[174:177], v[198:201], v[36:39]
	v_mfma_f32_16x16x32_bf16 v[28:31], v[182:185], v[198:201], v[28:31]
	v_mfma_f32_16x16x32_bf16 v[20:23], v[174:177], v[206:209], v[20:23]
	v_mfma_f32_16x16x32_bf16 v[16:19], v[182:185], v[206:209], v[16:19]
	v_mfma_f32_16x16x32_bf16 v[4:7], v[174:177], v[214:217], v[4:7]
	v_mfma_f32_16x16x32_bf16 v[0:3], v[182:185], v[214:217], v[0:3]
	s_barrier
	s_add_i32 s52, s52, 2
	s_add_u32 s50, s50, 0x100
	s_addc_u32 s51, s51, 0
	s_add_u32 s20, s20, 0x100
	s_addc_u32 s21, s21, 0
	s_cmp_gt_u32 s52, 29
	s_cbranch_scc0 .LBB0_659
	s_setprio 0
	s_and_b64 vcc, exec, s[8:9]
	s_cbranch_vccz .LBB0_662
	s_barrier

; #define PG8_STAGE(bufoff, gbase, voff) do { _Pragma("unroll") for (int _i = 0; _i < 2; ++_i) \
;         __builtin_amdgcn_global_load_lds((const unsigned*)((const char*)(gbase) + (voff)[_i]), (PG8_LAS unsigned*)(lds + (bufoff) + ldsw + _i * 8192), 16, 0, 0); } while (0)
; #define PG8_LDA(dst, b, h) do { _Pragma("unroll") for (int m = 0; m < 4; ++m) _Pragma("unroll") for (int k = 0; k < 2; ++k) dst[m][k] = *(const PG8_LAS bf16x8*)(lds + PG8_SA(b, h) + aoff + m * 2048 + k * 1024); } while (0)
; #define PG8_LDB(dst, b, h) do { _Pragma("unroll") for (int n = 0; n < 2; ++n) _Pragma("unroll") for (int k = 0; k < 2; ++k) dst[n][k] = *(const PG8_LAS bf16x8*)(lds + PG8_SB(b, h) + boff + n * 2048 + k * 1024); } while (0)
; #define PG8_MMA(ai, bj, At, Bt) do { __builtin_amdgcn_s_setprio(1); _Pragma("unroll") for (int m = 0; m < 4; ++m) _Pragma("unroll") for (int n = 0; n < 2; ++n) _Pragma("unroll") for (int k = 0; k < 2; ++k) \
;         acc[ai][bj][m][n] = __builtin_amdgcn_mfma_f32_16x16x32_bf16(Bt[n][k], At[m][k], acc[ai][bj][m][n], 0, 0, 0); __builtin_amdgcn_s_setprio(0); } while (0)
; #define PG8_WAIT_V(n) asm volatile("s_waitcnt vmcnt(" #n ")" ::: "memory")
; #define PG8_WAIT_L(n) asm volatile("s_waitcnt lgkmcnt(" #n ")" ::: "memory")
; template <class Epi, class Sched, bool ALIGN_EPI = false, bool SP2 = false>
; __device__ __forceinline__ void gemm_phase(PG8_LAS unsigned char* lds, const Gemm g, const Sched& S, const Epi& E, const int tid_in) {
;     ...
;         const bool has_next = S.next(ui + 1, nxt);
;         const char* nA = has_next ? (const char*)g.A + (size_t)nxt.pm * tstepA : cA; const char* nB = has_next ? (const char*)g.Bt + (size_t)nxt.pn * tstep : cB;
;         for (int t = 0; t < nt; t += 2) {
;             const bool last = (t == nt - 2);
;             const char* a1 = cA + (size_t)(t + 1) * kstep;
;             const char* a2 = last ? nA : cA + (size_t)(t + 2) * kstep; const char* b2 = last ? nB : cB + (size_t)(t + 2) * kstep;
;             const char* a3 = a2 + kstep; const char* b3 = b2 + kstep;
;             if (last && has_next) S.a_ready(nxt);
;             if constexpr (SP2) {
;             PG8_LDB(B0, 0, 0); PG8_LDB(B1, 0, 1); PG8_SCHED; PG8_LDA(At, 0, 0); PG8_STAGE(PG8_SA(1, 1), a1 + hstepA, voffA);
;             PG8_WAIT_V(8); PG8_WAIT_L(0); PG8_BAR; PG8_MMA(0, 0, At, B0); PG8_MMA(0, 1, At, B1); PG8_BAR; PG8_SCHED;
.LBB0_742:
	s_ashr_i32 s37, s36, 31
	s_lshl_b64 s[38:39], s[36:37], 20
	s_add_u32 s38, s8, s38
	s_addc_u32 s39, s9, s39
	s_and_b64 s[40:41], s[2:3], exec
	s_cselect_b32 s5, s39, s47
	s_cselect_b32 s37, s38, s46
	s_ashr_i32 s35, s34, 31
	s_lshl_b64 s[40:41], s[34:35], 20
	s_add_u32 s40, s27, s40
	s_addc_u32 s41, s29, s41
	s_and_b64 s[48:49], s[2:3], exec
	s_cselect_b32 s35, s41, s45
	s_cselect_b32 s61, s40, s44
	s_add_u32 s62, s44, 0x100
	s_addc_u32 s63, s45, 0
	s_add_u32 s44, s46, 0x80080
	v_mov_b32_e32 v0, 0
	s_addc_u32 s45, s47, 0
	s_mov_b32 s64, -2
	s_waitcnt lgkmcnt(0)
	v_mov_b32_e32 v1, v0
	v_mov_b32_e32 v2, v0
	v_mov_b32_e32 v3, v0
	v_mov_b32_e32 v4, v0
	v_mov_b32_e32 v5, v0
	v_mov_b32_e32 v6, v0
	v_mov_b32_e32 v7, v0
	v_mov_b32_e32 v16, v0
	v_mov_b32_e32 v17, v0
	v_mov_b32_e32 v18, v0
	v_mov_b32_e32 v19, v0
	v_mov_b32_e32 v20, v0
	v_mov_b32_e32 v21, v0
	v_mov_b32_e32 v22, v0
	v_mov_b32_e32 v23, v0
	v_mov_b32_e32 v32, v0
	v_mov_b32_e32 v33, v0
	v_mov_b32_e32 v34, v0
	v_mov_b32_e32 v35, v0
	v_mov_b32_e32 v36, v0
	v_mov_b32_e32 v37, v0
	v_mov_b32_e32 v38, v0
	v_mov_b32_e32 v39, v0
	v_mov_b32_e32 v64, v0
	v_mov_b32_e32 v65, v0
	v_mov_b32_e32 v66, v0
	v_mov_b32_e32 v67, v0
	v_mov_b32_e32 v68, v0
	v_mov_b32_e32 v69, v0
	v_mov_b32_e32 v70, v0
	v_mov_b32_e32 v71, v0
	v_mov_b32_e32 v8, v0
	v_mov_b32_e32 v9, v0
	v_mov_b32_e32 v10, v0
	v_mov_b32_e32 v11, v0
	v_mov_b32_e32 v12, v0
	v_mov_b32_e32 v13, v0
	v_mov_b32_e32 v14, v0
	v_mov_b32_e32 v15, v0
	v_mov_b32_e32 v24, v0
	v_mov_b32_e32 v25, v0
	v_mov_b32_e32 v26, v0
	v_mov_b32_e32 v27, v0
	v_mov_b32_e32 v28, v0
	v_mov_b32_e32 v29, v0
	v_mov_b32_e32 v30, v0
	v_mov_b32_e32 v31, v0
	v_mov_b32_e32 v44, v0
	v_mov_b32_e32 v45, v0
	v_mov_b32_e32 v46, v0
	v_mov_b32_e32 v47, v0
	v_mov_b32_e32 v56, v0
	v_mov_b32_e32 v57, v0
	v_mov_b32_e32 v58, v0
	v_mov_b32_e32 v59, v0
	v_mov_b32_e32 v72, v0
	v_mov_b32_e32 v73, v0
	v_mov_b32_e32 v74, v0
	v_mov_b32_e32 v75, v0
	v_mov_b32_e32 v76, v0
	v_mov_b32_e32 v77, v0
	v_mov_b32_e32 v78, v0
	v_mov_b32_e32 v79, v0
	v_mov_b32_e32 v80, v0
	v_mov_b32_e32 v81, v0
	v_mov_b32_e32 v82, v0
	v_mov_b32_e32 v83, v0
	v_mov_b32_e32 v84, v0
	v_mov_b32_e32 v85, v0
	v_mov_b32_e32 v86, v0
	v_mov_b32_e32 v87, v0
	v_mov_b32_e32 v96, v0
	v_mov_b32_e32 v97, v0
	v_mov_b32_e32 v98, v0
	v_mov_b32_e32 v99, v0
	v_mov_b32_e32 v100, v0
	v_mov_b32_e32 v101, v0
	v_mov_b32_e32 v102, v0
	v_mov_b32_e32 v103, v0
	v_mov_b32_e32 v112, v0
	v_mov_b32_e32 v113, v0
	v_mov_b32_e32 v114, v0
	v_mov_b32_e32 v115, v0
	v_mov_b32_e32 v116, v0
	v_mov_b32_e32 v117, v0
	v_mov_b32_e32 v118, v0
	v_mov_b32_e32 v119, v0
	v_mov_b32_e32 v128, v0
	v_mov_b32_e32 v129, v0
	v_mov_b32_e32 v130, v0
	v_mov_b32_e32 v131, v0
	v_mov_b32_e32 v132, v0
	v_mov_b32_e32 v133, v0
	v_mov_b32_e32 v134, v0
	v_mov_b32_e32 v135, v0
	v_mov_b32_e32 v88, v0
	v_mov_b32_e32 v89, v0
	v_mov_b32_e32 v90, v0
	v_mov_b32_e32 v91, v0
	v_mov_b32_e32 v92, v0
	v_mov_b32_e32 v93, v0
	v_mov_b32_e32 v94, v0
	v_mov_b32_e32 v95, v0
	v_mov_b32_e32 v104, v0
	v_mov_b32_e32 v105, v0
	v_mov_b32_e32 v106, v0
	v_mov_b32_e32 v107, v0
	v_mov_b32_e32 v108, v0
	v_mov_b32_e32 v109, v0
	v_mov_b32_e32 v110, v0
	v_mov_b32_e32 v111, v0
	v_mov_b32_e32 v120, v0
	v_mov_b32_e32 v121, v0
	v_mov_b32_e32 v122, v0
	v_mov_b32_e32 v123, v0
	v_mov_b32_e32 v124, v0
	v_mov_b32_e32 v125, v0
	v_mov_b32_e32 v126, v0
	v_mov_b32_e32 v127, v0
	v_mov_b32_e32 v136, v0
	v_mov_b32_e32 v137, v0
	v_mov_b32_e32 v138, v0
	v_mov_b32_e32 v139, v0
	v_mov_b32_e32 v140, v0
	v_mov_b32_e32 v141, v0
	v_mov_b32_e32 v142, v0
	v_mov_b32_e32 v143, v0
	s_cmp_lt_u32 s75, 4
	s_cbranch_scc1 .Lkprio_skip_8
	s_setprio 1
.Lkprio_skip_8:
.LBB0_743:
	ds_read_b128 v[40:43], v210
	ds_read_b128 v[48:51], v210 offset:1024
	ds_read_b128 v[52:55], v210 offset:2048
	ds_read_b128 v[60:63], v210 offset:3072
	ds_read_b128 v[144:147], v211
	ds_read_b128 v[148:151], v211 offset:1024
	ds_read_b128 v[152:155], v211 offset:2048
	ds_read_b128 v[156:159], v211 offset:3072
	s_add_u32 s46, s44, 0xfff80080
	s_addc_u32 s47, s45, -1
	s_cmp_eq_u32 s64, 28
	s_cselect_b32 s49, s5, s47
	s_cselect_b32 s48, s37, s46
	s_cselect_b32 s47, s35, s63
	s_cselect_b32 s46, s61, s62
	v_lshl_add_u64 v[218:219], s[44:45], 0, v[184:185]
	s_add_i32 m0, s33, 0xc000
	ds_read_b128 v[160:163], v212
	ds_read_b128 v[164:167], v212 offset:1024
	ds_read_b128 v[168:171], v212 offset:2048
	ds_read_b128 v[192:195], v212 offset:3072
	ds_read_b128 v[196:199], v212 offset:4096
	ds_read_b128 v[200:203], v212 offset:5120
	ds_read_b128 v[204:207], v212 offset:6144
	ds_read_b128 v[214:217], v212 offset:7168
	global_load_lds_dwordx4 v[218:219], off
	v_lshl_add_u64 v[218:219], s[44:45], 0, v[182:183]
	s_add_i32 m0, s33, 0xe000
	s_nop 0
	global_load_lds_dwordx4 v[218:219], off
	s_waitcnt vmcnt(8)
	s_waitcnt lgkmcnt(0)
	s_barrier
; #define PG8_STAGE(bufoff, gbase, voff) do { _Pragma("unroll") for (int _i = 0; _i < 2; ++_i) \
;         __builtin_amdgcn_global_load_lds((const unsigned*)((const char*)(gbase) + (voff)[_i]), (PG8_LAS unsigned*)(lds + (bufoff) + ldsw + _i * 8192), 16, 0, 0); } while (0)
; #define PG8_LDA(dst, b, h) do { _Pragma("unroll") for (int m = 0; m < 4; ++m) _Pragma("unroll") for (int k = 0; k < 2; ++k) dst[m][k] = *(const PG8_LAS bf16x8*)(lds + PG8_SA(b, h) + aoff + m * 2048 + k * 1024); } while (0)
; #define PG8_MMA(ai, bj, At, Bt) do { __builtin_amdgcn_s_setprio(1); _Pragma("unroll") for (int m = 0; m < 4; ++m) _Pragma("unroll") for (int n = 0; n < 2; ++n) _Pragma("unroll") for (int k = 0; k < 2; ++k) \
;         acc[ai][bj][m][n] = __builtin_amdgcn_mfma_f32_16x16x32_bf16(Bt[n][k], At[m][k], acc[ai][bj][m][n], 0, 0, 0); __builtin_amdgcn_s_setprio(0); } while (0)
; #define PG8_WAIT_V(n) asm volatile("s_waitcnt vmcnt(" #n ")" ::: "memory")
; #define PG8_WAIT_L(n) asm volatile("s_waitcnt lgkmcnt(" #n ")" ::: "memory")
; #define PG8_BAR __builtin_amdgcn_s_barrier()
; #define PG8_SCHED __builtin_amdgcn_sched_barrier(0)
; template <class Epi, class Sched, bool ALIGN_EPI = false, bool SP2 = false>
; __device__ __forceinline__ void gemm_phase(PG8_LAS unsigned char* lds, const Gemm g, const Sched& S, const Epi& E, const int tid_in) {
;     ...
;             PG8_WAIT_V(8); PG8_WAIT_L(0); PG8_BAR; PG8_MMA(0, 0, At, B0); PG8_MMA(0, 1, At, B1); PG8_BAR; PG8_SCHED;
;             PG8_LDA(At, 0, 1); PG8_STAGE(PG8_SB(0, 0), b2, voffB); PG8_STAGE(PG8_SB(0, 1), b2 + hstep, voffB); PG8_STAGE(PG8_SA(0, 0), a2, voffA);
;             PG8_WAIT_V(8); PG8_WAIT_L(0); PG8_BAR; PG8_MMA(1, 0, At, B0); PG8_MMA(1, 1, At, B1); PG8_BAR; PG8_SCHED;
	v_mfma_f32_16x16x32_bf16 v[140:143], v[40:43], v[160:163], v[140:143]
	v_mfma_f32_16x16x32_bf16 v[136:139], v[52:55], v[160:163], v[136:139]
	v_mfma_f32_16x16x32_bf16 v[124:127], v[40:43], v[168:171], v[124:127]
	v_mfma_f32_16x16x32_bf16 v[120:123], v[52:55], v[168:171], v[120:123]
	v_mfma_f32_16x16x32_bf16 v[108:111], v[40:43], v[196:199], v[108:111]
	v_mfma_f32_16x16x32_bf16 v[104:107], v[52:55], v[196:199], v[104:107]
	v_mfma_f32_16x16x32_bf16 v[92:95], v[40:43], v[204:207], v[92:95]
	v_mfma_f32_16x16x32_bf16 v[88:91], v[52:55], v[204:207], v[88:91]
	v_mfma_f32_16x16x32_bf16 v[140:143], v[48:51], v[164:167], v[140:143]
	v_mfma_f32_16x16x32_bf16 v[136:139], v[60:63], v[164:167], v[136:139]
	v_mfma_f32_16x16x32_bf16 v[124:127], v[48:51], v[192:195], v[124:127]
	v_mfma_f32_16x16x32_bf16 v[120:123], v[60:63], v[192:195], v[120:123]
	v_mfma_f32_16x16x32_bf16 v[108:111], v[48:51], v[200:203], v[108:111]
	v_mfma_f32_16x16x32_bf16 v[104:107], v[60:63], v[200:203], v[104:107]
	v_mfma_f32_16x16x32_bf16 v[92:95], v[48:51], v[214:217], v[92:95]
	v_mfma_f32_16x16x32_bf16 v[88:91], v[60:63], v[214:217], v[88:91]
	v_mfma_f32_16x16x32_bf16 v[132:135], v[144:147], v[160:163], v[132:135]
	v_mfma_f32_16x16x32_bf16 v[128:131], v[152:155], v[160:163], v[128:131]
	v_mfma_f32_16x16x32_bf16 v[116:119], v[144:147], v[168:171], v[116:119]
	v_mfma_f32_16x16x32_bf16 v[112:115], v[152:155], v[168:171], v[112:115]
	v_mfma_f32_16x16x32_bf16 v[100:103], v[144:147], v[196:199], v[100:103]
	v_mfma_f32_16x16x32_bf16 v[96:99], v[152:155], v[196:199], v[96:99]
	v_mfma_f32_16x16x32_bf16 v[84:87], v[144:147], v[204:207], v[84:87]
	v_mfma_f32_16x16x32_bf16 v[80:83], v[152:155], v[204:207], v[80:83]
	v_mfma_f32_16x16x32_bf16 v[132:135], v[148:151], v[164:167], v[132:135]
	v_mfma_f32_16x16x32_bf16 v[128:131], v[156:159], v[164:167], v[128:131]
	v_mfma_f32_16x16x32_bf16 v[116:119], v[148:151], v[192:195], v[116:119]
	v_mfma_f32_16x16x32_bf16 v[112:115], v[156:159], v[192:195], v[112:115]
	v_mfma_f32_16x16x32_bf16 v[100:103], v[148:151], v[200:203], v[100:103]
	v_mfma_f32_16x16x32_bf16 v[96:99], v[156:159], v[200:203], v[96:99]
	v_mfma_f32_16x16x32_bf16 v[84:87], v[148:151], v[214:217], v[84:87]
	v_mfma_f32_16x16x32_bf16 v[80:83], v[156:159], v[214:217], v[80:83]
	s_barrier
	s_add_i32 s65, s57, s31
	v_lshl_add_u64 v[218:219], s[46:47], 0, v[174:175]
	s_mov_b32 m0, s65
	ds_read_b128 v[160:163], v212 offset:16384
	ds_read_b128 v[164:167], v212 offset:17408
	ds_read_b128 v[168:171], v212 offset:18432
	ds_read_b128 v[192:195], v212 offset:19456
	ds_read_b128 v[196:199], v212 offset:20480
	ds_read_b128 v[200:203], v212 offset:21504
	ds_read_b128 v[204:207], v212 offset:22528
	ds_read_b128 v[214:217], v212 offset:23552
	global_load_lds_dwordx4 v[218:219], off
	s_add_i32 m0, s65, 0x2000
	s_add_u32 s66, s46, 0x80000
	v_lshl_add_u64 v[220:221], s[46:47], 0, v[178:179]
	s_addc_u32 s67, s47, 0
	s_add_i32 s65, s58, s31
	global_load_lds_dwordx4 v[220:221], off
	v_lshl_add_u64 v[222:223], s[66:67], 0, v[174:175]
	s_mov_b32 m0, s65
	v_lshl_add_u64 v[224:225], s[48:49], 0, v[176:177]
	global_load_lds_dwordx4 v[222:223], off
	v_lshl_add_u64 v[222:223], s[66:67], 0, v[178:179]
	s_add_i32 m0, s65, 0x2000
	s_nop 0
	global_load_lds_dwordx4 v[222:223], off
	v_lshl_add_u64 v[222:223], s[48:49], 0, v[172:173]
	s_mov_b32 m0, s33
	s_nop 0
	global_load_lds_dwordx4 v[222:223], off
	s_mov_b32 m0, s43
	s_nop 0
	global_load_lds_dwordx4 v[224:225], off
	s_waitcnt vmcnt(8)
	s_waitcnt lgkmcnt(0)
	s_barrier
	v_mfma_f32_16x16x32_bf16 v[76:79], v[40:43], v[160:163], v[76:79]
	v_mfma_f32_16x16x32_bf16 v[72:75], v[52:55], v[160:163], v[72:75]
	v_mfma_f32_16x16x32_bf16 v[56:59], v[40:43], v[168:171], v[56:59]
	v_mfma_f32_16x16x32_bf16 v[44:47], v[52:55], v[168:171], v[44:47]
	v_mfma_f32_16x16x32_bf16 v[28:31], v[40:43], v[196:199], v[28:31]
	v_mfma_f32_16x16x32_bf16 v[24:27], v[52:55], v[196:199], v[24:27]
	v_mfma_f32_16x16x32_bf16 v[12:15], v[40:43], v[204:207], v[12:15]
	v_mfma_f32_16x16x32_bf16 v[8:11], v[52:55], v[204:207], v[8:11]
	v_mfma_f32_16x16x32_bf16 v[76:79], v[48:51], v[164:167], v[76:79]
	v_mfma_f32_16x16x32_bf16 v[72:75], v[60:63], v[164:167], v[72:75]
	v_mfma_f32_16x16x32_bf16 v[56:59], v[48:51], v[192:195], v[56:59]
	v_mfma_f32_16x16x32_bf16 v[44:47], v[60:63], v[192:195], v[44:47]
	v_mfma_f32_16x16x32_bf16 v[28:31], v[48:51], v[200:203], v[28:31]
	v_mfma_f32_16x16x32_bf16 v[24:27], v[60:63], v[200:203], v[24:27]
	v_mfma_f32_16x16x32_bf16 v[12:15], v[48:51], v[214:217], v[12:15]
	v_mfma_f32_16x16x32_bf16 v[8:11], v[60:63], v[214:217], v[8:11]
	v_mfma_f32_16x16x32_bf16 v[36:39], v[144:147], v[168:171], v[36:39]
	v_mfma_f32_16x16x32_bf16 v[32:35], v[152:155], v[168:171], v[32:35]
	v_mfma_f32_16x16x32_bf16 v[20:23], v[144:147], v[196:199], v[20:23]
	v_mfma_f32_16x16x32_bf16 v[16:19], v[152:155], v[196:199], v[16:19]
	v_mfma_f32_16x16x32_bf16 v[4:7], v[144:147], v[204:207], v[4:7]
	v_mfma_f32_16x16x32_bf16 v[0:3], v[152:155], v[204:207], v[0:3]
	v_mfma_f32_16x16x32_bf16 v[40:43], v[144:147], v[160:163], v[68:71]
	v_mfma_f32_16x16x32_bf16 v[48:51], v[152:155], v[160:163], v[64:67]
	v_mfma_f32_16x16x32_bf16 v[36:39], v[148:151], v[192:195], v[36:39]
	v_mfma_f32_16x16x32_bf16 v[32:35], v[156:159], v[192:195], v[32:35]
	v_mfma_f32_16x16x32_bf16 v[20:23], v[148:151], v[200:203], v[20:23]
	v_mfma_f32_16x16x32_bf16 v[16:19], v[156:159], v[200:203], v[16:19]
	v_mfma_f32_16x16x32_bf16 v[4:7], v[148:151], v[214:217], v[4:7]
	v_mfma_f32_16x16x32_bf16 v[0:3], v[156:159], v[214:217], v[0:3]
	v_mfma_f32_16x16x32_bf16 v[40:43], v[148:151], v[164:167], v[40:43]
	v_mfma_f32_16x16x32_bf16 v[48:51], v[156:159], v[164:167], v[48:51]
	s_barrier
; #define PG8_STAGE(bufoff, gbase, voff) do { _Pragma("unroll") for (int _i = 0; _i < 2; ++_i) \
;         __builtin_amdgcn_global_load_lds((const unsigned*)((const char*)(gbase) + (voff)[_i]), (PG8_LAS unsigned*)(lds + (bufoff) + ldsw + _i * 8192), 16, 0, 0); } while (0)
; #define PG8_LDA(dst, b, h) do { _Pragma("unroll") for (int m = 0; m < 4; ++m) _Pragma("unroll") for (int k = 0; k < 2; ++k) dst[m][k] = *(const PG8_LAS bf16x8*)(lds + PG8_SA(b, h) + aoff + m * 2048 + k * 1024); } while (0)
; #define PG8_LDB(dst, b, h) do { _Pragma("unroll") for (int n = 0; n < 2; ++n) _Pragma("unroll") for (int k = 0; k < 2; ++k) dst[n][k] = *(const PG8_LAS bf16x8*)(lds + PG8_SB(b, h) + boff + n * 2048 + k * 1024); } while (0)
; #define PG8_MMA(ai, bj, At, Bt) do { __builtin_amdgcn_s_setprio(1); _Pragma("unroll") for (int m = 0; m < 4; ++m) _Pragma("unroll") for (int n = 0; n < 2; ++n) _Pragma("unroll") for (int k = 0; k < 2; ++k) \
;         acc[ai][bj][m][n] = __builtin_amdgcn_mfma_f32_16x16x32_bf16(Bt[n][k], At[m][k], acc[ai][bj][m][n], 0, 0, 0); __builtin_amdgcn_s_setprio(0); } while (0)
; #define PG8_WAIT_V(n) asm volatile("s_waitcnt vmcnt(" #n ")" ::: "memory")
; #define PG8_WAIT_L(n) asm volatile("s_waitcnt lgkmcnt(" #n ")" ::: "memory")
; #define PG8_BAR __builtin_amdgcn_s_barrier()
; #define PG8_SCHED __builtin_amdgcn_sched_barrier(0)
; template <class Epi, class Sched, bool ALIGN_EPI = false, bool SP2 = false>
; __device__ __forceinline__ void gemm_phase(PG8_LAS unsigned char* lds, const Gemm g, const Sched& S, const Epi& E, const int tid_in) {
;     ...
;             PG8_LDB(B0, 1, 0); PG8_LDB(B1, 1, 1); PG8_SCHED; PG8_LDA(At, 1, 0); PG8_STAGE(PG8_SA(0, 1), a2 + hstepA, voffA);
;             PG8_WAIT_V(8); PG8_WAIT_L(0); PG8_BAR; PG8_MMA(0, 0, At, B0); PG8_MMA(0, 1, At, B1); PG8_BAR; PG8_SCHED;
;             PG8_LDA(At, 1, 1); PG8_STAGE(PG8_SB(1, 0), b3, voffB); PG8_STAGE(PG8_SB(1, 1), b3 + hstep, voffB); PG8_STAGE(PG8_SA(1, 0), a3, voffA);
;             PG8_WAIT_V(8); PG8_WAIT_L(0); PG8_BAR; PG8_MMA(1, 0, At, B0); PG8_MMA(1, 1, At, B1); PG8_BAR; PG8_SCHED;
;     ...
;         }
	s_add_i32 s65, 0, 0x18000
	s_add_i32 s66, 0, 0x1c000
	v_add_u32_e32 v68, s65, v208
	v_add_u32_e32 v156, s66, v208
	ds_read_b128 v[52:55], v68
	ds_read_b128 v[60:63], v68 offset:1024
	ds_read_b128 v[64:67], v68 offset:2048
	ds_read_b128 v[68:71], v68 offset:3072
	ds_read_b128 v[144:147], v156
	ds_read_b128 v[148:151], v156 offset:1024
	ds_read_b128 v[152:155], v156 offset:2048
	ds_read_b128 v[156:159], v156 offset:3072
	s_add_u32 s48, s48, 0x80000
	s_addc_u32 s49, s49, 0
	s_mov_b32 m0, s50
	v_lshl_add_u64 v[226:227], s[48:49], 0, v[172:173]
	ds_read_b128 v[160:163], v212 offset:32768
	ds_read_b128 v[164:167], v212 offset:33792
	ds_read_b128 v[168:171], v212 offset:34816
	ds_read_b128 v[192:195], v212 offset:35840
	ds_read_b128 v[196:199], v212 offset:36864
	ds_read_b128 v[200:203], v212 offset:37888
	ds_read_b128 v[204:207], v212 offset:38912
	ds_read_b128 v[214:217], v212 offset:39936
	global_load_lds_dwordx4 v[226:227], off
	v_lshl_add_u64 v[226:227], s[48:49], 0, v[176:177]
	s_mov_b32 m0, s51
	s_nop 0
	global_load_lds_dwordx4 v[226:227], off
	s_waitcnt vmcnt(8)
	s_waitcnt lgkmcnt(0)
	s_barrier
	v_mfma_f32_16x16x32_bf16 v[140:143], v[52:55], v[160:163], v[140:143]
	v_mfma_f32_16x16x32_bf16 v[136:139], v[64:67], v[160:163], v[136:139]
	v_mfma_f32_16x16x32_bf16 v[124:127], v[52:55], v[168:171], v[124:127]
	v_mfma_f32_16x16x32_bf16 v[120:123], v[64:67], v[168:171], v[120:123]
	v_mfma_f32_16x16x32_bf16 v[108:111], v[52:55], v[196:199], v[108:111]
	v_mfma_f32_16x16x32_bf16 v[104:107], v[64:67], v[196:199], v[104:107]
	v_mfma_f32_16x16x32_bf16 v[92:95], v[52:55], v[204:207], v[92:95]
	v_mfma_f32_16x16x32_bf16 v[88:91], v[64:67], v[204:207], v[88:91]
	v_mfma_f32_16x16x32_bf16 v[140:143], v[60:63], v[164:167], v[140:143]
	v_mfma_f32_16x16x32_bf16 v[136:139], v[68:71], v[164:167], v[136:139]
	v_mfma_f32_16x16x32_bf16 v[124:127], v[60:63], v[192:195], v[124:127]
	v_mfma_f32_16x16x32_bf16 v[120:123], v[68:71], v[192:195], v[120:123]
	v_mfma_f32_16x16x32_bf16 v[108:111], v[60:63], v[200:203], v[108:111]
	v_mfma_f32_16x16x32_bf16 v[104:107], v[68:71], v[200:203], v[104:107]
	v_mfma_f32_16x16x32_bf16 v[92:95], v[60:63], v[214:217], v[92:95]
	v_mfma_f32_16x16x32_bf16 v[88:91], v[68:71], v[214:217], v[88:91]
	v_mfma_f32_16x16x32_bf16 v[132:135], v[144:147], v[160:163], v[132:135]
	v_mfma_f32_16x16x32_bf16 v[128:131], v[152:155], v[160:163], v[128:131]
	v_mfma_f32_16x16x32_bf16 v[116:119], v[144:147], v[168:171], v[116:119]
	v_mfma_f32_16x16x32_bf16 v[112:115], v[152:155], v[168:171], v[112:115]
	v_mfma_f32_16x16x32_bf16 v[100:103], v[144:147], v[196:199], v[100:103]
	v_mfma_f32_16x16x32_bf16 v[96:99], v[152:155], v[196:199], v[96:99]
	v_mfma_f32_16x16x32_bf16 v[84:87], v[144:147], v[204:207], v[84:87]
	v_mfma_f32_16x16x32_bf16 v[80:83], v[152:155], v[204:207], v[80:83]
	v_mfma_f32_16x16x32_bf16 v[132:135], v[148:151], v[164:167], v[132:135]
	v_mfma_f32_16x16x32_bf16 v[128:131], v[156:159], v[164:167], v[128:131]
	v_mfma_f32_16x16x32_bf16 v[116:119], v[148:151], v[192:195], v[116:119]
	v_mfma_f32_16x16x32_bf16 v[112:115], v[156:159], v[192:195], v[112:115]
	v_mfma_f32_16x16x32_bf16 v[100:103], v[148:151], v[200:203], v[100:103]
	v_mfma_f32_16x16x32_bf16 v[96:99], v[156:159], v[200:203], v[96:99]
	v_mfma_f32_16x16x32_bf16 v[84:87], v[148:151], v[214:217], v[84:87]
	v_mfma_f32_16x16x32_bf16 v[80:83], v[156:159], v[214:217], v[80:83]
	s_barrier
	s_add_i32 s48, s65, s31
	v_lshl_add_u64 v[218:219], v[218:219], 0, s[22:23]
	s_mov_b32 m0, s48
	ds_read_b128 v[160:163], v212 offset:49152
	ds_read_b128 v[164:167], v212 offset:50176
	ds_read_b128 v[168:171], v212 offset:51200
	ds_read_b128 v[192:195], v212 offset:52224
	ds_read_b128 v[196:199], v212 offset:53248
	ds_read_b128 v[200:203], v212 offset:54272
	ds_read_b128 v[204:207], v212 offset:55296
	ds_read_b128 v[214:217], v212 offset:56320
	global_load_lds_dwordx4 v[218:219], off
	s_add_i32 m0, s48, 0x2000
	s_add_u32 s46, s46, 0x80080
	v_lshl_add_u64 v[218:219], v[220:221], 0, s[22:23]
	s_addc_u32 s47, s47, 0
	s_add_i32 s48, s66, s31
	global_load_lds_dwordx4 v[218:219], off
	v_lshl_add_u64 v[218:219], s[46:47], 0, v[174:175]
	s_mov_b32 m0, s48
	s_nop 0
	global_load_lds_dwordx4 v[218:219], off
	v_lshl_add_u64 v[218:219], s[46:47], 0, v[178:179]
	s_add_i32 m0, s48, 0x2000
	s_nop 0
	global_load_lds_dwordx4 v[218:219], off
	v_lshl_add_u64 v[218:219], v[222:223], 0, s[22:23]
	s_mov_b32 m0, s53
	s_nop 0
	global_load_lds_dwordx4 v[218:219], off
	v_lshl_add_u64 v[218:219], v[224:225], 0, s[22:23]
	s_mov_b32 m0, s54
	s_nop 0
	global_load_lds_dwordx4 v[218:219], off
	s_waitcnt vmcnt(8)
	s_waitcnt lgkmcnt(0)
	s_barrier
	v_mfma_f32_16x16x32_bf16 v[76:79], v[52:55], v[160:163], v[76:79]
	v_mfma_f32_16x16x32_bf16 v[72:75], v[64:67], v[160:163], v[72:75]
	v_mfma_f32_16x16x32_bf16 v[56:59], v[52:55], v[168:171], v[56:59]
	v_mfma_f32_16x16x32_bf16 v[44:47], v[64:67], v[168:171], v[44:47]
	v_mfma_f32_16x16x32_bf16 v[28:31], v[52:55], v[196:199], v[28:31]
	v_mfma_f32_16x16x32_bf16 v[24:27], v[64:67], v[196:199], v[24:27]
	v_mfma_f32_16x16x32_bf16 v[12:15], v[52:55], v[204:207], v[12:15]
	v_mfma_f32_16x16x32_bf16 v[8:11], v[64:67], v[204:207], v[8:11]
	v_mfma_f32_16x16x32_bf16 v[76:79], v[60:63], v[164:167], v[76:79]
	v_mfma_f32_16x16x32_bf16 v[72:75], v[68:71], v[164:167], v[72:75]
	v_mfma_f32_16x16x32_bf16 v[56:59], v[60:63], v[192:195], v[56:59]
	v_mfma_f32_16x16x32_bf16 v[44:47], v[68:71], v[192:195], v[44:47]
	v_mfma_f32_16x16x32_bf16 v[28:31], v[60:63], v[200:203], v[28:31]
	v_mfma_f32_16x16x32_bf16 v[24:27], v[68:71], v[200:203], v[24:27]
	v_mfma_f32_16x16x32_bf16 v[12:15], v[60:63], v[214:217], v[12:15]
	v_mfma_f32_16x16x32_bf16 v[8:11], v[68:71], v[214:217], v[8:11]
	v_mfma_f32_16x16x32_bf16 v[40:43], v[144:147], v[160:163], v[40:43]
	v_mfma_f32_16x16x32_bf16 v[68:71], v[148:151], v[164:167], v[40:43]
	v_mfma_f32_16x16x32_bf16 v[40:43], v[152:155], v[160:163], v[48:51]
	v_mfma_f32_16x16x32_bf16 v[36:39], v[144:147], v[168:171], v[36:39]
	v_mfma_f32_16x16x32_bf16 v[32:35], v[152:155], v[168:171], v[32:35]
	v_mfma_f32_16x16x32_bf16 v[20:23], v[144:147], v[196:199], v[20:23]
	v_mfma_f32_16x16x32_bf16 v[16:19], v[152:155], v[196:199], v[16:19]
	v_mfma_f32_16x16x32_bf16 v[4:7], v[144:147], v[204:207], v[4:7]
	v_mfma_f32_16x16x32_bf16 v[0:3], v[152:155], v[204:207], v[0:3]
	v_mfma_f32_16x16x32_bf16 v[64:67], v[156:159], v[164:167], v[40:43]
	v_mfma_f32_16x16x32_bf16 v[36:39], v[148:151], v[192:195], v[36:39]
	v_mfma_f32_16x16x32_bf16 v[32:35], v[156:159], v[192:195], v[32:35]
	v_mfma_f32_16x16x32_bf16 v[20:23], v[148:151], v[200:203], v[20:23]
	v_mfma_f32_16x16x32_bf16 v[16:19], v[156:159], v[200:203], v[16:19]
	v_mfma_f32_16x16x32_bf16 v[4:7], v[148:151], v[214:217], v[4:7]
	v_mfma_f32_16x16x32_bf16 v[0:3], v[156:159], v[214:217], v[0:3]
	s_barrier
	s_add_i32 s64, s64, 2
	s_add_u32 s62, s62, 0x100
	s_addc_u32 s63, s63, 0
	s_add_u32 s44, s44, 0x100
	s_addc_u32 s45, s45, 0
	s_cmp_gt_u32 s64, 29
	s_cbranch_scc0 .LBB0_743
	s_setprio 0
	s_and_b64 vcc, exec, s[24:25]
	s_cbranch_vccz .LBB0_746
	s_barrier

; #define PG8_STAGE(bufoff, gbase, voff) do { _Pragma("unroll") for (int _i = 0; _i < 2; ++_i) \
;         __builtin_amdgcn_global_load_lds((const unsigned*)((const char*)(gbase) + (voff)[_i]), (PG8_LAS unsigned*)(lds + (bufoff) + ldsw + _i * 8192), 16, 0, 0); } while (0)
; #define PG8_LDA(dst, b, h) do { _Pragma("unroll") for (int m = 0; m < 4; ++m) _Pragma("unroll") for (int k = 0; k < 2; ++k) dst[m][k] = *(const PG8_LAS bf16x8*)(lds + PG8_SA(b, h) + aoff + m * 2048 + k * 1024); } while (0)
; #define PG8_LDB(dst, b, h) do { _Pragma("unroll") for (int n = 0; n < 2; ++n) _Pragma("unroll") for (int k = 0; k < 2; ++k) dst[n][k] = *(const PG8_LAS bf16x8*)(lds + PG8_SB(b, h) + boff + n * 2048 + k * 1024); } while (0)
; #define PG8_MMA(ai, bj, At, Bt) do { __builtin_amdgcn_s_setprio(1); _Pragma("unroll") for (int m = 0; m < 4; ++m) _Pragma("unroll") for (int n = 0; n < 2; ++n) _Pragma("unroll") for (int k = 0; k < 2; ++k) \
;         acc[ai][bj][m][n] = __builtin_amdgcn_mfma_f32_16x16x32_bf16(Bt[n][k], At[m][k], acc[ai][bj][m][n], 0, 0, 0); __builtin_amdgcn_s_setprio(0); } while (0)
; #define PG8_WAIT_V(n) asm volatile("s_waitcnt vmcnt(" #n ")" ::: "memory")
; #define PG8_WAIT_L(n) asm volatile("s_waitcnt lgkmcnt(" #n ")" ::: "memory")
; #define PG8_BAR __builtin_amdgcn_s_barrier()
; #define PG8_SCHED __builtin_amdgcn_sched_barrier(0)
; template <class Epi, class Sched, bool ALIGN_EPI = false, bool SP2 = false>
; __device__ __forceinline__ void gemm_phase(PG8_LAS unsigned char* lds, const Gemm g, const Sched& S, const Epi& E, const int tid_in) {
;     ...
;             PG8_LDB(B0, 0, 0); PG8_LDB(B1, 0, 1); PG8_SCHED; PG8_LDA(At, 0, 0); PG8_STAGE(PG8_SA(1, 1), a1 + hstepA, voffA);
;             PG8_WAIT_V(8); PG8_WAIT_L(0); PG8_BAR; PG8_MMA(0, 0, At, B0); PG8_MMA(0, 1, At, B1); PG8_BAR; PG8_SCHED;
;             PG8_LDA(At, 0, 1); PG8_STAGE(PG8_SB(0, 0), b2, voffB); PG8_STAGE(PG8_SB(0, 1), b2 + hstep, voffB); PG8_STAGE(PG8_SA(0, 0), a2, voffA);
.Lkprio_skip_9:
.LBB0_901:
	ds_read_b128 v[144:147], v155
	ds_read_b128 v[158:161], v155 offset:1024
	ds_read_b128 v[162:165], v155 offset:2048
	ds_read_b128 v[166:169], v155 offset:3072
	ds_read_b128 v[170:173], v156
	ds_read_b128 v[174:177], v156 offset:1024
	ds_read_b128 v[178:181], v156 offset:2048
	ds_read_b128 v[182:185], v156 offset:3072
	s_add_u32 s24, s22, 0xfff80080
	s_addc_u32 s25, s23, -1
	s_cmp_eq_u32 s53, 28
	s_cselect_b32 s27, s15, s25
	s_cselect_b32 s26, s49, s24
	s_cselect_b32 s25, s13, s52
	s_cselect_b32 s24, s50, s51
	v_lshl_add_u64 v[218:219], s[22:23], 0, v[138:139]
	s_add_i32 m0, s21, 0xc000
	ds_read_b128 v[186:189], v157
	ds_read_b128 v[190:193], v157 offset:1024
	ds_read_b128 v[194:197], v157 offset:2048
	ds_read_b128 v[198:201], v157 offset:3072
	ds_read_b128 v[202:205], v157 offset:4096
	ds_read_b128 v[206:209], v157 offset:5120
	ds_read_b128 v[210:213], v157 offset:6144
	ds_read_b128 v[214:217], v157 offset:7168
	global_load_lds_dwordx4 v[218:219], off
	v_lshl_add_u64 v[218:219], s[22:23], 0, v[136:137]
	s_add_i32 m0, s21, 0xe000
	s_nop 0
	global_load_lds_dwordx4 v[218:219], off
	s_waitcnt vmcnt(8)
	s_waitcnt lgkmcnt(0)
	s_barrier
	v_mfma_f32_16x16x32_bf16 v[124:127], v[144:147], v[186:189], v[124:127]
	v_mfma_f32_16x16x32_bf16 v[120:123], v[162:165], v[186:189], v[120:123]
	v_mfma_f32_16x16x32_bf16 v[112:115], v[144:147], v[194:197], v[112:115]
	v_mfma_f32_16x16x32_bf16 v[104:107], v[162:165], v[194:197], v[104:107]
	v_mfma_f32_16x16x32_bf16 v[96:99], v[144:147], v[202:205], v[96:99]
	v_mfma_f32_16x16x32_bf16 v[88:91], v[162:165], v[202:205], v[88:91]
	v_mfma_f32_16x16x32_bf16 v[80:83], v[144:147], v[210:213], v[80:83]
	v_mfma_f32_16x16x32_bf16 v[72:75], v[162:165], v[210:213], v[72:75]
	v_mfma_f32_16x16x32_bf16 v[124:127], v[158:161], v[190:193], v[124:127]
	v_mfma_f32_16x16x32_bf16 v[120:123], v[166:169], v[190:193], v[120:123]
	v_mfma_f32_16x16x32_bf16 v[112:115], v[158:161], v[198:201], v[112:115]
	v_mfma_f32_16x16x32_bf16 v[104:107], v[166:169], v[198:201], v[104:107]
	v_mfma_f32_16x16x32_bf16 v[96:99], v[158:161], v[206:209], v[96:99]
	v_mfma_f32_16x16x32_bf16 v[88:91], v[166:169], v[206:209], v[88:91]
	v_mfma_f32_16x16x32_bf16 v[80:83], v[158:161], v[214:217], v[80:83]
	v_mfma_f32_16x16x32_bf16 v[72:75], v[166:169], v[214:217], v[72:75]
	v_mfma_f32_16x16x32_bf16 v[116:119], v[170:173], v[186:189], v[116:119]
	v_mfma_f32_16x16x32_bf16 v[108:111], v[178:181], v[186:189], v[108:111]
	v_mfma_f32_16x16x32_bf16 v[100:103], v[170:173], v[194:197], v[100:103]
	v_mfma_f32_16x16x32_bf16 v[92:95], v[178:181], v[194:197], v[92:95]
	v_mfma_f32_16x16x32_bf16 v[84:87], v[170:173], v[202:205], v[84:87]
	v_mfma_f32_16x16x32_bf16 v[76:79], v[178:181], v[202:205], v[76:79]
	v_mfma_f32_16x16x32_bf16 v[68:71], v[170:173], v[210:213], v[68:71]
	v_mfma_f32_16x16x32_bf16 v[64:67], v[178:181], v[210:213], v[64:67]
	v_mfma_f32_16x16x32_bf16 v[116:119], v[174:177], v[190:193], v[116:119]
	v_mfma_f32_16x16x32_bf16 v[108:111], v[182:185], v[190:193], v[108:111]
	v_mfma_f32_16x16x32_bf16 v[100:103], v[174:177], v[198:201], v[100:103]
	v_mfma_f32_16x16x32_bf16 v[92:95], v[182:185], v[198:201], v[92:95]
	v_mfma_f32_16x16x32_bf16 v[84:87], v[174:177], v[206:209], v[84:87]
	v_mfma_f32_16x16x32_bf16 v[76:79], v[182:185], v[206:209], v[76:79]
	v_mfma_f32_16x16x32_bf16 v[68:71], v[174:177], v[214:217], v[68:71]
	v_mfma_f32_16x16x32_bf16 v[64:67], v[182:185], v[214:217], v[64:67]
	s_barrier
	s_add_i32 s54, s41, s30
	v_lshl_add_u64 v[218:219], s[24:25], 0, v[132:133]
	s_mov_b32 m0, s54
	ds_read_b128 v[186:189], v157 offset:16384
	ds_read_b128 v[190:193], v157 offset:17408
	ds_read_b128 v[194:197], v157 offset:18432
	ds_read_b128 v[198:201], v157 offset:19456
	ds_read_b128 v[202:205], v157 offset:20480
	ds_read_b128 v[206:209], v157 offset:21504
	ds_read_b128 v[210:213], v157 offset:22528
	ds_read_b128 v[214:217], v157 offset:23552
	global_load_lds_dwordx4 v[218:219], off
	s_add_i32 m0, s54, 0x2000
	s_add_u32 s54, s24, 0x80000
	v_lshl_add_u64 v[220:221], s[24:25], 0, v[128:129]
	s_addc_u32 s55, s25, 0
	s_add_i32 s56, s42, s30
	global_load_lds_dwordx4 v[220:221], off
	v_lshl_add_u64 v[222:223], s[54:55], 0, v[132:133]
	s_mov_b32 m0, s56
	v_lshl_add_u64 v[224:225], s[26:27], 0, v[130:131]
	global_load_lds_dwordx4 v[222:223], off
	v_lshl_add_u64 v[222:223], s[54:55], 0, v[128:129]
	s_add_i32 m0, s56, 0x2000
	s_nop 0
	global_load_lds_dwordx4 v[222:223], off
	v_lshl_add_u64 v[222:223], s[26:27], 0, v[134:135]
	s_mov_b32 m0, s21
	s_nop 0
	global_load_lds_dwordx4 v[222:223], off
	s_mov_b32 m0, s34
	s_nop 0
	global_load_lds_dwordx4 v[224:225], off
	s_waitcnt vmcnt(8)
	s_waitcnt lgkmcnt(0)
	s_barrier
; #define PG8_STAGE(bufoff, gbase, voff) do { _Pragma("unroll") for (int _i = 0; _i < 2; ++_i) \
;         __builtin_amdgcn_global_load_lds((const unsigned*)((const char*)(gbase) + (voff)[_i]), (PG8_LAS unsigned*)(lds + (bufoff) + ldsw + _i * 8192), 16, 0, 0); } while (0)
; #define PG8_LDA(dst, b, h) do { _Pragma("unroll") for (int m = 0; m < 4; ++m) _Pragma("unroll") for (int k = 0; k < 2; ++k) dst[m][k] = *(const PG8_LAS bf16x8*)(lds + PG8_SA(b, h) + aoff + m * 2048 + k * 1024); } while (0)
; #define PG8_LDB(dst, b, h) do { _Pragma("unroll") for (int n = 0; n < 2; ++n) _Pragma("unroll") for (int k = 0; k < 2; ++k) dst[n][k] = *(const PG8_LAS bf16x8*)(lds + PG8_SB(b, h) + boff + n * 2048 + k * 1024); } while (0)
; #define PG8_MMA(ai, bj, At, Bt) do { __builtin_amdgcn_s_setprio(1); _Pragma("unroll") for (int m = 0; m < 4; ++m) _Pragma("unroll") for (int n = 0; n < 2; ++n) _Pragma("unroll") for (int k = 0; k < 2; ++k) \
;         acc[ai][bj][m][n] = __builtin_amdgcn_mfma_f32_16x16x32_bf16(Bt[n][k], At[m][k], acc[ai][bj][m][n], 0, 0, 0); __builtin_amdgcn_s_setprio(0); } while (0)
; #define PG8_WAIT_V(n) asm volatile("s_waitcnt vmcnt(" #n ")" ::: "memory")
; #define PG8_WAIT_L(n) asm volatile("s_waitcnt lgkmcnt(" #n ")" ::: "memory")
; #define PG8_BAR __builtin_amdgcn_s_barrier()
; #define PG8_SCHED __builtin_amdgcn_sched_barrier(0)
; template <class Epi, class Sched, bool ALIGN_EPI = false, bool SP2 = false>
; __device__ __forceinline__ void gemm_phase(PG8_LAS unsigned char* lds, const Gemm g, const Sched& S, const Epi& E, const int tid_in) {
;     ...
;             PG8_LDA(At, 0, 1); PG8_STAGE(PG8_SB(0, 0), b2, voffB); PG8_STAGE(PG8_SB(0, 1), b2 + hstep, voffB); PG8_STAGE(PG8_SA(0, 0), a2, voffA);
;             PG8_WAIT_V(8); PG8_WAIT_L(0); PG8_BAR; PG8_MMA(1, 0, At, B0); PG8_MMA(1, 1, At, B1); PG8_BAR; PG8_SCHED;
;             PG8_LDB(B0, 1, 0); PG8_LDB(B1, 1, 1); PG8_SCHED; PG8_LDA(At, 1, 0); PG8_STAGE(PG8_SA(0, 1), a2 + hstepA, voffA);
;             PG8_WAIT_V(8); PG8_WAIT_L(0); PG8_BAR; PG8_MMA(0, 0, At, B0); PG8_MMA(0, 1, At, B1); PG8_BAR; PG8_SCHED;
	v_mfma_f32_16x16x32_bf16 v[60:63], v[144:147], v[186:189], v[60:63]
	v_mfma_f32_16x16x32_bf16 v[56:59], v[162:165], v[186:189], v[56:59]
	v_mfma_f32_16x16x32_bf16 v[48:51], v[144:147], v[194:197], v[48:51]
	v_mfma_f32_16x16x32_bf16 v[40:43], v[162:165], v[194:197], v[40:43]
	v_mfma_f32_16x16x32_bf16 v[32:35], v[144:147], v[202:205], v[32:35]
	v_mfma_f32_16x16x32_bf16 v[24:27], v[162:165], v[202:205], v[24:27]
	v_mfma_f32_16x16x32_bf16 v[12:15], v[144:147], v[210:213], v[12:15]
	v_mfma_f32_16x16x32_bf16 v[8:11], v[162:165], v[210:213], v[8:11]
	v_mfma_f32_16x16x32_bf16 v[60:63], v[158:161], v[190:193], v[60:63]
	v_mfma_f32_16x16x32_bf16 v[56:59], v[166:169], v[190:193], v[56:59]
	v_mfma_f32_16x16x32_bf16 v[48:51], v[158:161], v[198:201], v[48:51]
	v_mfma_f32_16x16x32_bf16 v[40:43], v[166:169], v[198:201], v[40:43]
	v_mfma_f32_16x16x32_bf16 v[32:35], v[158:161], v[206:209], v[32:35]
	v_mfma_f32_16x16x32_bf16 v[24:27], v[166:169], v[206:209], v[24:27]
	v_mfma_f32_16x16x32_bf16 v[12:15], v[158:161], v[214:217], v[12:15]
	v_mfma_f32_16x16x32_bf16 v[8:11], v[166:169], v[214:217], v[8:11]
	v_mfma_f32_16x16x32_bf16 v[52:55], v[170:173], v[186:189], v[52:55]
	v_mfma_f32_16x16x32_bf16 v[44:47], v[178:181], v[186:189], v[44:47]
	v_mfma_f32_16x16x32_bf16 v[36:39], v[170:173], v[194:197], v[36:39]
	v_mfma_f32_16x16x32_bf16 v[28:31], v[178:181], v[194:197], v[28:31]
	v_mfma_f32_16x16x32_bf16 v[20:23], v[170:173], v[202:205], v[20:23]
	v_mfma_f32_16x16x32_bf16 v[16:19], v[178:181], v[202:205], v[16:19]
	v_mfma_f32_16x16x32_bf16 v[4:7], v[170:173], v[210:213], v[4:7]
	v_mfma_f32_16x16x32_bf16 v[0:3], v[178:181], v[210:213], v[0:3]
	v_mfma_f32_16x16x32_bf16 v[52:55], v[174:177], v[190:193], v[52:55]
	v_mfma_f32_16x16x32_bf16 v[44:47], v[182:185], v[190:193], v[44:47]
	v_mfma_f32_16x16x32_bf16 v[36:39], v[174:177], v[198:201], v[36:39]
	v_mfma_f32_16x16x32_bf16 v[28:31], v[182:185], v[198:201], v[28:31]
	v_mfma_f32_16x16x32_bf16 v[20:23], v[174:177], v[206:209], v[20:23]
	v_mfma_f32_16x16x32_bf16 v[16:19], v[182:185], v[206:209], v[16:19]
	v_mfma_f32_16x16x32_bf16 v[4:7], v[174:177], v[214:217], v[4:7]
	v_mfma_f32_16x16x32_bf16 v[0:3], v[182:185], v[214:217], v[0:3]
	s_barrier
	s_add_i32 s54, 0, 0x18000
	v_add_u32_e32 v148, s54, v151
	s_add_i32 s55, 0, 0x1c000
	ds_read_b128 v[144:147], v148
	ds_read_b128 v[158:161], v148 offset:1024
	ds_read_b128 v[162:165], v148 offset:2048
	ds_read_b128 v[166:169], v148 offset:3072
	v_add_u32_e32 v148, s55, v151
	ds_read_b128 v[170:173], v148
	ds_read_b128 v[174:177], v148 offset:1024
	ds_read_b128 v[178:181], v148 offset:2048
	ds_read_b128 v[182:185], v148 offset:3072
	s_add_u32 s26, s26, 0x80000
	s_addc_u32 s27, s27, 0
	s_mov_b32 m0, s35
	v_lshl_add_u64 v[226:227], s[26:27], 0, v[134:135]
	ds_read_b128 v[186:189], v157 offset:32768
	ds_read_b128 v[190:193], v157 offset:33792
	ds_read_b128 v[194:197], v157 offset:34816
	ds_read_b128 v[198:201], v157 offset:35840
	ds_read_b128 v[202:205], v157 offset:36864
	ds_read_b128 v[206:209], v157 offset:37888
	ds_read_b128 v[210:213], v157 offset:38912
	ds_read_b128 v[214:217], v157 offset:39936
	global_load_lds_dwordx4 v[226:227], off
	v_lshl_add_u64 v[226:227], s[26:27], 0, v[130:131]
	s_mov_b32 m0, s36
	s_nop 0
	global_load_lds_dwordx4 v[226:227], off
	s_waitcnt vmcnt(8)
	s_waitcnt lgkmcnt(0)
	s_barrier
	v_mfma_f32_16x16x32_bf16 v[124:127], v[144:147], v[186:189], v[124:127]
	v_mfma_f32_16x16x32_bf16 v[120:123], v[162:165], v[186:189], v[120:123]
	v_mfma_f32_16x16x32_bf16 v[112:115], v[144:147], v[194:197], v[112:115]
	v_mfma_f32_16x16x32_bf16 v[104:107], v[162:165], v[194:197], v[104:107]
	v_mfma_f32_16x16x32_bf16 v[96:99], v[144:147], v[202:205], v[96:99]
	v_mfma_f32_16x16x32_bf16 v[88:91], v[162:165], v[202:205], v[88:91]
	v_mfma_f32_16x16x32_bf16 v[80:83], v[144:147], v[210:213], v[80:83]
	v_mfma_f32_16x16x32_bf16 v[72:75], v[162:165], v[210:213], v[72:75]
	v_mfma_f32_16x16x32_bf16 v[124:127], v[158:161], v[190:193], v[124:127]
	v_mfma_f32_16x16x32_bf16 v[120:123], v[166:169], v[190:193], v[120:123]
	v_mfma_f32_16x16x32_bf16 v[112:115], v[158:161], v[198:201], v[112:115]
	v_mfma_f32_16x16x32_bf16 v[104:107], v[166:169], v[198:201], v[104:107]
	v_mfma_f32_16x16x32_bf16 v[96:99], v[158:161], v[206:209], v[96:99]
	v_mfma_f32_16x16x32_bf16 v[88:91], v[166:169], v[206:209], v[88:91]
	v_mfma_f32_16x16x32_bf16 v[80:83], v[158:161], v[214:217], v[80:83]
	v_mfma_f32_16x16x32_bf16 v[72:75], v[166:169], v[214:217], v[72:75]
	v_mfma_f32_16x16x32_bf16 v[116:119], v[170:173], v[186:189], v[116:119]
	v_mfma_f32_16x16x32_bf16 v[108:111], v[178:181], v[186:189], v[108:111]
	v_mfma_f32_16x16x32_bf16 v[100:103], v[170:173], v[194:197], v[100:103]
	v_mfma_f32_16x16x32_bf16 v[92:95], v[178:181], v[194:197], v[92:95]
	v_mfma_f32_16x16x32_bf16 v[84:87], v[170:173], v[202:205], v[84:87]
	v_mfma_f32_16x16x32_bf16 v[76:79], v[178:181], v[202:205], v[76:79]
	v_mfma_f32_16x16x32_bf16 v[68:71], v[170:173], v[210:213], v[68:71]
	v_mfma_f32_16x16x32_bf16 v[64:67], v[178:181], v[210:213], v[64:67]
	v_mfma_f32_16x16x32_bf16 v[116:119], v[174:177], v[190:193], v[116:119]
	v_mfma_f32_16x16x32_bf16 v[108:111], v[182:185], v[190:193], v[108:111]
	v_mfma_f32_16x16x32_bf16 v[100:103], v[174:177], v[198:201], v[100:103]
	v_mfma_f32_16x16x32_bf16 v[92:95], v[182:185], v[198:201], v[92:95]
	v_mfma_f32_16x16x32_bf16 v[84:87], v[174:177], v[206:209], v[84:87]
	v_mfma_f32_16x16x32_bf16 v[76:79], v[182:185], v[206:209], v[76:79]
	v_mfma_f32_16x16x32_bf16 v[68:71], v[174:177], v[214:217], v[68:71]
	v_mfma_f32_16x16x32_bf16 v[64:67], v[182:185], v[214:217], v[64:67]
	s_barrier
; #define PG8_STAGE(bufoff, gbase, voff) do { _Pragma("unroll") for (int _i = 0; _i < 2; ++_i) \
;         __builtin_amdgcn_global_load_lds((const unsigned*)((const char*)(gbase) + (voff)[_i]), (PG8_LAS unsigned*)(lds + (bufoff) + ldsw + _i * 8192), 16, 0, 0); } while (0)
; #define PG8_LDA(dst, b, h) do { _Pragma("unroll") for (int m = 0; m < 4; ++m) _Pragma("unroll") for (int k = 0; k < 2; ++k) dst[m][k] = *(const PG8_LAS bf16x8*)(lds + PG8_SA(b, h) + aoff + m * 2048 + k * 1024); } while (0)
; #define PG8_MMA(ai, bj, At, Bt) do { __builtin_amdgcn_s_setprio(1); _Pragma("unroll") for (int m = 0; m < 4; ++m) _Pragma("unroll") for (int n = 0; n < 2; ++n) _Pragma("unroll") for (int k = 0; k < 2; ++k) \
;         acc[ai][bj][m][n] = __builtin_amdgcn_mfma_f32_16x16x32_bf16(Bt[n][k], At[m][k], acc[ai][bj][m][n], 0, 0, 0); __builtin_amdgcn_s_setprio(0); } while (0)
; #define PG8_WAIT_V(n) asm volatile("s_waitcnt vmcnt(" #n ")" ::: "memory")
; #define PG8_WAIT_L(n) asm volatile("s_waitcnt lgkmcnt(" #n ")" ::: "memory")
; #define PG8_BAR __builtin_amdgcn_s_barrier()
; #define PG8_SCHED __builtin_amdgcn_sched_barrier(0)
; template <class Epi, class Sched, bool ALIGN_EPI = false, bool SP2 = false>
; __device__ __forceinline__ void gemm_phase(PG8_LAS unsigned char* lds, const Gemm g, const Sched& S, const Epi& E, const int tid_in) {
;     ...
;             PG8_LDA(At, 1, 1); PG8_STAGE(PG8_SB(1, 0), b3, voffB); PG8_STAGE(PG8_SB(1, 1), b3 + hstep, voffB); PG8_STAGE(PG8_SA(1, 0), a3, voffA);
;             PG8_WAIT_V(8); PG8_WAIT_L(0); PG8_BAR; PG8_MMA(1, 0, At, B0); PG8_MMA(1, 1, At, B1); PG8_BAR; PG8_SCHED;
;     ...
;         }
	s_add_i32 s26, s54, s30
	v_lshl_add_u64 v[218:219], v[218:219], 0, s[8:9]
	s_mov_b32 m0, s26
	ds_read_b128 v[186:189], v157 offset:49152
	ds_read_b128 v[190:193], v157 offset:50176
	ds_read_b128 v[194:197], v157 offset:51200
	ds_read_b128 v[198:201], v157 offset:52224
	ds_read_b128 v[202:205], v157 offset:53248
	ds_read_b128 v[206:209], v157 offset:54272
	ds_read_b128 v[210:213], v157 offset:55296
	ds_read_b128 v[214:217], v157 offset:56320
	global_load_lds_dwordx4 v[218:219], off
	s_add_i32 m0, s26, 0x2000
	s_add_u32 s24, s24, 0x80080
	v_lshl_add_u64 v[218:219], v[220:221], 0, s[8:9]
	s_addc_u32 s25, s25, 0
	s_add_i32 s26, s55, s30
	global_load_lds_dwordx4 v[218:219], off
	v_lshl_add_u64 v[218:219], s[24:25], 0, v[132:133]
	s_mov_b32 m0, s26
	s_nop 0
	global_load_lds_dwordx4 v[218:219], off
	v_lshl_add_u64 v[218:219], s[24:25], 0, v[128:129]
	s_add_i32 m0, s26, 0x2000
	s_nop 0
	global_load_lds_dwordx4 v[218:219], off
	v_lshl_add_u64 v[218:219], v[222:223], 0, s[8:9]
	s_mov_b32 m0, s38
	s_nop 0
	global_load_lds_dwordx4 v[218:219], off
	v_lshl_add_u64 v[218:219], v[224:225], 0, s[8:9]
	s_mov_b32 m0, s39
	s_nop 0
	global_load_lds_dwordx4 v[218:219], off
	s_waitcnt vmcnt(8)
	s_waitcnt lgkmcnt(0)
	s_barrier
	v_mfma_f32_16x16x32_bf16 v[60:63], v[144:147], v[186:189], v[60:63]
	v_mfma_f32_16x16x32_bf16 v[56:59], v[162:165], v[186:189], v[56:59]
	v_mfma_f32_16x16x32_bf16 v[48:51], v[144:147], v[194:197], v[48:51]
	v_mfma_f32_16x16x32_bf16 v[40:43], v[162:165], v[194:197], v[40:43]
	v_mfma_f32_16x16x32_bf16 v[32:35], v[144:147], v[202:205], v[32:35]
	v_mfma_f32_16x16x32_bf16 v[24:27], v[162:165], v[202:205], v[24:27]
	v_mfma_f32_16x16x32_bf16 v[12:15], v[144:147], v[210:213], v[12:15]
	v_mfma_f32_16x16x32_bf16 v[8:11], v[162:165], v[210:213], v[8:11]
	v_mfma_f32_16x16x32_bf16 v[60:63], v[158:161], v[190:193], v[60:63]
	v_mfma_f32_16x16x32_bf16 v[56:59], v[166:169], v[190:193], v[56:59]
	v_mfma_f32_16x16x32_bf16 v[48:51], v[158:161], v[198:201], v[48:51]
	v_mfma_f32_16x16x32_bf16 v[40:43], v[166:169], v[198:201], v[40:43]
	v_mfma_f32_16x16x32_bf16 v[32:35], v[158:161], v[206:209], v[32:35]
	v_mfma_f32_16x16x32_bf16 v[24:27], v[166:169], v[206:209], v[24:27]
	v_mfma_f32_16x16x32_bf16 v[12:15], v[158:161], v[214:217], v[12:15]
	v_mfma_f32_16x16x32_bf16 v[8:11], v[166:169], v[214:217], v[8:11]
	v_mfma_f32_16x16x32_bf16 v[52:55], v[170:173], v[186:189], v[52:55]
	v_mfma_f32_16x16x32_bf16 v[44:47], v[178:181], v[186:189], v[44:47]
	v_mfma_f32_16x16x32_bf16 v[36:39], v[170:173], v[194:197], v[36:39]
	v_mfma_f32_16x16x32_bf16 v[28:31], v[178:181], v[194:197], v[28:31]
	v_mfma_f32_16x16x32_bf16 v[20:23], v[170:173], v[202:205], v[20:23]
	v_mfma_f32_16x16x32_bf16 v[16:19], v[178:181], v[202:205], v[16:19]
	v_mfma_f32_16x16x32_bf16 v[4:7], v[170:173], v[210:213], v[4:7]
	v_mfma_f32_16x16x32_bf16 v[0:3], v[178:181], v[210:213], v[0:3]
	v_mfma_f32_16x16x32_bf16 v[52:55], v[174:177], v[190:193], v[52:55]
	v_mfma_f32_16x16x32_bf16 v[44:47], v[182:185], v[190:193], v[44:47]
	v_mfma_f32_16x16x32_bf16 v[36:39], v[174:177], v[198:201], v[36:39]
	v_mfma_f32_16x16x32_bf16 v[28:31], v[182:185], v[198:201], v[28:31]
	v_mfma_f32_16x16x32_bf16 v[20:23], v[174:177], v[206:209], v[20:23]
	v_mfma_f32_16x16x32_bf16 v[16:19], v[182:185], v[206:209], v[16:19]
	v_mfma_f32_16x16x32_bf16 v[4:7], v[174:177], v[214:217], v[4:7]
	v_mfma_f32_16x16x32_bf16 v[0:3], v[182:185], v[214:217], v[0:3]
	s_barrier
	s_add_i32 s53, s53, 2
	s_add_u32 s51, s51, 0x100
	s_addc_u32 s52, s52, 0
	s_add_u32 s22, s22, 0x100
	s_addc_u32 s23, s23, 0
	s_cmp_gt_u32 s53, 29
	s_cbranch_scc0 .LBB0_901
	s_setprio 0
	s_and_b64 vcc, exec, s[10:11]
	s_cbranch_vccz .LBB0_904
	s_barrier

; #define PG8_STAGE(bufoff, gbase, voff) do { _Pragma("unroll") for (int _i = 0; _i < 2; ++_i) \
;         __builtin_amdgcn_global_load_lds((const unsigned*)((const char*)(gbase) + (voff)[_i]), (PG8_LAS unsigned*)(lds + (bufoff) + ldsw + _i * 8192), 16, 0, 0); } while (0)
; #define PG8_LDA(dst, b, h) do { _Pragma("unroll") for (int m = 0; m < 4; ++m) _Pragma("unroll") for (int k = 0; k < 2; ++k) dst[m][k] = *(const PG8_LAS bf16x8*)(lds + PG8_SA(b, h) + aoff + m * 2048 + k * 1024); } while (0)
; #define PG8_LDB(dst, b, h) do { _Pragma("unroll") for (int n = 0; n < 2; ++n) _Pragma("unroll") for (int k = 0; k < 2; ++k) dst[n][k] = *(const PG8_LAS bf16x8*)(lds + PG8_SB(b, h) + boff + n * 2048 + k * 1024); } while (0)
; #define PG8_MMA(ai, bj, At, Bt) do { __builtin_amdgcn_s_setprio(1); _Pragma("unroll") for (int m = 0; m < 4; ++m) _Pragma("unroll") for (int n = 0; n < 2; ++n) _Pragma("unroll") for (int k = 0; k < 2; ++k) \
;         acc[ai][bj][m][n] = __builtin_amdgcn_mfma_f32_16x16x32_bf16(Bt[n][k], At[m][k], acc[ai][bj][m][n], 0, 0, 0); __builtin_amdgcn_s_setprio(0); } while (0)
; #define PG8_WAIT_V(n) asm volatile("s_waitcnt vmcnt(" #n ")" ::: "memory")
; #define PG8_WAIT_L(n) asm volatile("s_waitcnt lgkmcnt(" #n ")" ::: "memory")
; template <class Epi, class Sched, bool ALIGN_EPI = false, bool SP2 = false>
; __device__ __forceinline__ void gemm_phase(PG8_LAS unsigned char* lds, const Gemm g, const Sched& S, const Epi& E, const int tid_in) {
;     ...
;         const bool has_next = S.next(ui + 1, nxt);
;         const char* nA = has_next ? (const char*)g.A + (size_t)nxt.pm * tstepA : cA; const char* nB = has_next ? (const char*)g.Bt + (size_t)nxt.pn * tstep : cB;
;         for (int t = 0; t < nt; t += 2) {
;             const bool last = (t == nt - 2);
;             const char* a1 = cA + (size_t)(t + 1) * kstep;
;             const char* a2 = last ? nA : cA + (size_t)(t + 2) * kstep; const char* b2 = last ? nB : cB + (size_t)(t + 2) * kstep;
;             const char* a3 = a2 + kstep; const char* b3 = b2 + kstep;
;             if (last && has_next) S.a_ready(nxt);
;             if constexpr (SP2) {
;             PG8_LDB(B0, 0, 0); PG8_LDB(B1, 0, 1); PG8_SCHED; PG8_LDA(At, 0, 0); PG8_STAGE(PG8_SA(1, 1), a1 + hstepA, voffA);
;             PG8_WAIT_V(8); PG8_WAIT_L(0); PG8_BAR; PG8_MMA(0, 0, At, B0); PG8_MMA(0, 1, At, B1); PG8_BAR; PG8_SCHED;
.LBB0_964:
	s_add_u32 s49, s22, 0x100
	v_mov_b32_e32 v0, 0
	s_addc_u32 s50, s23, 0
	s_mov_b32 s51, -2
	s_waitcnt lgkmcnt(0)
	v_mov_b32_e32 v1, v0
	v_mov_b32_e32 v2, v0
	v_mov_b32_e32 v3, v0
	v_mov_b32_e32 v4, v0
	v_mov_b32_e32 v5, v0
	v_mov_b32_e32 v6, v0
	v_mov_b32_e32 v7, v0
	v_mov_b32_e32 v16, v0
	v_mov_b32_e32 v17, v0
	v_mov_b32_e32 v18, v0
	v_mov_b32_e32 v19, v0
	v_mov_b32_e32 v20, v0
	v_mov_b32_e32 v21, v0
	v_mov_b32_e32 v22, v0
	v_mov_b32_e32 v23, v0
	v_mov_b32_e32 v32, v0
	v_mov_b32_e32 v33, v0
	v_mov_b32_e32 v34, v0
	v_mov_b32_e32 v35, v0
	v_mov_b32_e32 v36, v0
	v_mov_b32_e32 v37, v0
	v_mov_b32_e32 v38, v0
	v_mov_b32_e32 v39, v0
	v_mov_b32_e32 v48, v0
	v_mov_b32_e32 v49, v0
	v_mov_b32_e32 v50, v0
	v_mov_b32_e32 v51, v0
	v_mov_b32_e32 v52, v0
	v_mov_b32_e32 v53, v0
	v_mov_b32_e32 v54, v0
	v_mov_b32_e32 v55, v0
	v_mov_b32_e32 v8, v0
	v_mov_b32_e32 v9, v0
	v_mov_b32_e32 v10, v0
	v_mov_b32_e32 v11, v0
	v_mov_b32_e32 v12, v0
	v_mov_b32_e32 v13, v0
	v_mov_b32_e32 v14, v0
	v_mov_b32_e32 v15, v0
	v_mov_b32_e32 v24, v0
	v_mov_b32_e32 v25, v0
	v_mov_b32_e32 v26, v0
	v_mov_b32_e32 v27, v0
	v_mov_b32_e32 v28, v0
	v_mov_b32_e32 v29, v0
	v_mov_b32_e32 v30, v0
	v_mov_b32_e32 v31, v0
	v_mov_b32_e32 v40, v0
	v_mov_b32_e32 v41, v0
	v_mov_b32_e32 v42, v0
	v_mov_b32_e32 v43, v0
	v_mov_b32_e32 v44, v0
	v_mov_b32_e32 v45, v0
	v_mov_b32_e32 v46, v0
	v_mov_b32_e32 v47, v0
	v_mov_b32_e32 v56, v0
	v_mov_b32_e32 v57, v0
	v_mov_b32_e32 v58, v0
	v_mov_b32_e32 v59, v0
	v_mov_b32_e32 v60, v0
	v_mov_b32_e32 v61, v0
	v_mov_b32_e32 v62, v0
	v_mov_b32_e32 v63, v0
	v_mov_b32_e32 v64, v0
	v_mov_b32_e32 v65, v0
	v_mov_b32_e32 v66, v0
	v_mov_b32_e32 v67, v0
	v_mov_b32_e32 v68, v0
	v_mov_b32_e32 v69, v0
	v_mov_b32_e32 v70, v0
	v_mov_b32_e32 v71, v0
	v_mov_b32_e32 v80, v0
	v_mov_b32_e32 v81, v0
	v_mov_b32_e32 v82, v0
	v_mov_b32_e32 v83, v0
	v_mov_b32_e32 v84, v0
	v_mov_b32_e32 v85, v0
	v_mov_b32_e32 v86, v0
	v_mov_b32_e32 v87, v0
	v_mov_b32_e32 v96, v0
	v_mov_b32_e32 v97, v0
	v_mov_b32_e32 v98, v0
	v_mov_b32_e32 v99, v0
	v_mov_b32_e32 v100, v0
	v_mov_b32_e32 v101, v0
	v_mov_b32_e32 v102, v0
	v_mov_b32_e32 v103, v0
	v_mov_b32_e32 v120, v0
	v_mov_b32_e32 v121, v0
	v_mov_b32_e32 v122, v0
	v_mov_b32_e32 v123, v0
	v_mov_b32_e32 v124, v0
	v_mov_b32_e32 v125, v0
	v_mov_b32_e32 v126, v0
	v_mov_b32_e32 v127, v0
	v_mov_b32_e32 v72, v0
	v_mov_b32_e32 v73, v0
	v_mov_b32_e32 v74, v0
	v_mov_b32_e32 v75, v0
	v_mov_b32_e32 v76, v0
	v_mov_b32_e32 v77, v0
	v_mov_b32_e32 v78, v0
	v_mov_b32_e32 v79, v0
	v_mov_b32_e32 v88, v0
	v_mov_b32_e32 v89, v0
	v_mov_b32_e32 v90, v0
	v_mov_b32_e32 v91, v0
	v_mov_b32_e32 v92, v0
	v_mov_b32_e32 v93, v0
	v_mov_b32_e32 v94, v0
	v_mov_b32_e32 v95, v0
	v_mov_b32_e32 v108, v0
	v_mov_b32_e32 v109, v0
	v_mov_b32_e32 v110, v0
	v_mov_b32_e32 v111, v0
	v_mov_b32_e32 v112, v0
	v_mov_b32_e32 v113, v0
	v_mov_b32_e32 v114, v0
	v_mov_b32_e32 v115, v0
	v_mov_b32_e32 v132, v0
	v_mov_b32_e32 v133, v0
	v_mov_b32_e32 v134, v0
	v_mov_b32_e32 v135, v0
	v_mov_b32_e32 v136, v0
	v_mov_b32_e32 v137, v0
	v_mov_b32_e32 v138, v0
	v_mov_b32_e32 v139, v0
	s_cmp_lt_u32 s75, 4
	s_cbranch_scc1 .Lkprio_skip_10
	s_setprio 1
.Lkprio_skip_10:
.LBB0_965:
	ds_read_b128 v[104:107], v222
	ds_read_b128 v[116:119], v222 offset:1024
	ds_read_b128 v[128:131], v222 offset:2048
	ds_read_b128 v[140:143], v222 offset:3072
	ds_read_b128 v[144:147], v223
	ds_read_b128 v[148:151], v223 offset:1024
	ds_read_b128 v[152:155], v223 offset:2048
	ds_read_b128 v[156:159], v223 offset:3072
	s_add_u32 s22, s20, 0x100
	s_addc_u32 s23, s21, 0
	s_cmpk_eq_i32 s51, 0x52
	s_cselect_b32 s27, s5, s23
	s_cselect_b32 s26, s4, s22
	s_cselect_b32 s25, s19, s50
	s_cselect_b32 s24, s18, s49
	v_lshl_add_u64 v[208:209], s[20:21], 0, v[194:195]
	s_add_i32 m0, s34, 0xc000
	ds_read_b128 v[160:163], v224
	ds_read_b128 v[164:167], v224 offset:1024
	ds_read_b128 v[168:171], v224 offset:2048
	ds_read_b128 v[172:175], v224 offset:3072
	ds_read_b128 v[176:179], v224 offset:4096
	ds_read_b128 v[180:183], v224 offset:5120
	ds_read_b128 v[200:203], v224 offset:6144
	ds_read_b128 v[204:207], v224 offset:7168
	global_load_lds_dwordx4 v[208:209], off
	v_lshl_add_u64 v[208:209], s[20:21], 0, v[192:193]
	s_add_i32 m0, s34, 0xe000
	s_nop 0
	global_load_lds_dwordx4 v[208:209], off
	s_waitcnt vmcnt(8)
	s_waitcnt lgkmcnt(0)
	s_barrier
	v_mfma_f32_16x16x32_bf16 v[136:139], v[104:107], v[160:163], v[136:139]
	v_mfma_f32_16x16x32_bf16 v[132:135], v[128:131], v[160:163], v[132:135]
	v_mfma_f32_16x16x32_bf16 v[112:115], v[104:107], v[168:171], v[112:115]
	v_mfma_f32_16x16x32_bf16 v[108:111], v[128:131], v[168:171], v[108:111]
	v_mfma_f32_16x16x32_bf16 v[92:95], v[104:107], v[176:179], v[92:95]
	v_mfma_f32_16x16x32_bf16 v[88:91], v[128:131], v[176:179], v[88:91]
	v_mfma_f32_16x16x32_bf16 v[76:79], v[104:107], v[200:203], v[76:79]
	v_mfma_f32_16x16x32_bf16 v[72:75], v[128:131], v[200:203], v[72:75]
	v_mfma_f32_16x16x32_bf16 v[136:139], v[116:119], v[164:167], v[136:139]
	v_mfma_f32_16x16x32_bf16 v[132:135], v[140:143], v[164:167], v[132:135]
	v_mfma_f32_16x16x32_bf16 v[112:115], v[116:119], v[172:175], v[112:115]
	v_mfma_f32_16x16x32_bf16 v[108:111], v[140:143], v[172:175], v[108:111]
	v_mfma_f32_16x16x32_bf16 v[92:95], v[116:119], v[180:183], v[92:95]
	v_mfma_f32_16x16x32_bf16 v[88:91], v[140:143], v[180:183], v[88:91]
	v_mfma_f32_16x16x32_bf16 v[76:79], v[116:119], v[204:207], v[76:79]
	v_mfma_f32_16x16x32_bf16 v[72:75], v[140:143], v[204:207], v[72:75]
	v_mfma_f32_16x16x32_bf16 v[124:127], v[144:147], v[160:163], v[124:127]
	v_mfma_f32_16x16x32_bf16 v[120:123], v[152:155], v[160:163], v[120:123]
	v_mfma_f32_16x16x32_bf16 v[100:103], v[144:147], v[168:171], v[100:103]
	v_mfma_f32_16x16x32_bf16 v[96:99], v[152:155], v[168:171], v[96:99]
	v_mfma_f32_16x16x32_bf16 v[84:87], v[144:147], v[176:179], v[84:87]
	v_mfma_f32_16x16x32_bf16 v[80:83], v[152:155], v[176:179], v[80:83]
	v_mfma_f32_16x16x32_bf16 v[68:71], v[144:147], v[200:203], v[68:71]
	v_mfma_f32_16x16x32_bf16 v[64:67], v[152:155], v[200:203], v[64:67]
	v_mfma_f32_16x16x32_bf16 v[124:127], v[148:151], v[164:167], v[124:127]
	v_mfma_f32_16x16x32_bf16 v[120:123], v[156:159], v[164:167], v[120:123]
	v_mfma_f32_16x16x32_bf16 v[100:103], v[148:151], v[172:175], v[100:103]
	v_mfma_f32_16x16x32_bf16 v[96:99], v[156:159], v[172:175], v[96:99]
	v_mfma_f32_16x16x32_bf16 v[84:87], v[148:151], v[180:183], v[84:87]
	v_mfma_f32_16x16x32_bf16 v[80:83], v[156:159], v[180:183], v[80:83]
	v_mfma_f32_16x16x32_bf16 v[68:71], v[148:151], v[204:207], v[68:71]
	v_mfma_f32_16x16x32_bf16 v[64:67], v[156:159], v[204:207], v[64:67]
	s_barrier
; #define PG8_STAGE(bufoff, gbase, voff) do { _Pragma("unroll") for (int _i = 0; _i < 2; ++_i) \
;         __builtin_amdgcn_global_load_lds((const unsigned*)((const char*)(gbase) + (voff)[_i]), (PG8_LAS unsigned*)(lds + (bufoff) + ldsw + _i * 8192), 16, 0, 0); } while (0)
; #define PG8_LDA(dst, b, h) do { _Pragma("unroll") for (int m = 0; m < 4; ++m) _Pragma("unroll") for (int k = 0; k < 2; ++k) dst[m][k] = *(const PG8_LAS bf16x8*)(lds + PG8_SA(b, h) + aoff + m * 2048 + k * 1024); } while (0)
; #define PG8_LDB(dst, b, h) do { _Pragma("unroll") for (int n = 0; n < 2; ++n) _Pragma("unroll") for (int k = 0; k < 2; ++k) dst[n][k] = *(const PG8_LAS bf16x8*)(lds + PG8_SB(b, h) + boff + n * 2048 + k * 1024); } while (0)
; #define PG8_MMA(ai, bj, At, Bt) do { __builtin_amdgcn_s_setprio(1); _Pragma("unroll") for (int m = 0; m < 4; ++m) _Pragma("unroll") for (int n = 0; n < 2; ++n) _Pragma("unroll") for (int k = 0; k < 2; ++k) \
;         acc[ai][bj][m][n] = __builtin_amdgcn_mfma_f32_16x16x32_bf16(Bt[n][k], At[m][k], acc[ai][bj][m][n], 0, 0, 0); __builtin_amdgcn_s_setprio(0); } while (0)
; #define PG8_WAIT_V(n) asm volatile("s_waitcnt vmcnt(" #n ")" ::: "memory")
; #define PG8_WAIT_L(n) asm volatile("s_waitcnt lgkmcnt(" #n ")" ::: "memory")
; #define PG8_BAR __builtin_amdgcn_s_barrier()
; #define PG8_SCHED __builtin_amdgcn_sched_barrier(0)
; template <class Epi, class Sched, bool ALIGN_EPI = false, bool SP2 = false>
; __device__ __forceinline__ void gemm_phase(PG8_LAS unsigned char* lds, const Gemm g, const Sched& S, const Epi& E, const int tid_in) {
;     ...
;             PG8_LDA(At, 0, 1); PG8_STAGE(PG8_SB(0, 0), b2, voffB); PG8_STAGE(PG8_SB(0, 1), b2 + hstep, voffB); PG8_STAGE(PG8_SA(0, 0), a2, voffA);
;             PG8_WAIT_V(8); PG8_WAIT_L(0); PG8_BAR; PG8_MMA(1, 0, At, B0); PG8_MMA(1, 1, At, B1); PG8_BAR; PG8_SCHED;
;             PG8_LDB(B0, 1, 0); PG8_LDB(B1, 1, 1); PG8_SCHED; PG8_LDA(At, 1, 0); PG8_STAGE(PG8_SA(0, 1), a2 + hstepA, voffA);
	s_add_i32 s20, s43, s33
	v_lshl_add_u64 v[208:209], s[24:25], 0, v[186:187]
	s_mov_b32 m0, s20
	ds_read_b128 v[160:163], v224 offset:16384
	ds_read_b128 v[164:167], v224 offset:17408
	ds_read_b128 v[168:171], v224 offset:18432
	ds_read_b128 v[172:175], v224 offset:19456
	ds_read_b128 v[176:179], v224 offset:20480
	ds_read_b128 v[180:183], v224 offset:21504
	ds_read_b128 v[200:203], v224 offset:22528
	ds_read_b128 v[204:207], v224 offset:23552
	global_load_lds_dwordx4 v[208:209], off
	s_add_i32 m0, s20, 0x2000
	s_add_u32 s20, s24, 0x158000
	v_lshl_add_u64 v[210:211], s[24:25], 0, v[190:191]
	s_addc_u32 s21, s25, 0
	s_add_i32 s52, s44, s33
	global_load_lds_dwordx4 v[210:211], off
	v_lshl_add_u64 v[212:213], s[20:21], 0, v[186:187]
	s_mov_b32 m0, s52
	v_lshl_add_u64 v[214:215], s[26:27], 0, v[188:189]
	global_load_lds_dwordx4 v[212:213], off
	v_lshl_add_u64 v[212:213], s[20:21], 0, v[190:191]
	s_add_i32 m0, s52, 0x2000
	s_nop 0
	global_load_lds_dwordx4 v[212:213], off
	v_lshl_add_u64 v[212:213], s[26:27], 0, v[184:185]
	s_mov_b32 m0, s34
	s_nop 0
	global_load_lds_dwordx4 v[212:213], off
	s_mov_b32 m0, s35
	s_nop 0
	global_load_lds_dwordx4 v[214:215], off
	s_waitcnt vmcnt(8)
	s_waitcnt lgkmcnt(0)
	s_barrier
	v_mfma_f32_16x16x32_bf16 v[60:63], v[104:107], v[160:163], v[60:63]
	v_mfma_f32_16x16x32_bf16 v[56:59], v[128:131], v[160:163], v[56:59]
	v_mfma_f32_16x16x32_bf16 v[44:47], v[104:107], v[168:171], v[44:47]
	v_mfma_f32_16x16x32_bf16 v[40:43], v[128:131], v[168:171], v[40:43]
	v_mfma_f32_16x16x32_bf16 v[28:31], v[104:107], v[176:179], v[28:31]
	v_mfma_f32_16x16x32_bf16 v[24:27], v[128:131], v[176:179], v[24:27]
	v_mfma_f32_16x16x32_bf16 v[12:15], v[104:107], v[200:203], v[12:15]
	v_mfma_f32_16x16x32_bf16 v[8:11], v[128:131], v[200:203], v[8:11]
	v_mfma_f32_16x16x32_bf16 v[60:63], v[116:119], v[164:167], v[60:63]
	v_mfma_f32_16x16x32_bf16 v[56:59], v[140:143], v[164:167], v[56:59]
	v_mfma_f32_16x16x32_bf16 v[44:47], v[116:119], v[172:175], v[44:47]
	v_mfma_f32_16x16x32_bf16 v[40:43], v[140:143], v[172:175], v[40:43]
	v_mfma_f32_16x16x32_bf16 v[28:31], v[116:119], v[180:183], v[28:31]
	v_mfma_f32_16x16x32_bf16 v[24:27], v[140:143], v[180:183], v[24:27]
	v_mfma_f32_16x16x32_bf16 v[12:15], v[116:119], v[204:207], v[12:15]
	v_mfma_f32_16x16x32_bf16 v[8:11], v[140:143], v[204:207], v[8:11]
	v_mfma_f32_16x16x32_bf16 v[52:55], v[144:147], v[160:163], v[52:55]
	v_mfma_f32_16x16x32_bf16 v[48:51], v[152:155], v[160:163], v[48:51]
	v_mfma_f32_16x16x32_bf16 v[36:39], v[144:147], v[168:171], v[36:39]
	v_mfma_f32_16x16x32_bf16 v[32:35], v[152:155], v[168:171], v[32:35]
	v_mfma_f32_16x16x32_bf16 v[20:23], v[144:147], v[176:179], v[20:23]
	v_mfma_f32_16x16x32_bf16 v[16:19], v[152:155], v[176:179], v[16:19]
	v_mfma_f32_16x16x32_bf16 v[4:7], v[144:147], v[200:203], v[4:7]
	v_mfma_f32_16x16x32_bf16 v[0:3], v[152:155], v[200:203], v[0:3]
	v_mfma_f32_16x16x32_bf16 v[52:55], v[148:151], v[164:167], v[52:55]
	v_mfma_f32_16x16x32_bf16 v[48:51], v[156:159], v[164:167], v[48:51]
	v_mfma_f32_16x16x32_bf16 v[36:39], v[148:151], v[172:175], v[36:39]
	v_mfma_f32_16x16x32_bf16 v[32:35], v[156:159], v[172:175], v[32:35]
	v_mfma_f32_16x16x32_bf16 v[20:23], v[148:151], v[180:183], v[20:23]
	v_mfma_f32_16x16x32_bf16 v[16:19], v[156:159], v[180:183], v[16:19]
	v_mfma_f32_16x16x32_bf16 v[4:7], v[148:151], v[204:207], v[4:7]
	v_mfma_f32_16x16x32_bf16 v[0:3], v[156:159], v[204:207], v[0:3]
	s_barrier
	s_add_i32 s52, 0, 0x18000
	s_add_i32 s53, 0, 0x1c000
	v_add_u32_e32 v140, s52, v220
	v_add_u32_e32 v156, s53, v220
	ds_read_b128 v[104:107], v140
	ds_read_b128 v[116:119], v140 offset:1024
	ds_read_b128 v[128:131], v140 offset:2048
	ds_read_b128 v[140:143], v140 offset:3072
	ds_read_b128 v[144:147], v156
	ds_read_b128 v[148:151], v156 offset:1024
	ds_read_b128 v[152:155], v156 offset:2048
	ds_read_b128 v[156:159], v156 offset:3072
	s_add_u32 s20, s26, 0x158000
	s_addc_u32 s21, s27, 0
	s_mov_b32 m0, s36
	v_lshl_add_u64 v[216:217], s[20:21], 0, v[184:185]
	ds_read_b128 v[160:163], v224 offset:32768
	ds_read_b128 v[164:167], v224 offset:33792
	ds_read_b128 v[168:171], v224 offset:34816
	ds_read_b128 v[172:175], v224 offset:35840
	ds_read_b128 v[176:179], v224 offset:36864
	ds_read_b128 v[180:183], v224 offset:37888
	ds_read_b128 v[200:203], v224 offset:38912
	ds_read_b128 v[204:207], v224 offset:39936
	global_load_lds_dwordx4 v[216:217], off
	v_lshl_add_u64 v[216:217], s[20:21], 0, v[188:189]
	s_mov_b32 m0, s37
	s_nop 0
	global_load_lds_dwordx4 v[216:217], off
	s_waitcnt vmcnt(8)
	s_waitcnt lgkmcnt(0)
	s_barrier
; #define PG8_STAGE(bufoff, gbase, voff) do { _Pragma("unroll") for (int _i = 0; _i < 2; ++_i) \
;         __builtin_amdgcn_global_load_lds((const unsigned*)((const char*)(gbase) + (voff)[_i]), (PG8_LAS unsigned*)(lds + (bufoff) + ldsw + _i * 8192), 16, 0, 0); } while (0)
; #define PG8_LDA(dst, b, h) do { _Pragma("unroll") for (int m = 0; m < 4; ++m) _Pragma("unroll") for (int k = 0; k < 2; ++k) dst[m][k] = *(const PG8_LAS bf16x8*)(lds + PG8_SA(b, h) + aoff + m * 2048 + k * 1024); } while (0)
; #define PG8_MMA(ai, bj, At, Bt) do { __builtin_amdgcn_s_setprio(1); _Pragma("unroll") for (int m = 0; m < 4; ++m) _Pragma("unroll") for (int n = 0; n < 2; ++n) _Pragma("unroll") for (int k = 0; k < 2; ++k) \
;         acc[ai][bj][m][n] = __builtin_amdgcn_mfma_f32_16x16x32_bf16(Bt[n][k], At[m][k], acc[ai][bj][m][n], 0, 0, 0); __builtin_amdgcn_s_setprio(0); } while (0)
; #define PG8_WAIT_V(n) asm volatile("s_waitcnt vmcnt(" #n ")" ::: "memory")
; #define PG8_WAIT_L(n) asm volatile("s_waitcnt lgkmcnt(" #n ")" ::: "memory")
; #define PG8_BAR __builtin_amdgcn_s_barrier()
; #define PG8_SCHED __builtin_amdgcn_sched_barrier(0)
; template <class Epi, class Sched, bool ALIGN_EPI = false, bool SP2 = false>
; __device__ __forceinline__ void gemm_phase(PG8_LAS unsigned char* lds, const Gemm g, const Sched& S, const Epi& E, const int tid_in) {
;     ...
;             PG8_WAIT_V(8); PG8_WAIT_L(0); PG8_BAR; PG8_MMA(0, 0, At, B0); PG8_MMA(0, 1, At, B1); PG8_BAR; PG8_SCHED;
;             PG8_LDA(At, 1, 1); PG8_STAGE(PG8_SB(1, 0), b3, voffB); PG8_STAGE(PG8_SB(1, 1), b3 + hstep, voffB); PG8_STAGE(PG8_SA(1, 0), a3, voffA);
;             PG8_WAIT_V(8); PG8_WAIT_L(0); PG8_BAR; PG8_MMA(1, 0, At, B0); PG8_MMA(1, 1, At, B1); PG8_BAR; PG8_SCHED;
;     ...
;         }
	v_mfma_f32_16x16x32_bf16 v[136:139], v[104:107], v[160:163], v[136:139]
	v_mfma_f32_16x16x32_bf16 v[132:135], v[128:131], v[160:163], v[132:135]
	v_mfma_f32_16x16x32_bf16 v[112:115], v[104:107], v[168:171], v[112:115]
	v_mfma_f32_16x16x32_bf16 v[108:111], v[128:131], v[168:171], v[108:111]
	v_mfma_f32_16x16x32_bf16 v[92:95], v[104:107], v[176:179], v[92:95]
	v_mfma_f32_16x16x32_bf16 v[88:91], v[128:131], v[176:179], v[88:91]
	v_mfma_f32_16x16x32_bf16 v[76:79], v[104:107], v[200:203], v[76:79]
	v_mfma_f32_16x16x32_bf16 v[72:75], v[128:131], v[200:203], v[72:75]
	v_mfma_f32_16x16x32_bf16 v[136:139], v[116:119], v[164:167], v[136:139]
	v_mfma_f32_16x16x32_bf16 v[132:135], v[140:143], v[164:167], v[132:135]
	v_mfma_f32_16x16x32_bf16 v[112:115], v[116:119], v[172:175], v[112:115]
	v_mfma_f32_16x16x32_bf16 v[108:111], v[140:143], v[172:175], v[108:111]
	v_mfma_f32_16x16x32_bf16 v[92:95], v[116:119], v[180:183], v[92:95]
	v_mfma_f32_16x16x32_bf16 v[88:91], v[140:143], v[180:183], v[88:91]
	v_mfma_f32_16x16x32_bf16 v[76:79], v[116:119], v[204:207], v[76:79]
	v_mfma_f32_16x16x32_bf16 v[72:75], v[140:143], v[204:207], v[72:75]
	v_mfma_f32_16x16x32_bf16 v[124:127], v[144:147], v[160:163], v[124:127]
	v_mfma_f32_16x16x32_bf16 v[120:123], v[152:155], v[160:163], v[120:123]
	v_mfma_f32_16x16x32_bf16 v[100:103], v[144:147], v[168:171], v[100:103]
	v_mfma_f32_16x16x32_bf16 v[96:99], v[152:155], v[168:171], v[96:99]
	v_mfma_f32_16x16x32_bf16 v[84:87], v[144:147], v[176:179], v[84:87]
	v_mfma_f32_16x16x32_bf16 v[80:83], v[152:155], v[176:179], v[80:83]
	v_mfma_f32_16x16x32_bf16 v[68:71], v[144:147], v[200:203], v[68:71]
	v_mfma_f32_16x16x32_bf16 v[64:67], v[152:155], v[200:203], v[64:67]
	v_mfma_f32_16x16x32_bf16 v[124:127], v[148:151], v[164:167], v[124:127]
	v_mfma_f32_16x16x32_bf16 v[120:123], v[156:159], v[164:167], v[120:123]
	v_mfma_f32_16x16x32_bf16 v[100:103], v[148:151], v[172:175], v[100:103]
	v_mfma_f32_16x16x32_bf16 v[96:99], v[156:159], v[172:175], v[96:99]
	v_mfma_f32_16x16x32_bf16 v[84:87], v[148:151], v[180:183], v[84:87]
	v_mfma_f32_16x16x32_bf16 v[80:83], v[156:159], v[180:183], v[80:83]
	v_mfma_f32_16x16x32_bf16 v[68:71], v[148:151], v[204:207], v[68:71]
	v_mfma_f32_16x16x32_bf16 v[64:67], v[156:159], v[204:207], v[64:67]
	s_barrier
	s_add_i32 s20, s52, s33
	v_lshl_add_u64 v[208:209], v[208:209], 0, s[14:15]
	s_mov_b32 m0, s20
	ds_read_b128 v[160:163], v224 offset:49152
	ds_read_b128 v[164:167], v224 offset:50176
	ds_read_b128 v[168:171], v224 offset:51200
	ds_read_b128 v[172:175], v224 offset:52224
	ds_read_b128 v[176:179], v224 offset:53248
	ds_read_b128 v[180:183], v224 offset:54272
	ds_read_b128 v[200:203], v224 offset:55296
	ds_read_b128 v[204:207], v224 offset:56320
	global_load_lds_dwordx4 v[208:209], off
	s_add_i32 m0, s20, 0x2000
	s_add_u32 s20, s24, 0x158080
	v_lshl_add_u64 v[208:209], v[210:211], 0, s[14:15]
	s_addc_u32 s21, s25, 0
	s_add_i32 s24, s53, s33
	global_load_lds_dwordx4 v[208:209], off
	v_lshl_add_u64 v[208:209], s[20:21], 0, v[186:187]
	s_mov_b32 m0, s24
	s_nop 0
	global_load_lds_dwordx4 v[208:209], off
	v_lshl_add_u64 v[208:209], s[20:21], 0, v[190:191]
	s_add_i32 m0, s24, 0x2000
	s_nop 0
	global_load_lds_dwordx4 v[208:209], off
	v_lshl_add_u64 v[208:209], v[212:213], 0, s[14:15]
	s_mov_b32 m0, s39
	s_nop 0
	global_load_lds_dwordx4 v[208:209], off
	v_lshl_add_u64 v[208:209], v[214:215], 0, s[14:15]
	s_mov_b32 m0, s40
	s_nop 0
	global_load_lds_dwordx4 v[208:209], off
	s_waitcnt vmcnt(8)
	s_waitcnt lgkmcnt(0)
	s_barrier
	v_mfma_f32_16x16x32_bf16 v[60:63], v[104:107], v[160:163], v[60:63]
	v_mfma_f32_16x16x32_bf16 v[56:59], v[128:131], v[160:163], v[56:59]
	v_mfma_f32_16x16x32_bf16 v[44:47], v[104:107], v[168:171], v[44:47]
	v_mfma_f32_16x16x32_bf16 v[40:43], v[128:131], v[168:171], v[40:43]
	v_mfma_f32_16x16x32_bf16 v[28:31], v[104:107], v[176:179], v[28:31]
	v_mfma_f32_16x16x32_bf16 v[24:27], v[128:131], v[176:179], v[24:27]
	v_mfma_f32_16x16x32_bf16 v[12:15], v[104:107], v[200:203], v[12:15]
	v_mfma_f32_16x16x32_bf16 v[8:11], v[128:131], v[200:203], v[8:11]
	v_mfma_f32_16x16x32_bf16 v[60:63], v[116:119], v[164:167], v[60:63]
	v_mfma_f32_16x16x32_bf16 v[56:59], v[140:143], v[164:167], v[56:59]
	v_mfma_f32_16x16x32_bf16 v[44:47], v[116:119], v[172:175], v[44:47]
	v_mfma_f32_16x16x32_bf16 v[40:43], v[140:143], v[172:175], v[40:43]
	v_mfma_f32_16x16x32_bf16 v[28:31], v[116:119], v[180:183], v[28:31]
	v_mfma_f32_16x16x32_bf16 v[24:27], v[140:143], v[180:183], v[24:27]
	v_mfma_f32_16x16x32_bf16 v[12:15], v[116:119], v[204:207], v[12:15]
	v_mfma_f32_16x16x32_bf16 v[8:11], v[140:143], v[204:207], v[8:11]
	v_mfma_f32_16x16x32_bf16 v[52:55], v[144:147], v[160:163], v[52:55]
	v_mfma_f32_16x16x32_bf16 v[48:51], v[152:155], v[160:163], v[48:51]
	v_mfma_f32_16x16x32_bf16 v[36:39], v[144:147], v[168:171], v[36:39]
	v_mfma_f32_16x16x32_bf16 v[32:35], v[152:155], v[168:171], v[32:35]
	v_mfma_f32_16x16x32_bf16 v[20:23], v[144:147], v[176:179], v[20:23]
	v_mfma_f32_16x16x32_bf16 v[16:19], v[152:155], v[176:179], v[16:19]
	v_mfma_f32_16x16x32_bf16 v[4:7], v[144:147], v[200:203], v[4:7]
	v_mfma_f32_16x16x32_bf16 v[0:3], v[152:155], v[200:203], v[0:3]
	v_mfma_f32_16x16x32_bf16 v[52:55], v[148:151], v[164:167], v[52:55]
	v_mfma_f32_16x16x32_bf16 v[48:51], v[156:159], v[164:167], v[48:51]
	v_mfma_f32_16x16x32_bf16 v[36:39], v[148:151], v[172:175], v[36:39]
	v_mfma_f32_16x16x32_bf16 v[32:35], v[156:159], v[172:175], v[32:35]
	v_mfma_f32_16x16x32_bf16 v[20:23], v[148:151], v[180:183], v[20:23]
	v_mfma_f32_16x16x32_bf16 v[16:19], v[156:159], v[180:183], v[16:19]
	v_mfma_f32_16x16x32_bf16 v[4:7], v[148:151], v[204:207], v[4:7]
	v_mfma_f32_16x16x32_bf16 v[0:3], v[156:159], v[204:207], v[0:3]
	s_barrier
	s_add_i32 s51, s51, 2
	s_add_u32 s49, s49, 0x100
	s_addc_u32 s50, s50, 0
	s_cmpk_gt_u32 s51, 0x53
	s_mov_b64 s[20:21], s[22:23]
	s_cbranch_scc0 .LBB0_965
	s_setprio 0
	s_and_b64 vcc, exec, s[16:17]
	s_cbranch_vccz .LBB0_968
	s_barrier

; #define PG8_STAGE(bufoff, gbase, voff) do { _Pragma("unroll") for (int _i = 0; _i < 2; ++_i) \
;         __builtin_amdgcn_global_load_lds((const unsigned*)((const char*)(gbase) + (voff)[_i]), (PG8_LAS unsigned*)(lds + (bufoff) + ldsw + _i * 8192), 16, 0, 0); } while (0)
; #define PG8_LDA(dst, b, h) do { _Pragma("unroll") for (int m = 0; m < 4; ++m) _Pragma("unroll") for (int k = 0; k < 2; ++k) dst[m][k] = *(const PG8_LAS bf16x8*)(lds + PG8_SA(b, h) + aoff + m * 2048 + k * 1024); } while (0)
; #define PG8_LDB(dst, b, h) do { _Pragma("unroll") for (int n = 0; n < 2; ++n) _Pragma("unroll") for (int k = 0; k < 2; ++k) dst[n][k] = *(const PG8_LAS bf16x8*)(lds + PG8_SB(b, h) + boff + n * 2048 + k * 1024); } while (0)
; #define PG8_MMA(ai, bj, At, Bt) do { __builtin_amdgcn_s_setprio(1); _Pragma("unroll") for (int m = 0; m < 4; ++m) _Pragma("unroll") for (int n = 0; n < 2; ++n) _Pragma("unroll") for (int k = 0; k < 2; ++k) \
;         acc[ai][bj][m][n] = __builtin_amdgcn_mfma_f32_16x16x32_bf16(Bt[n][k], At[m][k], acc[ai][bj][m][n], 0, 0, 0); __builtin_amdgcn_s_setprio(0); } while (0)
; #define PG8_WAIT_V(n) asm volatile("s_waitcnt vmcnt(" #n ")" ::: "memory")
; #define PG8_WAIT_L(n) asm volatile("s_waitcnt lgkmcnt(" #n ")" ::: "memory")
; #define PG8_BAR __builtin_amdgcn_s_barrier()
; #define PG8_SCHED __builtin_amdgcn_sched_barrier(0)
; template <class Epi, class Sched, bool ALIGN_EPI = false, bool SP2 = false>
; __device__ __forceinline__ void gemm_phase(PG8_LAS unsigned char* lds, const Gemm g, const Sched& S, const Epi& E, const int tid_in) {
;     ...
;             PG8_LDB(B0, 0, 0); PG8_LDB(B1, 0, 1); PG8_SCHED; PG8_LDA(At, 0, 0); PG8_STAGE(PG8_SA(1, 1), a1 + hstepA, voffA);
;             PG8_WAIT_V(8); PG8_WAIT_L(0); PG8_BAR; PG8_MMA(0, 0, At, B0); PG8_MMA(0, 1, At, B1); PG8_BAR; PG8_SCHED;
;             PG8_LDA(At, 0, 1); PG8_STAGE(PG8_SB(0, 0), b2, voffB); PG8_STAGE(PG8_SB(0, 1), b2 + hstep, voffB); PG8_STAGE(PG8_SA(0, 0), a2, voffA);
.Lkprio_skip_11:
.LBB0_1008:
	ds_read_b128 v[144:147], v151
	ds_read_b128 v[156:159], v151 offset:1024
	ds_read_b128 v[160:163], v151 offset:2048
	ds_read_b128 v[164:167], v151 offset:3072
	ds_read_b128 v[168:171], v152
	ds_read_b128 v[172:175], v152 offset:1024
	ds_read_b128 v[176:179], v152 offset:2048
	ds_read_b128 v[180:183], v152 offset:3072
	s_add_u32 s28, s26, 0xfff80080
	s_addc_u32 s29, s27, -1
	s_cmp_eq_u32 s57, 28
	s_cselect_b32 s31, s5, s29
	s_cselect_b32 s30, s19, s28
	s_cselect_b32 s29, s17, s56
	s_cselect_b32 s28, s25, s55
	v_lshl_add_u64 v[216:217], s[26:27], 0, v[138:139]
	s_add_i32 m0, s38, 0xc000
	ds_read_b128 v[184:187], v153
	ds_read_b128 v[188:191], v153 offset:1024
	ds_read_b128 v[192:195], v153 offset:2048
	ds_read_b128 v[196:199], v153 offset:3072
	ds_read_b128 v[200:203], v153 offset:4096
	ds_read_b128 v[204:207], v153 offset:5120
	ds_read_b128 v[208:211], v153 offset:6144
	ds_read_b128 v[212:215], v153 offset:7168
	global_load_lds_dwordx4 v[216:217], off
	v_lshl_add_u64 v[216:217], s[26:27], 0, v[136:137]
	s_add_i32 m0, s38, 0xe000
	s_nop 0
	global_load_lds_dwordx4 v[216:217], off
	s_waitcnt vmcnt(8)
	s_waitcnt lgkmcnt(0)
	s_barrier
	v_mfma_f32_16x16x32_bf16 v[124:127], v[144:147], v[184:187], v[124:127]
	v_mfma_f32_16x16x32_bf16 v[120:123], v[160:163], v[184:187], v[120:123]
	v_mfma_f32_16x16x32_bf16 v[108:111], v[144:147], v[192:195], v[108:111]
	v_mfma_f32_16x16x32_bf16 v[104:107], v[160:163], v[192:195], v[104:107]
	v_mfma_f32_16x16x32_bf16 v[92:95], v[144:147], v[200:203], v[92:95]
	v_mfma_f32_16x16x32_bf16 v[88:91], v[160:163], v[200:203], v[88:91]
	v_mfma_f32_16x16x32_bf16 v[76:79], v[144:147], v[208:211], v[76:79]
	v_mfma_f32_16x16x32_bf16 v[72:75], v[160:163], v[208:211], v[72:75]
	v_mfma_f32_16x16x32_bf16 v[124:127], v[156:159], v[188:191], v[124:127]
	v_mfma_f32_16x16x32_bf16 v[120:123], v[164:167], v[188:191], v[120:123]
	v_mfma_f32_16x16x32_bf16 v[108:111], v[156:159], v[196:199], v[108:111]
	v_mfma_f32_16x16x32_bf16 v[104:107], v[164:167], v[196:199], v[104:107]
	v_mfma_f32_16x16x32_bf16 v[92:95], v[156:159], v[204:207], v[92:95]
	v_mfma_f32_16x16x32_bf16 v[88:91], v[164:167], v[204:207], v[88:91]
	v_mfma_f32_16x16x32_bf16 v[76:79], v[156:159], v[212:215], v[76:79]
	v_mfma_f32_16x16x32_bf16 v[72:75], v[164:167], v[212:215], v[72:75]
	v_mfma_f32_16x16x32_bf16 v[116:119], v[168:171], v[184:187], v[116:119]
	v_mfma_f32_16x16x32_bf16 v[112:115], v[176:179], v[184:187], v[112:115]
	v_mfma_f32_16x16x32_bf16 v[100:103], v[168:171], v[192:195], v[100:103]
	v_mfma_f32_16x16x32_bf16 v[96:99], v[176:179], v[192:195], v[96:99]
	v_mfma_f32_16x16x32_bf16 v[84:87], v[168:171], v[200:203], v[84:87]
	v_mfma_f32_16x16x32_bf16 v[80:83], v[176:179], v[200:203], v[80:83]
	v_mfma_f32_16x16x32_bf16 v[68:71], v[168:171], v[208:211], v[68:71]
	v_mfma_f32_16x16x32_bf16 v[64:67], v[176:179], v[208:211], v[64:67]
	v_mfma_f32_16x16x32_bf16 v[116:119], v[172:175], v[188:191], v[116:119]
	v_mfma_f32_16x16x32_bf16 v[112:115], v[180:183], v[188:191], v[112:115]
	v_mfma_f32_16x16x32_bf16 v[100:103], v[172:175], v[196:199], v[100:103]
	v_mfma_f32_16x16x32_bf16 v[96:99], v[180:183], v[196:199], v[96:99]
	v_mfma_f32_16x16x32_bf16 v[84:87], v[172:175], v[204:207], v[84:87]
	v_mfma_f32_16x16x32_bf16 v[80:83], v[180:183], v[204:207], v[80:83]
	v_mfma_f32_16x16x32_bf16 v[68:71], v[172:175], v[212:215], v[68:71]
	v_mfma_f32_16x16x32_bf16 v[64:67], v[180:183], v[212:215], v[64:67]
	s_barrier
	s_add_i32 s58, s48, s37
	v_lshl_add_u64 v[216:217], s[28:29], 0, v[130:131]
	s_mov_b32 m0, s58
	ds_read_b128 v[184:187], v153 offset:16384
	ds_read_b128 v[188:191], v153 offset:17408
	ds_read_b128 v[192:195], v153 offset:18432
	ds_read_b128 v[196:199], v153 offset:19456
	ds_read_b128 v[200:203], v153 offset:20480
	ds_read_b128 v[204:207], v153 offset:21504
	ds_read_b128 v[208:211], v153 offset:22528
	ds_read_b128 v[212:215], v153 offset:23552
	global_load_lds_dwordx4 v[216:217], off
	s_add_i32 m0, s58, 0x2000
	s_add_u32 s58, s28, 0x80000
	v_lshl_add_u64 v[218:219], s[28:29], 0, v[134:135]
	s_addc_u32 s59, s29, 0
	s_add_i32 s60, s49, s37
	global_load_lds_dwordx4 v[218:219], off
	v_lshl_add_u64 v[220:221], s[58:59], 0, v[130:131]
	s_mov_b32 m0, s60
	v_lshl_add_u64 v[222:223], s[30:31], 0, v[132:133]
	global_load_lds_dwordx4 v[220:221], off
	v_lshl_add_u64 v[220:221], s[58:59], 0, v[134:135]
	s_add_i32 m0, s60, 0x2000
	s_nop 0
	global_load_lds_dwordx4 v[220:221], off
	v_lshl_add_u64 v[220:221], s[30:31], 0, v[128:129]
	s_mov_b32 m0, s38
	s_nop 0
	global_load_lds_dwordx4 v[220:221], off
	s_mov_b32 m0, s39
	s_nop 0
	global_load_lds_dwordx4 v[222:223], off
	s_waitcnt vmcnt(8)
	s_waitcnt lgkmcnt(0)
	s_barrier
; #define PG8_STAGE(bufoff, gbase, voff) do { _Pragma("unroll") for (int _i = 0; _i < 2; ++_i) \
;         __builtin_amdgcn_global_load_lds((const unsigned*)((const char*)(gbase) + (voff)[_i]), (PG8_LAS unsigned*)(lds + (bufoff) + ldsw + _i * 8192), 16, 0, 0); } while (0)
; #define PG8_LDA(dst, b, h) do { _Pragma("unroll") for (int m = 0; m < 4; ++m) _Pragma("unroll") for (int k = 0; k < 2; ++k) dst[m][k] = *(const PG8_LAS bf16x8*)(lds + PG8_SA(b, h) + aoff + m * 2048 + k * 1024); } while (0)
; #define PG8_LDB(dst, b, h) do { _Pragma("unroll") for (int n = 0; n < 2; ++n) _Pragma("unroll") for (int k = 0; k < 2; ++k) dst[n][k] = *(const PG8_LAS bf16x8*)(lds + PG8_SB(b, h) + boff + n * 2048 + k * 1024); } while (0)
; #define PG8_MMA(ai, bj, At, Bt) do { __builtin_amdgcn_s_setprio(1); _Pragma("unroll") for (int m = 0; m < 4; ++m) _Pragma("unroll") for (int n = 0; n < 2; ++n) _Pragma("unroll") for (int k = 0; k < 2; ++k) \
;         acc[ai][bj][m][n] = __builtin_amdgcn_mfma_f32_16x16x32_bf16(Bt[n][k], At[m][k], acc[ai][bj][m][n], 0, 0, 0); __builtin_amdgcn_s_setprio(0); } while (0)
; #define PG8_WAIT_V(n) asm volatile("s_waitcnt vmcnt(" #n ")" ::: "memory")
; #define PG8_WAIT_L(n) asm volatile("s_waitcnt lgkmcnt(" #n ")" ::: "memory")
; #define PG8_BAR __builtin_amdgcn_s_barrier()
; #define PG8_SCHED __builtin_amdgcn_sched_barrier(0)
; template <class Epi, class Sched, bool ALIGN_EPI = false, bool SP2 = false>
; __device__ __forceinline__ void gemm_phase(PG8_LAS unsigned char* lds, const Gemm g, const Sched& S, const Epi& E, const int tid_in) {
;     ...
;             PG8_WAIT_V(8); PG8_WAIT_L(0); PG8_BAR; PG8_MMA(1, 0, At, B0); PG8_MMA(1, 1, At, B1); PG8_BAR; PG8_SCHED;
;             PG8_LDB(B0, 1, 0); PG8_LDB(B1, 1, 1); PG8_SCHED; PG8_LDA(At, 1, 0); PG8_STAGE(PG8_SA(0, 1), a2 + hstepA, voffA);
;             PG8_WAIT_V(8); PG8_WAIT_L(0); PG8_BAR; PG8_MMA(0, 0, At, B0); PG8_MMA(0, 1, At, B1); PG8_BAR; PG8_SCHED;
	v_mfma_f32_16x16x32_bf16 v[60:63], v[144:147], v[184:187], v[60:63]
	v_mfma_f32_16x16x32_bf16 v[56:59], v[160:163], v[184:187], v[56:59]
	v_mfma_f32_16x16x32_bf16 v[44:47], v[144:147], v[192:195], v[44:47]
	v_mfma_f32_16x16x32_bf16 v[40:43], v[160:163], v[192:195], v[40:43]
	v_mfma_f32_16x16x32_bf16 v[28:31], v[144:147], v[200:203], v[28:31]
	v_mfma_f32_16x16x32_bf16 v[24:27], v[160:163], v[200:203], v[24:27]
	v_mfma_f32_16x16x32_bf16 v[12:15], v[144:147], v[208:211], v[12:15]
	v_mfma_f32_16x16x32_bf16 v[8:11], v[160:163], v[208:211], v[8:11]
	v_mfma_f32_16x16x32_bf16 v[60:63], v[156:159], v[188:191], v[60:63]
	v_mfma_f32_16x16x32_bf16 v[56:59], v[164:167], v[188:191], v[56:59]
	v_mfma_f32_16x16x32_bf16 v[44:47], v[156:159], v[196:199], v[44:47]
	v_mfma_f32_16x16x32_bf16 v[40:43], v[164:167], v[196:199], v[40:43]
	v_mfma_f32_16x16x32_bf16 v[28:31], v[156:159], v[204:207], v[28:31]
	v_mfma_f32_16x16x32_bf16 v[24:27], v[164:167], v[204:207], v[24:27]
	v_mfma_f32_16x16x32_bf16 v[12:15], v[156:159], v[212:215], v[12:15]
	v_mfma_f32_16x16x32_bf16 v[8:11], v[164:167], v[212:215], v[8:11]
	v_mfma_f32_16x16x32_bf16 v[52:55], v[168:171], v[184:187], v[52:55]
	v_mfma_f32_16x16x32_bf16 v[48:51], v[176:179], v[184:187], v[48:51]
	v_mfma_f32_16x16x32_bf16 v[36:39], v[168:171], v[192:195], v[36:39]
	v_mfma_f32_16x16x32_bf16 v[32:35], v[176:179], v[192:195], v[32:35]
	v_mfma_f32_16x16x32_bf16 v[20:23], v[168:171], v[200:203], v[20:23]
	v_mfma_f32_16x16x32_bf16 v[16:19], v[176:179], v[200:203], v[16:19]
	v_mfma_f32_16x16x32_bf16 v[4:7], v[168:171], v[208:211], v[4:7]
	v_mfma_f32_16x16x32_bf16 v[0:3], v[176:179], v[208:211], v[0:3]
	v_mfma_f32_16x16x32_bf16 v[52:55], v[172:175], v[188:191], v[52:55]
	v_mfma_f32_16x16x32_bf16 v[48:51], v[180:183], v[188:191], v[48:51]
	v_mfma_f32_16x16x32_bf16 v[36:39], v[172:175], v[196:199], v[36:39]
	v_mfma_f32_16x16x32_bf16 v[32:35], v[180:183], v[196:199], v[32:35]
	v_mfma_f32_16x16x32_bf16 v[20:23], v[172:175], v[204:207], v[20:23]
	v_mfma_f32_16x16x32_bf16 v[16:19], v[180:183], v[204:207], v[16:19]
	v_mfma_f32_16x16x32_bf16 v[4:7], v[172:175], v[212:215], v[4:7]
	v_mfma_f32_16x16x32_bf16 v[0:3], v[180:183], v[212:215], v[0:3]
	s_barrier
	s_add_i32 s58, 0, 0x18000
	v_add_u32_e32 v155, s58, v149
	s_add_i32 s59, 0, 0x1c000
	ds_read_b128 v[144:147], v155
	ds_read_b128 v[156:159], v155 offset:1024
	ds_read_b128 v[160:163], v155 offset:2048
	ds_read_b128 v[164:167], v155 offset:3072
	v_add_u32_e32 v155, s59, v149
	ds_read_b128 v[168:171], v155
	ds_read_b128 v[172:175], v155 offset:1024
	ds_read_b128 v[176:179], v155 offset:2048
	ds_read_b128 v[180:183], v155 offset:3072
	s_add_u32 s30, s30, 0x80000
	s_addc_u32 s31, s31, 0
	s_mov_b32 m0, s40
	v_lshl_add_u64 v[224:225], s[30:31], 0, v[128:129]
	ds_read_b128 v[184:187], v153 offset:32768
	ds_read_b128 v[188:191], v153 offset:33792
	ds_read_b128 v[192:195], v153 offset:34816
	ds_read_b128 v[196:199], v153 offset:35840
	ds_read_b128 v[200:203], v153 offset:36864
	ds_read_b128 v[204:207], v153 offset:37888
	ds_read_b128 v[208:211], v153 offset:38912
	ds_read_b128 v[212:215], v153 offset:39936
	global_load_lds_dwordx4 v[224:225], off
	v_lshl_add_u64 v[224:225], s[30:31], 0, v[132:133]
	s_mov_b32 m0, s41
	s_nop 0
	global_load_lds_dwordx4 v[224:225], off
	s_waitcnt vmcnt(8)
	s_waitcnt lgkmcnt(0)
	s_barrier
	v_mfma_f32_16x16x32_bf16 v[124:127], v[144:147], v[184:187], v[124:127]
	v_mfma_f32_16x16x32_bf16 v[120:123], v[160:163], v[184:187], v[120:123]
	v_mfma_f32_16x16x32_bf16 v[108:111], v[144:147], v[192:195], v[108:111]
	v_mfma_f32_16x16x32_bf16 v[104:107], v[160:163], v[192:195], v[104:107]
	v_mfma_f32_16x16x32_bf16 v[92:95], v[144:147], v[200:203], v[92:95]
	v_mfma_f32_16x16x32_bf16 v[88:91], v[160:163], v[200:203], v[88:91]
	v_mfma_f32_16x16x32_bf16 v[76:79], v[144:147], v[208:211], v[76:79]
	v_mfma_f32_16x16x32_bf16 v[72:75], v[160:163], v[208:211], v[72:75]
	v_mfma_f32_16x16x32_bf16 v[124:127], v[156:159], v[188:191], v[124:127]
	v_mfma_f32_16x16x32_bf16 v[120:123], v[164:167], v[188:191], v[120:123]
	v_mfma_f32_16x16x32_bf16 v[108:111], v[156:159], v[196:199], v[108:111]
	v_mfma_f32_16x16x32_bf16 v[104:107], v[164:167], v[196:199], v[104:107]
	v_mfma_f32_16x16x32_bf16 v[92:95], v[156:159], v[204:207], v[92:95]
	v_mfma_f32_16x16x32_bf16 v[88:91], v[164:167], v[204:207], v[88:91]
	v_mfma_f32_16x16x32_bf16 v[76:79], v[156:159], v[212:215], v[76:79]
	v_mfma_f32_16x16x32_bf16 v[72:75], v[164:167], v[212:215], v[72:75]
	v_mfma_f32_16x16x32_bf16 v[116:119], v[168:171], v[184:187], v[116:119]
	v_mfma_f32_16x16x32_bf16 v[112:115], v[176:179], v[184:187], v[112:115]
	v_mfma_f32_16x16x32_bf16 v[100:103], v[168:171], v[192:195], v[100:103]
	v_mfma_f32_16x16x32_bf16 v[96:99], v[176:179], v[192:195], v[96:99]
	v_mfma_f32_16x16x32_bf16 v[84:87], v[168:171], v[200:203], v[84:87]
	v_mfma_f32_16x16x32_bf16 v[80:83], v[176:179], v[200:203], v[80:83]
	v_mfma_f32_16x16x32_bf16 v[68:71], v[168:171], v[208:211], v[68:71]
	v_mfma_f32_16x16x32_bf16 v[64:67], v[176:179], v[208:211], v[64:67]
	v_mfma_f32_16x16x32_bf16 v[116:119], v[172:175], v[188:191], v[116:119]
	v_mfma_f32_16x16x32_bf16 v[112:115], v[180:183], v[188:191], v[112:115]
	v_mfma_f32_16x16x32_bf16 v[100:103], v[172:175], v[196:199], v[100:103]
	v_mfma_f32_16x16x32_bf16 v[96:99], v[180:183], v[196:199], v[96:99]
	v_mfma_f32_16x16x32_bf16 v[84:87], v[172:175], v[204:207], v[84:87]
	v_mfma_f32_16x16x32_bf16 v[80:83], v[180:183], v[204:207], v[80:83]
	v_mfma_f32_16x16x32_bf16 v[68:71], v[172:175], v[212:215], v[68:71]
	v_mfma_f32_16x16x32_bf16 v[64:67], v[180:183], v[212:215], v[64:67]
	s_barrier
; #define PG8_STAGE(bufoff, gbase, voff) do { _Pragma("unroll") for (int _i = 0; _i < 2; ++_i) \
;         __builtin_amdgcn_global_load_lds((const unsigned*)((const char*)(gbase) + (voff)[_i]), (PG8_LAS unsigned*)(lds + (bufoff) + ldsw + _i * 8192), 16, 0, 0); } while (0)
; #define PG8_LDA(dst, b, h) do { _Pragma("unroll") for (int m = 0; m < 4; ++m) _Pragma("unroll") for (int k = 0; k < 2; ++k) dst[m][k] = *(const PG8_LAS bf16x8*)(lds + PG8_SA(b, h) + aoff + m * 2048 + k * 1024); } while (0)
; #define PG8_MMA(ai, bj, At, Bt) do { __builtin_amdgcn_s_setprio(1); _Pragma("unroll") for (int m = 0; m < 4; ++m) _Pragma("unroll") for (int n = 0; n < 2; ++n) _Pragma("unroll") for (int k = 0; k < 2; ++k) \
;         acc[ai][bj][m][n] = __builtin_amdgcn_mfma_f32_16x16x32_bf16(Bt[n][k], At[m][k], acc[ai][bj][m][n], 0, 0, 0); __builtin_amdgcn_s_setprio(0); } while (0)
; #define PG8_WAIT_V(n) asm volatile("s_waitcnt vmcnt(" #n ")" ::: "memory")
; #define PG8_WAIT_L(n) asm volatile("s_waitcnt lgkmcnt(" #n ")" ::: "memory")
; #define PG8_BAR __builtin_amdgcn_s_barrier()
; #define PG8_SCHED __builtin_amdgcn_sched_barrier(0)
; template <class Epi, class Sched, bool ALIGN_EPI = false, bool SP2 = false>
; __device__ __forceinline__ void gemm_phase(PG8_LAS unsigned char* lds, const Gemm g, const Sched& S, const Epi& E, const int tid_in) {
;     ...
;         for (int t = 0; t < nt; t += 2) {
;     ...
;             PG8_LDA(At, 1, 1); PG8_STAGE(PG8_SB(1, 0), b3, voffB); PG8_STAGE(PG8_SB(1, 1), b3 + hstep, voffB); PG8_STAGE(PG8_SA(1, 0), a3, voffA);
;             PG8_WAIT_V(8); PG8_WAIT_L(0); PG8_BAR; PG8_MMA(1, 0, At, B0); PG8_MMA(1, 1, At, B1); PG8_BAR; PG8_SCHED;
	s_add_i32 s30, s58, s37
	v_lshl_add_u64 v[216:217], v[216:217], 0, s[12:13]
	s_mov_b32 m0, s30
	ds_read_b128 v[184:187], v153 offset:49152
	ds_read_b128 v[188:191], v153 offset:50176
	ds_read_b128 v[192:195], v153 offset:51200
	ds_read_b128 v[196:199], v153 offset:52224
	ds_read_b128 v[200:203], v153 offset:53248
	ds_read_b128 v[204:207], v153 offset:54272
	ds_read_b128 v[208:211], v153 offset:55296
	ds_read_b128 v[212:215], v153 offset:56320
	global_load_lds_dwordx4 v[216:217], off
	s_add_i32 m0, s30, 0x2000
	s_add_u32 s28, s28, 0x80080
	v_lshl_add_u64 v[216:217], v[218:219], 0, s[12:13]
	s_addc_u32 s29, s29, 0
	s_add_i32 s30, s59, s37
	global_load_lds_dwordx4 v[216:217], off
	v_lshl_add_u64 v[216:217], s[28:29], 0, v[130:131]
	s_mov_b32 m0, s30
	s_nop 0
	global_load_lds_dwordx4 v[216:217], off
	v_lshl_add_u64 v[216:217], s[28:29], 0, v[134:135]
	s_add_i32 m0, s30, 0x2000
	s_nop 0
	global_load_lds_dwordx4 v[216:217], off
	v_lshl_add_u64 v[216:217], v[220:221], 0, s[12:13]
	s_mov_b32 m0, s43
	s_nop 0
	global_load_lds_dwordx4 v[216:217], off
	v_lshl_add_u64 v[216:217], v[222:223], 0, s[12:13]
	s_mov_b32 m0, s44
	s_nop 0
	global_load_lds_dwordx4 v[216:217], off
	s_waitcnt vmcnt(8)
	s_waitcnt lgkmcnt(0)
	s_barrier
	v_mfma_f32_16x16x32_bf16 v[60:63], v[144:147], v[184:187], v[60:63]
	v_mfma_f32_16x16x32_bf16 v[56:59], v[160:163], v[184:187], v[56:59]
	v_mfma_f32_16x16x32_bf16 v[44:47], v[144:147], v[192:195], v[44:47]
	v_mfma_f32_16x16x32_bf16 v[40:43], v[160:163], v[192:195], v[40:43]
	v_mfma_f32_16x16x32_bf16 v[28:31], v[144:147], v[200:203], v[28:31]
	v_mfma_f32_16x16x32_bf16 v[24:27], v[160:163], v[200:203], v[24:27]
	v_mfma_f32_16x16x32_bf16 v[12:15], v[144:147], v[208:211], v[12:15]
	v_mfma_f32_16x16x32_bf16 v[8:11], v[160:163], v[208:211], v[8:11]
	v_mfma_f32_16x16x32_bf16 v[60:63], v[156:159], v[188:191], v[60:63]
	v_mfma_f32_16x16x32_bf16 v[56:59], v[164:167], v[188:191], v[56:59]
	v_mfma_f32_16x16x32_bf16 v[44:47], v[156:159], v[196:199], v[44:47]
	v_mfma_f32_16x16x32_bf16 v[40:43], v[164:167], v[196:199], v[40:43]
	v_mfma_f32_16x16x32_bf16 v[28:31], v[156:159], v[204:207], v[28:31]
	v_mfma_f32_16x16x32_bf16 v[24:27], v[164:167], v[204:207], v[24:27]
	v_mfma_f32_16x16x32_bf16 v[12:15], v[156:159], v[212:215], v[12:15]
	v_mfma_f32_16x16x32_bf16 v[8:11], v[164:167], v[212:215], v[8:11]
	v_mfma_f32_16x16x32_bf16 v[52:55], v[168:171], v[184:187], v[52:55]
	v_mfma_f32_16x16x32_bf16 v[48:51], v[176:179], v[184:187], v[48:51]
	v_mfma_f32_16x16x32_bf16 v[36:39], v[168:171], v[192:195], v[36:39]
	v_mfma_f32_16x16x32_bf16 v[32:35], v[176:179], v[192:195], v[32:35]
	v_mfma_f32_16x16x32_bf16 v[20:23], v[168:171], v[200:203], v[20:23]
	v_mfma_f32_16x16x32_bf16 v[16:19], v[176:179], v[200:203], v[16:19]
	v_mfma_f32_16x16x32_bf16 v[4:7], v[168:171], v[208:211], v[4:7]
	v_mfma_f32_16x16x32_bf16 v[0:3], v[176:179], v[208:211], v[0:3]
	v_mfma_f32_16x16x32_bf16 v[52:55], v[172:175], v[188:191], v[52:55]
	v_mfma_f32_16x16x32_bf16 v[48:51], v[180:183], v[188:191], v[48:51]
	v_mfma_f32_16x16x32_bf16 v[36:39], v[172:175], v[196:199], v[36:39]
	v_mfma_f32_16x16x32_bf16 v[32:35], v[180:183], v[196:199], v[32:35]
	v_mfma_f32_16x16x32_bf16 v[20:23], v[172:175], v[204:207], v[20:23]
	v_mfma_f32_16x16x32_bf16 v[16:19], v[180:183], v[204:207], v[16:19]
	v_mfma_f32_16x16x32_bf16 v[4:7], v[172:175], v[212:215], v[4:7]
	v_mfma_f32_16x16x32_bf16 v[0:3], v[180:183], v[212:215], v[0:3]
	s_barrier
	s_add_i32 s57, s57, 2
	s_add_u32 s55, s55, 0x100
	s_addc_u32 s56, s56, 0
	s_add_u32 s26, s26, 0x100
	s_addc_u32 s27, s27, 0
	s_cmp_gt_u32 s57, 29
	s_cbranch_scc0 .LBB0_1008
	s_setprio 0
	s_and_b64 vcc, exec, s[14:15]
	s_cbranch_vccz .LBB0_1011
	s_barrier

; #define PG8_STAGE(bufoff, gbase, voff) do { _Pragma("unroll") for (int _i = 0; _i < 2; ++_i) \
;         __builtin_amdgcn_global_load_lds((const unsigned*)((const char*)(gbase) + (voff)[_i]), (PG8_LAS unsigned*)(lds + (bufoff) + ldsw + _i * 8192), 16, 0, 0); } while (0)
; #define PG8_LDA(dst, b, h) do { _Pragma("unroll") for (int m = 0; m < 4; ++m) _Pragma("unroll") for (int k = 0; k < 2; ++k) dst[m][k] = *(const PG8_LAS bf16x8*)(lds + PG8_SA(b, h) + aoff + m * 2048 + k * 1024); } while (0)
; #define PG8_LDB(dst, b, h) do { _Pragma("unroll") for (int n = 0; n < 2; ++n) _Pragma("unroll") for (int k = 0; k < 2; ++k) dst[n][k] = *(const PG8_LAS bf16x8*)(lds + PG8_SB(b, h) + boff + n * 2048 + k * 1024); } while (0)
; #define PG8_WAIT_V(n) asm volatile("s_waitcnt vmcnt(" #n ")" ::: "memory")
; #define PG8_WAIT_L(n) asm volatile("s_waitcnt lgkmcnt(" #n ")" ::: "memory")
; #define PG8_BAR __builtin_amdgcn_s_barrier()
; #define PG8_SCHED __builtin_amdgcn_sched_barrier(0)
; template <class Epi, class Sched, bool ALIGN_EPI = false, bool SP2 = false>
; __device__ __forceinline__ void gemm_phase(PG8_LAS unsigned char* lds, const Gemm g, const Sched& S, const Epi& E, const int tid_in) {
;     ...
;         const bool has_next = S.next(ui + 1, nxt);
;         const char* nA = has_next ? (const char*)g.A + (size_t)nxt.pm * tstepA : cA; const char* nB = has_next ? (const char*)g.Bt + (size_t)nxt.pn * tstep : cB;
;         for (int t = 0; t < nt; t += 2) {
;             const bool last = (t == nt - 2);
;             const char* a1 = cA + (size_t)(t + 1) * kstep;
;             const char* a2 = last ? nA : cA + (size_t)(t + 2) * kstep; const char* b2 = last ? nB : cB + (size_t)(t + 2) * kstep;
;             const char* a3 = a2 + kstep; const char* b3 = b2 + kstep;
;             if (last && has_next) S.a_ready(nxt);
;             if constexpr (SP2) {
;             PG8_LDB(B0, 0, 0); PG8_LDB(B1, 0, 1); PG8_SCHED; PG8_LDA(At, 0, 0); PG8_STAGE(PG8_SA(1, 1), a1 + hstepA, voffA);
;             PG8_WAIT_V(8); PG8_WAIT_L(0); PG8_BAR; PG8_MMA(0, 0, At, B0); PG8_MMA(0, 1, At, B1); PG8_BAR; PG8_SCHED;
;             PG8_LDA(At, 0, 1); PG8_STAGE(PG8_SB(0, 0), b2, voffB); PG8_STAGE(PG8_SB(0, 1), b2 + hstep, voffB); PG8_STAGE(PG8_SA(0, 0), a2, voffA);
;             PG8_WAIT_V(8); PG8_WAIT_L(0); PG8_BAR; PG8_MMA(1, 0, At, B0); PG8_MMA(1, 1, At, B1); PG8_BAR; PG8_SCHED;
.Lkprio_skip_12:
.LBB0_1067:
	ds_read_b128 v[144:147], v153
	ds_read_b128 v[156:159], v153 offset:1024
	ds_read_b128 v[160:163], v153 offset:2048
	ds_read_b128 v[164:167], v153 offset:3072
	ds_read_b128 v[168:171], v154
	ds_read_b128 v[172:175], v154 offset:1024
	ds_read_b128 v[176:179], v154 offset:2048
	ds_read_b128 v[180:183], v154 offset:3072
	s_add_u32 s2, s18, 0x100
	s_addc_u32 s3, s19, 0
	s_cmp_eq_u32 s53, 4
	s_cselect_b32 s23, s15, s3
	s_cselect_b32 s22, s14, s2
	s_cselect_b32 s21, s13, s52
	s_cselect_b32 s20, s50, s51
	v_lshl_add_u64 v[148:149], s[18:19], 0, v[138:139]
	s_add_i32 m0, s33, 0xc000
	ds_read_b128 v[184:187], v155
	ds_read_b128 v[188:191], v155 offset:1024
	ds_read_b128 v[192:195], v155 offset:2048
	ds_read_b128 v[196:199], v155 offset:3072
	ds_read_b128 v[200:203], v155 offset:4096
	ds_read_b128 v[204:207], v155 offset:5120
	ds_read_b128 v[208:211], v155 offset:6144
	ds_read_b128 v[212:215], v155 offset:7168
	global_load_lds_dwordx4 v[148:149], off
	v_lshl_add_u64 v[148:149], s[18:19], 0, v[136:137]
	s_add_i32 m0, s33, 0xe000
	s_nop 0
	global_load_lds_dwordx4 v[148:149], off
	s_waitcnt vmcnt(8)
	s_waitcnt lgkmcnt(0)
	s_barrier
	v_mfma_f32_16x16x32_bf16 v[124:127], v[144:147], v[184:187], v[124:127]
	v_mfma_f32_16x16x32_bf16 v[120:123], v[160:163], v[184:187], v[120:123]
	v_mfma_f32_16x16x32_bf16 v[116:119], v[144:147], v[192:195], v[116:119]
	v_mfma_f32_16x16x32_bf16 v[112:115], v[160:163], v[192:195], v[112:115]
	v_mfma_f32_16x16x32_bf16 v[100:103], v[144:147], v[200:203], v[100:103]
	v_mfma_f32_16x16x32_bf16 v[96:99], v[160:163], v[200:203], v[96:99]
	v_mfma_f32_16x16x32_bf16 v[84:87], v[144:147], v[208:211], v[84:87]
	v_mfma_f32_16x16x32_bf16 v[80:83], v[160:163], v[208:211], v[80:83]
	v_mfma_f32_16x16x32_bf16 v[124:127], v[156:159], v[188:191], v[124:127]
	v_mfma_f32_16x16x32_bf16 v[120:123], v[164:167], v[188:191], v[120:123]
	v_mfma_f32_16x16x32_bf16 v[116:119], v[156:159], v[196:199], v[116:119]
	v_mfma_f32_16x16x32_bf16 v[112:115], v[164:167], v[196:199], v[112:115]
	v_mfma_f32_16x16x32_bf16 v[100:103], v[156:159], v[204:207], v[100:103]
	v_mfma_f32_16x16x32_bf16 v[96:99], v[164:167], v[204:207], v[96:99]
	v_mfma_f32_16x16x32_bf16 v[84:87], v[156:159], v[212:215], v[84:87]
	v_mfma_f32_16x16x32_bf16 v[80:83], v[164:167], v[212:215], v[80:83]
	v_mfma_f32_16x16x32_bf16 v[108:111], v[168:171], v[184:187], v[108:111]
	v_mfma_f32_16x16x32_bf16 v[104:107], v[176:179], v[184:187], v[104:107]
	v_mfma_f32_16x16x32_bf16 v[92:95], v[168:171], v[192:195], v[92:95]
	v_mfma_f32_16x16x32_bf16 v[88:91], v[176:179], v[192:195], v[88:91]
	v_mfma_f32_16x16x32_bf16 v[76:79], v[168:171], v[200:203], v[76:79]
	v_mfma_f32_16x16x32_bf16 v[72:75], v[176:179], v[200:203], v[72:75]
	v_mfma_f32_16x16x32_bf16 v[68:71], v[168:171], v[208:211], v[68:71]
	v_mfma_f32_16x16x32_bf16 v[64:67], v[176:179], v[208:211], v[64:67]
	v_mfma_f32_16x16x32_bf16 v[108:111], v[172:175], v[188:191], v[108:111]
	v_mfma_f32_16x16x32_bf16 v[104:107], v[180:183], v[188:191], v[104:107]
	v_mfma_f32_16x16x32_bf16 v[92:95], v[172:175], v[196:199], v[92:95]
	v_mfma_f32_16x16x32_bf16 v[88:91], v[180:183], v[196:199], v[88:91]
	v_mfma_f32_16x16x32_bf16 v[76:79], v[172:175], v[204:207], v[76:79]
	v_mfma_f32_16x16x32_bf16 v[72:75], v[180:183], v[204:207], v[72:75]
	v_mfma_f32_16x16x32_bf16 v[68:71], v[172:175], v[212:215], v[68:71]
	v_mfma_f32_16x16x32_bf16 v[64:67], v[180:183], v[212:215], v[64:67]
	s_barrier
	s_add_i32 s18, s41, s28
	v_lshl_add_u64 v[148:149], s[20:21], 0, v[132:133]
	s_mov_b32 m0, s18
	ds_read_b128 v[184:187], v155 offset:16384
	ds_read_b128 v[188:191], v155 offset:17408
	ds_read_b128 v[192:195], v155 offset:18432
	ds_read_b128 v[196:199], v155 offset:19456
	ds_read_b128 v[200:203], v155 offset:20480
	ds_read_b128 v[204:207], v155 offset:21504
	ds_read_b128 v[208:211], v155 offset:22528
	ds_read_b128 v[212:215], v155 offset:23552
	global_load_lds_dwordx4 v[148:149], off
	s_add_i32 m0, s18, 0x2000
	s_add_u32 s18, s20, 0x20000
	v_lshl_add_u64 v[216:217], s[20:21], 0, v[128:129]
	s_addc_u32 s19, s21, 0
	s_add_i32 s54, s42, s28
	global_load_lds_dwordx4 v[216:217], off
	v_lshl_add_u64 v[218:219], s[18:19], 0, v[132:133]
	s_mov_b32 m0, s54
	v_lshl_add_u64 v[220:221], s[22:23], 0, v[130:131]
	global_load_lds_dwordx4 v[218:219], off
	v_lshl_add_u64 v[218:219], s[18:19], 0, v[128:129]
	s_add_i32 m0, s54, 0x2000
	s_nop 0
	global_load_lds_dwordx4 v[218:219], off
	v_lshl_add_u64 v[218:219], s[22:23], 0, v[134:135]
	s_mov_b32 m0, s33
	s_nop 0
	global_load_lds_dwordx4 v[218:219], off
	s_mov_b32 m0, s34
	s_nop 0
	global_load_lds_dwordx4 v[220:221], off
	s_waitcnt vmcnt(8)
	s_waitcnt lgkmcnt(0)
	s_barrier
; #define PG8_STAGE(bufoff, gbase, voff) do { _Pragma("unroll") for (int _i = 0; _i < 2; ++_i) \
;         __builtin_amdgcn_global_load_lds((const unsigned*)((const char*)(gbase) + (voff)[_i]), (PG8_LAS unsigned*)(lds + (bufoff) + ldsw + _i * 8192), 16, 0, 0); } while (0)
; #define PG8_LDA(dst, b, h) do { _Pragma("unroll") for (int m = 0; m < 4; ++m) _Pragma("unroll") for (int k = 0; k < 2; ++k) dst[m][k] = *(const PG8_LAS bf16x8*)(lds + PG8_SA(b, h) + aoff + m * 2048 + k * 1024); } while (0)
; #define PG8_LDB(dst, b, h) do { _Pragma("unroll") for (int n = 0; n < 2; ++n) _Pragma("unroll") for (int k = 0; k < 2; ++k) dst[n][k] = *(const PG8_LAS bf16x8*)(lds + PG8_SB(b, h) + boff + n * 2048 + k * 1024); } while (0)
; #define PG8_MMA(ai, bj, At, Bt) do { __builtin_amdgcn_s_setprio(1); _Pragma("unroll") for (int m = 0; m < 4; ++m) _Pragma("unroll") for (int n = 0; n < 2; ++n) _Pragma("unroll") for (int k = 0; k < 2; ++k) \
;         acc[ai][bj][m][n] = __builtin_amdgcn_mfma_f32_16x16x32_bf16(Bt[n][k], At[m][k], acc[ai][bj][m][n], 0, 0, 0); __builtin_amdgcn_s_setprio(0); } while (0)
; #define PG8_WAIT_V(n) asm volatile("s_waitcnt vmcnt(" #n ")" ::: "memory")
; #define PG8_WAIT_L(n) asm volatile("s_waitcnt lgkmcnt(" #n ")" ::: "memory")
; #define PG8_BAR __builtin_amdgcn_s_barrier()
; #define PG8_SCHED __builtin_amdgcn_sched_barrier(0)
; template <class Epi, class Sched, bool ALIGN_EPI = false, bool SP2 = false>
; __device__ __forceinline__ void gemm_phase(PG8_LAS unsigned char* lds, const Gemm g, const Sched& S, const Epi& E, const int tid_in) {
;     ...
;             PG8_WAIT_V(8); PG8_WAIT_L(0); PG8_BAR; PG8_MMA(1, 0, At, B0); PG8_MMA(1, 1, At, B1); PG8_BAR; PG8_SCHED;
;             PG8_LDB(B0, 1, 0); PG8_LDB(B1, 1, 1); PG8_SCHED; PG8_LDA(At, 1, 0); PG8_STAGE(PG8_SA(0, 1), a2 + hstepA, voffA);
;             PG8_WAIT_V(8); PG8_WAIT_L(0); PG8_BAR; PG8_MMA(0, 0, At, B0); PG8_MMA(0, 1, At, B1); PG8_BAR; PG8_SCHED;
	v_mfma_f32_16x16x32_bf16 v[60:63], v[144:147], v[184:187], v[60:63]
	v_mfma_f32_16x16x32_bf16 v[56:59], v[160:163], v[184:187], v[56:59]
	v_mfma_f32_16x16x32_bf16 v[52:55], v[144:147], v[192:195], v[52:55]
	v_mfma_f32_16x16x32_bf16 v[48:51], v[160:163], v[192:195], v[48:51]
	v_mfma_f32_16x16x32_bf16 v[36:39], v[144:147], v[200:203], v[36:39]
	v_mfma_f32_16x16x32_bf16 v[32:35], v[160:163], v[200:203], v[32:35]
	v_mfma_f32_16x16x32_bf16 v[20:23], v[144:147], v[208:211], v[20:23]
	v_mfma_f32_16x16x32_bf16 v[16:19], v[160:163], v[208:211], v[16:19]
	v_mfma_f32_16x16x32_bf16 v[60:63], v[156:159], v[188:191], v[60:63]
	v_mfma_f32_16x16x32_bf16 v[56:59], v[164:167], v[188:191], v[56:59]
	v_mfma_f32_16x16x32_bf16 v[52:55], v[156:159], v[196:199], v[52:55]
	v_mfma_f32_16x16x32_bf16 v[48:51], v[164:167], v[196:199], v[48:51]
	v_mfma_f32_16x16x32_bf16 v[36:39], v[156:159], v[204:207], v[36:39]
	v_mfma_f32_16x16x32_bf16 v[32:35], v[164:167], v[204:207], v[32:35]
	v_mfma_f32_16x16x32_bf16 v[20:23], v[156:159], v[212:215], v[20:23]
	v_mfma_f32_16x16x32_bf16 v[16:19], v[164:167], v[212:215], v[16:19]
	v_mfma_f32_16x16x32_bf16 v[44:47], v[168:171], v[184:187], v[44:47]
	v_mfma_f32_16x16x32_bf16 v[40:43], v[176:179], v[184:187], v[40:43]
	v_mfma_f32_16x16x32_bf16 v[28:31], v[168:171], v[192:195], v[28:31]
	v_mfma_f32_16x16x32_bf16 v[24:27], v[176:179], v[192:195], v[24:27]
	v_mfma_f32_16x16x32_bf16 v[12:15], v[168:171], v[200:203], v[12:15]
	v_mfma_f32_16x16x32_bf16 v[8:11], v[176:179], v[200:203], v[8:11]
	v_mfma_f32_16x16x32_bf16 v[4:7], v[168:171], v[208:211], v[4:7]
	v_mfma_f32_16x16x32_bf16 v[0:3], v[176:179], v[208:211], v[0:3]
	v_mfma_f32_16x16x32_bf16 v[44:47], v[172:175], v[188:191], v[44:47]
	v_mfma_f32_16x16x32_bf16 v[40:43], v[180:183], v[188:191], v[40:43]
	v_mfma_f32_16x16x32_bf16 v[28:31], v[172:175], v[196:199], v[28:31]
	v_mfma_f32_16x16x32_bf16 v[24:27], v[180:183], v[196:199], v[24:27]
	v_mfma_f32_16x16x32_bf16 v[12:15], v[172:175], v[204:207], v[12:15]
	v_mfma_f32_16x16x32_bf16 v[8:11], v[180:183], v[204:207], v[8:11]
	v_mfma_f32_16x16x32_bf16 v[4:7], v[172:175], v[212:215], v[4:7]
	v_mfma_f32_16x16x32_bf16 v[0:3], v[180:183], v[212:215], v[0:3]
	s_barrier
	s_add_i32 s54, 0, 0x18000
	s_add_i32 s55, 0, 0x1c000
	v_add_u32_e32 v164, s54, v151
	v_add_u32_e32 v180, s55, v151
	ds_read_b128 v[144:147], v164
	ds_read_b128 v[156:159], v164 offset:1024
	ds_read_b128 v[160:163], v164 offset:2048
	ds_read_b128 v[164:167], v164 offset:3072
	ds_read_b128 v[168:171], v180
	ds_read_b128 v[172:175], v180 offset:1024
	ds_read_b128 v[176:179], v180 offset:2048
	ds_read_b128 v[180:183], v180 offset:3072
	s_add_u32 s18, s22, 0xc0000
	s_addc_u32 s19, s23, 0
	s_mov_b32 m0, s35
	v_lshl_add_u64 v[222:223], s[18:19], 0, v[134:135]
	ds_read_b128 v[184:187], v155 offset:32768
	ds_read_b128 v[188:191], v155 offset:33792
	ds_read_b128 v[192:195], v155 offset:34816
	ds_read_b128 v[196:199], v155 offset:35840
	ds_read_b128 v[200:203], v155 offset:36864
	ds_read_b128 v[204:207], v155 offset:37888
	ds_read_b128 v[208:211], v155 offset:38912
	ds_read_b128 v[212:215], v155 offset:39936
	global_load_lds_dwordx4 v[222:223], off
	v_lshl_add_u64 v[222:223], s[18:19], 0, v[130:131]
	s_mov_b32 m0, s36
	s_nop 0
	global_load_lds_dwordx4 v[222:223], off
	s_waitcnt vmcnt(8)
	s_waitcnt lgkmcnt(0)
	s_barrier
	v_mfma_f32_16x16x32_bf16 v[124:127], v[144:147], v[184:187], v[124:127]
	v_mfma_f32_16x16x32_bf16 v[120:123], v[160:163], v[184:187], v[120:123]
	v_mfma_f32_16x16x32_bf16 v[116:119], v[144:147], v[192:195], v[116:119]
	v_mfma_f32_16x16x32_bf16 v[112:115], v[160:163], v[192:195], v[112:115]
	v_mfma_f32_16x16x32_bf16 v[100:103], v[144:147], v[200:203], v[100:103]
	v_mfma_f32_16x16x32_bf16 v[96:99], v[160:163], v[200:203], v[96:99]
	v_mfma_f32_16x16x32_bf16 v[84:87], v[144:147], v[208:211], v[84:87]
	v_mfma_f32_16x16x32_bf16 v[80:83], v[160:163], v[208:211], v[80:83]
	v_mfma_f32_16x16x32_bf16 v[124:127], v[156:159], v[188:191], v[124:127]
	v_mfma_f32_16x16x32_bf16 v[120:123], v[164:167], v[188:191], v[120:123]
	v_mfma_f32_16x16x32_bf16 v[116:119], v[156:159], v[196:199], v[116:119]
	v_mfma_f32_16x16x32_bf16 v[112:115], v[164:167], v[196:199], v[112:115]
	v_mfma_f32_16x16x32_bf16 v[100:103], v[156:159], v[204:207], v[100:103]
	v_mfma_f32_16x16x32_bf16 v[96:99], v[164:167], v[204:207], v[96:99]
	v_mfma_f32_16x16x32_bf16 v[84:87], v[156:159], v[212:215], v[84:87]
	v_mfma_f32_16x16x32_bf16 v[80:83], v[164:167], v[212:215], v[80:83]
	v_mfma_f32_16x16x32_bf16 v[108:111], v[168:171], v[184:187], v[108:111]
	v_mfma_f32_16x16x32_bf16 v[104:107], v[176:179], v[184:187], v[104:107]
	v_mfma_f32_16x16x32_bf16 v[92:95], v[168:171], v[192:195], v[92:95]
	v_mfma_f32_16x16x32_bf16 v[88:91], v[176:179], v[192:195], v[88:91]
	v_mfma_f32_16x16x32_bf16 v[76:79], v[168:171], v[200:203], v[76:79]
	v_mfma_f32_16x16x32_bf16 v[72:75], v[176:179], v[200:203], v[72:75]
	v_mfma_f32_16x16x32_bf16 v[68:71], v[168:171], v[208:211], v[68:71]
	v_mfma_f32_16x16x32_bf16 v[64:67], v[176:179], v[208:211], v[64:67]
	v_mfma_f32_16x16x32_bf16 v[108:111], v[172:175], v[188:191], v[108:111]
	v_mfma_f32_16x16x32_bf16 v[104:107], v[180:183], v[188:191], v[104:107]
	v_mfma_f32_16x16x32_bf16 v[92:95], v[172:175], v[196:199], v[92:95]
	v_mfma_f32_16x16x32_bf16 v[88:91], v[180:183], v[196:199], v[88:91]
	v_mfma_f32_16x16x32_bf16 v[76:79], v[172:175], v[204:207], v[76:79]
	v_mfma_f32_16x16x32_bf16 v[72:75], v[180:183], v[204:207], v[72:75]
	v_mfma_f32_16x16x32_bf16 v[68:71], v[172:175], v[212:215], v[68:71]
	v_mfma_f32_16x16x32_bf16 v[64:67], v[180:183], v[212:215], v[64:67]
	s_barrier
; #define PG8_STAGE(bufoff, gbase, voff) do { _Pragma("unroll") for (int _i = 0; _i < 2; ++_i) \
;         __builtin_amdgcn_global_load_lds((const unsigned*)((const char*)(gbase) + (voff)[_i]), (PG8_LAS unsigned*)(lds + (bufoff) + ldsw + _i * 8192), 16, 0, 0); } while (0)
; #define PG8_LDA(dst, b, h) do { _Pragma("unroll") for (int m = 0; m < 4; ++m) _Pragma("unroll") for (int k = 0; k < 2; ++k) dst[m][k] = *(const PG8_LAS bf16x8*)(lds + PG8_SA(b, h) + aoff + m * 2048 + k * 1024); } while (0)
; #define PG8_MMA(ai, bj, At, Bt) do { __builtin_amdgcn_s_setprio(1); _Pragma("unroll") for (int m = 0; m < 4; ++m) _Pragma("unroll") for (int n = 0; n < 2; ++n) _Pragma("unroll") for (int k = 0; k < 2; ++k) \
;         acc[ai][bj][m][n] = __builtin_amdgcn_mfma_f32_16x16x32_bf16(Bt[n][k], At[m][k], acc[ai][bj][m][n], 0, 0, 0); __builtin_amdgcn_s_setprio(0); } while (0)
; #define PG8_WAIT_V(n) asm volatile("s_waitcnt vmcnt(" #n ")" ::: "memory")
; #define PG8_WAIT_L(n) asm volatile("s_waitcnt lgkmcnt(" #n ")" ::: "memory")
; #define PG8_BAR __builtin_amdgcn_s_barrier()
; #define PG8_SCHED __builtin_amdgcn_sched_barrier(0)
; template <class Epi, class Sched, bool ALIGN_EPI = false, bool SP2 = false>
; __device__ __forceinline__ void gemm_phase(PG8_LAS unsigned char* lds, const Gemm g, const Sched& S, const Epi& E, const int tid_in) {
;     ...
;         for (int t = 0; t < nt; t += 2) {
;     ...
;             PG8_LDA(At, 1, 1); PG8_STAGE(PG8_SB(1, 0), b3, voffB); PG8_STAGE(PG8_SB(1, 1), b3 + hstep, voffB); PG8_STAGE(PG8_SA(1, 0), a3, voffA);
;             PG8_WAIT_V(8); PG8_WAIT_L(0); PG8_BAR; PG8_MMA(1, 0, At, B0); PG8_MMA(1, 1, At, B1); PG8_BAR; PG8_SCHED;
	s_add_i32 s18, s54, s28
	v_lshl_add_u64 v[148:149], v[148:149], 0, s[8:9]
	s_mov_b32 m0, s18
	ds_read_b128 v[184:187], v155 offset:49152
	ds_read_b128 v[188:191], v155 offset:50176
	ds_read_b128 v[192:195], v155 offset:51200
	ds_read_b128 v[196:199], v155 offset:52224
	ds_read_b128 v[200:203], v155 offset:53248
	ds_read_b128 v[204:207], v155 offset:54272
	ds_read_b128 v[208:211], v155 offset:55296
	ds_read_b128 v[212:215], v155 offset:56320
	global_load_lds_dwordx4 v[148:149], off
	s_add_i32 m0, s18, 0x2000
	s_add_u32 s18, s20, 0x20080
	v_lshl_add_u64 v[148:149], v[216:217], 0, s[8:9]
	s_addc_u32 s19, s21, 0
	s_add_i32 s20, s55, s28
	global_load_lds_dwordx4 v[148:149], off
	v_lshl_add_u64 v[148:149], s[18:19], 0, v[132:133]
	s_mov_b32 m0, s20
	s_nop 0
	global_load_lds_dwordx4 v[148:149], off
	v_lshl_add_u64 v[148:149], s[18:19], 0, v[128:129]
	s_add_i32 m0, s20, 0x2000
	s_nop 0
	global_load_lds_dwordx4 v[148:149], off
	v_lshl_add_u64 v[148:149], v[218:219], 0, s[8:9]
	s_mov_b32 m0, s38
	s_nop 0
	global_load_lds_dwordx4 v[148:149], off
	v_lshl_add_u64 v[148:149], v[220:221], 0, s[8:9]
	s_mov_b32 m0, s39
	s_nop 0
	global_load_lds_dwordx4 v[148:149], off
	s_waitcnt vmcnt(8)
	s_waitcnt lgkmcnt(0)
	s_barrier
	v_mfma_f32_16x16x32_bf16 v[60:63], v[144:147], v[184:187], v[60:63]
	v_mfma_f32_16x16x32_bf16 v[56:59], v[160:163], v[184:187], v[56:59]
	v_mfma_f32_16x16x32_bf16 v[52:55], v[144:147], v[192:195], v[52:55]
	v_mfma_f32_16x16x32_bf16 v[48:51], v[160:163], v[192:195], v[48:51]
	v_mfma_f32_16x16x32_bf16 v[36:39], v[144:147], v[200:203], v[36:39]
	v_mfma_f32_16x16x32_bf16 v[32:35], v[160:163], v[200:203], v[32:35]
	v_mfma_f32_16x16x32_bf16 v[20:23], v[144:147], v[208:211], v[20:23]
	v_mfma_f32_16x16x32_bf16 v[16:19], v[160:163], v[208:211], v[16:19]
	v_mfma_f32_16x16x32_bf16 v[60:63], v[156:159], v[188:191], v[60:63]
	v_mfma_f32_16x16x32_bf16 v[56:59], v[164:167], v[188:191], v[56:59]
	v_mfma_f32_16x16x32_bf16 v[52:55], v[156:159], v[196:199], v[52:55]
	v_mfma_f32_16x16x32_bf16 v[48:51], v[164:167], v[196:199], v[48:51]
	v_mfma_f32_16x16x32_bf16 v[36:39], v[156:159], v[204:207], v[36:39]
	v_mfma_f32_16x16x32_bf16 v[32:35], v[164:167], v[204:207], v[32:35]
	v_mfma_f32_16x16x32_bf16 v[20:23], v[156:159], v[212:215], v[20:23]
	v_mfma_f32_16x16x32_bf16 v[16:19], v[164:167], v[212:215], v[16:19]
	v_mfma_f32_16x16x32_bf16 v[44:47], v[168:171], v[184:187], v[44:47]
	v_mfma_f32_16x16x32_bf16 v[40:43], v[176:179], v[184:187], v[40:43]
	v_mfma_f32_16x16x32_bf16 v[28:31], v[168:171], v[192:195], v[28:31]
	v_mfma_f32_16x16x32_bf16 v[24:27], v[176:179], v[192:195], v[24:27]
	v_mfma_f32_16x16x32_bf16 v[12:15], v[168:171], v[200:203], v[12:15]
	v_mfma_f32_16x16x32_bf16 v[8:11], v[176:179], v[200:203], v[8:11]
	v_mfma_f32_16x16x32_bf16 v[4:7], v[168:171], v[208:211], v[4:7]
	v_mfma_f32_16x16x32_bf16 v[0:3], v[176:179], v[208:211], v[0:3]
	v_mfma_f32_16x16x32_bf16 v[44:47], v[172:175], v[188:191], v[44:47]
	v_mfma_f32_16x16x32_bf16 v[40:43], v[180:183], v[188:191], v[40:43]
	v_mfma_f32_16x16x32_bf16 v[28:31], v[172:175], v[196:199], v[28:31]
	v_mfma_f32_16x16x32_bf16 v[24:27], v[180:183], v[196:199], v[24:27]
	v_mfma_f32_16x16x32_bf16 v[12:15], v[172:175], v[204:207], v[12:15]
	v_mfma_f32_16x16x32_bf16 v[8:11], v[180:183], v[204:207], v[8:11]
	v_mfma_f32_16x16x32_bf16 v[4:7], v[172:175], v[212:215], v[4:7]
	v_mfma_f32_16x16x32_bf16 v[0:3], v[180:183], v[212:215], v[0:3]
	s_barrier
	s_add_i32 s53, s53, 2
	s_add_u32 s51, s51, 0x100
	s_addc_u32 s52, s52, 0
	s_cmp_gt_u32 s53, 5
	s_mov_b64 s[18:19], s[2:3]
	s_cbranch_scc0 .LBB0_1067
	s_setprio 0
	s_and_b64 vcc, exec, s[10:11]
	s_cbranch_vccz .LBB0_1070
	s_barrier

; #define PG8_STAGE(bufoff, gbase, voff) do { _Pragma("unroll") for (int _i = 0; _i < 2; ++_i) \
;         __builtin_amdgcn_global_load_lds((const unsigned*)((const char*)(gbase) + (voff)[_i]), (PG8_LAS unsigned*)(lds + (bufoff) + ldsw + _i * 8192), 16, 0, 0); } while (0)
; #define PG8_LDA(dst, b, h) do { _Pragma("unroll") for (int m = 0; m < 4; ++m) _Pragma("unroll") for (int k = 0; k < 2; ++k) dst[m][k] = *(const PG8_LAS bf16x8*)(lds + PG8_SA(b, h) + aoff + m * 2048 + k * 1024); } while (0)
; #define PG8_LDB(dst, b, h) do { _Pragma("unroll") for (int n = 0; n < 2; ++n) _Pragma("unroll") for (int k = 0; k < 2; ++k) dst[n][k] = *(const PG8_LAS bf16x8*)(lds + PG8_SB(b, h) + boff + n * 2048 + k * 1024); } while (0)
; #define PG8_WAIT_V(n) asm volatile("s_waitcnt vmcnt(" #n ")" ::: "memory")
; #define PG8_WAIT_L(n) asm volatile("s_waitcnt lgkmcnt(" #n ")" ::: "memory")
; #define PG8_BAR __builtin_amdgcn_s_barrier()
; #define PG8_SCHED __builtin_amdgcn_sched_barrier(0)
; template <class Epi, class Sched, bool ALIGN_EPI = false, bool SP2 = false>
; __device__ __forceinline__ void gemm_phase(PG8_LAS unsigned char* lds, const Gemm g, const Sched& S, const Epi& E, const int tid_in) {
;     ...
;         const bool has_next = S.next(ui + 1, nxt);
;         const char* nA = has_next ? (const char*)g.A + (size_t)nxt.pm * tstepA : cA; const char* nB = has_next ? (const char*)g.Bt + (size_t)nxt.pn * tstep : cB;
;         for (int t = 0; t < nt; t += 2) {
;             const bool last = (t == nt - 2);
;             const char* a1 = cA + (size_t)(t + 1) * kstep;
;             const char* a2 = last ? nA : cA + (size_t)(t + 2) * kstep; const char* b2 = last ? nB : cB + (size_t)(t + 2) * kstep;
;             const char* a3 = a2 + kstep; const char* b3 = b2 + kstep;
;             if (last && has_next) S.a_ready(nxt);
;             if constexpr (SP2) {
;             PG8_LDB(B0, 0, 0); PG8_LDB(B1, 0, 1); PG8_SCHED; PG8_LDA(At, 0, 0); PG8_STAGE(PG8_SA(1, 1), a1 + hstepA, voffA);
;             PG8_WAIT_V(8); PG8_WAIT_L(0); PG8_BAR; PG8_MMA(0, 0, At, B0); PG8_MMA(0, 1, At, B1); PG8_BAR; PG8_SCHED;
;             PG8_LDA(At, 0, 1); PG8_STAGE(PG8_SB(0, 0), b2, voffB); PG8_STAGE(PG8_SB(0, 1), b2 + hstep, voffB); PG8_STAGE(PG8_SA(0, 0), a2, voffA);
;             PG8_WAIT_V(8); PG8_WAIT_L(0); PG8_BAR; PG8_MMA(1, 0, At, B0); PG8_MMA(1, 1, At, B1); PG8_BAR; PG8_SCHED;
.Lkprio_skip_13:
.LBB0_1088:
	s_add_u32 s25, s20, s24
	s_addc_u32 s30, s21, 0
	s_add_u32 s28, s25, 0x100
	s_addc_u32 s29, s30, 0
	s_and_b64 s[26:27], s[22:23], exec
	s_cselect_b32 s27, s15, s29
	s_cselect_b32 s26, s14, s28
	s_add_u32 s24, s18, s24
	s_addc_u32 s28, s19, 0
	s_add_u32 s24, s24, 0x100
	s_addc_u32 s28, s28, 0
	s_and_b64 s[22:23], s[22:23], exec
	s_cselect_b32 s29, s13, s28
	s_cselect_b32 s28, s56, s24
	s_add_u32 s34, s25, 0xc0080
	ds_read_b128 v[140:143], v149
	ds_read_b128 v[152:155], v149 offset:1024
	ds_read_b128 v[156:159], v149 offset:2048
	ds_read_b128 v[160:163], v149 offset:3072
	ds_read_b128 v[164:167], v150
	ds_read_b128 v[168:171], v150 offset:1024
	ds_read_b128 v[172:175], v150 offset:2048
	ds_read_b128 v[176:179], v150 offset:3072
	s_addc_u32 s35, s30, 0
	s_add_i32 s66, s50, s39
	s_add_i32 m0, s42, 0xc000
	s_add_i32 s67, s42, 0xe000
	s_add_i32 s63, s66, 0x2000
	s_add_u32 s30, s28, 0x10000
	s_addc_u32 s31, s29, 0
	s_add_i32 s65, s51, s39
	s_add_i32 s64, s65, 0x2000
	s_add_i32 s62, 0, 0x18000
	s_add_i32 s61, 0, 0x1c000
	s_add_u32 s24, s26, 0xc0000
	s_addc_u32 s25, s27, 0
	s_add_i32 s60, s62, s39
	s_add_i32 s58, s60, 0x2000
	s_add_u32 s22, s28, 0x10080
	s_addc_u32 s23, s29, 0
	s_add_i32 s59, s61, s39
	s_add_i32 s57, s59, 0x2000
	v_lshl_add_u64 v[144:145], s[34:35], 0, v[134:135]
	ds_read_b128 v[180:183], v151
	ds_read_b128 v[184:187], v151 offset:1024
	ds_read_b128 v[188:191], v151 offset:2048
	ds_read_b128 v[192:195], v151 offset:3072
	ds_read_b128 v[196:199], v151 offset:4096
	ds_read_b128 v[200:203], v151 offset:5120
	ds_read_b128 v[204:207], v151 offset:6144
	ds_read_b128 v[208:211], v151 offset:7168
	global_load_lds_dwordx4 v[144:145], off
	v_lshl_add_u64 v[144:145], s[34:35], 0, v[130:131]
	s_mov_b32 m0, s67
	s_nop 0
	global_load_lds_dwordx4 v[144:145], off
	s_waitcnt vmcnt(8)
	s_waitcnt lgkmcnt(0)
	s_barrier
	v_mfma_f32_16x16x32_bf16 v[124:127], v[140:143], v[180:183], v[124:127]
	v_mfma_f32_16x16x32_bf16 v[120:123], v[156:159], v[180:183], v[120:123]
	v_mfma_f32_16x16x32_bf16 v[116:119], v[140:143], v[188:191], v[116:119]
	v_mfma_f32_16x16x32_bf16 v[112:115], v[156:159], v[188:191], v[112:115]
	v_mfma_f32_16x16x32_bf16 v[100:103], v[140:143], v[196:199], v[100:103]
	v_mfma_f32_16x16x32_bf16 v[96:99], v[156:159], v[196:199], v[96:99]
	v_mfma_f32_16x16x32_bf16 v[84:87], v[140:143], v[204:207], v[84:87]
	v_mfma_f32_16x16x32_bf16 v[80:83], v[156:159], v[204:207], v[80:83]
	v_mfma_f32_16x16x32_bf16 v[124:127], v[152:155], v[184:187], v[124:127]
	v_mfma_f32_16x16x32_bf16 v[120:123], v[160:163], v[184:187], v[120:123]
	v_mfma_f32_16x16x32_bf16 v[116:119], v[152:155], v[192:195], v[116:119]
	v_mfma_f32_16x16x32_bf16 v[112:115], v[160:163], v[192:195], v[112:115]
	v_mfma_f32_16x16x32_bf16 v[100:103], v[152:155], v[200:203], v[100:103]
	v_mfma_f32_16x16x32_bf16 v[96:99], v[160:163], v[200:203], v[96:99]
	v_mfma_f32_16x16x32_bf16 v[84:87], v[152:155], v[208:211], v[84:87]
	v_mfma_f32_16x16x32_bf16 v[80:83], v[160:163], v[208:211], v[80:83]
	v_mfma_f32_16x16x32_bf16 v[108:111], v[164:167], v[180:183], v[108:111]
	v_mfma_f32_16x16x32_bf16 v[104:107], v[172:175], v[180:183], v[104:107]
	v_mfma_f32_16x16x32_bf16 v[92:95], v[164:167], v[188:191], v[92:95]
	v_mfma_f32_16x16x32_bf16 v[88:91], v[172:175], v[188:191], v[88:91]
	v_mfma_f32_16x16x32_bf16 v[76:79], v[164:167], v[196:199], v[76:79]
	v_mfma_f32_16x16x32_bf16 v[72:75], v[172:175], v[196:199], v[72:75]
	v_mfma_f32_16x16x32_bf16 v[68:71], v[164:167], v[204:207], v[68:71]
	v_mfma_f32_16x16x32_bf16 v[64:67], v[172:175], v[204:207], v[64:67]
	v_mfma_f32_16x16x32_bf16 v[108:111], v[168:171], v[184:187], v[108:111]
	v_mfma_f32_16x16x32_bf16 v[104:107], v[176:179], v[184:187], v[104:107]
	v_mfma_f32_16x16x32_bf16 v[92:95], v[168:171], v[192:195], v[92:95]
	v_mfma_f32_16x16x32_bf16 v[88:91], v[176:179], v[192:195], v[88:91]
	v_mfma_f32_16x16x32_bf16 v[76:79], v[168:171], v[200:203], v[76:79]
	v_mfma_f32_16x16x32_bf16 v[72:75], v[176:179], v[200:203], v[72:75]
	v_mfma_f32_16x16x32_bf16 v[68:71], v[168:171], v[208:211], v[68:71]
	v_mfma_f32_16x16x32_bf16 v[64:67], v[176:179], v[208:211], v[64:67]
	s_barrier
	s_mov_b32 m0, s66
	v_lshl_add_u64 v[144:145], s[28:29], 0, v[132:133]
	ds_read_b128 v[180:183], v151 offset:16384
	ds_read_b128 v[184:187], v151 offset:17408
	ds_read_b128 v[188:191], v151 offset:18432
	ds_read_b128 v[192:195], v151 offset:19456
	ds_read_b128 v[196:199], v151 offset:20480
	ds_read_b128 v[200:203], v151 offset:21504
	ds_read_b128 v[204:207], v151 offset:22528
	ds_read_b128 v[208:211], v151 offset:23552
	global_load_lds_dwordx4 v[144:145], off
	v_lshl_add_u64 v[212:213], s[28:29], 0, v[128:129]
	s_mov_b32 m0, s63
	v_lshl_add_u64 v[214:215], s[30:31], 0, v[132:133]
	global_load_lds_dwordx4 v[212:213], off
	s_mov_b32 m0, s65
	v_lshl_add_u64 v[216:217], s[26:27], 0, v[130:131]
	global_load_lds_dwordx4 v[214:215], off
	v_lshl_add_u64 v[214:215], s[30:31], 0, v[128:129]
	s_mov_b32 m0, s64
	s_nop 0
	global_load_lds_dwordx4 v[214:215], off
	v_lshl_add_u64 v[214:215], s[26:27], 0, v[134:135]
	s_mov_b32 m0, s42
	s_nop 0
	global_load_lds_dwordx4 v[214:215], off
	s_mov_b32 m0, s43
	s_nop 0
	global_load_lds_dwordx4 v[216:217], off
	s_waitcnt vmcnt(8)
	s_waitcnt lgkmcnt(0)
	s_barrier
; #define PG8_STAGE(bufoff, gbase, voff) do { _Pragma("unroll") for (int _i = 0; _i < 2; ++_i) \
;         __builtin_amdgcn_global_load_lds((const unsigned*)((const char*)(gbase) + (voff)[_i]), (PG8_LAS unsigned*)(lds + (bufoff) + ldsw + _i * 8192), 16, 0, 0); } while (0)
; #define PG8_LDA(dst, b, h) do { _Pragma("unroll") for (int m = 0; m < 4; ++m) _Pragma("unroll") for (int k = 0; k < 2; ++k) dst[m][k] = *(const PG8_LAS bf16x8*)(lds + PG8_SA(b, h) + aoff + m * 2048 + k * 1024); } while (0)
; #define PG8_LDB(dst, b, h) do { _Pragma("unroll") for (int n = 0; n < 2; ++n) _Pragma("unroll") for (int k = 0; k < 2; ++k) dst[n][k] = *(const PG8_LAS bf16x8*)(lds + PG8_SB(b, h) + boff + n * 2048 + k * 1024); } while (0)
; #define PG8_MMA(ai, bj, At, Bt) do { __builtin_amdgcn_s_setprio(1); _Pragma("unroll") for (int m = 0; m < 4; ++m) _Pragma("unroll") for (int n = 0; n < 2; ++n) _Pragma("unroll") for (int k = 0; k < 2; ++k) \
;         acc[ai][bj][m][n] = __builtin_amdgcn_mfma_f32_16x16x32_bf16(Bt[n][k], At[m][k], acc[ai][bj][m][n], 0, 0, 0); __builtin_amdgcn_s_setprio(0); } while (0)
; #define PG8_WAIT_V(n) asm volatile("s_waitcnt vmcnt(" #n ")" ::: "memory")
; #define PG8_WAIT_L(n) asm volatile("s_waitcnt lgkmcnt(" #n ")" ::: "memory")
; #define PG8_BAR __builtin_amdgcn_s_barrier()
; #define PG8_SCHED __builtin_amdgcn_sched_barrier(0)
; template <class Epi, class Sched, bool ALIGN_EPI = false, bool SP2 = false>
; __device__ __forceinline__ void gemm_phase(PG8_LAS unsigned char* lds, const Gemm g, const Sched& S, const Epi& E, const int tid_in) {
;     ...
;             PG8_WAIT_V(8); PG8_WAIT_L(0); PG8_BAR; PG8_MMA(1, 0, At, B0); PG8_MMA(1, 1, At, B1); PG8_BAR; PG8_SCHED;
;             PG8_LDB(B0, 1, 0); PG8_LDB(B1, 1, 1); PG8_SCHED; PG8_LDA(At, 1, 0); PG8_STAGE(PG8_SA(0, 1), a2 + hstepA, voffA);
;             PG8_WAIT_V(8); PG8_WAIT_L(0); PG8_BAR; PG8_MMA(0, 0, At, B0); PG8_MMA(0, 1, At, B1); PG8_BAR; PG8_SCHED;
	v_mfma_f32_16x16x32_bf16 v[60:63], v[140:143], v[180:183], v[60:63]
	v_mfma_f32_16x16x32_bf16 v[56:59], v[156:159], v[180:183], v[56:59]
	v_mfma_f32_16x16x32_bf16 v[52:55], v[140:143], v[188:191], v[52:55]
	v_mfma_f32_16x16x32_bf16 v[48:51], v[156:159], v[188:191], v[48:51]
	v_mfma_f32_16x16x32_bf16 v[36:39], v[140:143], v[196:199], v[36:39]
	v_mfma_f32_16x16x32_bf16 v[32:35], v[156:159], v[196:199], v[32:35]
	v_mfma_f32_16x16x32_bf16 v[20:23], v[140:143], v[204:207], v[20:23]
	v_mfma_f32_16x16x32_bf16 v[16:19], v[156:159], v[204:207], v[16:19]
	v_mfma_f32_16x16x32_bf16 v[60:63], v[152:155], v[184:187], v[60:63]
	v_mfma_f32_16x16x32_bf16 v[56:59], v[160:163], v[184:187], v[56:59]
	v_mfma_f32_16x16x32_bf16 v[52:55], v[152:155], v[192:195], v[52:55]
	v_mfma_f32_16x16x32_bf16 v[48:51], v[160:163], v[192:195], v[48:51]
	v_mfma_f32_16x16x32_bf16 v[36:39], v[152:155], v[200:203], v[36:39]
	v_mfma_f32_16x16x32_bf16 v[32:35], v[160:163], v[200:203], v[32:35]
	v_mfma_f32_16x16x32_bf16 v[20:23], v[152:155], v[208:211], v[20:23]
	v_mfma_f32_16x16x32_bf16 v[16:19], v[160:163], v[208:211], v[16:19]
	v_mfma_f32_16x16x32_bf16 v[44:47], v[164:167], v[180:183], v[44:47]
	v_mfma_f32_16x16x32_bf16 v[40:43], v[172:175], v[180:183], v[40:43]
	v_mfma_f32_16x16x32_bf16 v[28:31], v[164:167], v[188:191], v[28:31]
	v_mfma_f32_16x16x32_bf16 v[24:27], v[172:175], v[188:191], v[24:27]
	v_mfma_f32_16x16x32_bf16 v[12:15], v[164:167], v[196:199], v[12:15]
	v_mfma_f32_16x16x32_bf16 v[8:11], v[172:175], v[196:199], v[8:11]
	v_mfma_f32_16x16x32_bf16 v[4:7], v[164:167], v[204:207], v[4:7]
	v_mfma_f32_16x16x32_bf16 v[0:3], v[172:175], v[204:207], v[0:3]
	v_mfma_f32_16x16x32_bf16 v[44:47], v[168:171], v[184:187], v[44:47]
	v_mfma_f32_16x16x32_bf16 v[40:43], v[176:179], v[184:187], v[40:43]
	v_mfma_f32_16x16x32_bf16 v[28:31], v[168:171], v[192:195], v[28:31]
	v_mfma_f32_16x16x32_bf16 v[24:27], v[176:179], v[192:195], v[24:27]
	v_mfma_f32_16x16x32_bf16 v[12:15], v[168:171], v[200:203], v[12:15]
	v_mfma_f32_16x16x32_bf16 v[8:11], v[176:179], v[200:203], v[8:11]
	v_mfma_f32_16x16x32_bf16 v[4:7], v[168:171], v[208:211], v[4:7]
	v_mfma_f32_16x16x32_bf16 v[0:3], v[176:179], v[208:211], v[0:3]
	s_barrier
	v_add_u32_e32 v160, s62, v147
	v_add_u32_e32 v176, s61, v147
	ds_read_b128 v[140:143], v160
	ds_read_b128 v[152:155], v160 offset:1024
	ds_read_b128 v[156:159], v160 offset:2048
	ds_read_b128 v[160:163], v160 offset:3072
	ds_read_b128 v[164:167], v176
	ds_read_b128 v[168:171], v176 offset:1024
	ds_read_b128 v[172:175], v176 offset:2048
	ds_read_b128 v[176:179], v176 offset:3072
	s_mov_b32 m0, s44
	v_lshl_add_u64 v[218:219], s[24:25], 0, v[134:135]
	ds_read_b128 v[180:183], v151 offset:32768
	ds_read_b128 v[184:187], v151 offset:33792
	ds_read_b128 v[188:191], v151 offset:34816
	ds_read_b128 v[192:195], v151 offset:35840
	ds_read_b128 v[196:199], v151 offset:36864
	ds_read_b128 v[200:203], v151 offset:37888
	ds_read_b128 v[204:207], v151 offset:38912
	ds_read_b128 v[208:211], v151 offset:39936
	global_load_lds_dwordx4 v[218:219], off
	v_lshl_add_u64 v[218:219], s[24:25], 0, v[130:131]
	s_mov_b32 m0, s45
	s_nop 0
	global_load_lds_dwordx4 v[218:219], off
	s_waitcnt vmcnt(8)
	s_waitcnt lgkmcnt(0)
	s_barrier
	v_mfma_f32_16x16x32_bf16 v[124:127], v[140:143], v[180:183], v[124:127]
	v_mfma_f32_16x16x32_bf16 v[120:123], v[156:159], v[180:183], v[120:123]
	v_mfma_f32_16x16x32_bf16 v[116:119], v[140:143], v[188:191], v[116:119]
	v_mfma_f32_16x16x32_bf16 v[112:115], v[156:159], v[188:191], v[112:115]
	v_mfma_f32_16x16x32_bf16 v[100:103], v[140:143], v[196:199], v[100:103]
	v_mfma_f32_16x16x32_bf16 v[96:99], v[156:159], v[196:199], v[96:99]
	v_mfma_f32_16x16x32_bf16 v[84:87], v[140:143], v[204:207], v[84:87]
	v_mfma_f32_16x16x32_bf16 v[80:83], v[156:159], v[204:207], v[80:83]
	v_mfma_f32_16x16x32_bf16 v[124:127], v[152:155], v[184:187], v[124:127]
	v_mfma_f32_16x16x32_bf16 v[120:123], v[160:163], v[184:187], v[120:123]
	v_mfma_f32_16x16x32_bf16 v[116:119], v[152:155], v[192:195], v[116:119]
	v_mfma_f32_16x16x32_bf16 v[112:115], v[160:163], v[192:195], v[112:115]
	v_mfma_f32_16x16x32_bf16 v[100:103], v[152:155], v[200:203], v[100:103]
	v_mfma_f32_16x16x32_bf16 v[96:99], v[160:163], v[200:203], v[96:99]
	v_mfma_f32_16x16x32_bf16 v[84:87], v[152:155], v[208:211], v[84:87]
	v_mfma_f32_16x16x32_bf16 v[80:83], v[160:163], v[208:211], v[80:83]
	v_mfma_f32_16x16x32_bf16 v[108:111], v[164:167], v[180:183], v[108:111]
	v_mfma_f32_16x16x32_bf16 v[104:107], v[172:175], v[180:183], v[104:107]
	v_mfma_f32_16x16x32_bf16 v[92:95], v[164:167], v[188:191], v[92:95]
	v_mfma_f32_16x16x32_bf16 v[88:91], v[172:175], v[188:191], v[88:91]
	v_mfma_f32_16x16x32_bf16 v[76:79], v[164:167], v[196:199], v[76:79]
	v_mfma_f32_16x16x32_bf16 v[72:75], v[172:175], v[196:199], v[72:75]
	v_mfma_f32_16x16x32_bf16 v[68:71], v[164:167], v[204:207], v[68:71]
	v_mfma_f32_16x16x32_bf16 v[64:67], v[172:175], v[204:207], v[64:67]
	v_mfma_f32_16x16x32_bf16 v[108:111], v[168:171], v[184:187], v[108:111]
	v_mfma_f32_16x16x32_bf16 v[104:107], v[176:179], v[184:187], v[104:107]
	v_mfma_f32_16x16x32_bf16 v[92:95], v[168:171], v[192:195], v[92:95]
	v_mfma_f32_16x16x32_bf16 v[88:91], v[176:179], v[192:195], v[88:91]
	v_mfma_f32_16x16x32_bf16 v[76:79], v[168:171], v[200:203], v[76:79]
	v_mfma_f32_16x16x32_bf16 v[72:75], v[176:179], v[200:203], v[72:75]
	v_mfma_f32_16x16x32_bf16 v[68:71], v[168:171], v[208:211], v[68:71]
	v_mfma_f32_16x16x32_bf16 v[64:67], v[176:179], v[208:211], v[64:67]
	s_barrier
; #define PG8_STAGE(bufoff, gbase, voff) do { _Pragma("unroll") for (int _i = 0; _i < 2; ++_i) \
;         __builtin_amdgcn_global_load_lds((const unsigned*)((const char*)(gbase) + (voff)[_i]), (PG8_LAS unsigned*)(lds + (bufoff) + ldsw + _i * 8192), 16, 0, 0); } while (0)
; #define PG8_LDA(dst, b, h) do { _Pragma("unroll") for (int m = 0; m < 4; ++m) _Pragma("unroll") for (int k = 0; k < 2; ++k) dst[m][k] = *(const PG8_LAS bf16x8*)(lds + PG8_SA(b, h) + aoff + m * 2048 + k * 1024); } while (0)
; #define PG8_MMA(ai, bj, At, Bt) do { __builtin_amdgcn_s_setprio(1); _Pragma("unroll") for (int m = 0; m < 4; ++m) _Pragma("unroll") for (int n = 0; n < 2; ++n) _Pragma("unroll") for (int k = 0; k < 2; ++k) \
;         acc[ai][bj][m][n] = __builtin_amdgcn_mfma_f32_16x16x32_bf16(Bt[n][k], At[m][k], acc[ai][bj][m][n], 0, 0, 0); __builtin_amdgcn_s_setprio(0); } while (0)
; #define PG8_WAIT_V(n) asm volatile("s_waitcnt vmcnt(" #n ")" ::: "memory")
; #define PG8_WAIT_L(n) asm volatile("s_waitcnt lgkmcnt(" #n ")" ::: "memory")
; #define PG8_BAR __builtin_amdgcn_s_barrier()
; #define PG8_SCHED __builtin_amdgcn_sched_barrier(0)
; template <class Epi, class Sched, bool ALIGN_EPI = false, bool SP2 = false>
; __device__ __forceinline__ void gemm_phase(PG8_LAS unsigned char* lds, const Gemm g, const Sched& S, const Epi& E, const int tid_in) {
;     ...
;             PG8_LDA(At, 1, 1); PG8_STAGE(PG8_SB(1, 0), b3, voffB); PG8_STAGE(PG8_SB(1, 1), b3 + hstep, voffB); PG8_STAGE(PG8_SA(1, 0), a3, voffA);
;             PG8_WAIT_V(8); PG8_WAIT_L(0); PG8_BAR; PG8_MMA(1, 0, At, B0); PG8_MMA(1, 1, At, B1); PG8_BAR; PG8_SCHED;
	s_mov_b32 m0, s60
	v_lshl_add_u64 v[144:145], v[144:145], 0, s[8:9]
	ds_read_b128 v[180:183], v151 offset:49152
	ds_read_b128 v[184:187], v151 offset:50176
	ds_read_b128 v[188:191], v151 offset:51200
	ds_read_b128 v[192:195], v151 offset:52224
	ds_read_b128 v[196:199], v151 offset:53248
	ds_read_b128 v[200:203], v151 offset:54272
	ds_read_b128 v[204:207], v151 offset:55296
	ds_read_b128 v[208:211], v151 offset:56320
	global_load_lds_dwordx4 v[144:145], off
	v_lshl_add_u64 v[144:145], v[212:213], 0, s[8:9]
	s_mov_b32 m0, s58
	s_nop 0
	global_load_lds_dwordx4 v[144:145], off
	v_lshl_add_u64 v[144:145], s[22:23], 0, v[132:133]
	s_mov_b32 m0, s59
	s_nop 0
	global_load_lds_dwordx4 v[144:145], off
	v_lshl_add_u64 v[144:145], s[22:23], 0, v[128:129]
	s_mov_b32 m0, s57
	s_nop 0
	global_load_lds_dwordx4 v[144:145], off
	v_lshl_add_u64 v[144:145], v[214:215], 0, s[8:9]
	s_mov_b32 m0, s47
	s_nop 0
	global_load_lds_dwordx4 v[144:145], off
	v_lshl_add_u64 v[144:145], v[216:217], 0, s[8:9]
	s_mov_b32 m0, s48
	s_nop 0
	global_load_lds_dwordx4 v[144:145], off
	s_waitcnt vmcnt(8)
	s_waitcnt lgkmcnt(0)
	s_barrier
	v_mfma_f32_16x16x32_bf16 v[60:63], v[140:143], v[180:183], v[60:63]
	v_mfma_f32_16x16x32_bf16 v[56:59], v[156:159], v[180:183], v[56:59]
	v_mfma_f32_16x16x32_bf16 v[52:55], v[140:143], v[188:191], v[52:55]
	v_mfma_f32_16x16x32_bf16 v[48:51], v[156:159], v[188:191], v[48:51]
	v_mfma_f32_16x16x32_bf16 v[36:39], v[140:143], v[196:199], v[36:39]
	v_mfma_f32_16x16x32_bf16 v[32:35], v[156:159], v[196:199], v[32:35]
	v_mfma_f32_16x16x32_bf16 v[20:23], v[140:143], v[204:207], v[20:23]
	v_mfma_f32_16x16x32_bf16 v[16:19], v[156:159], v[204:207], v[16:19]
	v_mfma_f32_16x16x32_bf16 v[60:63], v[152:155], v[184:187], v[60:63]
	v_mfma_f32_16x16x32_bf16 v[56:59], v[160:163], v[184:187], v[56:59]
	v_mfma_f32_16x16x32_bf16 v[52:55], v[152:155], v[192:195], v[52:55]
	v_mfma_f32_16x16x32_bf16 v[48:51], v[160:163], v[192:195], v[48:51]
	v_mfma_f32_16x16x32_bf16 v[36:39], v[152:155], v[200:203], v[36:39]
	v_mfma_f32_16x16x32_bf16 v[32:35], v[160:163], v[200:203], v[32:35]
	v_mfma_f32_16x16x32_bf16 v[20:23], v[152:155], v[208:211], v[20:23]
	v_mfma_f32_16x16x32_bf16 v[16:19], v[160:163], v[208:211], v[16:19]
	v_mfma_f32_16x16x32_bf16 v[44:47], v[164:167], v[180:183], v[44:47]
	v_mfma_f32_16x16x32_bf16 v[40:43], v[172:175], v[180:183], v[40:43]
	v_mfma_f32_16x16x32_bf16 v[28:31], v[164:167], v[188:191], v[28:31]
	v_mfma_f32_16x16x32_bf16 v[24:27], v[172:175], v[188:191], v[24:27]
	v_mfma_f32_16x16x32_bf16 v[12:15], v[164:167], v[196:199], v[12:15]
	v_mfma_f32_16x16x32_bf16 v[8:11], v[172:175], v[196:199], v[8:11]
	v_mfma_f32_16x16x32_bf16 v[4:7], v[164:167], v[204:207], v[4:7]
	v_mfma_f32_16x16x32_bf16 v[0:3], v[172:175], v[204:207], v[0:3]
	v_mfma_f32_16x16x32_bf16 v[44:47], v[168:171], v[184:187], v[44:47]
	v_mfma_f32_16x16x32_bf16 v[40:43], v[176:179], v[184:187], v[40:43]
	v_mfma_f32_16x16x32_bf16 v[28:31], v[168:171], v[192:195], v[28:31]
	v_mfma_f32_16x16x32_bf16 v[24:27], v[176:179], v[192:195], v[24:27]
	v_mfma_f32_16x16x32_bf16 v[12:15], v[168:171], v[200:203], v[12:15]
	v_mfma_f32_16x16x32_bf16 v[8:11], v[176:179], v[200:203], v[8:11]
	v_mfma_f32_16x16x32_bf16 v[4:7], v[168:171], v[208:211], v[4:7]
	v_mfma_f32_16x16x32_bf16 v[0:3], v[176:179], v[208:211], v[0:3]
	s_barrier
	s_movk_i32 s24, 0x100
	s_andn2_b64 vcc, exec, s[2:3]
	s_mov_b64 s[22:23], -1
	s_mov_b64 s[2:3], 0
	s_cbranch_vccz .LBB0_1088
	s_setprio 0
	s_and_b64 vcc, exec, s[10:11]
	s_cbranch_vccz .LBB0_1091
	s_barrier

; #define PG8_STAGE(bufoff, gbase, voff) do { _Pragma("unroll") for (int _i = 0; _i < 2; ++_i) \
;         __builtin_amdgcn_global_load_lds((const unsigned*)((const char*)(gbase) + (voff)[_i]), (PG8_LAS unsigned*)(lds + (bufoff) + ldsw + _i * 8192), 16, 0, 0); } while (0)
; #define PG8_LDA(dst, b, h) do { _Pragma("unroll") for (int m = 0; m < 4; ++m) _Pragma("unroll") for (int k = 0; k < 2; ++k) dst[m][k] = *(const PG8_LAS bf16x8*)(lds + PG8_SA(b, h) + aoff + m * 2048 + k * 1024); } while (0)
; #define PG8_LDB(dst, b, h) do { _Pragma("unroll") for (int n = 0; n < 2; ++n) _Pragma("unroll") for (int k = 0; k < 2; ++k) dst[n][k] = *(const PG8_LAS bf16x8*)(lds + PG8_SB(b, h) + boff + n * 2048 + k * 1024); } while (0)
; #define PG8_WAIT_V(n) asm volatile("s_waitcnt vmcnt(" #n ")" ::: "memory")
; #define PG8_WAIT_L(n) asm volatile("s_waitcnt lgkmcnt(" #n ")" ::: "memory")
; #define PG8_BAR __builtin_amdgcn_s_barrier()
; template <class Epi, class Sched, bool ALIGN_EPI = false, bool SP2 = false>
; __device__ __forceinline__ void gemm_phase(PG8_LAS unsigned char* lds, const Gemm g, const Sched& S, const Epi& E, const int tid_in) {
;     ...
;         const bool has_next = S.next(ui + 1, nxt);
;         const char* nA = has_next ? (const char*)g.A + (size_t)nxt.pm * tstepA : cA; const char* nB = has_next ? (const char*)g.Bt + (size_t)nxt.pn * tstep : cB;
;         for (int t = 0; t < nt; t += 2) {
;             const bool last = (t == nt - 2);
;             const char* a1 = cA + (size_t)(t + 1) * kstep;
;             const char* a2 = last ? nA : cA + (size_t)(t + 2) * kstep; const char* b2 = last ? nB : cB + (size_t)(t + 2) * kstep;
;             const char* a3 = a2 + kstep; const char* b3 = b2 + kstep;
;             if (last && has_next) S.a_ready(nxt);
;             if constexpr (SP2) {
;             PG8_LDB(B0, 0, 0); PG8_LDB(B1, 0, 1); PG8_SCHED; PG8_LDA(At, 0, 0); PG8_STAGE(PG8_SA(1, 1), a1 + hstepA, voffA);
;             PG8_WAIT_V(8); PG8_WAIT_L(0); PG8_BAR; PG8_MMA(0, 0, At, B0); PG8_MMA(0, 1, At, B1); PG8_BAR; PG8_SCHED;
;     ...
; #pragma unroll
;         for (int a = 0; a < 2; ++a)
; #pragma unroll
;             for (int b = 0; b < 2; ++b)
; #pragma unroll
;                 for (int m = 0; m < 4; ++m)
; #pragma unroll
;                     for (int n = 0; n < 2; ++n) acc[a][b][m][n] = (f32x4){0.f, 0.f, 0.f, 0.f};
;         cur = nxt; cA = nA; cB = nB; ++ui;
.LBB0_1404:
	s_ashr_i32 s13, s12, 31
	s_lshl_b64 s[14:15], s[12:13], 20
	s_add_u32 s14, s26, s14
	s_addc_u32 s15, s27, s15
	s_and_b64 s[16:17], s[0:1], exec
	s_cselect_b32 s13, s15, s23
	s_cselect_b32 s49, s14, s22
	s_ashr_i32 s11, s10, 31
	s_lshl_b64 s[16:17], s[10:11], 20
	s_add_u32 s16, s28, s16
	s_addc_u32 s17, s29, s17
	s_and_b64 s[24:25], s[0:1], exec
	s_cselect_b32 s11, s17, s21
	s_cselect_b32 s50, s16, s20
	s_add_u32 s51, s20, 0x100
	s_addc_u32 s52, s21, 0
	s_add_u32 s20, s22, 0x80080
	v_mov_b32_e32 v0, 0
	s_addc_u32 s21, s23, 0
	s_mov_b32 s53, -2
	v_mov_b32_e32 v1, v0
	v_mov_b32_e32 v2, v0
	v_mov_b32_e32 v3, v0
	v_mov_b32_e32 v4, v0
	v_mov_b32_e32 v5, v0
	v_mov_b32_e32 v6, v0
	v_mov_b32_e32 v7, v0
	v_mov_b32_e32 v16, v0
	v_mov_b32_e32 v17, v0
	v_mov_b32_e32 v18, v0
	v_mov_b32_e32 v19, v0
	v_mov_b32_e32 v20, v0
	v_mov_b32_e32 v21, v0
	v_mov_b32_e32 v22, v0
	v_mov_b32_e32 v23, v0
	v_mov_b32_e32 v28, v0
	v_mov_b32_e32 v29, v0
	v_mov_b32_e32 v30, v0
	v_mov_b32_e32 v31, v0
	v_mov_b32_e32 v36, v0
	v_mov_b32_e32 v37, v0
	v_mov_b32_e32 v38, v0
	v_mov_b32_e32 v39, v0
	v_mov_b32_e32 v44, v0
	v_mov_b32_e32 v45, v0
	v_mov_b32_e32 v46, v0
	v_mov_b32_e32 v47, v0
	v_mov_b32_e32 v52, v0
	v_mov_b32_e32 v53, v0
	v_mov_b32_e32 v54, v0
	v_mov_b32_e32 v55, v0
	v_mov_b32_e32 v8, v0
	v_mov_b32_e32 v9, v0
	v_mov_b32_e32 v10, v0
	v_mov_b32_e32 v11, v0
	v_mov_b32_e32 v12, v0
	v_mov_b32_e32 v13, v0
	v_mov_b32_e32 v14, v0
	v_mov_b32_e32 v15, v0
	v_mov_b32_e32 v24, v0
	v_mov_b32_e32 v25, v0
	v_mov_b32_e32 v26, v0
	v_mov_b32_e32 v27, v0
	v_mov_b32_e32 v32, v0
	v_mov_b32_e32 v33, v0
	v_mov_b32_e32 v34, v0
	v_mov_b32_e32 v35, v0
	v_mov_b32_e32 v40, v0
	v_mov_b32_e32 v41, v0
	v_mov_b32_e32 v42, v0
	v_mov_b32_e32 v43, v0
	v_mov_b32_e32 v48, v0
	v_mov_b32_e32 v49, v0
	v_mov_b32_e32 v50, v0
	v_mov_b32_e32 v51, v0
	v_mov_b32_e32 v56, v0
	v_mov_b32_e32 v57, v0
	v_mov_b32_e32 v58, v0
	v_mov_b32_e32 v59, v0
	v_mov_b32_e32 v60, v0
	v_mov_b32_e32 v61, v0
	v_mov_b32_e32 v62, v0
	v_mov_b32_e32 v63, v0
	v_mov_b32_e32 v64, v0
	v_mov_b32_e32 v65, v0
	v_mov_b32_e32 v66, v0
	v_mov_b32_e32 v67, v0
	v_mov_b32_e32 v68, v0
	v_mov_b32_e32 v69, v0
	v_mov_b32_e32 v70, v0
	v_mov_b32_e32 v71, v0
	v_mov_b32_e32 v76, v0
	v_mov_b32_e32 v77, v0
	v_mov_b32_e32 v78, v0
	v_mov_b32_e32 v79, v0
	v_mov_b32_e32 v84, v0
	v_mov_b32_e32 v85, v0
	v_mov_b32_e32 v86, v0
	v_mov_b32_e32 v87, v0
	v_mov_b32_e32 v92, v0
	v_mov_b32_e32 v93, v0
	v_mov_b32_e32 v94, v0
	v_mov_b32_e32 v95, v0
	v_mov_b32_e32 v100, v0
	v_mov_b32_e32 v101, v0
	v_mov_b32_e32 v102, v0
	v_mov_b32_e32 v103, v0
	v_mov_b32_e32 v108, v0
	v_mov_b32_e32 v109, v0
	v_mov_b32_e32 v110, v0
	v_mov_b32_e32 v111, v0
	v_mov_b32_e32 v116, v0
	v_mov_b32_e32 v117, v0
	v_mov_b32_e32 v118, v0
	v_mov_b32_e32 v119, v0
	v_mov_b32_e32 v72, v0
	v_mov_b32_e32 v73, v0
	v_mov_b32_e32 v74, v0
	v_mov_b32_e32 v75, v0
	v_mov_b32_e32 v80, v0
	v_mov_b32_e32 v81, v0
	v_mov_b32_e32 v82, v0
	v_mov_b32_e32 v83, v0
	v_mov_b32_e32 v88, v0
	v_mov_b32_e32 v89, v0
	v_mov_b32_e32 v90, v0
	v_mov_b32_e32 v91, v0
	v_mov_b32_e32 v96, v0
	v_mov_b32_e32 v97, v0
	v_mov_b32_e32 v98, v0
	v_mov_b32_e32 v99, v0
	v_mov_b32_e32 v104, v0
	v_mov_b32_e32 v105, v0
	v_mov_b32_e32 v106, v0
	v_mov_b32_e32 v107, v0
	v_mov_b32_e32 v112, v0
	v_mov_b32_e32 v113, v0
	v_mov_b32_e32 v114, v0
	v_mov_b32_e32 v115, v0
	v_mov_b32_e32 v120, v0
	v_mov_b32_e32 v121, v0
	v_mov_b32_e32 v122, v0
	v_mov_b32_e32 v123, v0
	v_mov_b32_e32 v124, v0
	v_mov_b32_e32 v125, v0
	v_mov_b32_e32 v126, v0
	v_mov_b32_e32 v127, v0
	s_cmp_lt_u32 s75, 4
	s_cbranch_scc1 .Lkprio_skip_15
	s_setprio 1
.Lkprio_skip_15:
.LBB0_1405:
	ds_read_b128 v[144:147], v155
	ds_read_b128 v[158:161], v155 offset:1024
	ds_read_b128 v[162:165], v155 offset:2048
	ds_read_b128 v[166:169], v155 offset:3072
	ds_read_b128 v[170:173], v156
	ds_read_b128 v[174:177], v156 offset:1024
	ds_read_b128 v[178:181], v156 offset:2048
	ds_read_b128 v[182:185], v156 offset:3072
	s_add_u32 s22, s20, 0xfff80080
	s_addc_u32 s23, s21, -1
	s_cmp_eq_u32 s53, 28
	s_cselect_b32 s25, s13, s23
	s_cselect_b32 s24, s49, s22
	s_cselect_b32 s23, s11, s52
	s_cselect_b32 s22, s50, s51
	v_lshl_add_u64 v[218:219], s[20:21], 0, v[138:139]
	s_add_i32 m0, s19, 0xc000
	ds_read_b128 v[186:189], v157
	ds_read_b128 v[190:193], v157 offset:1024
	ds_read_b128 v[194:197], v157 offset:2048
	ds_read_b128 v[198:201], v157 offset:3072
	ds_read_b128 v[202:205], v157 offset:4096
	ds_read_b128 v[206:209], v157 offset:5120
	ds_read_b128 v[210:213], v157 offset:6144
	ds_read_b128 v[214:217], v157 offset:7168
	global_load_lds_dwordx4 v[218:219], off
	v_lshl_add_u64 v[218:219], s[20:21], 0, v[136:137]
	s_add_i32 m0, s19, 0xe000
	s_nop 0
	global_load_lds_dwordx4 v[218:219], off
	s_waitcnt vmcnt(8)
	s_waitcnt lgkmcnt(0)
	s_barrier
; #define PG8_STAGE(bufoff, gbase, voff) do { _Pragma("unroll") for (int _i = 0; _i < 2; ++_i) \
;         __builtin_amdgcn_global_load_lds((const unsigned*)((const char*)(gbase) + (voff)[_i]), (PG8_LAS unsigned*)(lds + (bufoff) + ldsw + _i * 8192), 16, 0, 0); } while (0)
; #define PG8_LDA(dst, b, h) do { _Pragma("unroll") for (int m = 0; m < 4; ++m) _Pragma("unroll") for (int k = 0; k < 2; ++k) dst[m][k] = *(const PG8_LAS bf16x8*)(lds + PG8_SA(b, h) + aoff + m * 2048 + k * 1024); } while (0)
; #define PG8_MMA(ai, bj, At, Bt) do { __builtin_amdgcn_s_setprio(1); _Pragma("unroll") for (int m = 0; m < 4; ++m) _Pragma("unroll") for (int n = 0; n < 2; ++n) _Pragma("unroll") for (int k = 0; k < 2; ++k) \
;         acc[ai][bj][m][n] = __builtin_amdgcn_mfma_f32_16x16x32_bf16(Bt[n][k], At[m][k], acc[ai][bj][m][n], 0, 0, 0); __builtin_amdgcn_s_setprio(0); } while (0)
; #define PG8_WAIT_V(n) asm volatile("s_waitcnt vmcnt(" #n ")" ::: "memory")
; #define PG8_WAIT_L(n) asm volatile("s_waitcnt lgkmcnt(" #n ")" ::: "memory")
; #define PG8_BAR __builtin_amdgcn_s_barrier()
; #define PG8_SCHED __builtin_amdgcn_sched_barrier(0)
; template <class Epi, class Sched, bool ALIGN_EPI = false, bool SP2 = false>
; __device__ __forceinline__ void gemm_phase(PG8_LAS unsigned char* lds, const Gemm g, const Sched& S, const Epi& E, const int tid_in) {
;     ...
;             PG8_WAIT_V(8); PG8_WAIT_L(0); PG8_BAR; PG8_MMA(0, 0, At, B0); PG8_MMA(0, 1, At, B1); PG8_BAR; PG8_SCHED;
;             PG8_LDA(At, 0, 1); PG8_STAGE(PG8_SB(0, 0), b2, voffB); PG8_STAGE(PG8_SB(0, 1), b2 + hstep, voffB); PG8_STAGE(PG8_SA(0, 0), a2, voffA);
;             PG8_WAIT_V(8); PG8_WAIT_L(0); PG8_BAR; PG8_MMA(1, 0, At, B0); PG8_MMA(1, 1, At, B1); PG8_BAR; PG8_SCHED;
	v_mfma_f32_16x16x32_bf16 v[124:127], v[144:147], v[186:189], v[124:127]
	v_mfma_f32_16x16x32_bf16 v[120:123], v[162:165], v[186:189], v[120:123]
	v_mfma_f32_16x16x32_bf16 v[112:115], v[144:147], v[194:197], v[112:115]
	v_mfma_f32_16x16x32_bf16 v[104:107], v[162:165], v[194:197], v[104:107]
	v_mfma_f32_16x16x32_bf16 v[96:99], v[144:147], v[202:205], v[96:99]
	v_mfma_f32_16x16x32_bf16 v[88:91], v[162:165], v[202:205], v[88:91]
	v_mfma_f32_16x16x32_bf16 v[80:83], v[144:147], v[210:213], v[80:83]
	v_mfma_f32_16x16x32_bf16 v[72:75], v[162:165], v[210:213], v[72:75]
	v_mfma_f32_16x16x32_bf16 v[124:127], v[158:161], v[190:193], v[124:127]
	v_mfma_f32_16x16x32_bf16 v[120:123], v[166:169], v[190:193], v[120:123]
	v_mfma_f32_16x16x32_bf16 v[112:115], v[158:161], v[198:201], v[112:115]
	v_mfma_f32_16x16x32_bf16 v[104:107], v[166:169], v[198:201], v[104:107]
	v_mfma_f32_16x16x32_bf16 v[96:99], v[158:161], v[206:209], v[96:99]
	v_mfma_f32_16x16x32_bf16 v[88:91], v[166:169], v[206:209], v[88:91]
	v_mfma_f32_16x16x32_bf16 v[80:83], v[158:161], v[214:217], v[80:83]
	v_mfma_f32_16x16x32_bf16 v[72:75], v[166:169], v[214:217], v[72:75]
	v_mfma_f32_16x16x32_bf16 v[116:119], v[170:173], v[186:189], v[116:119]
	v_mfma_f32_16x16x32_bf16 v[108:111], v[178:181], v[186:189], v[108:111]
	v_mfma_f32_16x16x32_bf16 v[100:103], v[170:173], v[194:197], v[100:103]
	v_mfma_f32_16x16x32_bf16 v[92:95], v[178:181], v[194:197], v[92:95]
	v_mfma_f32_16x16x32_bf16 v[84:87], v[170:173], v[202:205], v[84:87]
	v_mfma_f32_16x16x32_bf16 v[76:79], v[178:181], v[202:205], v[76:79]
	v_mfma_f32_16x16x32_bf16 v[68:71], v[170:173], v[210:213], v[68:71]
	v_mfma_f32_16x16x32_bf16 v[64:67], v[178:181], v[210:213], v[64:67]
	v_mfma_f32_16x16x32_bf16 v[116:119], v[174:177], v[190:193], v[116:119]
	v_mfma_f32_16x16x32_bf16 v[108:111], v[182:185], v[190:193], v[108:111]
	v_mfma_f32_16x16x32_bf16 v[100:103], v[174:177], v[198:201], v[100:103]
	v_mfma_f32_16x16x32_bf16 v[92:95], v[182:185], v[198:201], v[92:95]
	v_mfma_f32_16x16x32_bf16 v[84:87], v[174:177], v[206:209], v[84:87]
	v_mfma_f32_16x16x32_bf16 v[76:79], v[182:185], v[206:209], v[76:79]
	v_mfma_f32_16x16x32_bf16 v[68:71], v[174:177], v[214:217], v[68:71]
	v_mfma_f32_16x16x32_bf16 v[64:67], v[182:185], v[214:217], v[64:67]
	s_barrier
	s_add_i32 s54, s41, s30
	v_lshl_add_u64 v[218:219], s[22:23], 0, v[132:133]
	s_mov_b32 m0, s54
	ds_read_b128 v[186:189], v157 offset:16384
	ds_read_b128 v[190:193], v157 offset:17408
	ds_read_b128 v[194:197], v157 offset:18432
	ds_read_b128 v[198:201], v157 offset:19456
	ds_read_b128 v[202:205], v157 offset:20480
	ds_read_b128 v[206:209], v157 offset:21504
	ds_read_b128 v[210:213], v157 offset:22528
	ds_read_b128 v[214:217], v157 offset:23552
	global_load_lds_dwordx4 v[218:219], off
	s_add_i32 m0, s54, 0x2000
	s_add_u32 s54, s22, 0x80000
	v_lshl_add_u64 v[220:221], s[22:23], 0, v[128:129]
	s_addc_u32 s55, s23, 0
	s_add_i32 s56, s42, s30
	global_load_lds_dwordx4 v[220:221], off
	v_lshl_add_u64 v[222:223], s[54:55], 0, v[132:133]
	s_mov_b32 m0, s56
	v_lshl_add_u64 v[224:225], s[24:25], 0, v[130:131]
	global_load_lds_dwordx4 v[222:223], off
	v_lshl_add_u64 v[222:223], s[54:55], 0, v[128:129]
	s_add_i32 m0, s56, 0x2000
	s_nop 0
	global_load_lds_dwordx4 v[222:223], off
	v_lshl_add_u64 v[222:223], s[24:25], 0, v[134:135]
	s_mov_b32 m0, s19
	s_nop 0
	global_load_lds_dwordx4 v[222:223], off
	s_mov_b32 m0, s34
	s_nop 0
	global_load_lds_dwordx4 v[224:225], off
	s_waitcnt vmcnt(8)
	s_waitcnt lgkmcnt(0)
	s_barrier
	v_mfma_f32_16x16x32_bf16 v[60:63], v[144:147], v[186:189], v[60:63]
	v_mfma_f32_16x16x32_bf16 v[56:59], v[162:165], v[186:189], v[56:59]
	v_mfma_f32_16x16x32_bf16 v[48:51], v[144:147], v[194:197], v[48:51]
	v_mfma_f32_16x16x32_bf16 v[40:43], v[162:165], v[194:197], v[40:43]
	v_mfma_f32_16x16x32_bf16 v[32:35], v[144:147], v[202:205], v[32:35]
	v_mfma_f32_16x16x32_bf16 v[24:27], v[162:165], v[202:205], v[24:27]
	v_mfma_f32_16x16x32_bf16 v[12:15], v[144:147], v[210:213], v[12:15]
	v_mfma_f32_16x16x32_bf16 v[8:11], v[162:165], v[210:213], v[8:11]
	v_mfma_f32_16x16x32_bf16 v[60:63], v[158:161], v[190:193], v[60:63]
	v_mfma_f32_16x16x32_bf16 v[56:59], v[166:169], v[190:193], v[56:59]
	v_mfma_f32_16x16x32_bf16 v[48:51], v[158:161], v[198:201], v[48:51]
	v_mfma_f32_16x16x32_bf16 v[40:43], v[166:169], v[198:201], v[40:43]
	v_mfma_f32_16x16x32_bf16 v[32:35], v[158:161], v[206:209], v[32:35]
	v_mfma_f32_16x16x32_bf16 v[24:27], v[166:169], v[206:209], v[24:27]
	v_mfma_f32_16x16x32_bf16 v[12:15], v[158:161], v[214:217], v[12:15]
	v_mfma_f32_16x16x32_bf16 v[8:11], v[166:169], v[214:217], v[8:11]
	v_mfma_f32_16x16x32_bf16 v[52:55], v[170:173], v[186:189], v[52:55]
	v_mfma_f32_16x16x32_bf16 v[44:47], v[178:181], v[186:189], v[44:47]
	v_mfma_f32_16x16x32_bf16 v[36:39], v[170:173], v[194:197], v[36:39]
	v_mfma_f32_16x16x32_bf16 v[28:31], v[178:181], v[194:197], v[28:31]
	v_mfma_f32_16x16x32_bf16 v[20:23], v[170:173], v[202:205], v[20:23]
	v_mfma_f32_16x16x32_bf16 v[16:19], v[178:181], v[202:205], v[16:19]
	v_mfma_f32_16x16x32_bf16 v[4:7], v[170:173], v[210:213], v[4:7]
	v_mfma_f32_16x16x32_bf16 v[0:3], v[178:181], v[210:213], v[0:3]
	v_mfma_f32_16x16x32_bf16 v[52:55], v[174:177], v[190:193], v[52:55]
	v_mfma_f32_16x16x32_bf16 v[44:47], v[182:185], v[190:193], v[44:47]
	v_mfma_f32_16x16x32_bf16 v[36:39], v[174:177], v[198:201], v[36:39]
	v_mfma_f32_16x16x32_bf16 v[28:31], v[182:185], v[198:201], v[28:31]
	v_mfma_f32_16x16x32_bf16 v[20:23], v[174:177], v[206:209], v[20:23]
	v_mfma_f32_16x16x32_bf16 v[16:19], v[182:185], v[206:209], v[16:19]
	v_mfma_f32_16x16x32_bf16 v[4:7], v[174:177], v[214:217], v[4:7]
	v_mfma_f32_16x16x32_bf16 v[0:3], v[182:185], v[214:217], v[0:3]
	s_barrier
; #define PG8_STAGE(bufoff, gbase, voff) do { _Pragma("unroll") for (int _i = 0; _i < 2; ++_i) \
;         __builtin_amdgcn_global_load_lds((const unsigned*)((const char*)(gbase) + (voff)[_i]), (PG8_LAS unsigned*)(lds + (bufoff) + ldsw + _i * 8192), 16, 0, 0); } while (0)
; #define PG8_LDA(dst, b, h) do { _Pragma("unroll") for (int m = 0; m < 4; ++m) _Pragma("unroll") for (int k = 0; k < 2; ++k) dst[m][k] = *(const PG8_LAS bf16x8*)(lds + PG8_SA(b, h) + aoff + m * 2048 + k * 1024); } while (0)
; #define PG8_LDB(dst, b, h) do { _Pragma("unroll") for (int n = 0; n < 2; ++n) _Pragma("unroll") for (int k = 0; k < 2; ++k) dst[n][k] = *(const PG8_LAS bf16x8*)(lds + PG8_SB(b, h) + boff + n * 2048 + k * 1024); } while (0)
; #define PG8_MMA(ai, bj, At, Bt) do { __builtin_amdgcn_s_setprio(1); _Pragma("unroll") for (int m = 0; m < 4; ++m) _Pragma("unroll") for (int n = 0; n < 2; ++n) _Pragma("unroll") for (int k = 0; k < 2; ++k) \
;         acc[ai][bj][m][n] = __builtin_amdgcn_mfma_f32_16x16x32_bf16(Bt[n][k], At[m][k], acc[ai][bj][m][n], 0, 0, 0); __builtin_amdgcn_s_setprio(0); } while (0)
; #define PG8_WAIT_V(n) asm volatile("s_waitcnt vmcnt(" #n ")" ::: "memory")
; #define PG8_WAIT_L(n) asm volatile("s_waitcnt lgkmcnt(" #n ")" ::: "memory")
; #define PG8_BAR __builtin_amdgcn_s_barrier()
; #define PG8_SCHED __builtin_amdgcn_sched_barrier(0)
; template <class Epi, class Sched, bool ALIGN_EPI = false, bool SP2 = false>
; __device__ __forceinline__ void gemm_phase(PG8_LAS unsigned char* lds, const Gemm g, const Sched& S, const Epi& E, const int tid_in) {
;     ...
;             PG8_LDB(B0, 1, 0); PG8_LDB(B1, 1, 1); PG8_SCHED; PG8_LDA(At, 1, 0); PG8_STAGE(PG8_SA(0, 1), a2 + hstepA, voffA);
;             PG8_WAIT_V(8); PG8_WAIT_L(0); PG8_BAR; PG8_MMA(0, 0, At, B0); PG8_MMA(0, 1, At, B1); PG8_BAR; PG8_SCHED;
	s_add_i32 s54, 0, 0x18000
	v_add_u32_e32 v148, s54, v151
	s_add_i32 s55, 0, 0x1c000
	ds_read_b128 v[144:147], v148
	ds_read_b128 v[158:161], v148 offset:1024
	ds_read_b128 v[162:165], v148 offset:2048
	ds_read_b128 v[166:169], v148 offset:3072
	v_add_u32_e32 v148, s55, v151
	ds_read_b128 v[170:173], v148
	ds_read_b128 v[174:177], v148 offset:1024
	ds_read_b128 v[178:181], v148 offset:2048
	ds_read_b128 v[182:185], v148 offset:3072
	s_add_u32 s24, s24, 0x80000
	s_addc_u32 s25, s25, 0
	s_mov_b32 m0, s35
	v_lshl_add_u64 v[226:227], s[24:25], 0, v[134:135]
	ds_read_b128 v[186:189], v157 offset:32768
	ds_read_b128 v[190:193], v157 offset:33792
	ds_read_b128 v[194:197], v157 offset:34816
	ds_read_b128 v[198:201], v157 offset:35840
	ds_read_b128 v[202:205], v157 offset:36864
	ds_read_b128 v[206:209], v157 offset:37888
	ds_read_b128 v[210:213], v157 offset:38912
	ds_read_b128 v[214:217], v157 offset:39936
	global_load_lds_dwordx4 v[226:227], off
	v_lshl_add_u64 v[226:227], s[24:25], 0, v[130:131]
	s_mov_b32 m0, s36
	s_nop 0
	global_load_lds_dwordx4 v[226:227], off
	s_waitcnt vmcnt(8)
	s_waitcnt lgkmcnt(0)
	s_barrier
	v_mfma_f32_16x16x32_bf16 v[124:127], v[144:147], v[186:189], v[124:127]
	v_mfma_f32_16x16x32_bf16 v[120:123], v[162:165], v[186:189], v[120:123]
	v_mfma_f32_16x16x32_bf16 v[112:115], v[144:147], v[194:197], v[112:115]
	v_mfma_f32_16x16x32_bf16 v[104:107], v[162:165], v[194:197], v[104:107]
	v_mfma_f32_16x16x32_bf16 v[96:99], v[144:147], v[202:205], v[96:99]
	v_mfma_f32_16x16x32_bf16 v[88:91], v[162:165], v[202:205], v[88:91]
	v_mfma_f32_16x16x32_bf16 v[80:83], v[144:147], v[210:213], v[80:83]
	v_mfma_f32_16x16x32_bf16 v[72:75], v[162:165], v[210:213], v[72:75]
	v_mfma_f32_16x16x32_bf16 v[124:127], v[158:161], v[190:193], v[124:127]
	v_mfma_f32_16x16x32_bf16 v[120:123], v[166:169], v[190:193], v[120:123]
	v_mfma_f32_16x16x32_bf16 v[112:115], v[158:161], v[198:201], v[112:115]
	v_mfma_f32_16x16x32_bf16 v[104:107], v[166:169], v[198:201], v[104:107]
	v_mfma_f32_16x16x32_bf16 v[96:99], v[158:161], v[206:209], v[96:99]
	v_mfma_f32_16x16x32_bf16 v[88:91], v[166:169], v[206:209], v[88:91]
	v_mfma_f32_16x16x32_bf16 v[80:83], v[158:161], v[214:217], v[80:83]
	v_mfma_f32_16x16x32_bf16 v[72:75], v[166:169], v[214:217], v[72:75]
	v_mfma_f32_16x16x32_bf16 v[116:119], v[170:173], v[186:189], v[116:119]
	v_mfma_f32_16x16x32_bf16 v[108:111], v[178:181], v[186:189], v[108:111]
	v_mfma_f32_16x16x32_bf16 v[100:103], v[170:173], v[194:197], v[100:103]
	v_mfma_f32_16x16x32_bf16 v[92:95], v[178:181], v[194:197], v[92:95]
	v_mfma_f32_16x16x32_bf16 v[84:87], v[170:173], v[202:205], v[84:87]
	v_mfma_f32_16x16x32_bf16 v[76:79], v[178:181], v[202:205], v[76:79]
	v_mfma_f32_16x16x32_bf16 v[68:71], v[170:173], v[210:213], v[68:71]
	v_mfma_f32_16x16x32_bf16 v[64:67], v[178:181], v[210:213], v[64:67]
	v_mfma_f32_16x16x32_bf16 v[116:119], v[174:177], v[190:193], v[116:119]
	v_mfma_f32_16x16x32_bf16 v[108:111], v[182:185], v[190:193], v[108:111]
	v_mfma_f32_16x16x32_bf16 v[100:103], v[174:177], v[198:201], v[100:103]
	v_mfma_f32_16x16x32_bf16 v[92:95], v[182:185], v[198:201], v[92:95]
	v_mfma_f32_16x16x32_bf16 v[84:87], v[174:177], v[206:209], v[84:87]
	v_mfma_f32_16x16x32_bf16 v[76:79], v[182:185], v[206:209], v[76:79]
	v_mfma_f32_16x16x32_bf16 v[68:71], v[174:177], v[214:217], v[68:71]
	v_mfma_f32_16x16x32_bf16 v[64:67], v[182:185], v[214:217], v[64:67]
	s_barrier
; #define PG8_STAGE(bufoff, gbase, voff) do { _Pragma("unroll") for (int _i = 0; _i < 2; ++_i) \
;         __builtin_amdgcn_global_load_lds((const unsigned*)((const char*)(gbase) + (voff)[_i]), (PG8_LAS unsigned*)(lds + (bufoff) + ldsw + _i * 8192), 16, 0, 0); } while (0)
; #define PG8_LDA(dst, b, h) do { _Pragma("unroll") for (int m = 0; m < 4; ++m) _Pragma("unroll") for (int k = 0; k < 2; ++k) dst[m][k] = *(const PG8_LAS bf16x8*)(lds + PG8_SA(b, h) + aoff + m * 2048 + k * 1024); } while (0)
; #define PG8_MMA(ai, bj, At, Bt) do { __builtin_amdgcn_s_setprio(1); _Pragma("unroll") for (int m = 0; m < 4; ++m) _Pragma("unroll") for (int n = 0; n < 2; ++n) _Pragma("unroll") for (int k = 0; k < 2; ++k) \
;         acc[ai][bj][m][n] = __builtin_amdgcn_mfma_f32_16x16x32_bf16(Bt[n][k], At[m][k], acc[ai][bj][m][n], 0, 0, 0); __builtin_amdgcn_s_setprio(0); } while (0)
; #define PG8_WAIT_V(n) asm volatile("s_waitcnt vmcnt(" #n ")" ::: "memory")
; #define PG8_WAIT_L(n) asm volatile("s_waitcnt lgkmcnt(" #n ")" ::: "memory")
; #define PG8_BAR __builtin_amdgcn_s_barrier()
; #define PG8_SCHED __builtin_amdgcn_sched_barrier(0)
; template <class Epi, class Sched, bool ALIGN_EPI = false, bool SP2 = false>
; __device__ __forceinline__ void gemm_phase(PG8_LAS unsigned char* lds, const Gemm g, const Sched& S, const Epi& E, const int tid_in) {
;     ...
;         for (int t = 0; t < nt; t += 2) {
;     ...
;             PG8_LDA(At, 1, 1); PG8_STAGE(PG8_SB(1, 0), b3, voffB); PG8_STAGE(PG8_SB(1, 1), b3 + hstep, voffB); PG8_STAGE(PG8_SA(1, 0), a3, voffA);
;             PG8_WAIT_V(8); PG8_WAIT_L(0); PG8_BAR; PG8_MMA(1, 0, At, B0); PG8_MMA(1, 1, At, B1); PG8_BAR; PG8_SCHED;
	s_add_i32 s24, s54, s30
	v_lshl_add_u64 v[218:219], v[218:219], 0, s[6:7]
	s_mov_b32 m0, s24
	ds_read_b128 v[186:189], v157 offset:49152
	ds_read_b128 v[190:193], v157 offset:50176
	ds_read_b128 v[194:197], v157 offset:51200
	ds_read_b128 v[198:201], v157 offset:52224
	ds_read_b128 v[202:205], v157 offset:53248
	ds_read_b128 v[206:209], v157 offset:54272
	ds_read_b128 v[210:213], v157 offset:55296
	ds_read_b128 v[214:217], v157 offset:56320
	global_load_lds_dwordx4 v[218:219], off
	s_add_i32 m0, s24, 0x2000
	s_add_u32 s22, s22, 0x80080
	v_lshl_add_u64 v[218:219], v[220:221], 0, s[6:7]
	s_addc_u32 s23, s23, 0
	s_add_i32 s24, s55, s30
	global_load_lds_dwordx4 v[218:219], off
	v_lshl_add_u64 v[218:219], s[22:23], 0, v[132:133]
	s_mov_b32 m0, s24
	s_nop 0
	global_load_lds_dwordx4 v[218:219], off
	v_lshl_add_u64 v[218:219], s[22:23], 0, v[128:129]
	s_add_i32 m0, s24, 0x2000
	s_nop 0
	global_load_lds_dwordx4 v[218:219], off
	v_lshl_add_u64 v[218:219], v[222:223], 0, s[6:7]
	s_mov_b32 m0, s38
	s_nop 0
	global_load_lds_dwordx4 v[218:219], off
	v_lshl_add_u64 v[218:219], v[224:225], 0, s[6:7]
	s_mov_b32 m0, s39
	s_nop 0
	global_load_lds_dwordx4 v[218:219], off
	s_waitcnt vmcnt(8)
	s_waitcnt lgkmcnt(0)
	s_barrier
	v_mfma_f32_16x16x32_bf16 v[60:63], v[144:147], v[186:189], v[60:63]
	v_mfma_f32_16x16x32_bf16 v[56:59], v[162:165], v[186:189], v[56:59]
	v_mfma_f32_16x16x32_bf16 v[48:51], v[144:147], v[194:197], v[48:51]
	v_mfma_f32_16x16x32_bf16 v[40:43], v[162:165], v[194:197], v[40:43]
	v_mfma_f32_16x16x32_bf16 v[32:35], v[144:147], v[202:205], v[32:35]
	v_mfma_f32_16x16x32_bf16 v[24:27], v[162:165], v[202:205], v[24:27]
	v_mfma_f32_16x16x32_bf16 v[12:15], v[144:147], v[210:213], v[12:15]
	v_mfma_f32_16x16x32_bf16 v[8:11], v[162:165], v[210:213], v[8:11]
	v_mfma_f32_16x16x32_bf16 v[60:63], v[158:161], v[190:193], v[60:63]
	v_mfma_f32_16x16x32_bf16 v[56:59], v[166:169], v[190:193], v[56:59]
	v_mfma_f32_16x16x32_bf16 v[48:51], v[158:161], v[198:201], v[48:51]
	v_mfma_f32_16x16x32_bf16 v[40:43], v[166:169], v[198:201], v[40:43]
	v_mfma_f32_16x16x32_bf16 v[32:35], v[158:161], v[206:209], v[32:35]
	v_mfma_f32_16x16x32_bf16 v[24:27], v[166:169], v[206:209], v[24:27]
	v_mfma_f32_16x16x32_bf16 v[12:15], v[158:161], v[214:217], v[12:15]
	v_mfma_f32_16x16x32_bf16 v[8:11], v[166:169], v[214:217], v[8:11]
	v_mfma_f32_16x16x32_bf16 v[52:55], v[170:173], v[186:189], v[52:55]
	v_mfma_f32_16x16x32_bf16 v[44:47], v[178:181], v[186:189], v[44:47]
	v_mfma_f32_16x16x32_bf16 v[36:39], v[170:173], v[194:197], v[36:39]
	v_mfma_f32_16x16x32_bf16 v[28:31], v[178:181], v[194:197], v[28:31]
	v_mfma_f32_16x16x32_bf16 v[20:23], v[170:173], v[202:205], v[20:23]
	v_mfma_f32_16x16x32_bf16 v[16:19], v[178:181], v[202:205], v[16:19]
	v_mfma_f32_16x16x32_bf16 v[4:7], v[170:173], v[210:213], v[4:7]
	v_mfma_f32_16x16x32_bf16 v[0:3], v[178:181], v[210:213], v[0:3]
	v_mfma_f32_16x16x32_bf16 v[52:55], v[174:177], v[190:193], v[52:55]
	v_mfma_f32_16x16x32_bf16 v[44:47], v[182:185], v[190:193], v[44:47]
	v_mfma_f32_16x16x32_bf16 v[36:39], v[174:177], v[198:201], v[36:39]
	v_mfma_f32_16x16x32_bf16 v[28:31], v[182:185], v[198:201], v[28:31]
	v_mfma_f32_16x16x32_bf16 v[20:23], v[174:177], v[206:209], v[20:23]
	v_mfma_f32_16x16x32_bf16 v[16:19], v[182:185], v[206:209], v[16:19]
	v_mfma_f32_16x16x32_bf16 v[4:7], v[174:177], v[214:217], v[4:7]
	v_mfma_f32_16x16x32_bf16 v[0:3], v[182:185], v[214:217], v[0:3]
	s_barrier
	s_add_i32 s53, s53, 2
	s_add_u32 s51, s51, 0x100
	s_addc_u32 s52, s52, 0
	s_add_u32 s20, s20, 0x100
	s_addc_u32 s21, s21, 0
	s_cmp_gt_u32 s53, 29
	s_cbranch_scc0 .LBB0_1405
	s_setprio 0
	s_and_b64 vcc, exec, s[8:9]
	s_cbranch_vccz .LBB0_1408
	s_barrier

; #define PG8_STAGE(bufoff, gbase, voff) do { _Pragma("unroll") for (int _i = 0; _i < 2; ++_i) \
;         __builtin_amdgcn_global_load_lds((const unsigned*)((const char*)(gbase) + (voff)[_i]), (PG8_LAS unsigned*)(lds + (bufoff) + ldsw + _i * 8192), 16, 0, 0); } while (0)
; #define PG8_LDA(dst, b, h) do { _Pragma("unroll") for (int m = 0; m < 4; ++m) _Pragma("unroll") for (int k = 0; k < 2; ++k) dst[m][k] = *(const PG8_LAS bf16x8*)(lds + PG8_SA(b, h) + aoff + m * 2048 + k * 1024); } while (0)
; #define PG8_LDB(dst, b, h) do { _Pragma("unroll") for (int n = 0; n < 2; ++n) _Pragma("unroll") for (int k = 0; k < 2; ++k) dst[n][k] = *(const PG8_LAS bf16x8*)(lds + PG8_SB(b, h) + boff + n * 2048 + k * 1024); } while (0)
; #define PG8_WAIT_V(n) asm volatile("s_waitcnt vmcnt(" #n ")" ::: "memory")
; #define PG8_WAIT_L(n) asm volatile("s_waitcnt lgkmcnt(" #n ")" ::: "memory")
; #define PG8_BAR __builtin_amdgcn_s_barrier()
; template <class Epi, class Sched, bool ALIGN_EPI = false, bool SP2 = false>
; __device__ __forceinline__ void gemm_phase(PG8_LAS unsigned char* lds, const Gemm g, const Sched& S, const Epi& E, const int tid_in) {
;     ...
;         const bool has_next = S.next(ui + 1, nxt);
;         const char* nA = has_next ? (const char*)g.A + (size_t)nxt.pm * tstepA : cA; const char* nB = has_next ? (const char*)g.Bt + (size_t)nxt.pn * tstep : cB;
;         for (int t = 0; t < nt; t += 2) {
;             const bool last = (t == nt - 2);
;             const char* a1 = cA + (size_t)(t + 1) * kstep;
;             const char* a2 = last ? nA : cA + (size_t)(t + 2) * kstep; const char* b2 = last ? nB : cB + (size_t)(t + 2) * kstep;
;             const char* a3 = a2 + kstep; const char* b3 = b2 + kstep;
;             if (last && has_next) S.a_ready(nxt);
;             if constexpr (SP2) {
;             PG8_LDB(B0, 0, 0); PG8_LDB(B1, 0, 1); PG8_SCHED; PG8_LDA(At, 0, 0); PG8_STAGE(PG8_SA(1, 1), a1 + hstepA, voffA);
;             PG8_WAIT_V(8); PG8_WAIT_L(0); PG8_BAR; PG8_MMA(0, 0, At, B0); PG8_MMA(0, 1, At, B1); PG8_BAR; PG8_SCHED;
;     ...
; #pragma unroll
;         for (int a = 0; a < 2; ++a)
; #pragma unroll
;             for (int b = 0; b < 2; ++b)
; #pragma unroll
;                 for (int m = 0; m < 4; ++m)
; #pragma unroll
;                     for (int n = 0; n < 2; ++n) acc[a][b][m][n] = (f32x4){0.f, 0.f, 0.f, 0.f};
;         cur = nxt; cA = nA; cB = nB; ++ui;
.LBB0_1486:
	s_ashr_i32 s35, s34, 31
	s_lshl_b64 s[36:37], s[34:35], 20
	s_add_u32 s36, s8, s36
	s_addc_u32 s37, s9, s37
	s_and_b64 s[38:39], s[0:1], exec
	s_cselect_b32 s35, s37, s43
	s_cselect_b32 s61, s36, s42
	s_ashr_i32 s31, s30, 31
	s_lshl_b64 s[38:39], s[30:31], 20
	s_add_u32 s38, s46, s38
	s_addc_u32 s39, s47, s39
	s_and_b64 s[44:45], s[0:1], exec
	s_cselect_b32 s31, s39, s41
	s_cselect_b32 s62, s38, s40
	s_add_u32 s63, s40, 0x100
	s_addc_u32 s64, s41, 0
	s_add_u32 s40, s42, 0x80080
	v_mov_b32_e32 v0, 0
	s_addc_u32 s41, s43, 0
	s_mov_b32 s65, -2
	v_mov_b32_e32 v1, v0
	v_mov_b32_e32 v2, v0
	v_mov_b32_e32 v3, v0
	v_mov_b32_e32 v4, v0
	v_mov_b32_e32 v5, v0
	v_mov_b32_e32 v6, v0
	v_mov_b32_e32 v7, v0
	v_mov_b32_e32 v16, v0
	v_mov_b32_e32 v17, v0
	v_mov_b32_e32 v18, v0
	v_mov_b32_e32 v19, v0
	v_mov_b32_e32 v20, v0
	v_mov_b32_e32 v21, v0
	v_mov_b32_e32 v22, v0
	v_mov_b32_e32 v23, v0
	v_mov_b32_e32 v32, v0
	v_mov_b32_e32 v33, v0
	v_mov_b32_e32 v34, v0
	v_mov_b32_e32 v35, v0
	v_mov_b32_e32 v36, v0
	v_mov_b32_e32 v37, v0
	v_mov_b32_e32 v38, v0
	v_mov_b32_e32 v39, v0
	v_mov_b32_e32 v52, v0
	v_mov_b32_e32 v53, v0
	v_mov_b32_e32 v54, v0
	v_mov_b32_e32 v55, v0
	v_mov_b32_e32 v60, v0
	v_mov_b32_e32 v61, v0
	v_mov_b32_e32 v62, v0
	v_mov_b32_e32 v63, v0
	v_mov_b32_e32 v8, v0
	v_mov_b32_e32 v9, v0
	v_mov_b32_e32 v10, v0
	v_mov_b32_e32 v11, v0
	v_mov_b32_e32 v12, v0
	v_mov_b32_e32 v13, v0
	v_mov_b32_e32 v14, v0
	v_mov_b32_e32 v15, v0
	v_mov_b32_e32 v24, v0
	v_mov_b32_e32 v25, v0
	v_mov_b32_e32 v26, v0
	v_mov_b32_e32 v27, v0
	v_mov_b32_e32 v28, v0
	v_mov_b32_e32 v29, v0
	v_mov_b32_e32 v30, v0
	v_mov_b32_e32 v31, v0
	v_mov_b32_e32 v40, v0
	v_mov_b32_e32 v41, v0
	v_mov_b32_e32 v42, v0
	v_mov_b32_e32 v43, v0
	v_mov_b32_e32 v44, v0
	v_mov_b32_e32 v45, v0
	v_mov_b32_e32 v46, v0
	v_mov_b32_e32 v47, v0
	v_mov_b32_e32 v72, v0
	v_mov_b32_e32 v73, v0
	v_mov_b32_e32 v74, v0
	v_mov_b32_e32 v75, v0
	v_mov_b32_e32 v76, v0
	v_mov_b32_e32 v77, v0
	v_mov_b32_e32 v78, v0
	v_mov_b32_e32 v79, v0
	v_mov_b32_e32 v80, v0
	v_mov_b32_e32 v81, v0
	v_mov_b32_e32 v82, v0
	v_mov_b32_e32 v83, v0
	v_mov_b32_e32 v84, v0
	v_mov_b32_e32 v85, v0
	v_mov_b32_e32 v86, v0
	v_mov_b32_e32 v87, v0
	v_mov_b32_e32 v96, v0
	v_mov_b32_e32 v97, v0
	v_mov_b32_e32 v98, v0
	v_mov_b32_e32 v99, v0
	v_mov_b32_e32 v100, v0
	v_mov_b32_e32 v101, v0
	v_mov_b32_e32 v102, v0
	v_mov_b32_e32 v103, v0
	v_mov_b32_e32 v112, v0
	v_mov_b32_e32 v113, v0
	v_mov_b32_e32 v114, v0
	v_mov_b32_e32 v115, v0
	v_mov_b32_e32 v116, v0
	v_mov_b32_e32 v117, v0
	v_mov_b32_e32 v118, v0
	v_mov_b32_e32 v119, v0
	v_mov_b32_e32 v128, v0
	v_mov_b32_e32 v129, v0
	v_mov_b32_e32 v130, v0
	v_mov_b32_e32 v131, v0
	v_mov_b32_e32 v132, v0
	v_mov_b32_e32 v133, v0
	v_mov_b32_e32 v134, v0
	v_mov_b32_e32 v135, v0
	v_mov_b32_e32 v88, v0
	v_mov_b32_e32 v89, v0
	v_mov_b32_e32 v90, v0
	v_mov_b32_e32 v91, v0
	v_mov_b32_e32 v92, v0
	v_mov_b32_e32 v93, v0
	v_mov_b32_e32 v94, v0
	v_mov_b32_e32 v95, v0
	v_mov_b32_e32 v104, v0
	v_mov_b32_e32 v105, v0
	v_mov_b32_e32 v106, v0
	v_mov_b32_e32 v107, v0
	v_mov_b32_e32 v108, v0
	v_mov_b32_e32 v109, v0
	v_mov_b32_e32 v110, v0
	v_mov_b32_e32 v111, v0
	v_mov_b32_e32 v120, v0
	v_mov_b32_e32 v121, v0
	v_mov_b32_e32 v122, v0
	v_mov_b32_e32 v123, v0
	v_mov_b32_e32 v124, v0
	v_mov_b32_e32 v125, v0
	v_mov_b32_e32 v126, v0
	v_mov_b32_e32 v127, v0
	v_mov_b32_e32 v136, v0
	v_mov_b32_e32 v137, v0
	v_mov_b32_e32 v138, v0
	v_mov_b32_e32 v139, v0
	v_mov_b32_e32 v140, v0
	v_mov_b32_e32 v141, v0
	v_mov_b32_e32 v142, v0
	v_mov_b32_e32 v143, v0
	s_cmp_lt_u32 s75, 4
	s_cbranch_scc1 .Lkprio_skip_17
	s_setprio 1
.Lkprio_skip_17:
.LBB0_1487:
	ds_read_b128 v[48:51], v205
	ds_read_b128 v[56:59], v205 offset:1024
	ds_read_b128 v[64:67], v205 offset:2048
	ds_read_b128 v[68:71], v205 offset:3072
	ds_read_b128 v[144:147], v206
	ds_read_b128 v[148:151], v206 offset:1024
	ds_read_b128 v[152:155], v206 offset:2048
	ds_read_b128 v[156:159], v206 offset:3072
	s_add_u32 s42, s40, 0xfff80080
	s_addc_u32 s43, s41, -1
	s_cmp_eq_u32 s65, 28
	s_cselect_b32 s45, s35, s43
	s_cselect_b32 s44, s61, s42
	s_cselect_b32 s43, s31, s64
	s_cselect_b32 s42, s62, s63
	v_lshl_add_u64 v[218:219], s[40:41], 0, v[180:181]
	s_add_i32 m0, s49, 0xc000
	ds_read_b128 v[160:163], v207
	ds_read_b128 v[164:167], v207 offset:1024
	ds_read_b128 v[186:189], v207 offset:2048
	ds_read_b128 v[190:193], v207 offset:3072
	ds_read_b128 v[194:197], v207 offset:4096
	ds_read_b128 v[198:201], v207 offset:5120
	ds_read_b128 v[210:213], v207 offset:6144
	ds_read_b128 v[214:217], v207 offset:7168
	global_load_lds_dwordx4 v[218:219], off
	v_lshl_add_u64 v[218:219], s[40:41], 0, v[178:179]
	s_add_i32 m0, s49, 0xe000
	s_nop 0
	global_load_lds_dwordx4 v[218:219], off
	s_waitcnt vmcnt(8)
	s_waitcnt lgkmcnt(0)
	s_barrier
; #define PG8_STAGE(bufoff, gbase, voff) do { _Pragma("unroll") for (int _i = 0; _i < 2; ++_i) \
;         __builtin_amdgcn_global_load_lds((const unsigned*)((const char*)(gbase) + (voff)[_i]), (PG8_LAS unsigned*)(lds + (bufoff) + ldsw + _i * 8192), 16, 0, 0); } while (0)
; #define PG8_LDA(dst, b, h) do { _Pragma("unroll") for (int m = 0; m < 4; ++m) _Pragma("unroll") for (int k = 0; k < 2; ++k) dst[m][k] = *(const PG8_LAS bf16x8*)(lds + PG8_SA(b, h) + aoff + m * 2048 + k * 1024); } while (0)
; #define PG8_MMA(ai, bj, At, Bt) do { __builtin_amdgcn_s_setprio(1); _Pragma("unroll") for (int m = 0; m < 4; ++m) _Pragma("unroll") for (int n = 0; n < 2; ++n) _Pragma("unroll") for (int k = 0; k < 2; ++k) \
;         acc[ai][bj][m][n] = __builtin_amdgcn_mfma_f32_16x16x32_bf16(Bt[n][k], At[m][k], acc[ai][bj][m][n], 0, 0, 0); __builtin_amdgcn_s_setprio(0); } while (0)
; #define PG8_WAIT_V(n) asm volatile("s_waitcnt vmcnt(" #n ")" ::: "memory")
; #define PG8_WAIT_L(n) asm volatile("s_waitcnt lgkmcnt(" #n ")" ::: "memory")
; #define PG8_BAR __builtin_amdgcn_s_barrier()
; #define PG8_SCHED __builtin_amdgcn_sched_barrier(0)
; template <class Epi, class Sched, bool ALIGN_EPI = false, bool SP2 = false>
; __device__ __forceinline__ void gemm_phase(PG8_LAS unsigned char* lds, const Gemm g, const Sched& S, const Epi& E, const int tid_in) {
;     ...
;             PG8_WAIT_V(8); PG8_WAIT_L(0); PG8_BAR; PG8_MMA(0, 0, At, B0); PG8_MMA(0, 1, At, B1); PG8_BAR; PG8_SCHED;
;             PG8_LDA(At, 0, 1); PG8_STAGE(PG8_SB(0, 0), b2, voffB); PG8_STAGE(PG8_SB(0, 1), b2 + hstep, voffB); PG8_STAGE(PG8_SA(0, 0), a2, voffA);
;             PG8_WAIT_V(8); PG8_WAIT_L(0); PG8_BAR; PG8_MMA(1, 0, At, B0); PG8_MMA(1, 1, At, B1); PG8_BAR; PG8_SCHED;
	v_mfma_f32_16x16x32_bf16 v[140:143], v[48:51], v[160:163], v[140:143]
	v_mfma_f32_16x16x32_bf16 v[136:139], v[64:67], v[160:163], v[136:139]
	v_mfma_f32_16x16x32_bf16 v[124:127], v[48:51], v[186:189], v[124:127]
	v_mfma_f32_16x16x32_bf16 v[120:123], v[64:67], v[186:189], v[120:123]
	v_mfma_f32_16x16x32_bf16 v[108:111], v[48:51], v[194:197], v[108:111]
	v_mfma_f32_16x16x32_bf16 v[104:107], v[64:67], v[194:197], v[104:107]
	v_mfma_f32_16x16x32_bf16 v[92:95], v[48:51], v[210:213], v[92:95]
	v_mfma_f32_16x16x32_bf16 v[88:91], v[64:67], v[210:213], v[88:91]
	v_mfma_f32_16x16x32_bf16 v[140:143], v[56:59], v[164:167], v[140:143]
	v_mfma_f32_16x16x32_bf16 v[136:139], v[68:71], v[164:167], v[136:139]
	v_mfma_f32_16x16x32_bf16 v[124:127], v[56:59], v[190:193], v[124:127]
	v_mfma_f32_16x16x32_bf16 v[120:123], v[68:71], v[190:193], v[120:123]
	v_mfma_f32_16x16x32_bf16 v[108:111], v[56:59], v[198:201], v[108:111]
	v_mfma_f32_16x16x32_bf16 v[104:107], v[68:71], v[198:201], v[104:107]
	v_mfma_f32_16x16x32_bf16 v[92:95], v[56:59], v[214:217], v[92:95]
	v_mfma_f32_16x16x32_bf16 v[88:91], v[68:71], v[214:217], v[88:91]
	v_mfma_f32_16x16x32_bf16 v[132:135], v[144:147], v[160:163], v[132:135]
	v_mfma_f32_16x16x32_bf16 v[128:131], v[152:155], v[160:163], v[128:131]
	v_mfma_f32_16x16x32_bf16 v[116:119], v[144:147], v[186:189], v[116:119]
	v_mfma_f32_16x16x32_bf16 v[112:115], v[152:155], v[186:189], v[112:115]
	v_mfma_f32_16x16x32_bf16 v[100:103], v[144:147], v[194:197], v[100:103]
	v_mfma_f32_16x16x32_bf16 v[96:99], v[152:155], v[194:197], v[96:99]
	v_mfma_f32_16x16x32_bf16 v[84:87], v[144:147], v[210:213], v[84:87]
	v_mfma_f32_16x16x32_bf16 v[80:83], v[152:155], v[210:213], v[80:83]
	v_mfma_f32_16x16x32_bf16 v[132:135], v[148:151], v[164:167], v[132:135]
	v_mfma_f32_16x16x32_bf16 v[128:131], v[156:159], v[164:167], v[128:131]
	v_mfma_f32_16x16x32_bf16 v[116:119], v[148:151], v[190:193], v[116:119]
	v_mfma_f32_16x16x32_bf16 v[112:115], v[156:159], v[190:193], v[112:115]
	v_mfma_f32_16x16x32_bf16 v[100:103], v[148:151], v[198:201], v[100:103]
	v_mfma_f32_16x16x32_bf16 v[96:99], v[156:159], v[198:201], v[96:99]
	v_mfma_f32_16x16x32_bf16 v[84:87], v[148:151], v[214:217], v[84:87]
	v_mfma_f32_16x16x32_bf16 v[80:83], v[156:159], v[214:217], v[80:83]
	s_barrier
	s_add_i32 s66, s57, s48
	v_lshl_add_u64 v[218:219], s[42:43], 0, v[170:171]
	s_mov_b32 m0, s66
	ds_read_b128 v[160:163], v207 offset:16384
	ds_read_b128 v[164:167], v207 offset:17408
	ds_read_b128 v[186:189], v207 offset:18432
	ds_read_b128 v[190:193], v207 offset:19456
	ds_read_b128 v[194:197], v207 offset:20480
	ds_read_b128 v[198:201], v207 offset:21504
	ds_read_b128 v[210:213], v207 offset:22528
	ds_read_b128 v[214:217], v207 offset:23552
	global_load_lds_dwordx4 v[218:219], off
	s_add_i32 m0, s66, 0x2000
	s_add_u32 s66, s42, 0x80000
	v_lshl_add_u64 v[220:221], s[42:43], 0, v[174:175]
	s_addc_u32 s67, s43, 0
	s_add_i32 s68, s58, s48
	global_load_lds_dwordx4 v[220:221], off
	v_lshl_add_u64 v[222:223], s[66:67], 0, v[170:171]
	s_mov_b32 m0, s68
	v_lshl_add_u64 v[224:225], s[44:45], 0, v[172:173]
	global_load_lds_dwordx4 v[222:223], off
	v_lshl_add_u64 v[222:223], s[66:67], 0, v[174:175]
	s_add_i32 m0, s68, 0x2000
	s_nop 0
	global_load_lds_dwordx4 v[222:223], off
	v_lshl_add_u64 v[222:223], s[44:45], 0, v[168:169]
	s_mov_b32 m0, s49
	s_nop 0
	global_load_lds_dwordx4 v[222:223], off
	s_mov_b32 m0, s50
	s_nop 0
	global_load_lds_dwordx4 v[224:225], off
	s_waitcnt vmcnt(8)
	s_waitcnt lgkmcnt(0)
	s_barrier
	v_mfma_f32_16x16x32_bf16 v[76:79], v[48:51], v[160:163], v[76:79]
	v_mfma_f32_16x16x32_bf16 v[72:75], v[64:67], v[160:163], v[72:75]
	v_mfma_f32_16x16x32_bf16 v[44:47], v[48:51], v[186:189], v[44:47]
	v_mfma_f32_16x16x32_bf16 v[40:43], v[64:67], v[186:189], v[40:43]
	v_mfma_f32_16x16x32_bf16 v[28:31], v[48:51], v[194:197], v[28:31]
	v_mfma_f32_16x16x32_bf16 v[24:27], v[64:67], v[194:197], v[24:27]
	v_mfma_f32_16x16x32_bf16 v[12:15], v[48:51], v[210:213], v[12:15]
	v_mfma_f32_16x16x32_bf16 v[8:11], v[64:67], v[210:213], v[8:11]
	v_mfma_f32_16x16x32_bf16 v[76:79], v[56:59], v[164:167], v[76:79]
	v_mfma_f32_16x16x32_bf16 v[72:75], v[68:71], v[164:167], v[72:75]
	v_mfma_f32_16x16x32_bf16 v[44:47], v[56:59], v[190:193], v[44:47]
	v_mfma_f32_16x16x32_bf16 v[40:43], v[68:71], v[190:193], v[40:43]
	v_mfma_f32_16x16x32_bf16 v[28:31], v[56:59], v[198:201], v[28:31]
	v_mfma_f32_16x16x32_bf16 v[24:27], v[68:71], v[198:201], v[24:27]
	v_mfma_f32_16x16x32_bf16 v[12:15], v[56:59], v[214:217], v[12:15]
	v_mfma_f32_16x16x32_bf16 v[8:11], v[68:71], v[214:217], v[8:11]
	v_mfma_f32_16x16x32_bf16 v[52:55], v[152:155], v[160:163], v[52:55]
	v_mfma_f32_16x16x32_bf16 v[36:39], v[144:147], v[186:189], v[36:39]
	v_mfma_f32_16x16x32_bf16 v[32:35], v[152:155], v[186:189], v[32:35]
	v_mfma_f32_16x16x32_bf16 v[20:23], v[144:147], v[194:197], v[20:23]
	v_mfma_f32_16x16x32_bf16 v[16:19], v[152:155], v[194:197], v[16:19]
	v_mfma_f32_16x16x32_bf16 v[4:7], v[144:147], v[210:213], v[4:7]
	v_mfma_f32_16x16x32_bf16 v[0:3], v[152:155], v[210:213], v[0:3]
	v_mfma_f32_16x16x32_bf16 v[48:51], v[144:147], v[160:163], v[60:63]
	v_mfma_f32_16x16x32_bf16 v[52:55], v[156:159], v[164:167], v[52:55]
	v_mfma_f32_16x16x32_bf16 v[36:39], v[148:151], v[190:193], v[36:39]
	v_mfma_f32_16x16x32_bf16 v[32:35], v[156:159], v[190:193], v[32:35]
	v_mfma_f32_16x16x32_bf16 v[20:23], v[148:151], v[198:201], v[20:23]
	v_mfma_f32_16x16x32_bf16 v[16:19], v[156:159], v[198:201], v[16:19]
	v_mfma_f32_16x16x32_bf16 v[4:7], v[148:151], v[214:217], v[4:7]
	v_mfma_f32_16x16x32_bf16 v[0:3], v[156:159], v[214:217], v[0:3]
	v_mfma_f32_16x16x32_bf16 v[48:51], v[148:151], v[164:167], v[48:51]
	s_barrier
; #define PG8_STAGE(bufoff, gbase, voff) do { _Pragma("unroll") for (int _i = 0; _i < 2; ++_i) \
;         __builtin_amdgcn_global_load_lds((const unsigned*)((const char*)(gbase) + (voff)[_i]), (PG8_LAS unsigned*)(lds + (bufoff) + ldsw + _i * 8192), 16, 0, 0); } while (0)
; #define PG8_LDA(dst, b, h) do { _Pragma("unroll") for (int m = 0; m < 4; ++m) _Pragma("unroll") for (int k = 0; k < 2; ++k) dst[m][k] = *(const PG8_LAS bf16x8*)(lds + PG8_SA(b, h) + aoff + m * 2048 + k * 1024); } while (0)
; #define PG8_LDB(dst, b, h) do { _Pragma("unroll") for (int n = 0; n < 2; ++n) _Pragma("unroll") for (int k = 0; k < 2; ++k) dst[n][k] = *(const PG8_LAS bf16x8*)(lds + PG8_SB(b, h) + boff + n * 2048 + k * 1024); } while (0)
; #define PG8_MMA(ai, bj, At, Bt) do { __builtin_amdgcn_s_setprio(1); _Pragma("unroll") for (int m = 0; m < 4; ++m) _Pragma("unroll") for (int n = 0; n < 2; ++n) _Pragma("unroll") for (int k = 0; k < 2; ++k) \
;         acc[ai][bj][m][n] = __builtin_amdgcn_mfma_f32_16x16x32_bf16(Bt[n][k], At[m][k], acc[ai][bj][m][n], 0, 0, 0); __builtin_amdgcn_s_setprio(0); } while (0)
; #define PG8_WAIT_V(n) asm volatile("s_waitcnt vmcnt(" #n ")" ::: "memory")
; #define PG8_WAIT_L(n) asm volatile("s_waitcnt lgkmcnt(" #n ")" ::: "memory")
; #define PG8_BAR __builtin_amdgcn_s_barrier()
; #define PG8_SCHED __builtin_amdgcn_sched_barrier(0)
; template <class Epi, class Sched, bool ALIGN_EPI = false, bool SP2 = false>
; __device__ __forceinline__ void gemm_phase(PG8_LAS unsigned char* lds, const Gemm g, const Sched& S, const Epi& E, const int tid_in) {
;     ...
;         for (int t = 0; t < nt; t += 2) {
;     ...
;             PG8_LDB(B0, 1, 0); PG8_LDB(B1, 1, 1); PG8_SCHED; PG8_LDA(At, 1, 0); PG8_STAGE(PG8_SA(0, 1), a2 + hstepA, voffA);
;             PG8_WAIT_V(8); PG8_WAIT_L(0); PG8_BAR; PG8_MMA(0, 0, At, B0); PG8_MMA(0, 1, At, B1); PG8_BAR; PG8_SCHED;
;             PG8_LDA(At, 1, 1); PG8_STAGE(PG8_SB(1, 0), b3, voffB); PG8_STAGE(PG8_SB(1, 1), b3 + hstep, voffB); PG8_STAGE(PG8_SA(1, 0), a3, voffA);
;             PG8_WAIT_V(8); PG8_WAIT_L(0); PG8_BAR; PG8_MMA(1, 0, At, B0); PG8_MMA(1, 1, At, B1); PG8_BAR; PG8_SCHED;
	s_add_i32 s66, 0, 0x18000
	s_add_i32 s67, 0, 0x1c000
	v_add_u32_e32 v68, s66, v203
	v_add_u32_e32 v156, s67, v203
	ds_read_b128 v[56:59], v68
	ds_read_b128 v[60:63], v68 offset:1024
	ds_read_b128 v[64:67], v68 offset:2048
	ds_read_b128 v[68:71], v68 offset:3072
	ds_read_b128 v[144:147], v156
	ds_read_b128 v[148:151], v156 offset:1024
	ds_read_b128 v[152:155], v156 offset:2048
	ds_read_b128 v[156:159], v156 offset:3072
	s_add_u32 s44, s44, 0x80000
	s_addc_u32 s45, s45, 0
	s_mov_b32 m0, s51
	v_lshl_add_u64 v[226:227], s[44:45], 0, v[168:169]
	ds_read_b128 v[160:163], v207 offset:32768
	ds_read_b128 v[164:167], v207 offset:33792
	ds_read_b128 v[186:189], v207 offset:34816
	ds_read_b128 v[190:193], v207 offset:35840
	ds_read_b128 v[194:197], v207 offset:36864
	ds_read_b128 v[198:201], v207 offset:37888
	ds_read_b128 v[210:213], v207 offset:38912
	ds_read_b128 v[214:217], v207 offset:39936
	global_load_lds_dwordx4 v[226:227], off
	v_lshl_add_u64 v[226:227], s[44:45], 0, v[172:173]
	s_mov_b32 m0, s52
	s_nop 0
	global_load_lds_dwordx4 v[226:227], off
	s_waitcnt vmcnt(8)
	s_waitcnt lgkmcnt(0)
	s_barrier
	v_mfma_f32_16x16x32_bf16 v[140:143], v[56:59], v[160:163], v[140:143]
	v_mfma_f32_16x16x32_bf16 v[136:139], v[64:67], v[160:163], v[136:139]
	v_mfma_f32_16x16x32_bf16 v[124:127], v[56:59], v[186:189], v[124:127]
	v_mfma_f32_16x16x32_bf16 v[120:123], v[64:67], v[186:189], v[120:123]
	v_mfma_f32_16x16x32_bf16 v[108:111], v[56:59], v[194:197], v[108:111]
	v_mfma_f32_16x16x32_bf16 v[104:107], v[64:67], v[194:197], v[104:107]
	v_mfma_f32_16x16x32_bf16 v[92:95], v[56:59], v[210:213], v[92:95]
	v_mfma_f32_16x16x32_bf16 v[88:91], v[64:67], v[210:213], v[88:91]
	v_mfma_f32_16x16x32_bf16 v[140:143], v[60:63], v[164:167], v[140:143]
	v_mfma_f32_16x16x32_bf16 v[136:139], v[68:71], v[164:167], v[136:139]
	v_mfma_f32_16x16x32_bf16 v[124:127], v[60:63], v[190:193], v[124:127]
	v_mfma_f32_16x16x32_bf16 v[120:123], v[68:71], v[190:193], v[120:123]
	v_mfma_f32_16x16x32_bf16 v[108:111], v[60:63], v[198:201], v[108:111]
	v_mfma_f32_16x16x32_bf16 v[104:107], v[68:71], v[198:201], v[104:107]
	v_mfma_f32_16x16x32_bf16 v[92:95], v[60:63], v[214:217], v[92:95]
	v_mfma_f32_16x16x32_bf16 v[88:91], v[68:71], v[214:217], v[88:91]
	v_mfma_f32_16x16x32_bf16 v[132:135], v[144:147], v[160:163], v[132:135]
	v_mfma_f32_16x16x32_bf16 v[128:131], v[152:155], v[160:163], v[128:131]
	v_mfma_f32_16x16x32_bf16 v[116:119], v[144:147], v[186:189], v[116:119]
	v_mfma_f32_16x16x32_bf16 v[112:115], v[152:155], v[186:189], v[112:115]
	v_mfma_f32_16x16x32_bf16 v[100:103], v[144:147], v[194:197], v[100:103]
	v_mfma_f32_16x16x32_bf16 v[96:99], v[152:155], v[194:197], v[96:99]
	v_mfma_f32_16x16x32_bf16 v[84:87], v[144:147], v[210:213], v[84:87]
	v_mfma_f32_16x16x32_bf16 v[80:83], v[152:155], v[210:213], v[80:83]
	v_mfma_f32_16x16x32_bf16 v[132:135], v[148:151], v[164:167], v[132:135]
	v_mfma_f32_16x16x32_bf16 v[128:131], v[156:159], v[164:167], v[128:131]
	v_mfma_f32_16x16x32_bf16 v[116:119], v[148:151], v[190:193], v[116:119]
	v_mfma_f32_16x16x32_bf16 v[112:115], v[156:159], v[190:193], v[112:115]
	v_mfma_f32_16x16x32_bf16 v[100:103], v[148:151], v[198:201], v[100:103]
	v_mfma_f32_16x16x32_bf16 v[96:99], v[156:159], v[198:201], v[96:99]
	v_mfma_f32_16x16x32_bf16 v[84:87], v[148:151], v[214:217], v[84:87]
	v_mfma_f32_16x16x32_bf16 v[80:83], v[156:159], v[214:217], v[80:83]
	s_barrier
	s_add_i32 s44, s66, s48
	v_lshl_add_u64 v[218:219], v[218:219], 0, s[18:19]
	s_mov_b32 m0, s44
	ds_read_b128 v[160:163], v207 offset:49152
	ds_read_b128 v[164:167], v207 offset:50176
	ds_read_b128 v[186:189], v207 offset:51200
	ds_read_b128 v[190:193], v207 offset:52224
	ds_read_b128 v[194:197], v207 offset:53248
	ds_read_b128 v[198:201], v207 offset:54272
	ds_read_b128 v[210:213], v207 offset:55296
	ds_read_b128 v[214:217], v207 offset:56320
	global_load_lds_dwordx4 v[218:219], off
	s_add_i32 m0, s44, 0x2000
	s_add_u32 s42, s42, 0x80080
	v_lshl_add_u64 v[218:219], v[220:221], 0, s[18:19]
	s_addc_u32 s43, s43, 0
	s_add_i32 s44, s67, s48
	global_load_lds_dwordx4 v[218:219], off
	v_lshl_add_u64 v[218:219], s[42:43], 0, v[170:171]
	s_mov_b32 m0, s44
	s_nop 0
	global_load_lds_dwordx4 v[218:219], off
	v_lshl_add_u64 v[218:219], s[42:43], 0, v[174:175]
	s_add_i32 m0, s44, 0x2000
	s_nop 0
	global_load_lds_dwordx4 v[218:219], off
	v_lshl_add_u64 v[218:219], v[222:223], 0, s[18:19]
	s_mov_b32 m0, s54
	s_nop 0
	global_load_lds_dwordx4 v[218:219], off
	v_lshl_add_u64 v[218:219], v[224:225], 0, s[18:19]
	s_mov_b32 m0, s55
	s_nop 0
	global_load_lds_dwordx4 v[218:219], off
	s_waitcnt vmcnt(8)
	s_waitcnt lgkmcnt(0)
	s_barrier
	v_mfma_f32_16x16x32_bf16 v[76:79], v[56:59], v[160:163], v[76:79]
	v_mfma_f32_16x16x32_bf16 v[72:75], v[64:67], v[160:163], v[72:75]
	v_mfma_f32_16x16x32_bf16 v[44:47], v[56:59], v[186:189], v[44:47]
	v_mfma_f32_16x16x32_bf16 v[40:43], v[64:67], v[186:189], v[40:43]
	v_mfma_f32_16x16x32_bf16 v[28:31], v[56:59], v[194:197], v[28:31]
	v_mfma_f32_16x16x32_bf16 v[24:27], v[64:67], v[194:197], v[24:27]
	v_mfma_f32_16x16x32_bf16 v[12:15], v[56:59], v[210:213], v[12:15]
	v_mfma_f32_16x16x32_bf16 v[8:11], v[64:67], v[210:213], v[8:11]
	v_mfma_f32_16x16x32_bf16 v[76:79], v[60:63], v[164:167], v[76:79]
	v_mfma_f32_16x16x32_bf16 v[72:75], v[68:71], v[164:167], v[72:75]
	v_mfma_f32_16x16x32_bf16 v[44:47], v[60:63], v[190:193], v[44:47]
	v_mfma_f32_16x16x32_bf16 v[40:43], v[68:71], v[190:193], v[40:43]
	v_mfma_f32_16x16x32_bf16 v[28:31], v[60:63], v[198:201], v[28:31]
	v_mfma_f32_16x16x32_bf16 v[24:27], v[68:71], v[198:201], v[24:27]
	v_mfma_f32_16x16x32_bf16 v[12:15], v[60:63], v[214:217], v[12:15]
	v_mfma_f32_16x16x32_bf16 v[8:11], v[68:71], v[214:217], v[8:11]
	v_mfma_f32_16x16x32_bf16 v[48:51], v[144:147], v[160:163], v[48:51]
	v_mfma_f32_16x16x32_bf16 v[60:63], v[148:151], v[164:167], v[48:51]
	v_mfma_f32_16x16x32_bf16 v[48:51], v[152:155], v[160:163], v[52:55]
	v_mfma_f32_16x16x32_bf16 v[36:39], v[144:147], v[186:189], v[36:39]
	v_mfma_f32_16x16x32_bf16 v[32:35], v[152:155], v[186:189], v[32:35]
	v_mfma_f32_16x16x32_bf16 v[20:23], v[144:147], v[194:197], v[20:23]
	v_mfma_f32_16x16x32_bf16 v[16:19], v[152:155], v[194:197], v[16:19]
	v_mfma_f32_16x16x32_bf16 v[4:7], v[144:147], v[210:213], v[4:7]
	v_mfma_f32_16x16x32_bf16 v[0:3], v[152:155], v[210:213], v[0:3]
	v_mfma_f32_16x16x32_bf16 v[52:55], v[156:159], v[164:167], v[48:51]
	v_mfma_f32_16x16x32_bf16 v[36:39], v[148:151], v[190:193], v[36:39]
	v_mfma_f32_16x16x32_bf16 v[32:35], v[156:159], v[190:193], v[32:35]
	v_mfma_f32_16x16x32_bf16 v[20:23], v[148:151], v[198:201], v[20:23]
	v_mfma_f32_16x16x32_bf16 v[16:19], v[156:159], v[198:201], v[16:19]
	v_mfma_f32_16x16x32_bf16 v[4:7], v[148:151], v[214:217], v[4:7]
	v_mfma_f32_16x16x32_bf16 v[0:3], v[156:159], v[214:217], v[0:3]
	s_barrier
	s_add_i32 s65, s65, 2
	s_add_u32 s63, s63, 0x100
	s_addc_u32 s64, s64, 0
	s_add_u32 s40, s40, 0x100
	s_addc_u32 s41, s41, 0
	s_cmp_gt_u32 s65, 29
	s_cbranch_scc0 .LBB0_1487
	s_setprio 0
	s_and_b64 vcc, exec, s[20:21]
	s_cbranch_vccz .LBB0_1490
	s_barrier
